# GEMM epilogue stores write-through (sc1) so the phase-end release fence has little dirty L2 to write back
# baseline (speedup 1.0000x reference)
; __device__ __forceinline__ unsigned cvt_pk_bf16(float lo, float hi) { const f32x2_t v = {lo, hi}; const bf16x2_t b = __builtin_convertvector(v, bf16x2_t); return __builtin_bit_cast(unsigned, b); }
; __device__ __forceinline__ unsigned cvt_pk_f16(float lo, float hi) { const f32x2 v = {lo, hi}; const h16x2_t h = __builtin_convertvector(v, h16x2_t); return __builtin_bit_cast(unsigned, h); }
; __device__ __forceinline__ u64 ssq_fix(float s) { return (u64)__float2ull_rn(s * 16777216.0f); }
;     __device__ __forceinline__ void operator()(const Acc& acc, const Unit& u, int wr, int wc, int fr, int fq) const {
;         const int row0 = u.pm * BM + wr * 64 + fr, col0 = u.pn * BM + wc * 32 + 8 * fq;
; #pragma unroll
;         for (int ai = 0; ai < 2; ++ai)
; #pragma unroll
;             for (int m = 0; m < 4; ++m) {
;                 asm volatile("" ::: "memory");
;                 const int r = row0 + ai * HALF + m * 16; float part = 0.f;
; #pragma unroll
;                 for (int bj = 0; bj < 2; ++bj) {
;                     const size_t off = (size_t)r * D + col0 + bj * HALF;
;                     const u32x4 hw = *(const u32x4*)(H16 + off);
;                     const f32x2 a = unpk_f16(hw.x), b2 = unpk_f16(hw.y), c = unpk_f16(hw.z), d = unpk_f16(hw.w);
;                     f32x4 v0, v1;
;                     v0[0] = a.x + acc[ai][bj][m][0][0]; v0[1] = a.y + acc[ai][bj][m][0][1]; v0[2] = b2.x + acc[ai][bj][m][0][2]; v0[3] = b2.y + acc[ai][bj][m][0][3];
;                     v1[0] = c.x + acc[ai][bj][m][1][0]; v1[1] = c.y + acc[ai][bj][m][1][1]; v1[2] = d.x + acc[ai][bj][m][1][2]; v1[3] = d.y + acc[ai][bj][m][1][3];
;                     u32x4 w; w.x = cvt_pk_bf16(v0[0], v0[1]); w.y = cvt_pk_bf16(v0[2], v0[3]); w.z = cvt_pk_bf16(v1[0], v1[1]); w.w = cvt_pk_bf16(v1[2], v1[3]);
;                     u32x4 hq; hq.x = cvt_pk_f16(v0[0], v0[1]); hq.y = cvt_pk_f16(v0[2], v0[3]); hq.z = cvt_pk_f16(v1[0], v1[1]); hq.w = cvt_pk_f16(v1[2], v1[3]);
;                     if (!dry) { *(u32x4*)(HB + off) = w; *(u32x4*)(H16 + off) = hq; }
;                     part += v0[0] * v0[0] + v0[1] * v0[1] + v0[2] * v0[2] + v0[3] * v0[3] + v1[0] * v1[0] + v1[1] * v1[1] + v1[2] * v1[2] + v1[3] * v1[3];
;                 }
;                 part += __shfl_xor(part, 16); part += __shfl_xor(part, 32);
;                 if (fq == 0 && !dry) atomicAdd(ssq_out + r, ssq_fix(part));
.LBB0_43:
	v_lshl_add_u32 v142, s66, 8, v144
	v_lshl_or_b32 v140, s72, 8, v146
	v_ashrrev_i32_e32 v143, 31, v142
	v_ashrrev_i32_e32 v141, 31, v140
	v_lshlrev_b64 v[138:139], 11, v[142:143]
	v_lshl_add_u64 v[138:139], v[138:139], 0, v[140:141]
	v_lshlrev_b64 v[138:139], 1, v[138:139]
	v_mov_b32_e32 v214, v138
	global_load_dwordx4 v[170:173], v214, s[16:17]
	global_load_dwordx4 v[174:177], v214, s[16:17] offset:256
	v_add_u32_e32 v215, 0x10000, v214
	global_load_dwordx4 v[178:181], v215, s[16:17]
	global_load_dwordx4 v[182:185], v215, s[16:17] offset:256
	v_add_u32_e32 v215, 0x20000, v214
	global_load_dwordx4 v[186:189], v215, s[16:17]
	global_load_dwordx4 v[190:193], v215, s[16:17] offset:256
	v_add_u32_e32 v215, 0x30000, v214
	global_load_dwordx4 v[194:197], v215, s[16:17]
	global_load_dwordx4 v[198:201], v215, s[16:17] offset:256
	v_add_u32_e32 v215, 0x80000, v214
	global_load_dwordx4 v[202:205], v215, s[16:17]
	global_load_dwordx4 v[206:209], v215, s[16:17] offset:256
	v_add_u32_e32 v215, 0x90000, v214
	global_load_dwordx4 v[210:213], v215, s[16:17]
	v_lshl_add_u64 v[152:153], s[16:17], 0, v[138:139]
	s_waitcnt vmcnt(10)
	s_nop 1
	v_mov_b64_e32 v[148:149], v[170:171]
	v_mov_b64_e32 v[150:151], v[172:173]
	global_load_dwordx4 v[170:173], v215, s[16:17] offset:256
	v_lshl_add_u64 v[158:159], s[80:81], 0, v[138:139]
	v_cvt_f32_f16_e32 v154, v148
	v_cvt_f32_f16_sdwa v155, v148 dst_sel:DWORD dst_unused:UNUSED_PAD src0_sel:WORD_1
	v_cvt_f32_f16_e32 v148, v149
	v_cvt_f32_f16_sdwa v149, v149 dst_sel:DWORD dst_unused:UNUSED_PAD src0_sel:WORD_1
	v_cvt_f32_f16_e32 v156, v150
	v_cvt_f32_f16_sdwa v157, v150 dst_sel:DWORD dst_unused:UNUSED_PAD src0_sel:WORD_1
	v_cvt_f32_f16_e32 v150, v151
	v_cvt_f32_f16_sdwa v151, v151 dst_sel:DWORD dst_unused:UNUSED_PAD src0_sel:WORD_1
	v_pk_add_f32 v[154:155], v[124:125], v[154:155]
	v_pk_add_f32 v[148:149], v[126:127], v[148:149]
	v_pk_add_f32 v[156:157], v[120:121], v[156:157]
	v_pk_add_f32 v[150:151], v[122:123], v[150:151]
	v_cvt_pk_bf16_f32 v126, v156, v157
	v_cvt_pk_bf16_f32 v127, v150, v151
	v_cvt_pk_bf16_f32 v125, v148, v149
	v_cvt_pk_bf16_f32 v124, v154, v155
	v_cvt_pk_f16_f32 v123, v150, v151
	v_cvt_pk_f16_f32 v122, v156, v157
	v_cvt_pk_f16_f32 v121, v148, v149
	v_cvt_pk_f16_f32 v120, v154, v155
	global_store_dwordx4 v[158:159], v[124:127], off sc1
	global_store_dwordx4 v[152:153], v[120:123], off sc1
	v_or_b32_e32 v152, 0x100, v138
	v_mov_b32_e32 v153, v139
	v_pk_mul_f32 v[124:125], v[154:155], v[154:155]
	v_lshl_add_u64 v[154:155], s[16:17], 0, v[152:153]
	s_waitcnt vmcnt(12)
	s_nop 1
	v_mov_b64_e32 v[120:121], v[174:175]
	v_mov_b64_e32 v[122:123], v[176:177]
	v_add_u32_e32 v215, 0xa0000, v214
	global_load_dwordx4 v[174:177], v215, s[16:17]
	v_pk_mul_f32 v[126:127], v[148:149], v[148:149]
	v_pk_mul_f32 v[148:149], v[156:157], v[156:157]
	v_lshl_add_u64 v[152:153], s[80:81], 0, v[152:153]
	v_pk_mul_f32 v[150:151], v[150:151], v[150:151]
	v_cvt_f32_f16_e32 v156, v120
	v_cvt_f32_f16_sdwa v157, v120 dst_sel:DWORD dst_unused:UNUSED_PAD src0_sel:WORD_1
	v_cvt_f32_f16_e32 v120, v121
	v_cvt_f32_f16_sdwa v121, v121 dst_sel:DWORD dst_unused:UNUSED_PAD src0_sel:WORD_1
	v_cvt_f32_f16_e32 v158, v122
	v_cvt_f32_f16_sdwa v159, v122 dst_sel:DWORD dst_unused:UNUSED_PAD src0_sel:WORD_1
	v_cvt_f32_f16_e32 v122, v123
	v_cvt_f32_f16_sdwa v123, v123 dst_sel:DWORD dst_unused:UNUSED_PAD src0_sel:WORD_1
	v_pk_add_f32 v[156:157], v[116:117], v[156:157]
	v_pk_add_f32 v[120:121], v[118:119], v[120:121]
	v_pk_add_f32 v[158:159], v[112:113], v[158:159]
	v_pk_add_f32 v[122:123], v[114:115], v[122:123]
	v_cvt_pk_f16_f32 v113, v120, v121
	v_cvt_pk_f16_f32 v112, v156, v157
	v_cvt_pk_bf16_f32 v119, v122, v123
	v_cvt_pk_bf16_f32 v118, v158, v159
	v_cvt_pk_bf16_f32 v117, v120, v121
	v_cvt_pk_bf16_f32 v116, v156, v157
	v_cvt_pk_f16_f32 v115, v122, v123
	v_cvt_pk_f16_f32 v114, v158, v159
	global_store_dwordx4 v[152:153], v[116:119], off sc1
	global_store_dwordx4 v[154:155], v[112:115], off sc1
	s_nop 0
	v_pk_mul_f32 v[116:117], v[158:159], v[158:159]
	v_pk_mul_f32 v[112:113], v[156:157], v[156:157]
	v_pk_mul_f32 v[114:115], v[120:121], v[120:121]
	v_add_f32_e32 v112, v112, v113
	v_add_f32_e32 v113, v124, v125
	v_add_f32_e32 v112, v114, v112
	v_add_f32_e32 v113, v126, v113
	v_add_f32_e32 v112, v115, v112
	v_add_f32_e32 v113, v127, v113
	v_add_f32_e32 v112, v116, v112
	v_add_f32_e32 v113, v148, v113
	v_pk_mul_f32 v[118:119], v[122:123], v[122:123]
	v_add_f32_e32 v112, v117, v112
	v_add_f32_e32 v113, v149, v113
	v_add_f32_e32 v112, v118, v112
	v_add_f32_e32 v113, v150, v113
	v_add_f32_e32 v112, v119, v112
	v_add_f32_e32 v113, v151, v113
	v_and_b32_e32 v114, 64, v240
	v_add_f32_e32 v112, v113, v112
	v_xor_b32_e32 v113, 16, v240
	v_add_u32_e32 v115, 64, v114
	v_cmp_lt_i32_e32 vcc, v113, v115
	s_nop 1
	v_cndmask_b32_e32 v113, v240, v113, vcc
	v_lshlrev_b32_e32 v116, 2, v113
	ds_bpermute_b32 v113, v116, v112
	s_waitcnt lgkmcnt(0)
	v_add_f32_e32 v114, v112, v113
	v_xor_b32_e32 v112, 32, v240
	v_cmp_lt_i32_e32 vcc, v112, v115
	s_nop 1
	v_cndmask_b32_e32 v112, v240, v112, vcc
	v_lshlrev_b32_e32 v117, 2, v112
	ds_bpermute_b32 v115, v117, v114
	v_lshl_add_u64 v[112:113], v[142:143], 3, s[18:19]
	s_and_saveexec_b64 s[2:3], s[4:5]
	s_cbranch_execz .LBB0_45
	s_waitcnt lgkmcnt(0)
	v_add_f32_e32 v114, v114, v115
	v_mul_f32_e32 v114, 0x4b800000, v114
	v_rndne_f32_e32 v114, v114
	v_mul_f32_e32 v115, 0x2f800000, v114
	v_floor_f32_e32 v115, v115
	v_fmac_f32_e32 v114, 0xcf800000, v115
	v_cvt_u32_f32_e32 v114, v114
	v_cvt_u32_f32_e32 v115, v115
	global_atomic_add_x2 v[112:113], v[114:115], off
; __device__ __forceinline__ unsigned cvt_pk_bf16(float lo, float hi) { const f32x2_t v = {lo, hi}; const bf16x2_t b = __builtin_convertvector(v, bf16x2_t); return __builtin_bit_cast(unsigned, b); }
; __device__ __forceinline__ unsigned cvt_pk_f16(float lo, float hi) { const f32x2 v = {lo, hi}; const h16x2_t h = __builtin_convertvector(v, h16x2_t); return __builtin_bit_cast(unsigned, h); }
; __device__ __forceinline__ f32x2 unpk_f16(unsigned u) { const h16x2_t h = __builtin_bit_cast(h16x2_t, u); return __builtin_convertvector(h, f32x2); }
; __device__ __forceinline__ u64 ssq_fix(float s) { return (u64)__float2ull_rn(s * 16777216.0f); }
;     __device__ __forceinline__ void operator()(const Acc& acc, const Unit& u, int wr, int wc, int fr, int fq) const {
;     ...
;             for (int m = 0; m < 4; ++m) {
;                 asm volatile("" ::: "memory");
;                 const int r = row0 + ai * HALF + m * 16; float part = 0.f;
; #pragma unroll
;                 for (int bj = 0; bj < 2; ++bj) {
;                     const size_t off = (size_t)r * D + col0 + bj * HALF;
;                     const u32x4 hw = *(const u32x4*)(H16 + off);
;                     const f32x2 a = unpk_f16(hw.x), b2 = unpk_f16(hw.y), c = unpk_f16(hw.z), d = unpk_f16(hw.w);
;                     f32x4 v0, v1;
;                     v0[0] = a.x + acc[ai][bj][m][0][0]; v0[1] = a.y + acc[ai][bj][m][0][1]; v0[2] = b2.x + acc[ai][bj][m][0][2]; v0[3] = b2.y + acc[ai][bj][m][0][3];
;                     v1[0] = c.x + acc[ai][bj][m][1][0]; v1[1] = c.y + acc[ai][bj][m][1][1]; v1[2] = d.x + acc[ai][bj][m][1][2]; v1[3] = d.y + acc[ai][bj][m][1][3];
;                     u32x4 w; w.x = cvt_pk_bf16(v0[0], v0[1]); w.y = cvt_pk_bf16(v0[2], v0[3]); w.z = cvt_pk_bf16(v1[0], v1[1]); w.w = cvt_pk_bf16(v1[2], v1[3]);
;                     u32x4 hq; hq.x = cvt_pk_f16(v0[0], v0[1]); hq.y = cvt_pk_f16(v0[2], v0[3]); hq.z = cvt_pk_f16(v1[0], v1[1]); hq.w = cvt_pk_f16(v1[2], v1[3]);
;                     if (!dry) { *(u32x4*)(HB + off) = w; *(u32x4*)(H16 + off) = hq; }
;                     part += v0[0] * v0[0] + v0[1] * v0[1] + v0[2] * v0[2] + v0[3] * v0[3] + v1[0] * v1[0] + v1[1] * v1[1] + v1[2] * v1[2] + v1[3] * v1[3];
;                 }
;                 part += __shfl_xor(part, 16); part += __shfl_xor(part, 32);
;                 if (fq == 0 && !dry) atomicAdd(ssq_out + r, ssq_fix(part));
.LBB0_45:
	s_or_b64 exec, exec, s[2:3]
	v_or_b32_e32 v114, 16, v142
	s_waitcnt lgkmcnt(0)
	v_ashrrev_i32_e32 v115, 31, v114
	v_lshlrev_b64 v[114:115], 11, v[114:115]
	v_lshl_add_u64 v[114:115], v[114:115], 0, v[140:141]
	v_lshlrev_b64 v[114:115], 1, v[114:115]
	v_lshl_add_u64 v[122:123], s[16:17], 0, v[114:115]
	s_waitcnt vmcnt(14)
	s_nop 1
	v_mov_b64_e32 v[118:119], v[178:179]
	v_mov_b64_e32 v[120:121], v[180:181]
	global_load_dwordx4 v[178:181], v215, s[16:17] offset:256
	v_lshl_add_u64 v[148:149], s[80:81], 0, v[114:115]
	v_or_b32_e32 v114, 0x100, v114
	v_cvt_f32_f16_e32 v124, v118
	v_cvt_f32_f16_sdwa v125, v118 dst_sel:DWORD dst_unused:UNUSED_PAD src0_sel:WORD_1
	v_cvt_f32_f16_e32 v118, v119
	v_cvt_f32_f16_sdwa v119, v119 dst_sel:DWORD dst_unused:UNUSED_PAD src0_sel:WORD_1
	v_cvt_f32_f16_e32 v126, v120
	v_cvt_f32_f16_sdwa v127, v120 dst_sel:DWORD dst_unused:UNUSED_PAD src0_sel:WORD_1
	v_cvt_f32_f16_e32 v120, v121
	v_cvt_f32_f16_sdwa v121, v121 dst_sel:DWORD dst_unused:UNUSED_PAD src0_sel:WORD_1
	v_pk_add_f32 v[124:125], v[108:109], v[124:125]
	v_pk_add_f32 v[118:119], v[110:111], v[118:119]
	v_pk_add_f32 v[126:127], v[104:105], v[126:127]
	v_pk_add_f32 v[120:121], v[106:107], v[120:121]
	v_cvt_pk_bf16_f32 v110, v126, v127
	v_cvt_pk_bf16_f32 v111, v120, v121
	v_cvt_pk_bf16_f32 v109, v118, v119
	v_cvt_pk_bf16_f32 v108, v124, v125
	v_cvt_pk_f16_f32 v107, v120, v121
	v_cvt_pk_f16_f32 v106, v126, v127
	v_cvt_pk_f16_f32 v105, v118, v119
	v_cvt_pk_f16_f32 v104, v124, v125
	global_store_dwordx4 v[148:149], v[108:111], off sc1
	global_store_dwordx4 v[122:123], v[104:107], off sc1
	v_lshl_add_u64 v[122:123], s[16:17], 0, v[114:115]
	v_pk_mul_f32 v[108:109], v[118:119], v[118:119]
	v_pk_mul_f32 v[104:105], v[120:121], v[120:121]
	s_waitcnt vmcnt(16)
	s_nop 1
	v_mov_b64_e32 v[118:119], v[182:183]
	v_mov_b64_e32 v[120:121], v[184:185]
	v_add_u32_e32 v215, 0xb0000, v214
	global_load_dwordx4 v[182:185], v215, s[16:17]
	v_pk_mul_f32 v[110:111], v[124:125], v[124:125]
	v_pk_mul_f32 v[106:107], v[126:127], v[126:127]
	v_lshl_add_u64 v[114:115], s[80:81], 0, v[114:115]
	v_cvt_f32_f16_e32 v124, v118
	v_cvt_f32_f16_sdwa v125, v118 dst_sel:DWORD dst_unused:UNUSED_PAD src0_sel:WORD_1
	v_cvt_f32_f16_e32 v118, v119
	v_cvt_f32_f16_sdwa v119, v119 dst_sel:DWORD dst_unused:UNUSED_PAD src0_sel:WORD_1
	v_cvt_f32_f16_e32 v126, v120
	v_cvt_f32_f16_sdwa v127, v120 dst_sel:DWORD dst_unused:UNUSED_PAD src0_sel:WORD_1
	v_cvt_f32_f16_e32 v120, v121
	v_cvt_f32_f16_sdwa v121, v121 dst_sel:DWORD dst_unused:UNUSED_PAD src0_sel:WORD_1
	v_pk_add_f32 v[124:125], v[100:101], v[124:125]
	v_pk_add_f32 v[118:119], v[102:103], v[118:119]
	v_pk_add_f32 v[126:127], v[96:97], v[126:127]
	v_pk_add_f32 v[120:121], v[98:99], v[120:121]
	v_cvt_pk_f16_f32 v97, v118, v119
	v_cvt_pk_f16_f32 v96, v124, v125
	v_cvt_pk_bf16_f32 v103, v120, v121
	v_cvt_pk_bf16_f32 v102, v126, v127
	v_cvt_pk_bf16_f32 v101, v118, v119
	v_cvt_pk_bf16_f32 v100, v124, v125
	v_cvt_pk_f16_f32 v99, v120, v121
	v_cvt_pk_f16_f32 v98, v126, v127
	global_store_dwordx4 v[114:115], v[100:103], off sc1
	global_store_dwordx4 v[122:123], v[96:99], off sc1
	s_nop 0
	v_pk_mul_f32 v[100:101], v[126:127], v[126:127]
	v_pk_mul_f32 v[96:97], v[124:125], v[124:125]
	v_pk_mul_f32 v[98:99], v[118:119], v[118:119]
	v_add_f32_e32 v96, v96, v97
	v_add_f32_e32 v97, v110, v111
	v_add_f32_e32 v96, v98, v96
	v_add_f32_e32 v97, v108, v97
	v_add_f32_e32 v96, v99, v96
	v_add_f32_e32 v97, v109, v97
	v_add_f32_e32 v96, v100, v96
	v_add_f32_e32 v97, v106, v97
	v_pk_mul_f32 v[102:103], v[120:121], v[120:121]
	v_add_f32_e32 v96, v101, v96
	v_add_f32_e32 v97, v107, v97
	v_add_f32_e32 v96, v102, v96
	v_add_f32_e32 v97, v104, v97
	v_add_f32_e32 v96, v103, v96
	v_add_f32_e32 v97, v105, v97
	v_add_f32_e32 v96, v97, v96
	ds_bpermute_b32 v97, v116, v96
	s_waitcnt lgkmcnt(0)
	v_add_f32_e32 v96, v96, v97
	ds_bpermute_b32 v97, v117, v96
	s_and_saveexec_b64 s[2:3], s[4:5]
	s_cbranch_execz .LBB0_47
	s_waitcnt lgkmcnt(0)
	v_add_f32_e32 v96, v96, v97
	v_mul_f32_e32 v96, 0x4b800000, v96
	v_rndne_f32_e32 v96, v96
	v_mul_f32_e32 v97, 0x2f800000, v96
	v_floor_f32_e32 v97, v97
	v_fmac_f32_e32 v96, 0xcf800000, v97
	v_cvt_u32_f32_e32 v96, v96
	v_cvt_u32_f32_e32 v97, v97
	global_atomic_add_x2 v[112:113], v[96:97], off offset:128
; __device__ __forceinline__ unsigned cvt_pk_bf16(float lo, float hi) { const f32x2_t v = {lo, hi}; const bf16x2_t b = __builtin_convertvector(v, bf16x2_t); return __builtin_bit_cast(unsigned, b); }
; __device__ __forceinline__ unsigned cvt_pk_f16(float lo, float hi) { const f32x2 v = {lo, hi}; const h16x2_t h = __builtin_convertvector(v, h16x2_t); return __builtin_bit_cast(unsigned, h); }
; __device__ __forceinline__ f32x2 unpk_f16(unsigned u) { const h16x2_t h = __builtin_bit_cast(h16x2_t, u); return __builtin_convertvector(h, f32x2); }
; __device__ __forceinline__ u64 ssq_fix(float s) { return (u64)__float2ull_rn(s * 16777216.0f); }
;     __device__ __forceinline__ void operator()(const Acc& acc, const Unit& u, int wr, int wc, int fr, int fq) const {
;     ...
;             for (int m = 0; m < 4; ++m) {
;                 asm volatile("" ::: "memory");
;                 const int r = row0 + ai * HALF + m * 16; float part = 0.f;
; #pragma unroll
;                 for (int bj = 0; bj < 2; ++bj) {
;                     const size_t off = (size_t)r * D + col0 + bj * HALF;
;                     const u32x4 hw = *(const u32x4*)(H16 + off);
;                     const f32x2 a = unpk_f16(hw.x), b2 = unpk_f16(hw.y), c = unpk_f16(hw.z), d = unpk_f16(hw.w);
;                     f32x4 v0, v1;
;                     v0[0] = a.x + acc[ai][bj][m][0][0]; v0[1] = a.y + acc[ai][bj][m][0][1]; v0[2] = b2.x + acc[ai][bj][m][0][2]; v0[3] = b2.y + acc[ai][bj][m][0][3];
;                     v1[0] = c.x + acc[ai][bj][m][1][0]; v1[1] = c.y + acc[ai][bj][m][1][1]; v1[2] = d.x + acc[ai][bj][m][1][2]; v1[3] = d.y + acc[ai][bj][m][1][3];
;                     u32x4 w; w.x = cvt_pk_bf16(v0[0], v0[1]); w.y = cvt_pk_bf16(v0[2], v0[3]); w.z = cvt_pk_bf16(v1[0], v1[1]); w.w = cvt_pk_bf16(v1[2], v1[3]);
;                     u32x4 hq; hq.x = cvt_pk_f16(v0[0], v0[1]); hq.y = cvt_pk_f16(v0[2], v0[3]); hq.z = cvt_pk_f16(v1[0], v1[1]); hq.w = cvt_pk_f16(v1[2], v1[3]);
;                     if (!dry) { *(u32x4*)(HB + off) = w; *(u32x4*)(H16 + off) = hq; }
;                     part += v0[0] * v0[0] + v0[1] * v0[1] + v0[2] * v0[2] + v0[3] * v0[3] + v1[0] * v1[0] + v1[1] * v1[1] + v1[2] * v1[2] + v1[3] * v1[3];
;                 }
;                 part += __shfl_xor(part, 16); part += __shfl_xor(part, 32);
;                 if (fq == 0 && !dry) atomicAdd(ssq_out + r, ssq_fix(part));
.LBB0_47:
	s_or_b64 exec, exec, s[2:3]
	v_or_b32_e32 v96, 32, v142
	s_waitcnt lgkmcnt(0)
	v_ashrrev_i32_e32 v97, 31, v96
	v_lshlrev_b64 v[96:97], 11, v[96:97]
	v_lshl_add_u64 v[96:97], v[96:97], 0, v[140:141]
	v_lshlrev_b64 v[96:97], 1, v[96:97]
	v_lshl_add_u64 v[102:103], s[16:17], 0, v[96:97]
	s_waitcnt vmcnt(18)
	s_nop 1
	v_mov_b64_e32 v[98:99], v[186:187]
	v_mov_b64_e32 v[100:101], v[188:189]
	global_load_dwordx4 v[186:189], v215, s[16:17] offset:256
	v_lshl_add_u64 v[108:109], s[80:81], 0, v[96:97]
	v_or_b32_e32 v96, 0x100, v96
	v_cvt_f32_f16_e32 v104, v98
	v_cvt_f32_f16_sdwa v105, v98 dst_sel:DWORD dst_unused:UNUSED_PAD src0_sel:WORD_1
	v_cvt_f32_f16_e32 v98, v99
	v_cvt_f32_f16_sdwa v99, v99 dst_sel:DWORD dst_unused:UNUSED_PAD src0_sel:WORD_1
	v_cvt_f32_f16_e32 v106, v100
	v_cvt_f32_f16_sdwa v107, v100 dst_sel:DWORD dst_unused:UNUSED_PAD src0_sel:WORD_1
	v_cvt_f32_f16_e32 v100, v101
	v_cvt_f32_f16_sdwa v101, v101 dst_sel:DWORD dst_unused:UNUSED_PAD src0_sel:WORD_1
	v_pk_add_f32 v[104:105], v[92:93], v[104:105]
	v_pk_add_f32 v[98:99], v[94:95], v[98:99]
	v_pk_add_f32 v[106:107], v[88:89], v[106:107]
	v_pk_add_f32 v[100:101], v[90:91], v[100:101]
	v_cvt_pk_bf16_f32 v94, v106, v107
	v_cvt_pk_bf16_f32 v95, v100, v101
	v_cvt_pk_bf16_f32 v93, v98, v99
	v_cvt_pk_bf16_f32 v92, v104, v105
	v_cvt_pk_f16_f32 v91, v100, v101
	v_cvt_pk_f16_f32 v90, v106, v107
	v_cvt_pk_f16_f32 v89, v98, v99
	v_cvt_pk_f16_f32 v88, v104, v105
	global_store_dwordx4 v[108:109], v[92:95], off sc1
	global_store_dwordx4 v[102:103], v[88:91], off sc1
	v_lshl_add_u64 v[102:103], s[16:17], 0, v[96:97]
	v_pk_mul_f32 v[92:93], v[98:99], v[98:99]
	v_pk_mul_f32 v[88:89], v[100:101], v[100:101]
	s_waitcnt vmcnt(20)
	s_nop 1
	v_mov_b64_e32 v[98:99], v[190:191]
	v_mov_b64_e32 v[100:101], v[192:193]
	v_pk_mul_f32 v[94:95], v[104:105], v[104:105]
	v_pk_mul_f32 v[90:91], v[106:107], v[106:107]
	v_lshl_add_u64 v[96:97], s[80:81], 0, v[96:97]
	v_cvt_f32_f16_e32 v104, v98
	v_cvt_f32_f16_sdwa v105, v98 dst_sel:DWORD dst_unused:UNUSED_PAD src0_sel:WORD_1
	v_cvt_f32_f16_e32 v98, v99
	v_cvt_f32_f16_sdwa v99, v99 dst_sel:DWORD dst_unused:UNUSED_PAD src0_sel:WORD_1
	v_cvt_f32_f16_e32 v106, v100
	v_cvt_f32_f16_sdwa v107, v100 dst_sel:DWORD dst_unused:UNUSED_PAD src0_sel:WORD_1
	v_cvt_f32_f16_e32 v100, v101
	v_cvt_f32_f16_sdwa v101, v101 dst_sel:DWORD dst_unused:UNUSED_PAD src0_sel:WORD_1
	v_pk_add_f32 v[104:105], v[84:85], v[104:105]
	v_pk_add_f32 v[98:99], v[86:87], v[98:99]
	v_pk_add_f32 v[106:107], v[80:81], v[106:107]
	v_pk_add_f32 v[100:101], v[82:83], v[100:101]
	v_cvt_pk_f16_f32 v81, v98, v99
	v_cvt_pk_f16_f32 v80, v104, v105
	v_cvt_pk_bf16_f32 v87, v100, v101
	v_cvt_pk_bf16_f32 v86, v106, v107
	v_cvt_pk_bf16_f32 v85, v98, v99
	v_cvt_pk_bf16_f32 v84, v104, v105
	v_cvt_pk_f16_f32 v83, v100, v101
	v_cvt_pk_f16_f32 v82, v106, v107
	global_store_dwordx4 v[96:97], v[84:87], off sc1
	global_store_dwordx4 v[102:103], v[80:83], off sc1
	s_nop 0
	v_pk_mul_f32 v[84:85], v[106:107], v[106:107]
	v_pk_mul_f32 v[80:81], v[104:105], v[104:105]
	v_pk_mul_f32 v[82:83], v[98:99], v[98:99]
	v_add_f32_e32 v80, v80, v81
	v_add_f32_e32 v81, v94, v95
	v_add_f32_e32 v80, v82, v80
	v_add_f32_e32 v81, v92, v81
	v_add_f32_e32 v80, v83, v80
	v_add_f32_e32 v81, v93, v81
	v_add_f32_e32 v80, v84, v80
	v_add_f32_e32 v81, v90, v81
	v_pk_mul_f32 v[86:87], v[100:101], v[100:101]
	v_add_f32_e32 v80, v85, v80
	v_add_f32_e32 v81, v91, v81
	v_add_f32_e32 v80, v86, v80
	v_add_f32_e32 v81, v88, v81
	v_add_f32_e32 v80, v87, v80
	v_add_f32_e32 v81, v89, v81
	v_add_f32_e32 v80, v81, v80
	ds_bpermute_b32 v81, v116, v80
	s_waitcnt lgkmcnt(0)
	v_add_f32_e32 v80, v80, v81
	ds_bpermute_b32 v81, v117, v80
	s_and_saveexec_b64 s[2:3], s[4:5]
	s_mov_b64 s[48:49], s[12:13]
	s_cbranch_execz .LBB0_49
	s_waitcnt lgkmcnt(0)
	v_add_f32_e32 v80, v80, v81
	v_mul_f32_e32 v80, 0x4b800000, v80
	v_rndne_f32_e32 v80, v80
	v_mul_f32_e32 v81, 0x2f800000, v80
	v_floor_f32_e32 v81, v81
	v_fmac_f32_e32 v80, 0xcf800000, v81
	v_cvt_u32_f32_e32 v80, v80
	v_cvt_u32_f32_e32 v81, v81
	global_atomic_add_x2 v[112:113], v[80:81], off offset:256
.LBB0_49:
	s_or_b64 exec, exec, s[2:3]
	v_or_b32_e32 v80, 48, v142
	s_waitcnt lgkmcnt(0)
	v_ashrrev_i32_e32 v81, 31, v80
	v_lshlrev_b64 v[80:81], 11, v[80:81]
	v_lshl_add_u64 v[80:81], v[80:81], 0, v[140:141]
	v_lshlrev_b64 v[80:81], 1, v[80:81]
	v_lshl_add_u64 v[86:87], s[16:17], 0, v[80:81]
	s_waitcnt vmcnt(21)
	s_nop 1
	v_mov_b64_e32 v[82:83], v[194:195]
	v_mov_b64_e32 v[84:85], v[196:197]
	v_lshl_add_u64 v[92:93], s[80:81], 0, v[80:81]
	v_or_b32_e32 v80, 0x100, v80
	v_cvt_f32_f16_e32 v88, v82
	v_cvt_f32_f16_sdwa v89, v82 dst_sel:DWORD dst_unused:UNUSED_PAD src0_sel:WORD_1
	v_cvt_f32_f16_e32 v82, v83
	v_cvt_f32_f16_sdwa v83, v83 dst_sel:DWORD dst_unused:UNUSED_PAD src0_sel:WORD_1
	v_cvt_f32_f16_e32 v90, v84
	v_cvt_f32_f16_sdwa v91, v84 dst_sel:DWORD dst_unused:UNUSED_PAD src0_sel:WORD_1
	v_cvt_f32_f16_e32 v84, v85
	v_cvt_f32_f16_sdwa v85, v85 dst_sel:DWORD dst_unused:UNUSED_PAD src0_sel:WORD_1
	v_pk_add_f32 v[88:89], v[76:77], v[88:89]
	v_pk_add_f32 v[82:83], v[78:79], v[82:83]
	v_pk_add_f32 v[90:91], v[72:73], v[90:91]
	v_pk_add_f32 v[84:85], v[74:75], v[84:85]
	v_cvt_pk_bf16_f32 v78, v90, v91
	v_cvt_pk_bf16_f32 v79, v84, v85
	v_cvt_pk_bf16_f32 v77, v82, v83
	v_cvt_pk_bf16_f32 v76, v88, v89
	v_cvt_pk_f16_f32 v75, v84, v85
	v_cvt_pk_f16_f32 v74, v90, v91
	v_cvt_pk_f16_f32 v73, v82, v83
	v_cvt_pk_f16_f32 v72, v88, v89
	global_store_dwordx4 v[92:93], v[76:79], off sc1
	global_store_dwordx4 v[86:87], v[72:75], off sc1
	v_lshl_add_u64 v[86:87], s[16:17], 0, v[80:81]
	v_pk_mul_f32 v[76:77], v[82:83], v[82:83]
	v_pk_mul_f32 v[72:73], v[84:85], v[84:85]
	s_waitcnt vmcnt(22)
; __device__ __forceinline__ unsigned cvt_pk_bf16(float lo, float hi) { const f32x2_t v = {lo, hi}; const bf16x2_t b = __builtin_convertvector(v, bf16x2_t); return __builtin_bit_cast(unsigned, b); }
; __device__ __forceinline__ unsigned cvt_pk_f16(float lo, float hi) { const f32x2 v = {lo, hi}; const h16x2_t h = __builtin_convertvector(v, h16x2_t); return __builtin_bit_cast(unsigned, h); }
; __device__ __forceinline__ f32x2 unpk_f16(unsigned u) { const h16x2_t h = __builtin_bit_cast(h16x2_t, u); return __builtin_convertvector(h, f32x2); }
; __device__ __forceinline__ u64 ssq_fix(float s) { return (u64)__float2ull_rn(s * 16777216.0f); }
;     __device__ __forceinline__ void operator()(const Acc& acc, const Unit& u, int wr, int wc, int fr, int fq) const {
;     ...
;             for (int m = 0; m < 4; ++m) {
;                 asm volatile("" ::: "memory");
;                 const int r = row0 + ai * HALF + m * 16; float part = 0.f;
; #pragma unroll
;                 for (int bj = 0; bj < 2; ++bj) {
;                     const size_t off = (size_t)r * D + col0 + bj * HALF;
;                     const u32x4 hw = *(const u32x4*)(H16 + off);
;                     const f32x2 a = unpk_f16(hw.x), b2 = unpk_f16(hw.y), c = unpk_f16(hw.z), d = unpk_f16(hw.w);
;                     f32x4 v0, v1;
;                     v0[0] = a.x + acc[ai][bj][m][0][0]; v0[1] = a.y + acc[ai][bj][m][0][1]; v0[2] = b2.x + acc[ai][bj][m][0][2]; v0[3] = b2.y + acc[ai][bj][m][0][3];
;                     v1[0] = c.x + acc[ai][bj][m][1][0]; v1[1] = c.y + acc[ai][bj][m][1][1]; v1[2] = d.x + acc[ai][bj][m][1][2]; v1[3] = d.y + acc[ai][bj][m][1][3];
;                     u32x4 w; w.x = cvt_pk_bf16(v0[0], v0[1]); w.y = cvt_pk_bf16(v0[2], v0[3]); w.z = cvt_pk_bf16(v1[0], v1[1]); w.w = cvt_pk_bf16(v1[2], v1[3]);
;                     u32x4 hq; hq.x = cvt_pk_f16(v0[0], v0[1]); hq.y = cvt_pk_f16(v0[2], v0[3]); hq.z = cvt_pk_f16(v1[0], v1[1]); hq.w = cvt_pk_f16(v1[2], v1[3]);
;                     if (!dry) { *(u32x4*)(HB + off) = w; *(u32x4*)(H16 + off) = hq; }
;                     part += v0[0] * v0[0] + v0[1] * v0[1] + v0[2] * v0[2] + v0[3] * v0[3] + v1[0] * v1[0] + v1[1] * v1[1] + v1[2] * v1[2] + v1[3] * v1[3];
;                 }
;                 part += __shfl_xor(part, 16); part += __shfl_xor(part, 32);
;                 if (fq == 0 && !dry) atomicAdd(ssq_out + r, ssq_fix(part));
	s_nop 1
	v_mov_b64_e32 v[82:83], v[198:199]
	v_mov_b64_e32 v[84:85], v[200:201]
	v_pk_mul_f32 v[78:79], v[88:89], v[88:89]
	v_pk_mul_f32 v[74:75], v[90:91], v[90:91]
	v_lshl_add_u64 v[80:81], s[80:81], 0, v[80:81]
	v_cvt_f32_f16_e32 v88, v82
	v_cvt_f32_f16_sdwa v89, v82 dst_sel:DWORD dst_unused:UNUSED_PAD src0_sel:WORD_1
	v_cvt_f32_f16_e32 v82, v83
	v_cvt_f32_f16_sdwa v83, v83 dst_sel:DWORD dst_unused:UNUSED_PAD src0_sel:WORD_1
	v_cvt_f32_f16_e32 v90, v84
	v_cvt_f32_f16_sdwa v91, v84 dst_sel:DWORD dst_unused:UNUSED_PAD src0_sel:WORD_1
	v_cvt_f32_f16_e32 v84, v85
	v_cvt_f32_f16_sdwa v85, v85 dst_sel:DWORD dst_unused:UNUSED_PAD src0_sel:WORD_1
	v_pk_add_f32 v[88:89], v[68:69], v[88:89]
	v_pk_add_f32 v[82:83], v[70:71], v[82:83]
	v_pk_add_f32 v[90:91], v[64:65], v[90:91]
	v_pk_add_f32 v[84:85], v[66:67], v[84:85]
	v_cvt_pk_f16_f32 v65, v82, v83
	v_cvt_pk_f16_f32 v64, v88, v89
	v_cvt_pk_bf16_f32 v71, v84, v85
	v_cvt_pk_bf16_f32 v70, v90, v91
	v_cvt_pk_bf16_f32 v69, v82, v83
	v_cvt_pk_bf16_f32 v68, v88, v89
	v_cvt_pk_f16_f32 v67, v84, v85
	v_cvt_pk_f16_f32 v66, v90, v91
	global_store_dwordx4 v[80:81], v[68:71], off sc1
	global_store_dwordx4 v[86:87], v[64:67], off sc1
	s_nop 0
	v_pk_mul_f32 v[68:69], v[90:91], v[90:91]
	v_pk_mul_f32 v[64:65], v[88:89], v[88:89]
	v_pk_mul_f32 v[66:67], v[82:83], v[82:83]
	v_add_f32_e32 v64, v64, v65
	v_add_f32_e32 v65, v78, v79
	v_add_f32_e32 v64, v66, v64
	v_add_f32_e32 v65, v76, v65
	v_add_f32_e32 v64, v67, v64
	v_add_f32_e32 v65, v77, v65
	v_add_f32_e32 v64, v68, v64
	v_add_f32_e32 v65, v74, v65
	v_pk_mul_f32 v[70:71], v[84:85], v[84:85]
	v_add_f32_e32 v64, v69, v64
	v_add_f32_e32 v65, v75, v65
	v_add_f32_e32 v64, v70, v64
	v_add_f32_e32 v65, v72, v65
	v_add_f32_e32 v64, v71, v64
	v_add_f32_e32 v65, v73, v65
	v_add_f32_e32 v64, v65, v64
	ds_bpermute_b32 v65, v116, v64
	s_waitcnt lgkmcnt(0)
	v_add_f32_e32 v64, v64, v65
	ds_bpermute_b32 v65, v117, v64
	s_and_saveexec_b64 s[2:3], s[4:5]
	s_cbranch_execz .LBB0_51
	s_waitcnt lgkmcnt(0)
	v_add_f32_e32 v64, v64, v65
	v_mul_f32_e32 v64, 0x4b800000, v64
	v_rndne_f32_e32 v64, v64
	v_mul_f32_e32 v65, 0x2f800000, v64
	v_floor_f32_e32 v65, v65
	v_fmac_f32_e32 v64, 0xcf800000, v65
	v_cvt_u32_f32_e32 v64, v64
	v_cvt_u32_f32_e32 v65, v65
	global_atomic_add_x2 v[112:113], v[64:65], off offset:384
.LBB0_51:
	s_or_b64 exec, exec, s[2:3]
	v_lshl_add_u64 v[68:69], v[138:139], 0, s[74:75]
	v_lshl_add_u64 v[70:71], s[16:17], 0, v[68:69]
	s_waitcnt lgkmcnt(0)
	s_waitcnt vmcnt(23)
	s_nop 1
	v_mov_b64_e32 v[64:65], v[202:203]
	v_mov_b64_e32 v[66:67], v[204:205]
	v_lshl_add_u64 v[68:69], s[80:81], 0, v[68:69]
	s_mov_b64 s[2:3], 0x80100
	v_cvt_f32_f16_e32 v72, v64
	v_cvt_f32_f16_sdwa v73, v64 dst_sel:DWORD dst_unused:UNUSED_PAD src0_sel:WORD_1
	v_cvt_f32_f16_e32 v64, v65
	v_cvt_f32_f16_sdwa v65, v65 dst_sel:DWORD dst_unused:UNUSED_PAD src0_sel:WORD_1
	v_cvt_f32_f16_e32 v74, v66
	v_cvt_f32_f16_sdwa v75, v66 dst_sel:DWORD dst_unused:UNUSED_PAD src0_sel:WORD_1
	v_cvt_f32_f16_e32 v66, v67
	v_cvt_f32_f16_sdwa v67, v67 dst_sel:DWORD dst_unused:UNUSED_PAD src0_sel:WORD_1
	v_pk_add_f32 v[72:73], v[60:61], v[72:73]
	v_pk_add_f32 v[64:65], v[62:63], v[64:65]
	v_pk_add_f32 v[74:75], v[56:57], v[74:75]
	v_pk_add_f32 v[66:67], v[58:59], v[66:67]
	v_cvt_pk_bf16_f32 v62, v74, v75
	v_cvt_pk_bf16_f32 v63, v66, v67
	v_cvt_pk_bf16_f32 v61, v64, v65
	v_cvt_pk_bf16_f32 v60, v72, v73
	v_cvt_pk_f16_f32 v59, v66, v67
	v_cvt_pk_f16_f32 v58, v74, v75
	v_cvt_pk_f16_f32 v57, v64, v65
	v_cvt_pk_f16_f32 v56, v72, v73
	global_store_dwordx4 v[68:69], v[60:63], off sc1
	global_store_dwordx4 v[70:71], v[56:59], off sc1
	v_lshl_add_u64 v[68:69], v[138:139], 0, s[2:3]
	v_lshl_add_u64 v[70:71], s[16:17], 0, v[68:69]
	v_pk_mul_f32 v[60:61], v[64:65], v[64:65]
	v_pk_mul_f32 v[56:57], v[66:67], v[66:67]
	s_waitcnt vmcnt(24)
	s_nop 1
	v_mov_b64_e32 v[64:65], v[206:207]
	v_mov_b64_e32 v[66:67], v[208:209]
	v_pk_mul_f32 v[62:63], v[72:73], v[72:73]
	v_pk_mul_f32 v[58:59], v[74:75], v[74:75]
	v_lshl_add_u64 v[68:69], s[80:81], 0, v[68:69]
	v_cvt_f32_f16_e32 v72, v64
	v_cvt_f32_f16_sdwa v73, v64 dst_sel:DWORD dst_unused:UNUSED_PAD src0_sel:WORD_1
	v_cvt_f32_f16_e32 v64, v65
	v_cvt_f32_f16_sdwa v65, v65 dst_sel:DWORD dst_unused:UNUSED_PAD src0_sel:WORD_1
	v_cvt_f32_f16_e32 v74, v66
	v_cvt_f32_f16_sdwa v75, v66 dst_sel:DWORD dst_unused:UNUSED_PAD src0_sel:WORD_1
	v_cvt_f32_f16_e32 v66, v67
	v_cvt_f32_f16_sdwa v67, v67 dst_sel:DWORD dst_unused:UNUSED_PAD src0_sel:WORD_1
	v_pk_add_f32 v[72:73], v[52:53], v[72:73]
	v_pk_add_f32 v[64:65], v[54:55], v[64:65]
	v_pk_add_f32 v[74:75], v[48:49], v[74:75]
	v_pk_add_f32 v[66:67], v[50:51], v[66:67]
	v_cvt_pk_f16_f32 v49, v64, v65
	v_cvt_pk_f16_f32 v48, v72, v73
	v_cvt_pk_bf16_f32 v55, v66, v67
	v_cvt_pk_bf16_f32 v54, v74, v75
	v_cvt_pk_bf16_f32 v53, v64, v65
	v_cvt_pk_bf16_f32 v52, v72, v73
	v_cvt_pk_f16_f32 v51, v66, v67
	v_cvt_pk_f16_f32 v50, v74, v75
	global_store_dwordx4 v[68:69], v[52:55], off sc1
	global_store_dwordx4 v[70:71], v[48:51], off sc1
	s_nop 0
	v_pk_mul_f32 v[52:53], v[74:75], v[74:75]
	v_pk_mul_f32 v[48:49], v[72:73], v[72:73]
	v_pk_mul_f32 v[50:51], v[64:65], v[64:65]
	v_add_f32_e32 v48, v48, v49
	v_add_f32_e32 v49, v62, v63
	v_add_f32_e32 v48, v50, v48
	v_add_f32_e32 v49, v60, v49
	v_add_f32_e32 v48, v51, v48
	v_add_f32_e32 v49, v61, v49
	v_add_f32_e32 v48, v52, v48
	v_add_f32_e32 v49, v58, v49
	v_pk_mul_f32 v[54:55], v[66:67], v[66:67]
	v_add_f32_e32 v48, v53, v48
	v_add_f32_e32 v49, v59, v49
	v_add_f32_e32 v48, v54, v48
	v_add_f32_e32 v49, v56, v49
	v_add_f32_e32 v48, v55, v48
	v_add_f32_e32 v49, v57, v49
	v_add_f32_e32 v48, v49, v48
	ds_bpermute_b32 v49, v116, v48
	s_waitcnt lgkmcnt(0)
	v_add_f32_e32 v48, v48, v49
	ds_bpermute_b32 v49, v117, v48
	s_and_saveexec_b64 s[2:3], s[4:5]
	s_cbranch_execz .LBB0_53
	s_waitcnt lgkmcnt(0)
	v_add_f32_e32 v48, v48, v49
	v_mul_f32_e32 v48, 0x4b800000, v48
	v_rndne_f32_e32 v48, v48
	v_mul_f32_e32 v49, 0x2f800000, v48
	v_floor_f32_e32 v49, v49
	v_fmac_f32_e32 v48, 0xcf800000, v49
	v_cvt_u32_f32_e32 v48, v48
	v_cvt_u32_f32_e32 v49, v49
	global_atomic_add_x2 v[112:113], v[48:49], off offset:1024
; __device__ __forceinline__ unsigned cvt_pk_bf16(float lo, float hi) { const f32x2_t v = {lo, hi}; const bf16x2_t b = __builtin_convertvector(v, bf16x2_t); return __builtin_bit_cast(unsigned, b); }
; __device__ __forceinline__ unsigned cvt_pk_f16(float lo, float hi) { const f32x2 v = {lo, hi}; const h16x2_t h = __builtin_convertvector(v, h16x2_t); return __builtin_bit_cast(unsigned, h); }
; __device__ __forceinline__ f32x2 unpk_f16(unsigned u) { const h16x2_t h = __builtin_bit_cast(h16x2_t, u); return __builtin_convertvector(h, f32x2); }
; __device__ __forceinline__ u64 ssq_fix(float s) { return (u64)__float2ull_rn(s * 16777216.0f); }
;     __device__ __forceinline__ void operator()(const Acc& acc, const Unit& u, int wr, int wc, int fr, int fq) const {
;     ...
;             for (int m = 0; m < 4; ++m) {
;                 asm volatile("" ::: "memory");
;                 const int r = row0 + ai * HALF + m * 16; float part = 0.f;
; #pragma unroll
;                 for (int bj = 0; bj < 2; ++bj) {
;                     const size_t off = (size_t)r * D + col0 + bj * HALF;
;                     const u32x4 hw = *(const u32x4*)(H16 + off);
;                     const f32x2 a = unpk_f16(hw.x), b2 = unpk_f16(hw.y), c = unpk_f16(hw.z), d = unpk_f16(hw.w);
;                     f32x4 v0, v1;
;                     v0[0] = a.x + acc[ai][bj][m][0][0]; v0[1] = a.y + acc[ai][bj][m][0][1]; v0[2] = b2.x + acc[ai][bj][m][0][2]; v0[3] = b2.y + acc[ai][bj][m][0][3];
;                     v1[0] = c.x + acc[ai][bj][m][1][0]; v1[1] = c.y + acc[ai][bj][m][1][1]; v1[2] = d.x + acc[ai][bj][m][1][2]; v1[3] = d.y + acc[ai][bj][m][1][3];
;                     u32x4 w; w.x = cvt_pk_bf16(v0[0], v0[1]); w.y = cvt_pk_bf16(v0[2], v0[3]); w.z = cvt_pk_bf16(v1[0], v1[1]); w.w = cvt_pk_bf16(v1[2], v1[3]);
;                     u32x4 hq; hq.x = cvt_pk_f16(v0[0], v0[1]); hq.y = cvt_pk_f16(v0[2], v0[3]); hq.z = cvt_pk_f16(v1[0], v1[1]); hq.w = cvt_pk_f16(v1[2], v1[3]);
;                     if (!dry) { *(u32x4*)(HB + off) = w; *(u32x4*)(H16 + off) = hq; }
;                     part += v0[0] * v0[0] + v0[1] * v0[1] + v0[2] * v0[2] + v0[3] * v0[3] + v1[0] * v1[0] + v1[1] * v1[1] + v1[2] * v1[2] + v1[3] * v1[3];
;                 }
;                 part += __shfl_xor(part, 16); part += __shfl_xor(part, 32);
;                 if (fq == 0 && !dry) atomicAdd(ssq_out + r, ssq_fix(part));
.LBB0_53:
	s_or_b64 exec, exec, s[2:3]
	s_mov_b64 s[2:3], 0x90000
	v_lshl_add_u64 v[52:53], v[138:139], 0, s[2:3]
	v_lshl_add_u64 v[54:55], s[16:17], 0, v[52:53]
	s_waitcnt lgkmcnt(0)
	s_waitcnt vmcnt(25)
	s_nop 1
	v_mov_b64_e32 v[48:49], v[210:211]
	v_mov_b64_e32 v[50:51], v[212:213]
	v_lshl_add_u64 v[52:53], s[80:81], 0, v[52:53]
	s_mov_b64 s[2:3], 0x90100
	v_cvt_f32_f16_e32 v56, v48
	v_cvt_f32_f16_sdwa v57, v48 dst_sel:DWORD dst_unused:UNUSED_PAD src0_sel:WORD_1
	v_cvt_f32_f16_e32 v48, v49
	v_cvt_f32_f16_sdwa v49, v49 dst_sel:DWORD dst_unused:UNUSED_PAD src0_sel:WORD_1
	v_cvt_f32_f16_e32 v58, v50
	v_cvt_f32_f16_sdwa v59, v50 dst_sel:DWORD dst_unused:UNUSED_PAD src0_sel:WORD_1
	v_cvt_f32_f16_e32 v50, v51
	v_cvt_f32_f16_sdwa v51, v51 dst_sel:DWORD dst_unused:UNUSED_PAD src0_sel:WORD_1
	v_pk_add_f32 v[56:57], v[44:45], v[56:57]
	v_pk_add_f32 v[48:49], v[46:47], v[48:49]
	v_pk_add_f32 v[58:59], v[40:41], v[58:59]
	v_pk_add_f32 v[50:51], v[42:43], v[50:51]
	v_cvt_pk_bf16_f32 v46, v58, v59
	v_cvt_pk_bf16_f32 v47, v50, v51
	v_cvt_pk_bf16_f32 v45, v48, v49
	v_cvt_pk_bf16_f32 v44, v56, v57
	v_cvt_pk_f16_f32 v43, v50, v51
	v_cvt_pk_f16_f32 v42, v58, v59
	v_cvt_pk_f16_f32 v41, v48, v49
	v_cvt_pk_f16_f32 v40, v56, v57
	global_store_dwordx4 v[52:53], v[44:47], off sc1
	global_store_dwordx4 v[54:55], v[40:43], off sc1
	v_lshl_add_u64 v[52:53], v[138:139], 0, s[2:3]
	v_lshl_add_u64 v[54:55], s[16:17], 0, v[52:53]
	v_pk_mul_f32 v[44:45], v[48:49], v[48:49]
	v_pk_mul_f32 v[40:41], v[50:51], v[50:51]
	s_waitcnt vmcnt(26)
	s_nop 1
	v_mov_b64_e32 v[48:49], v[170:171]
	v_mov_b64_e32 v[50:51], v[172:173]
	v_pk_mul_f32 v[46:47], v[56:57], v[56:57]
	v_pk_mul_f32 v[42:43], v[58:59], v[58:59]
	v_lshl_add_u64 v[52:53], s[80:81], 0, v[52:53]
	v_cvt_f32_f16_e32 v56, v48
	v_cvt_f32_f16_sdwa v57, v48 dst_sel:DWORD dst_unused:UNUSED_PAD src0_sel:WORD_1
	v_cvt_f32_f16_e32 v48, v49
	v_cvt_f32_f16_sdwa v49, v49 dst_sel:DWORD dst_unused:UNUSED_PAD src0_sel:WORD_1
	v_cvt_f32_f16_e32 v58, v50
	v_cvt_f32_f16_sdwa v59, v50 dst_sel:DWORD dst_unused:UNUSED_PAD src0_sel:WORD_1
	v_cvt_f32_f16_e32 v50, v51
	v_cvt_f32_f16_sdwa v51, v51 dst_sel:DWORD dst_unused:UNUSED_PAD src0_sel:WORD_1
	v_pk_add_f32 v[56:57], v[36:37], v[56:57]
	v_pk_add_f32 v[48:49], v[38:39], v[48:49]
	v_pk_add_f32 v[58:59], v[32:33], v[58:59]
	v_pk_add_f32 v[50:51], v[34:35], v[50:51]
	v_cvt_pk_f16_f32 v33, v48, v49
	v_cvt_pk_f16_f32 v32, v56, v57
	v_cvt_pk_bf16_f32 v39, v50, v51
	v_cvt_pk_bf16_f32 v38, v58, v59
	v_cvt_pk_bf16_f32 v37, v48, v49
	v_cvt_pk_bf16_f32 v36, v56, v57
	v_cvt_pk_f16_f32 v35, v50, v51
	v_cvt_pk_f16_f32 v34, v58, v59
	global_store_dwordx4 v[52:53], v[36:39], off sc1
	global_store_dwordx4 v[54:55], v[32:35], off sc1
	s_nop 0
	v_pk_mul_f32 v[36:37], v[58:59], v[58:59]
	v_pk_mul_f32 v[32:33], v[56:57], v[56:57]
	v_pk_mul_f32 v[34:35], v[48:49], v[48:49]
	v_add_f32_e32 v32, v32, v33
	v_add_f32_e32 v33, v46, v47
	v_add_f32_e32 v32, v34, v32
	v_add_f32_e32 v33, v44, v33
	v_add_f32_e32 v32, v35, v32
	v_add_f32_e32 v33, v45, v33
	v_add_f32_e32 v32, v36, v32
	v_add_f32_e32 v33, v42, v33
	v_pk_mul_f32 v[38:39], v[50:51], v[50:51]
	v_add_f32_e32 v32, v37, v32
	v_add_f32_e32 v33, v43, v33
	v_add_f32_e32 v32, v38, v32
	v_add_f32_e32 v33, v40, v33
	v_add_f32_e32 v32, v39, v32
	v_add_f32_e32 v33, v41, v33
	v_add_f32_e32 v32, v33, v32
	ds_bpermute_b32 v33, v116, v32
	s_waitcnt lgkmcnt(0)
	v_add_f32_e32 v32, v32, v33
	ds_bpermute_b32 v33, v117, v32
	s_and_saveexec_b64 s[2:3], s[4:5]
	s_cbranch_execz .LBB0_55
	s_waitcnt lgkmcnt(0)
	v_add_f32_e32 v32, v32, v33
	v_mul_f32_e32 v32, 0x4b800000, v32
	v_rndne_f32_e32 v32, v32
	v_mul_f32_e32 v33, 0x2f800000, v32
	v_floor_f32_e32 v33, v33
	v_fmac_f32_e32 v32, 0xcf800000, v33
	v_cvt_u32_f32_e32 v32, v32
	v_cvt_u32_f32_e32 v33, v33
	global_atomic_add_x2 v[112:113], v[32:33], off offset:1152
.LBB0_55:
	s_or_b64 exec, exec, s[2:3]
	s_mov_b64 s[2:3], 0xa0000
	v_lshl_add_u64 v[36:37], v[138:139], 0, s[2:3]
	v_lshl_add_u64 v[38:39], s[16:17], 0, v[36:37]
	s_waitcnt lgkmcnt(0)
	s_waitcnt vmcnt(25)
	s_nop 1
	v_mov_b64_e32 v[32:33], v[174:175]
	v_mov_b64_e32 v[34:35], v[176:177]
	v_lshl_add_u64 v[36:37], s[80:81], 0, v[36:37]
	s_mov_b64 s[2:3], 0xa0100
	v_cvt_f32_f16_e32 v40, v32
	v_cvt_f32_f16_sdwa v41, v32 dst_sel:DWORD dst_unused:UNUSED_PAD src0_sel:WORD_1
	v_cvt_f32_f16_e32 v32, v33
	v_cvt_f32_f16_sdwa v33, v33 dst_sel:DWORD dst_unused:UNUSED_PAD src0_sel:WORD_1
	v_cvt_f32_f16_e32 v42, v34
	v_cvt_f32_f16_sdwa v43, v34 dst_sel:DWORD dst_unused:UNUSED_PAD src0_sel:WORD_1
	v_cvt_f32_f16_e32 v34, v35
	v_cvt_f32_f16_sdwa v35, v35 dst_sel:DWORD dst_unused:UNUSED_PAD src0_sel:WORD_1
	v_pk_add_f32 v[40:41], v[28:29], v[40:41]
	v_pk_add_f32 v[32:33], v[30:31], v[32:33]
	v_pk_add_f32 v[42:43], v[24:25], v[42:43]
	v_pk_add_f32 v[34:35], v[26:27], v[34:35]
	v_cvt_pk_bf16_f32 v30, v42, v43
	v_cvt_pk_bf16_f32 v31, v34, v35
	v_cvt_pk_bf16_f32 v29, v32, v33
	v_cvt_pk_bf16_f32 v28, v40, v41
	v_cvt_pk_f16_f32 v27, v34, v35
	v_cvt_pk_f16_f32 v26, v42, v43
	v_cvt_pk_f16_f32 v25, v32, v33
	v_cvt_pk_f16_f32 v24, v40, v41
	global_store_dwordx4 v[36:37], v[28:31], off sc1
	global_store_dwordx4 v[38:39], v[24:27], off sc1
	v_lshl_add_u64 v[36:37], v[138:139], 0, s[2:3]
	v_lshl_add_u64 v[38:39], s[16:17], 0, v[36:37]
	v_pk_mul_f32 v[28:29], v[32:33], v[32:33]
	v_pk_mul_f32 v[24:25], v[34:35], v[34:35]
	s_waitcnt vmcnt(24)
; __device__ __forceinline__ unsigned cvt_pk_bf16(float lo, float hi) { const f32x2_t v = {lo, hi}; const bf16x2_t b = __builtin_convertvector(v, bf16x2_t); return __builtin_bit_cast(unsigned, b); }
; __device__ __forceinline__ unsigned cvt_pk_f16(float lo, float hi) { const f32x2 v = {lo, hi}; const h16x2_t h = __builtin_convertvector(v, h16x2_t); return __builtin_bit_cast(unsigned, h); }
; __device__ __forceinline__ f32x2 unpk_f16(unsigned u) { const h16x2_t h = __builtin_bit_cast(h16x2_t, u); return __builtin_convertvector(h, f32x2); }
; __device__ __forceinline__ u64 ssq_fix(float s) { return (u64)__float2ull_rn(s * 16777216.0f); }
;     __device__ __forceinline__ void operator()(const Acc& acc, const Unit& u, int wr, int wc, int fr, int fq) const {
;     ...
;             for (int m = 0; m < 4; ++m) {
;                 asm volatile("" ::: "memory");
;                 const int r = row0 + ai * HALF + m * 16; float part = 0.f;
; #pragma unroll
;                 for (int bj = 0; bj < 2; ++bj) {
;                     const size_t off = (size_t)r * D + col0 + bj * HALF;
;                     const u32x4 hw = *(const u32x4*)(H16 + off);
;                     const f32x2 a = unpk_f16(hw.x), b2 = unpk_f16(hw.y), c = unpk_f16(hw.z), d = unpk_f16(hw.w);
;                     f32x4 v0, v1;
;                     v0[0] = a.x + acc[ai][bj][m][0][0]; v0[1] = a.y + acc[ai][bj][m][0][1]; v0[2] = b2.x + acc[ai][bj][m][0][2]; v0[3] = b2.y + acc[ai][bj][m][0][3];
;                     v1[0] = c.x + acc[ai][bj][m][1][0]; v1[1] = c.y + acc[ai][bj][m][1][1]; v1[2] = d.x + acc[ai][bj][m][1][2]; v1[3] = d.y + acc[ai][bj][m][1][3];
;                     u32x4 w; w.x = cvt_pk_bf16(v0[0], v0[1]); w.y = cvt_pk_bf16(v0[2], v0[3]); w.z = cvt_pk_bf16(v1[0], v1[1]); w.w = cvt_pk_bf16(v1[2], v1[3]);
;                     u32x4 hq; hq.x = cvt_pk_f16(v0[0], v0[1]); hq.y = cvt_pk_f16(v0[2], v0[3]); hq.z = cvt_pk_f16(v1[0], v1[1]); hq.w = cvt_pk_f16(v1[2], v1[3]);
;                     if (!dry) { *(u32x4*)(HB + off) = w; *(u32x4*)(H16 + off) = hq; }
;                     part += v0[0] * v0[0] + v0[1] * v0[1] + v0[2] * v0[2] + v0[3] * v0[3] + v1[0] * v1[0] + v1[1] * v1[1] + v1[2] * v1[2] + v1[3] * v1[3];
;                 }
;                 part += __shfl_xor(part, 16); part += __shfl_xor(part, 32);
;                 if (fq == 0 && !dry) atomicAdd(ssq_out + r, ssq_fix(part));
	s_nop 1
	v_mov_b64_e32 v[32:33], v[178:179]
	v_mov_b64_e32 v[34:35], v[180:181]
	v_pk_mul_f32 v[30:31], v[40:41], v[40:41]
	v_pk_mul_f32 v[26:27], v[42:43], v[42:43]
	v_lshl_add_u64 v[36:37], s[80:81], 0, v[36:37]
	v_cvt_f32_f16_e32 v40, v32
	v_cvt_f32_f16_sdwa v41, v32 dst_sel:DWORD dst_unused:UNUSED_PAD src0_sel:WORD_1
	v_cvt_f32_f16_e32 v32, v33
	v_cvt_f32_f16_sdwa v33, v33 dst_sel:DWORD dst_unused:UNUSED_PAD src0_sel:WORD_1
	v_cvt_f32_f16_e32 v42, v34
	v_cvt_f32_f16_sdwa v43, v34 dst_sel:DWORD dst_unused:UNUSED_PAD src0_sel:WORD_1
	v_cvt_f32_f16_e32 v34, v35
	v_cvt_f32_f16_sdwa v35, v35 dst_sel:DWORD dst_unused:UNUSED_PAD src0_sel:WORD_1
	v_pk_add_f32 v[40:41], v[20:21], v[40:41]
	v_pk_add_f32 v[32:33], v[22:23], v[32:33]
	v_pk_add_f32 v[42:43], v[16:17], v[42:43]
	v_pk_add_f32 v[34:35], v[18:19], v[34:35]
	v_cvt_pk_f16_f32 v17, v32, v33
	v_cvt_pk_f16_f32 v16, v40, v41
	v_cvt_pk_bf16_f32 v23, v34, v35
	v_cvt_pk_bf16_f32 v22, v42, v43
	v_cvt_pk_bf16_f32 v21, v32, v33
	v_cvt_pk_bf16_f32 v20, v40, v41
	v_cvt_pk_f16_f32 v19, v34, v35
	v_cvt_pk_f16_f32 v18, v42, v43
	global_store_dwordx4 v[36:37], v[20:23], off sc1
	global_store_dwordx4 v[38:39], v[16:19], off sc1
	s_nop 0
	v_pk_mul_f32 v[20:21], v[42:43], v[42:43]
	v_pk_mul_f32 v[16:17], v[40:41], v[40:41]
	v_pk_mul_f32 v[18:19], v[32:33], v[32:33]
	v_add_f32_e32 v16, v16, v17
	v_add_f32_e32 v17, v30, v31
	v_add_f32_e32 v16, v18, v16
	v_add_f32_e32 v17, v28, v17
	v_add_f32_e32 v16, v19, v16
	v_add_f32_e32 v17, v29, v17
	v_add_f32_e32 v16, v20, v16
	v_add_f32_e32 v17, v26, v17
	v_pk_mul_f32 v[22:23], v[34:35], v[34:35]
	v_add_f32_e32 v16, v21, v16
	v_add_f32_e32 v17, v27, v17
	v_add_f32_e32 v16, v22, v16
	v_add_f32_e32 v17, v24, v17
	v_add_f32_e32 v16, v23, v16
	v_add_f32_e32 v17, v25, v17
	v_add_f32_e32 v16, v17, v16
	ds_bpermute_b32 v17, v116, v16
	s_waitcnt lgkmcnt(0)
	v_add_f32_e32 v16, v16, v17
	ds_bpermute_b32 v17, v117, v16
	s_and_saveexec_b64 s[2:3], s[4:5]
	s_cbranch_execz .LBB0_57
	s_waitcnt lgkmcnt(0)
	v_add_f32_e32 v16, v16, v17
	v_mul_f32_e32 v16, 0x4b800000, v16
	v_rndne_f32_e32 v16, v16
	v_mul_f32_e32 v17, 0x2f800000, v16
	v_floor_f32_e32 v17, v17
	v_fmac_f32_e32 v16, 0xcf800000, v17
	v_cvt_u32_f32_e32 v16, v16
	v_cvt_u32_f32_e32 v17, v17
	global_atomic_add_x2 v[112:113], v[16:17], off offset:1280
.LBB0_57:
	s_or_b64 exec, exec, s[2:3]
	s_mov_b64 s[2:3], 0xb0000
	v_lshl_add_u64 v[20:21], v[138:139], 0, s[2:3]
	v_lshl_add_u64 v[22:23], s[16:17], 0, v[20:21]
	s_waitcnt lgkmcnt(0)
	s_waitcnt vmcnt(23)
	s_nop 1
	v_mov_b64_e32 v[16:17], v[182:183]
	v_mov_b64_e32 v[18:19], v[184:185]
	v_lshl_add_u64 v[20:21], s[80:81], 0, v[20:21]
	s_mov_b64 s[2:3], 0xb0100
	v_cvt_f32_f16_e32 v24, v16
	v_cvt_f32_f16_sdwa v25, v16 dst_sel:DWORD dst_unused:UNUSED_PAD src0_sel:WORD_1
	v_cvt_f32_f16_e32 v16, v17
	v_cvt_f32_f16_sdwa v17, v17 dst_sel:DWORD dst_unused:UNUSED_PAD src0_sel:WORD_1
	v_cvt_f32_f16_e32 v26, v18
	v_cvt_f32_f16_sdwa v27, v18 dst_sel:DWORD dst_unused:UNUSED_PAD src0_sel:WORD_1
	v_cvt_f32_f16_e32 v18, v19
	v_cvt_f32_f16_sdwa v19, v19 dst_sel:DWORD dst_unused:UNUSED_PAD src0_sel:WORD_1
	v_pk_add_f32 v[24:25], v[12:13], v[24:25]
	v_pk_add_f32 v[16:17], v[14:15], v[16:17]
	v_pk_add_f32 v[26:27], v[8:9], v[26:27]
	v_pk_add_f32 v[18:19], v[10:11], v[18:19]
	v_cvt_pk_bf16_f32 v14, v26, v27
	v_cvt_pk_bf16_f32 v15, v18, v19
	v_cvt_pk_bf16_f32 v13, v16, v17
	v_cvt_pk_bf16_f32 v12, v24, v25
	v_cvt_pk_f16_f32 v11, v18, v19
	v_cvt_pk_f16_f32 v10, v26, v27
	v_cvt_pk_f16_f32 v9, v16, v17
	v_cvt_pk_f16_f32 v8, v24, v25
	global_store_dwordx4 v[20:21], v[12:15], off sc1
	global_store_dwordx4 v[22:23], v[8:11], off sc1
	v_lshl_add_u64 v[20:21], v[138:139], 0, s[2:3]
	v_lshl_add_u64 v[22:23], s[16:17], 0, v[20:21]
	v_pk_mul_f32 v[12:13], v[16:17], v[16:17]
	v_pk_mul_f32 v[8:9], v[18:19], v[18:19]
	s_waitcnt vmcnt(22)
	s_nop 1
	v_mov_b64_e32 v[16:17], v[186:187]
	v_mov_b64_e32 v[18:19], v[188:189]
	v_pk_mul_f32 v[14:15], v[24:25], v[24:25]
	v_pk_mul_f32 v[10:11], v[26:27], v[26:27]
	v_lshl_add_u64 v[20:21], s[80:81], 0, v[20:21]
	v_cvt_f32_f16_e32 v24, v16
	v_cvt_f32_f16_sdwa v25, v16 dst_sel:DWORD dst_unused:UNUSED_PAD src0_sel:WORD_1
	v_cvt_f32_f16_e32 v16, v17
	v_cvt_f32_f16_sdwa v17, v17 dst_sel:DWORD dst_unused:UNUSED_PAD src0_sel:WORD_1
	v_cvt_f32_f16_e32 v26, v18
	v_cvt_f32_f16_sdwa v27, v18 dst_sel:DWORD dst_unused:UNUSED_PAD src0_sel:WORD_1
	v_cvt_f32_f16_e32 v18, v19
	v_cvt_f32_f16_sdwa v19, v19 dst_sel:DWORD dst_unused:UNUSED_PAD src0_sel:WORD_1
	v_pk_add_f32 v[24:25], v[4:5], v[24:25]
	v_pk_add_f32 v[16:17], v[6:7], v[16:17]
	v_pk_add_f32 v[26:27], v[0:1], v[26:27]
	v_pk_add_f32 v[18:19], v[2:3], v[18:19]
	v_cvt_pk_f16_f32 v1, v16, v17
	v_cvt_pk_f16_f32 v0, v24, v25
	v_cvt_pk_bf16_f32 v7, v18, v19
	v_cvt_pk_bf16_f32 v6, v26, v27
	v_cvt_pk_bf16_f32 v5, v16, v17
	v_cvt_pk_bf16_f32 v4, v24, v25
	v_cvt_pk_f16_f32 v3, v18, v19
	v_cvt_pk_f16_f32 v2, v26, v27
	global_store_dwordx4 v[20:21], v[4:7], off sc1
	global_store_dwordx4 v[22:23], v[0:3], off sc1
	s_nop 0
	v_pk_mul_f32 v[4:5], v[26:27], v[26:27]
	v_pk_mul_f32 v[0:1], v[24:25], v[24:25]
	v_pk_mul_f32 v[2:3], v[16:17], v[16:17]
	v_add_f32_e32 v0, v0, v1
	v_add_f32_e32 v1, v14, v15
	v_add_f32_e32 v0, v2, v0
	v_add_f32_e32 v1, v12, v1
	v_add_f32_e32 v0, v3, v0
	v_add_f32_e32 v1, v13, v1
	v_add_f32_e32 v0, v4, v0
	v_add_f32_e32 v1, v10, v1
	v_pk_mul_f32 v[6:7], v[18:19], v[18:19]
	v_add_f32_e32 v0, v5, v0
	v_add_f32_e32 v1, v11, v1
	v_add_f32_e32 v0, v6, v0
	v_add_f32_e32 v1, v8, v1
	v_add_f32_e32 v0, v7, v0
	v_add_f32_e32 v1, v9, v1
	v_add_f32_e32 v0, v1, v0
	ds_bpermute_b32 v1, v116, v0
	s_waitcnt lgkmcnt(0)
	v_add_f32_e32 v0, v0, v1
	ds_bpermute_b32 v1, v117, v0
	s_and_saveexec_b64 s[2:3], s[4:5]
	s_cbranch_execz .LBB0_59
	s_waitcnt lgkmcnt(0)
	v_add_f32_e32 v0, v0, v1
	v_mul_f32_e32 v0, 0x4b800000, v0
	v_rndne_f32_e32 v0, v0
	v_mul_f32_e32 v1, 0x2f800000, v0
	v_floor_f32_e32 v1, v1
	v_fmac_f32_e32 v0, 0xcf800000, v1
	v_cvt_u32_f32_e32 v0, v0
	v_cvt_u32_f32_e32 v1, v1
	global_atomic_add_x2 v[112:113], v[0:1], off offset:1408

; __device__ __forceinline__ unsigned cvt_pk_bf16(float lo, float hi) { const f32x2_t v = {lo, hi}; const bf16x2_t b = __builtin_convertvector(v, bf16x2_t); return __builtin_bit_cast(unsigned, b); }
; __device__ __forceinline__ float rstd_of(u64 ssq) { return frsq((float)ssq * (1.0f / (2048.0f * 16777216.0f)) + EPS); }
;     __device__ __forceinline__ void operator()(const Acc& acc, const Unit& u, int wr, int wc, int fr, int fq) const {
;         const int row0 = u.pm * BM + wr * 64 + fr, col0 = u.pn * BM + wc * 32 + 8 * fq;
; #pragma unroll
;         for (int ai = 0; ai < 2; ++ai)
; #pragma unroll
;             for (int m = 0; m < 4; ++m) {
;                 asm volatile("" ::: "memory");
;                 const int r = row0 + ai * HALF + m * 16; const float rs = rstd_of(ssq[r]);
; #pragma unroll
;                 for (int bj = 0; bj < 2; ++bj) {
;                     const f32x4 v0 = acc[ai][bj][m][0] * rs, v1 = acc[ai][bj][m][1] * rs;
;                     u32x4 w; w.x = cvt_pk_bf16(v0[0], v0[1]); w.y = cvt_pk_bf16(v0[2], v0[3]); w.z = cvt_pk_bf16(v1[0], v1[1]); w.w = cvt_pk_bf16(v1[2], v1[3]);
;                     *(u32x4*)(O + (size_t)r * ldc + col0 + bj * HALF) = w;
;                 }
;             }
.LBB0_96:
	v_lshl_add_u32 v140, s60, 8, v142
	v_ashrrev_i32_e32 v141, 31, v140
	v_lshl_add_u64 v[138:139], v[140:141], 3, s[10:11]
	global_load_dwordx2 v[148:149], v[138:139], off
	global_load_dwordx2 v[170:171], v[138:139], off offset:128
	global_load_dwordx2 v[172:173], v[138:139], off offset:256
	global_load_dwordx2 v[174:175], v[138:139], off offset:384
	global_load_dwordx2 v[176:177], v[138:139], off offset:1024
	global_load_dwordx2 v[178:179], v[138:139], off offset:1152
	global_load_dwordx2 v[180:181], v[138:139], off offset:1280
	global_load_dwordx2 v[182:183], v[138:139], off offset:1408
	v_lshl_or_b32 v146, s90, 8, v144
	v_ashrrev_i32_e32 v147, 31, v146
	s_mov_b64 s[2:3], 0x20000
	s_mov_b64 s[24:25], -1
	s_waitcnt vmcnt(0)
	v_ffbh_u32_e32 v150, v149
	v_min_u32_e32 v150, 32, v150
	v_lshlrev_b64 v[148:149], v150, v[148:149]
	v_min_u32_e32 v148, 1, v148
	v_or_b32_e32 v148, v149, v148
	v_cvt_f32_u32_e32 v148, v148
	v_sub_u32_e32 v149, 32, v150
	v_ldexp_f32 v148, v148, v149
	v_fmamk_f32 v148, v148, 0x2e000000, v239
	v_rsq_f32_e32 v148, v148
	s_nop 0
	v_pk_mul_f32 v[126:127], v[126:127], v[148:149] op_sel_hi:[1,0]
	v_pk_mul_f32 v[124:125], v[124:125], v[148:149] op_sel_hi:[1,0]
	v_pk_mul_f32 v[120:121], v[120:121], v[148:149] op_sel_hi:[1,0]
	v_pk_mul_f32 v[122:123], v[122:123], v[148:149] op_sel_hi:[1,0]
	v_cvt_pk_bf16_f32 v124, v124, v125
	v_cvt_pk_bf16_f32 v125, v126, v127
	v_cvt_pk_bf16_f32 v126, v120, v121
	v_lshlrev_b64 v[120:121], 10, v[140:141]
	v_cvt_pk_bf16_f32 v127, v122, v123
	v_lshl_add_u64 v[120:121], s[64:65], 0, v[120:121]
	v_lshlrev_b64 v[122:123], 1, v[146:147]
	v_lshl_add_u64 v[120:121], v[120:121], 0, v[122:123]
	global_store_dwordx4 v[120:121], v[124:127], off sc1
	v_pk_mul_f32 v[118:119], v[118:119], v[148:149] op_sel_hi:[1,0]
	v_pk_mul_f32 v[116:117], v[116:117], v[148:149] op_sel_hi:[1,0]
	v_pk_mul_f32 v[124:125], v[114:115], v[148:149] op_sel_hi:[1,0]
	v_pk_mul_f32 v[114:115], v[112:113], v[148:149] op_sel_hi:[1,0]
	v_cvt_pk_bf16_f32 v112, v116, v117
	v_cvt_pk_bf16_f32 v113, v118, v119
	v_cvt_pk_bf16_f32 v114, v114, v115
	v_cvt_pk_bf16_f32 v115, v124, v125
	global_store_dwordx4 v[120:121], v[112:115], off offset:256 sc1
	s_nop 1
	v_mov_b64_e32 v[114:115], v[170:171]
	v_ffbh_u32_e32 v116, v115
	v_min_u32_e32 v116, 32, v116
	v_lshlrev_b64 v[114:115], v116, v[114:115]
	v_min_u32_e32 v114, 1, v114
	v_or_b32_e32 v114, v115, v114
	v_cvt_f32_u32_e32 v114, v114
	v_sub_u32_e32 v115, 32, v116
	v_or_b32_e32 v112, 16, v140
	v_ashrrev_i32_e32 v113, 31, v112
	v_ldexp_f32 v114, v114, v115
	v_fmamk_f32 v114, v114, 0x2e000000, v239
	v_rsq_f32_e32 v114, v114
	s_nop 0
	v_pk_mul_f32 v[108:109], v[108:109], v[114:115] op_sel_hi:[1,0]
	v_pk_mul_f32 v[116:117], v[106:107], v[114:115] op_sel_hi:[1,0]
	v_pk_mul_f32 v[106:107], v[104:105], v[114:115] op_sel_hi:[1,0]
	v_cvt_pk_bf16_f32 v104, v108, v109
	v_lshlrev_b64 v[108:109], 10, v[112:113]
	v_pk_mul_f32 v[110:111], v[110:111], v[114:115] op_sel_hi:[1,0]
	v_lshl_add_u64 v[108:109], s[64:65], 0, v[108:109]
	v_cvt_pk_bf16_f32 v105, v110, v111
	v_cvt_pk_bf16_f32 v106, v106, v107
	v_cvt_pk_bf16_f32 v107, v116, v117
	v_lshl_add_u64 v[108:109], v[108:109], 0, v[122:123]
	global_store_dwordx4 v[108:109], v[104:107], off sc1
	v_pk_mul_f32 v[102:103], v[102:103], v[114:115] op_sel_hi:[1,0]
	v_pk_mul_f32 v[100:101], v[100:101], v[114:115] op_sel_hi:[1,0]
	v_pk_mul_f32 v[104:105], v[98:99], v[114:115] op_sel_hi:[1,0]
	v_pk_mul_f32 v[98:99], v[96:97], v[114:115] op_sel_hi:[1,0]
	v_cvt_pk_bf16_f32 v96, v100, v101
	v_cvt_pk_bf16_f32 v97, v102, v103
	v_cvt_pk_bf16_f32 v98, v98, v99
	v_cvt_pk_bf16_f32 v99, v104, v105
	global_store_dwordx4 v[108:109], v[96:99], off offset:256 sc1
	s_nop 1
	v_mov_b64_e32 v[98:99], v[172:173]
	v_ffbh_u32_e32 v100, v99
	v_min_u32_e32 v100, 32, v100
	v_lshlrev_b64 v[98:99], v100, v[98:99]
	v_min_u32_e32 v98, 1, v98
	v_or_b32_e32 v98, v99, v98
	v_cvt_f32_u32_e32 v98, v98
	v_sub_u32_e32 v99, 32, v100
	v_or_b32_e32 v96, 32, v140
	v_ashrrev_i32_e32 v97, 31, v96
	v_ldexp_f32 v98, v98, v99
	v_fmamk_f32 v98, v98, 0x2e000000, v239
	v_rsq_f32_e32 v98, v98
	s_nop 0
	v_pk_mul_f32 v[92:93], v[92:93], v[98:99] op_sel_hi:[1,0]
	v_pk_mul_f32 v[100:101], v[90:91], v[98:99] op_sel_hi:[1,0]
	v_pk_mul_f32 v[90:91], v[88:89], v[98:99] op_sel_hi:[1,0]
	v_cvt_pk_bf16_f32 v88, v92, v93
	v_lshlrev_b64 v[92:93], 10, v[96:97]
	v_pk_mul_f32 v[94:95], v[94:95], v[98:99] op_sel_hi:[1,0]
	v_lshl_add_u64 v[92:93], s[64:65], 0, v[92:93]
	v_cvt_pk_bf16_f32 v89, v94, v95
	v_cvt_pk_bf16_f32 v90, v90, v91
	v_cvt_pk_bf16_f32 v91, v100, v101
	v_lshl_add_u64 v[92:93], v[92:93], 0, v[122:123]
	global_store_dwordx4 v[92:93], v[88:91], off sc1
	v_pk_mul_f32 v[86:87], v[86:87], v[98:99] op_sel_hi:[1,0]
	v_pk_mul_f32 v[84:85], v[84:85], v[98:99] op_sel_hi:[1,0]
	v_pk_mul_f32 v[88:89], v[82:83], v[98:99] op_sel_hi:[1,0]
	v_pk_mul_f32 v[82:83], v[80:81], v[98:99] op_sel_hi:[1,0]
	v_cvt_pk_bf16_f32 v80, v84, v85
	v_cvt_pk_bf16_f32 v81, v86, v87
	v_cvt_pk_bf16_f32 v82, v82, v83
	v_cvt_pk_bf16_f32 v83, v88, v89
	global_store_dwordx4 v[92:93], v[80:83], off offset:256 sc1
	s_nop 1
	v_mov_b64_e32 v[82:83], v[174:175]
	v_ffbh_u32_e32 v84, v83
	v_min_u32_e32 v84, 32, v84
	v_lshlrev_b64 v[82:83], v84, v[82:83]
	v_min_u32_e32 v82, 1, v82
	v_or_b32_e32 v82, v83, v82
	v_cvt_f32_u32_e32 v82, v82
	v_sub_u32_e32 v83, 32, v84
	v_or_b32_e32 v80, 48, v140
	v_ashrrev_i32_e32 v81, 31, v80
	v_ldexp_f32 v82, v82, v83
	v_fmamk_f32 v82, v82, 0x2e000000, v239
	v_rsq_f32_e32 v82, v82
	s_nop 0
	v_pk_mul_f32 v[76:77], v[76:77], v[82:83] op_sel_hi:[1,0]
	v_pk_mul_f32 v[84:85], v[74:75], v[82:83] op_sel_hi:[1,0]
; __device__ __forceinline__ unsigned cvt_pk_bf16(float lo, float hi) { const f32x2_t v = {lo, hi}; const bf16x2_t b = __builtin_convertvector(v, bf16x2_t); return __builtin_bit_cast(unsigned, b); }
; __device__ __forceinline__ float rstd_of(u64 ssq) { return frsq((float)ssq * (1.0f / (2048.0f * 16777216.0f)) + EPS); }
;     __device__ __forceinline__ void operator()(const Acc& acc, const Unit& u, int wr, int wc, int fr, int fq) const {
;         const int row0 = u.pm * BM + wr * 64 + fr, col0 = u.pn * BM + wc * 32 + 8 * fq;
; #pragma unroll
;         for (int ai = 0; ai < 2; ++ai)
; #pragma unroll
;             for (int m = 0; m < 4; ++m) {
;                 asm volatile("" ::: "memory");
;                 const int r = row0 + ai * HALF + m * 16; const float rs = rstd_of(ssq[r]);
; #pragma unroll
;                 for (int bj = 0; bj < 2; ++bj) {
;                     const f32x4 v0 = acc[ai][bj][m][0] * rs, v1 = acc[ai][bj][m][1] * rs;
;                     u32x4 w; w.x = cvt_pk_bf16(v0[0], v0[1]); w.y = cvt_pk_bf16(v0[2], v0[3]); w.z = cvt_pk_bf16(v1[0], v1[1]); w.w = cvt_pk_bf16(v1[2], v1[3]);
;                     *(u32x4*)(O + (size_t)r * ldc + col0 + bj * HALF) = w;
;                 }
;             }
	v_pk_mul_f32 v[74:75], v[72:73], v[82:83] op_sel_hi:[1,0]
	v_cvt_pk_bf16_f32 v72, v76, v77
	v_lshlrev_b64 v[76:77], 10, v[80:81]
	v_pk_mul_f32 v[78:79], v[78:79], v[82:83] op_sel_hi:[1,0]
	v_lshl_add_u64 v[76:77], s[64:65], 0, v[76:77]
	v_cvt_pk_bf16_f32 v73, v78, v79
	v_cvt_pk_bf16_f32 v74, v74, v75
	v_cvt_pk_bf16_f32 v75, v84, v85
	v_lshl_add_u64 v[76:77], v[76:77], 0, v[122:123]
	global_store_dwordx4 v[76:77], v[72:75], off sc1
	v_pk_mul_f32 v[70:71], v[70:71], v[82:83] op_sel_hi:[1,0]
	v_pk_mul_f32 v[68:69], v[68:69], v[82:83] op_sel_hi:[1,0]
	v_pk_mul_f32 v[72:73], v[66:67], v[82:83] op_sel_hi:[1,0]
	v_pk_mul_f32 v[66:67], v[64:65], v[82:83] op_sel_hi:[1,0]
	v_cvt_pk_bf16_f32 v64, v68, v69
	v_cvt_pk_bf16_f32 v65, v70, v71
	v_cvt_pk_bf16_f32 v66, v66, v67
	v_cvt_pk_bf16_f32 v67, v72, v73
	global_store_dwordx4 v[76:77], v[64:67], off offset:256 sc1
	s_nop 1
	v_mov_b64_e32 v[64:65], v[176:177]
	v_ffbh_u32_e32 v66, v65
	v_min_u32_e32 v66, 32, v66
	v_lshlrev_b64 v[64:65], v66, v[64:65]
	v_min_u32_e32 v64, 1, v64
	v_or_b32_e32 v64, v65, v64
	v_cvt_f32_u32_e32 v64, v64
	v_sub_u32_e32 v65, 32, v66
	v_ldexp_f32 v64, v64, v65
	v_fmamk_f32 v64, v64, 0x2e000000, v239
	v_rsq_f32_e32 v64, v64
	s_nop 0
	v_pk_mul_f32 v[60:61], v[60:61], v[64:65] op_sel_hi:[1,0]
	v_pk_mul_f32 v[62:63], v[62:63], v[64:65] op_sel_hi:[1,0]
	v_pk_mul_f32 v[66:67], v[58:59], v[64:65] op_sel_hi:[1,0]
	v_pk_mul_f32 v[58:59], v[56:57], v[64:65] op_sel_hi:[1,0]
	v_cvt_pk_bf16_f32 v56, v60, v61
	v_lshl_add_u64 v[60:61], v[120:121], 0, s[2:3]
	s_mov_b32 s2, 0x20000
	v_cvt_pk_bf16_f32 v57, v62, v63
	v_add_co_u32_e32 v62, vcc, s2, v120
	v_cvt_pk_bf16_f32 v58, v58, v59
	v_cvt_pk_bf16_f32 v59, v66, v67
	v_addc_co_u32_e32 v63, vcc, 0, v121, vcc
	global_store_dwordx4 v[62:63], v[56:59], off sc1
	v_pk_mul_f32 v[54:55], v[54:55], v[64:65] op_sel_hi:[1,0]
	v_pk_mul_f32 v[52:53], v[52:53], v[64:65] op_sel_hi:[1,0]
	v_pk_mul_f32 v[56:57], v[50:51], v[64:65] op_sel_hi:[1,0]
	v_pk_mul_f32 v[50:51], v[48:49], v[64:65] op_sel_hi:[1,0]
	v_cvt_pk_bf16_f32 v48, v52, v53
	v_cvt_pk_bf16_f32 v49, v54, v55
	v_cvt_pk_bf16_f32 v50, v50, v51
	v_cvt_pk_bf16_f32 v51, v56, v57
	global_store_dwordx4 v[60:61], v[48:51], off offset:256 sc1
	s_nop 1
	v_mov_b64_e32 v[48:49], v[178:179]
	s_mov_b64 s[2:3], 0x24000
	v_ffbh_u32_e32 v50, v49
	v_min_u32_e32 v50, 32, v50
	v_lshlrev_b64 v[48:49], v50, v[48:49]
	v_min_u32_e32 v48, 1, v48
	v_or_b32_e32 v48, v49, v48
	v_cvt_f32_u32_e32 v48, v48
	v_sub_u32_e32 v49, 32, v50
	v_ldexp_f32 v48, v48, v49
	v_fmamk_f32 v48, v48, 0x2e000000, v239
	v_rsq_f32_e32 v48, v48
	s_nop 0
	v_pk_mul_f32 v[44:45], v[44:45], v[48:49] op_sel_hi:[1,0]
	v_pk_mul_f32 v[46:47], v[46:47], v[48:49] op_sel_hi:[1,0]
	v_pk_mul_f32 v[50:51], v[42:43], v[48:49] op_sel_hi:[1,0]
	v_pk_mul_f32 v[42:43], v[40:41], v[48:49] op_sel_hi:[1,0]
	v_cvt_pk_bf16_f32 v40, v44, v45
	v_lshl_add_u64 v[44:45], v[120:121], 0, s[2:3]
	s_mov_b32 s2, 0x24000
	v_cvt_pk_bf16_f32 v41, v46, v47
	v_add_co_u32_e32 v46, vcc, s2, v120
	v_cvt_pk_bf16_f32 v42, v42, v43
	v_cvt_pk_bf16_f32 v43, v50, v51
	v_addc_co_u32_e32 v47, vcc, 0, v121, vcc
	global_store_dwordx4 v[46:47], v[40:43], off sc1
	v_pk_mul_f32 v[38:39], v[38:39], v[48:49] op_sel_hi:[1,0]
	v_pk_mul_f32 v[36:37], v[36:37], v[48:49] op_sel_hi:[1,0]
	v_pk_mul_f32 v[40:41], v[34:35], v[48:49] op_sel_hi:[1,0]
	v_pk_mul_f32 v[34:35], v[32:33], v[48:49] op_sel_hi:[1,0]
	v_cvt_pk_bf16_f32 v32, v36, v37
	v_cvt_pk_bf16_f32 v33, v38, v39
	v_cvt_pk_bf16_f32 v34, v34, v35
	v_cvt_pk_bf16_f32 v35, v40, v41
	global_store_dwordx4 v[44:45], v[32:35], off offset:256 sc1
	s_nop 1
	v_mov_b64_e32 v[32:33], v[180:181]
	s_mov_b64 s[2:3], 0x28000
	v_ffbh_u32_e32 v34, v33
	v_min_u32_e32 v34, 32, v34
	v_lshlrev_b64 v[32:33], v34, v[32:33]
	v_min_u32_e32 v32, 1, v32
	v_or_b32_e32 v32, v33, v32
	v_cvt_f32_u32_e32 v32, v32
	v_sub_u32_e32 v33, 32, v34
	v_ldexp_f32 v32, v32, v33
	v_fmamk_f32 v32, v32, 0x2e000000, v239
	v_rsq_f32_e32 v32, v32
	s_nop 0
	v_pk_mul_f32 v[28:29], v[28:29], v[32:33] op_sel_hi:[1,0]
	v_pk_mul_f32 v[30:31], v[30:31], v[32:33] op_sel_hi:[1,0]
	v_pk_mul_f32 v[34:35], v[26:27], v[32:33] op_sel_hi:[1,0]
	v_pk_mul_f32 v[26:27], v[24:25], v[32:33] op_sel_hi:[1,0]
	v_cvt_pk_bf16_f32 v24, v28, v29
	v_lshl_add_u64 v[28:29], v[120:121], 0, s[2:3]
	s_mov_b32 s2, 0x28000
	v_cvt_pk_bf16_f32 v25, v30, v31
	v_add_co_u32_e32 v30, vcc, s2, v120
	v_cvt_pk_bf16_f32 v26, v26, v27
	v_cvt_pk_bf16_f32 v27, v34, v35
	v_addc_co_u32_e32 v31, vcc, 0, v121, vcc
	global_store_dwordx4 v[30:31], v[24:27], off sc1
	v_pk_mul_f32 v[22:23], v[22:23], v[32:33] op_sel_hi:[1,0]
	v_pk_mul_f32 v[20:21], v[20:21], v[32:33] op_sel_hi:[1,0]
	v_pk_mul_f32 v[24:25], v[18:19], v[32:33] op_sel_hi:[1,0]
	v_pk_mul_f32 v[18:19], v[16:17], v[32:33] op_sel_hi:[1,0]
	v_cvt_pk_bf16_f32 v16, v20, v21
	v_cvt_pk_bf16_f32 v17, v22, v23
	v_cvt_pk_bf16_f32 v18, v18, v19
	v_cvt_pk_bf16_f32 v19, v24, v25
	global_store_dwordx4 v[28:29], v[16:19], off offset:256 sc1
	s_nop 1
	v_mov_b64_e32 v[16:17], v[182:183]
	s_mov_b64 s[2:3], 0x2c000
	v_ffbh_u32_e32 v18, v17
	v_min_u32_e32 v18, 32, v18
	v_lshlrev_b64 v[16:17], v18, v[16:17]
	v_min_u32_e32 v16, 1, v16
	v_or_b32_e32 v16, v17, v16
	v_cvt_f32_u32_e32 v16, v16
	v_sub_u32_e32 v17, 32, v18
	v_ldexp_f32 v16, v16, v17
	v_fmamk_f32 v16, v16, 0x2e000000, v239
	v_rsq_f32_e32 v16, v16
	s_nop 0
	v_pk_mul_f32 v[12:13], v[12:13], v[16:17] op_sel_hi:[1,0]
	v_pk_mul_f32 v[14:15], v[14:15], v[16:17] op_sel_hi:[1,0]
	v_pk_mul_f32 v[18:19], v[10:11], v[16:17] op_sel_hi:[1,0]
	v_pk_mul_f32 v[10:11], v[8:9], v[16:17] op_sel_hi:[1,0]
	v_cvt_pk_bf16_f32 v8, v12, v13
	v_lshl_add_u64 v[12:13], v[120:121], 0, s[2:3]
	s_mov_b32 s2, 0x2c000
	v_cvt_pk_bf16_f32 v9, v14, v15
	v_add_co_u32_e32 v14, vcc, s2, v120
	v_cvt_pk_bf16_f32 v10, v10, v11
	v_cvt_pk_bf16_f32 v11, v18, v19
	v_addc_co_u32_e32 v15, vcc, 0, v121, vcc
	global_store_dwordx4 v[14:15], v[8:11], off sc1
	v_pk_mul_f32 v[6:7], v[6:7], v[16:17] op_sel_hi:[1,0]
	v_pk_mul_f32 v[4:5], v[4:5], v[16:17] op_sel_hi:[1,0]
	v_pk_mul_f32 v[8:9], v[2:3], v[16:17] op_sel_hi:[1,0]
	v_pk_mul_f32 v[2:3], v[0:1], v[16:17] op_sel_hi:[1,0]
	v_cvt_pk_bf16_f32 v0, v4, v5
	v_cvt_pk_bf16_f32 v1, v6, v7
	v_cvt_pk_bf16_f32 v2, v2, v3
	v_cvt_pk_bf16_f32 v3, v8, v9
	s_andn2_b64 vcc, exec, s[4:5]
	global_store_dwordx4 v[12:13], v[0:3], off offset:256 sc1
	s_cbranch_vccnz .LBB0_85
	s_andn2_b64 vcc, exec, s[6:7]
	s_cbranch_vccnz .LBB0_84
	s_barrier
	s_branch .LBB0_84

; __device__ __forceinline__ unsigned cvt_pk_bf16(float lo, float hi) { const f32x2_t v = {lo, hi}; const bf16x2_t b = __builtin_convertvector(v, bf16x2_t); return __builtin_bit_cast(unsigned, b); }
; __device__ __forceinline__ float rstd_of(u64 ssq) { return frsq((float)ssq * (1.0f / (2048.0f * 16777216.0f)) + EPS); }
;     __device__ __forceinline__ void operator()(const Acc& acc, const Unit& u, int wr, int wc, int fr, int fq) const {
;         const int row0 = u.pm * BM + wr * 64 + fr, col0 = u.pn * BM + wc * 32 + 8 * fq;
; #pragma unroll
;         for (int ai = 0; ai < 2; ++ai)
; #pragma unroll
;             for (int m = 0; m < 4; ++m) {
;                 asm volatile("" ::: "memory");
;                 const int r = row0 + ai * HALF + m * 16; const float rs = rstd_of(ssq[r]);
; #pragma unroll
;                 for (int bj = 0; bj < 2; ++bj) {
;                     const f32x4 v0 = acc[ai][bj][m][0] * rs, v1 = acc[ai][bj][m][1] * rs;
;                     u32x4 w; w.x = cvt_pk_bf16(v0[0], v0[1]); w.y = cvt_pk_bf16(v0[2], v0[3]); w.z = cvt_pk_bf16(v1[0], v1[1]); w.w = cvt_pk_bf16(v1[2], v1[3]);
;                     *(u32x4*)(O + (size_t)r * ldc + col0 + bj * HALF) = w;
;                 }
;             }
.LBB0_120:
	v_lshl_add_u32 v140, s60, 8, v142
	v_ashrrev_i32_e32 v141, 31, v140
	v_lshl_add_u64 v[138:139], v[140:141], 3, s[6:7]
	global_load_dwordx2 v[148:149], v[138:139], off
	global_load_dwordx2 v[170:171], v[138:139], off offset:128
	global_load_dwordx2 v[172:173], v[138:139], off offset:256
	global_load_dwordx2 v[174:175], v[138:139], off offset:384
	global_load_dwordx2 v[176:177], v[138:139], off offset:1024
	global_load_dwordx2 v[178:179], v[138:139], off offset:1152
	global_load_dwordx2 v[180:181], v[138:139], off offset:1280
	global_load_dwordx2 v[182:183], v[138:139], off offset:1408
	v_lshl_or_b32 v146, s93, 8, v144
	v_ashrrev_i32_e32 v147, 31, v146
	s_mov_b64 s[2:3], 0x40000
	s_mov_b64 s[24:25], -1
	s_waitcnt vmcnt(0)
	v_ffbh_u32_e32 v150, v149
	v_min_u32_e32 v150, 32, v150
	v_lshlrev_b64 v[148:149], v150, v[148:149]
	v_min_u32_e32 v148, 1, v148
	v_or_b32_e32 v148, v149, v148
	v_cvt_f32_u32_e32 v148, v148
	v_sub_u32_e32 v149, 32, v150
	v_ldexp_f32 v148, v148, v149
	v_fmamk_f32 v148, v148, 0x2e000000, v239
	v_rsq_f32_e32 v148, v148
	s_nop 0
	v_pk_mul_f32 v[126:127], v[126:127], v[148:149] op_sel_hi:[1,0]
	v_pk_mul_f32 v[124:125], v[124:125], v[148:149] op_sel_hi:[1,0]
	v_pk_mul_f32 v[120:121], v[120:121], v[148:149] op_sel_hi:[1,0]
	v_pk_mul_f32 v[122:123], v[122:123], v[148:149] op_sel_hi:[1,0]
	v_cvt_pk_bf16_f32 v124, v124, v125
	v_cvt_pk_bf16_f32 v125, v126, v127
	v_cvt_pk_bf16_f32 v126, v120, v121
	v_lshlrev_b64 v[120:121], 11, v[140:141]
	v_cvt_pk_bf16_f32 v127, v122, v123
	v_lshl_add_u64 v[120:121], s[14:15], 0, v[120:121]
	v_lshlrev_b64 v[122:123], 1, v[146:147]
	v_lshl_add_u64 v[120:121], v[120:121], 0, v[122:123]
	global_store_dwordx4 v[120:121], v[124:127], off sc1
	v_pk_mul_f32 v[118:119], v[118:119], v[148:149] op_sel_hi:[1,0]
	v_pk_mul_f32 v[116:117], v[116:117], v[148:149] op_sel_hi:[1,0]
	v_pk_mul_f32 v[124:125], v[114:115], v[148:149] op_sel_hi:[1,0]
	v_pk_mul_f32 v[114:115], v[112:113], v[148:149] op_sel_hi:[1,0]
	v_cvt_pk_bf16_f32 v112, v116, v117
	v_cvt_pk_bf16_f32 v113, v118, v119
	v_cvt_pk_bf16_f32 v114, v114, v115
	v_cvt_pk_bf16_f32 v115, v124, v125
	global_store_dwordx4 v[120:121], v[112:115], off offset:256 sc1
	s_nop 1
	v_or_b32_e32 v112, 16, v140
	v_ashrrev_i32_e32 v113, 31, v112
	v_lshl_add_u64 v[114:115], v[112:113], 3, s[6:7]
	s_nop 1
	v_mov_b64_e32 v[114:115], v[170:171]
	v_ffbh_u32_e32 v116, v115
	v_min_u32_e32 v116, 32, v116
	v_lshlrev_b64 v[114:115], v116, v[114:115]
	v_min_u32_e32 v114, 1, v114
	v_or_b32_e32 v114, v115, v114
	v_cvt_f32_u32_e32 v114, v114
	v_sub_u32_e32 v115, 32, v116
	v_ldexp_f32 v114, v114, v115
	v_fmamk_f32 v114, v114, 0x2e000000, v239
	v_rsq_f32_e32 v114, v114
	s_nop 0
	v_pk_mul_f32 v[108:109], v[108:109], v[114:115] op_sel_hi:[1,0]
	v_pk_mul_f32 v[116:117], v[106:107], v[114:115] op_sel_hi:[1,0]
	v_pk_mul_f32 v[106:107], v[104:105], v[114:115] op_sel_hi:[1,0]
	v_cvt_pk_bf16_f32 v104, v108, v109
	v_lshlrev_b64 v[108:109], 11, v[112:113]
	v_pk_mul_f32 v[110:111], v[110:111], v[114:115] op_sel_hi:[1,0]
	v_lshl_add_u64 v[108:109], s[14:15], 0, v[108:109]
	v_cvt_pk_bf16_f32 v105, v110, v111
	v_cvt_pk_bf16_f32 v106, v106, v107
	v_cvt_pk_bf16_f32 v107, v116, v117
	v_lshl_add_u64 v[108:109], v[108:109], 0, v[122:123]
	global_store_dwordx4 v[108:109], v[104:107], off sc1
	v_pk_mul_f32 v[102:103], v[102:103], v[114:115] op_sel_hi:[1,0]
	v_pk_mul_f32 v[100:101], v[100:101], v[114:115] op_sel_hi:[1,0]
	v_pk_mul_f32 v[104:105], v[98:99], v[114:115] op_sel_hi:[1,0]
	v_pk_mul_f32 v[98:99], v[96:97], v[114:115] op_sel_hi:[1,0]
	v_cvt_pk_bf16_f32 v96, v100, v101
	v_cvt_pk_bf16_f32 v97, v102, v103
	v_cvt_pk_bf16_f32 v98, v98, v99
	v_cvt_pk_bf16_f32 v99, v104, v105
	global_store_dwordx4 v[108:109], v[96:99], off offset:256 sc1
	s_nop 1
	v_or_b32_e32 v96, 32, v140
	v_ashrrev_i32_e32 v97, 31, v96
	v_lshl_add_u64 v[98:99], v[96:97], 3, s[6:7]
	s_nop 1
	v_mov_b64_e32 v[98:99], v[172:173]
	v_ffbh_u32_e32 v100, v99
	v_min_u32_e32 v100, 32, v100
	v_lshlrev_b64 v[98:99], v100, v[98:99]
	v_min_u32_e32 v98, 1, v98
	v_or_b32_e32 v98, v99, v98
	v_cvt_f32_u32_e32 v98, v98
	v_sub_u32_e32 v99, 32, v100
	v_ldexp_f32 v98, v98, v99
	v_fmamk_f32 v98, v98, 0x2e000000, v239
	v_rsq_f32_e32 v98, v98
	s_nop 0
	v_pk_mul_f32 v[92:93], v[92:93], v[98:99] op_sel_hi:[1,0]
	v_pk_mul_f32 v[100:101], v[90:91], v[98:99] op_sel_hi:[1,0]
	v_pk_mul_f32 v[90:91], v[88:89], v[98:99] op_sel_hi:[1,0]
	v_cvt_pk_bf16_f32 v88, v92, v93
	v_lshlrev_b64 v[92:93], 11, v[96:97]
	v_pk_mul_f32 v[94:95], v[94:95], v[98:99] op_sel_hi:[1,0]
	v_lshl_add_u64 v[92:93], s[14:15], 0, v[92:93]
	v_cvt_pk_bf16_f32 v89, v94, v95
	v_cvt_pk_bf16_f32 v90, v90, v91
	v_cvt_pk_bf16_f32 v91, v100, v101
	v_lshl_add_u64 v[92:93], v[92:93], 0, v[122:123]
	global_store_dwordx4 v[92:93], v[88:91], off sc1
	v_pk_mul_f32 v[86:87], v[86:87], v[98:99] op_sel_hi:[1,0]
	v_pk_mul_f32 v[84:85], v[84:85], v[98:99] op_sel_hi:[1,0]
	v_pk_mul_f32 v[88:89], v[82:83], v[98:99] op_sel_hi:[1,0]
	v_pk_mul_f32 v[82:83], v[80:81], v[98:99] op_sel_hi:[1,0]
	v_cvt_pk_bf16_f32 v80, v84, v85
	v_cvt_pk_bf16_f32 v81, v86, v87
	v_cvt_pk_bf16_f32 v82, v82, v83
	v_cvt_pk_bf16_f32 v83, v88, v89
	global_store_dwordx4 v[92:93], v[80:83], off offset:256 sc1
	s_nop 1
	v_or_b32_e32 v80, 48, v140
	v_ashrrev_i32_e32 v81, 31, v80
	v_lshl_add_u64 v[82:83], v[80:81], 3, s[6:7]
	s_nop 1
	v_mov_b64_e32 v[82:83], v[174:175]
	v_ffbh_u32_e32 v84, v83
	v_min_u32_e32 v84, 32, v84
	v_lshlrev_b64 v[82:83], v84, v[82:83]
	v_min_u32_e32 v82, 1, v82
	v_or_b32_e32 v82, v83, v82
	v_cvt_f32_u32_e32 v82, v82
	v_sub_u32_e32 v83, 32, v84
	v_ldexp_f32 v82, v82, v83
	v_fmamk_f32 v82, v82, 0x2e000000, v239
; __device__ __forceinline__ unsigned cvt_pk_bf16(float lo, float hi) { const f32x2_t v = {lo, hi}; const bf16x2_t b = __builtin_convertvector(v, bf16x2_t); return __builtin_bit_cast(unsigned, b); }
; __device__ __forceinline__ float rstd_of(u64 ssq) { return frsq((float)ssq * (1.0f / (2048.0f * 16777216.0f)) + EPS); }
;     __device__ __forceinline__ void operator()(const Acc& acc, const Unit& u, int wr, int wc, int fr, int fq) const {
;         const int row0 = u.pm * BM + wr * 64 + fr, col0 = u.pn * BM + wc * 32 + 8 * fq;
; #pragma unroll
;         for (int ai = 0; ai < 2; ++ai)
; #pragma unroll
;             for (int m = 0; m < 4; ++m) {
;                 asm volatile("" ::: "memory");
;                 const int r = row0 + ai * HALF + m * 16; const float rs = rstd_of(ssq[r]);
; #pragma unroll
;                 for (int bj = 0; bj < 2; ++bj) {
;                     const f32x4 v0 = acc[ai][bj][m][0] * rs, v1 = acc[ai][bj][m][1] * rs;
;                     u32x4 w; w.x = cvt_pk_bf16(v0[0], v0[1]); w.y = cvt_pk_bf16(v0[2], v0[3]); w.z = cvt_pk_bf16(v1[0], v1[1]); w.w = cvt_pk_bf16(v1[2], v1[3]);
;                     *(u32x4*)(O + (size_t)r * ldc + col0 + bj * HALF) = w;
;                 }
;             }
	v_rsq_f32_e32 v82, v82
	s_nop 0
	v_pk_mul_f32 v[76:77], v[76:77], v[82:83] op_sel_hi:[1,0]
	v_pk_mul_f32 v[84:85], v[74:75], v[82:83] op_sel_hi:[1,0]
	v_pk_mul_f32 v[74:75], v[72:73], v[82:83] op_sel_hi:[1,0]
	v_cvt_pk_bf16_f32 v72, v76, v77
	v_lshlrev_b64 v[76:77], 11, v[80:81]
	v_pk_mul_f32 v[78:79], v[78:79], v[82:83] op_sel_hi:[1,0]
	v_lshl_add_u64 v[76:77], s[14:15], 0, v[76:77]
	v_cvt_pk_bf16_f32 v73, v78, v79
	v_cvt_pk_bf16_f32 v74, v74, v75
	v_cvt_pk_bf16_f32 v75, v84, v85
	v_lshl_add_u64 v[76:77], v[76:77], 0, v[122:123]
	global_store_dwordx4 v[76:77], v[72:75], off sc1
	v_pk_mul_f32 v[70:71], v[70:71], v[82:83] op_sel_hi:[1,0]
	v_pk_mul_f32 v[68:69], v[68:69], v[82:83] op_sel_hi:[1,0]
	v_pk_mul_f32 v[72:73], v[66:67], v[82:83] op_sel_hi:[1,0]
	v_pk_mul_f32 v[66:67], v[64:65], v[82:83] op_sel_hi:[1,0]
	v_cvt_pk_bf16_f32 v64, v68, v69
	v_cvt_pk_bf16_f32 v65, v70, v71
	v_cvt_pk_bf16_f32 v66, v66, v67
	v_cvt_pk_bf16_f32 v67, v72, v73
	global_store_dwordx4 v[76:77], v[64:67], off offset:256 sc1
	s_nop 1
	v_mov_b64_e32 v[64:65], v[176:177]
	v_ffbh_u32_e32 v66, v65
	v_min_u32_e32 v66, 32, v66
	v_lshlrev_b64 v[64:65], v66, v[64:65]
	v_min_u32_e32 v64, 1, v64
	v_or_b32_e32 v64, v65, v64
	v_cvt_f32_u32_e32 v64, v64
	v_sub_u32_e32 v65, 32, v66
	v_ldexp_f32 v64, v64, v65
	v_fmamk_f32 v64, v64, 0x2e000000, v239
	v_rsq_f32_e32 v64, v64
	s_nop 0
	v_pk_mul_f32 v[60:61], v[60:61], v[64:65] op_sel_hi:[1,0]
	v_pk_mul_f32 v[62:63], v[62:63], v[64:65] op_sel_hi:[1,0]
	v_pk_mul_f32 v[66:67], v[58:59], v[64:65] op_sel_hi:[1,0]
	v_pk_mul_f32 v[58:59], v[56:57], v[64:65] op_sel_hi:[1,0]
	v_cvt_pk_bf16_f32 v56, v60, v61
	v_lshl_add_u64 v[60:61], v[120:121], 0, s[2:3]
	s_mov_b32 s2, 0x40000
	v_cvt_pk_bf16_f32 v57, v62, v63
	v_add_co_u32_e32 v62, vcc, s2, v120
	v_cvt_pk_bf16_f32 v58, v58, v59
	v_cvt_pk_bf16_f32 v59, v66, v67
	v_addc_co_u32_e32 v63, vcc, 0, v121, vcc
	global_store_dwordx4 v[62:63], v[56:59], off sc1
	v_pk_mul_f32 v[54:55], v[54:55], v[64:65] op_sel_hi:[1,0]
	v_pk_mul_f32 v[52:53], v[52:53], v[64:65] op_sel_hi:[1,0]
	v_pk_mul_f32 v[56:57], v[50:51], v[64:65] op_sel_hi:[1,0]
	v_pk_mul_f32 v[50:51], v[48:49], v[64:65] op_sel_hi:[1,0]
	v_cvt_pk_bf16_f32 v48, v52, v53
	v_cvt_pk_bf16_f32 v49, v54, v55
	v_cvt_pk_bf16_f32 v50, v50, v51
	v_cvt_pk_bf16_f32 v51, v56, v57
	global_store_dwordx4 v[60:61], v[48:51], off offset:256 sc1
	s_nop 1
	v_mov_b64_e32 v[48:49], v[178:179]
	s_mov_b64 s[2:3], 0x48000
	v_ffbh_u32_e32 v50, v49
	v_min_u32_e32 v50, 32, v50
	v_lshlrev_b64 v[48:49], v50, v[48:49]
	v_min_u32_e32 v48, 1, v48
	v_or_b32_e32 v48, v49, v48
	v_cvt_f32_u32_e32 v48, v48
	v_sub_u32_e32 v49, 32, v50
	v_ldexp_f32 v48, v48, v49
	v_fmamk_f32 v48, v48, 0x2e000000, v239
	v_rsq_f32_e32 v48, v48
	s_nop 0
	v_pk_mul_f32 v[44:45], v[44:45], v[48:49] op_sel_hi:[1,0]
	v_pk_mul_f32 v[46:47], v[46:47], v[48:49] op_sel_hi:[1,0]
	v_pk_mul_f32 v[50:51], v[42:43], v[48:49] op_sel_hi:[1,0]
	v_pk_mul_f32 v[42:43], v[40:41], v[48:49] op_sel_hi:[1,0]
	v_cvt_pk_bf16_f32 v40, v44, v45
	v_lshl_add_u64 v[44:45], v[120:121], 0, s[2:3]
	s_mov_b32 s2, 0x48000
	v_cvt_pk_bf16_f32 v41, v46, v47
	v_add_co_u32_e32 v46, vcc, s2, v120
	v_cvt_pk_bf16_f32 v42, v42, v43
	v_cvt_pk_bf16_f32 v43, v50, v51
	v_addc_co_u32_e32 v47, vcc, 0, v121, vcc
	global_store_dwordx4 v[46:47], v[40:43], off sc1
	v_pk_mul_f32 v[38:39], v[38:39], v[48:49] op_sel_hi:[1,0]
	v_pk_mul_f32 v[36:37], v[36:37], v[48:49] op_sel_hi:[1,0]
	v_pk_mul_f32 v[40:41], v[34:35], v[48:49] op_sel_hi:[1,0]
	v_pk_mul_f32 v[34:35], v[32:33], v[48:49] op_sel_hi:[1,0]
	v_cvt_pk_bf16_f32 v32, v36, v37
	v_cvt_pk_bf16_f32 v33, v38, v39
	v_cvt_pk_bf16_f32 v34, v34, v35
	v_cvt_pk_bf16_f32 v35, v40, v41
	global_store_dwordx4 v[44:45], v[32:35], off offset:256 sc1
	s_nop 1
	v_mov_b64_e32 v[32:33], v[180:181]
	s_mov_b64 s[2:3], 0x50000
	v_ffbh_u32_e32 v34, v33
	v_min_u32_e32 v34, 32, v34
	v_lshlrev_b64 v[32:33], v34, v[32:33]
	v_min_u32_e32 v32, 1, v32
	v_or_b32_e32 v32, v33, v32
	v_cvt_f32_u32_e32 v32, v32
	v_sub_u32_e32 v33, 32, v34
	v_ldexp_f32 v32, v32, v33
	v_fmamk_f32 v32, v32, 0x2e000000, v239
	v_rsq_f32_e32 v32, v32
	s_nop 0
	v_pk_mul_f32 v[28:29], v[28:29], v[32:33] op_sel_hi:[1,0]
	v_pk_mul_f32 v[30:31], v[30:31], v[32:33] op_sel_hi:[1,0]
	v_pk_mul_f32 v[34:35], v[26:27], v[32:33] op_sel_hi:[1,0]
	v_pk_mul_f32 v[26:27], v[24:25], v[32:33] op_sel_hi:[1,0]
	v_cvt_pk_bf16_f32 v24, v28, v29
	v_lshl_add_u64 v[28:29], v[120:121], 0, s[2:3]
	s_mov_b32 s2, 0x50000
	v_cvt_pk_bf16_f32 v25, v30, v31
	v_add_co_u32_e32 v30, vcc, s2, v120
	v_cvt_pk_bf16_f32 v26, v26, v27
	v_cvt_pk_bf16_f32 v27, v34, v35
	v_addc_co_u32_e32 v31, vcc, 0, v121, vcc
	global_store_dwordx4 v[30:31], v[24:27], off sc1
	v_pk_mul_f32 v[22:23], v[22:23], v[32:33] op_sel_hi:[1,0]
	v_pk_mul_f32 v[20:21], v[20:21], v[32:33] op_sel_hi:[1,0]
	v_pk_mul_f32 v[24:25], v[18:19], v[32:33] op_sel_hi:[1,0]
	v_pk_mul_f32 v[18:19], v[16:17], v[32:33] op_sel_hi:[1,0]
	v_cvt_pk_bf16_f32 v16, v20, v21
	v_cvt_pk_bf16_f32 v17, v22, v23
	v_cvt_pk_bf16_f32 v18, v18, v19
	v_cvt_pk_bf16_f32 v19, v24, v25
	global_store_dwordx4 v[28:29], v[16:19], off offset:256 sc1
	s_nop 1
	v_mov_b64_e32 v[16:17], v[182:183]
	s_mov_b64 s[2:3], 0x58000
	v_ffbh_u32_e32 v18, v17
	v_min_u32_e32 v18, 32, v18
	v_lshlrev_b64 v[16:17], v18, v[16:17]
	v_min_u32_e32 v16, 1, v16
	v_or_b32_e32 v16, v17, v16
	v_cvt_f32_u32_e32 v16, v16
	v_sub_u32_e32 v17, 32, v18
	v_ldexp_f32 v16, v16, v17
	v_fmamk_f32 v16, v16, 0x2e000000, v239
	v_rsq_f32_e32 v16, v16
	s_nop 0
	v_pk_mul_f32 v[12:13], v[12:13], v[16:17] op_sel_hi:[1,0]
	v_pk_mul_f32 v[14:15], v[14:15], v[16:17] op_sel_hi:[1,0]
	v_pk_mul_f32 v[18:19], v[10:11], v[16:17] op_sel_hi:[1,0]
	v_pk_mul_f32 v[10:11], v[8:9], v[16:17] op_sel_hi:[1,0]
	v_cvt_pk_bf16_f32 v8, v12, v13
	v_lshl_add_u64 v[12:13], v[120:121], 0, s[2:3]
	s_mov_b32 s2, 0x58000
	v_cvt_pk_bf16_f32 v9, v14, v15
	v_add_co_u32_e32 v14, vcc, s2, v120
	v_cvt_pk_bf16_f32 v10, v10, v11
	v_cvt_pk_bf16_f32 v11, v18, v19
	v_addc_co_u32_e32 v15, vcc, 0, v121, vcc
	global_store_dwordx4 v[14:15], v[8:11], off sc1
	v_pk_mul_f32 v[6:7], v[6:7], v[16:17] op_sel_hi:[1,0]
	v_pk_mul_f32 v[4:5], v[4:5], v[16:17] op_sel_hi:[1,0]
	v_pk_mul_f32 v[8:9], v[2:3], v[16:17] op_sel_hi:[1,0]
	v_pk_mul_f32 v[2:3], v[0:1], v[16:17] op_sel_hi:[1,0]
	v_cvt_pk_bf16_f32 v0, v4, v5
	v_cvt_pk_bf16_f32 v1, v6, v7
	v_cvt_pk_bf16_f32 v2, v2, v3
	v_cvt_pk_bf16_f32 v3, v8, v9
	s_andn2_b64 vcc, exec, s[54:55]
	global_store_dwordx4 v[12:13], v[0:3], off offset:256 sc1
	s_cbranch_vccnz .LBB0_109
	s_andn2_b64 vcc, exec, s[4:5]
	s_cbranch_vccnz .LBB0_108
	s_barrier
	s_branch .LBB0_108

; __device__ __forceinline__ unsigned cvt_pk_bf16(float lo, float hi) { const f32x2_t v = {lo, hi}; const bf16x2_t b = __builtin_convertvector(v, bf16x2_t); return __builtin_bit_cast(unsigned, b); }
; __device__ __forceinline__ unsigned cvt_pk_f16(float lo, float hi) { const f32x2 v = {lo, hi}; const h16x2_t h = __builtin_convertvector(v, h16x2_t); return __builtin_bit_cast(unsigned, h); }
; __device__ __forceinline__ u64 ssq_fix(float s) { return (u64)__float2ull_rn(s * 16777216.0f); }
;     __device__ __forceinline__ void operator()(const Acc& acc, const Unit& u, int wr, int wc, int fr, int fq) const {
;         const int row0 = u.pm * BM + wr * 64 + fr, col0 = u.pn * BM + wc * 32 + 8 * fq;
; #pragma unroll
;         for (int ai = 0; ai < 2; ++ai)
; #pragma unroll
;             for (int m = 0; m < 4; ++m) {
;                 asm volatile("" ::: "memory");
;                 const int r = row0 + ai * HALF + m * 16; float part = 0.f;
; #pragma unroll
;                 for (int bj = 0; bj < 2; ++bj) {
;                     const size_t off = (size_t)r * D + col0 + bj * HALF;
;                     const u32x4 hw = *(const u32x4*)(H16 + off);
;                     const f32x2 a = unpk_f16(hw.x), b2 = unpk_f16(hw.y), c = unpk_f16(hw.z), d = unpk_f16(hw.w);
;                     f32x4 v0, v1;
;                     v0[0] = a.x + acc[ai][bj][m][0][0]; v0[1] = a.y + acc[ai][bj][m][0][1]; v0[2] = b2.x + acc[ai][bj][m][0][2]; v0[3] = b2.y + acc[ai][bj][m][0][3];
;                     v1[0] = c.x + acc[ai][bj][m][1][0]; v1[1] = c.y + acc[ai][bj][m][1][1]; v1[2] = d.x + acc[ai][bj][m][1][2]; v1[3] = d.y + acc[ai][bj][m][1][3];
;                     u32x4 w; w.x = cvt_pk_bf16(v0[0], v0[1]); w.y = cvt_pk_bf16(v0[2], v0[3]); w.z = cvt_pk_bf16(v1[0], v1[1]); w.w = cvt_pk_bf16(v1[2], v1[3]);
;                     u32x4 hq; hq.x = cvt_pk_f16(v0[0], v0[1]); hq.y = cvt_pk_f16(v0[2], v0[3]); hq.z = cvt_pk_f16(v1[0], v1[1]); hq.w = cvt_pk_f16(v1[2], v1[3]);
;                     if (!dry) { *(u32x4*)(HB + off) = w; *(u32x4*)(H16 + off) = hq; }
;                     part += v0[0] * v0[0] + v0[1] * v0[1] + v0[2] * v0[2] + v0[3] * v0[3] + v1[0] * v1[0] + v1[1] * v1[1] + v1[2] * v1[2] + v1[3] * v1[3];
;                 }
;                 part += __shfl_xor(part, 16); part += __shfl_xor(part, 32);
;                 if (fq == 0 && !dry) atomicAdd(ssq_out + r, ssq_fix(part));
.LBB0_148:
	v_lshl_add_u32 v142, s62, 8, v144
	v_lshl_or_b32 v140, s66, 8, v146
	v_ashrrev_i32_e32 v143, 31, v142
	v_ashrrev_i32_e32 v141, 31, v140
	v_lshlrev_b64 v[138:139], 11, v[142:143]
	v_lshl_add_u64 v[138:139], v[138:139], 0, v[140:141]
	v_lshlrev_b64 v[138:139], 1, v[138:139]
	v_mov_b32_e32 v214, v138
	global_load_dwordx4 v[170:173], v214, s[14:15]
	global_load_dwordx4 v[174:177], v214, s[14:15] offset:256
	v_add_u32_e32 v215, 0x10000, v214
	global_load_dwordx4 v[178:181], v215, s[14:15]
	global_load_dwordx4 v[182:185], v215, s[14:15] offset:256
	v_add_u32_e32 v215, 0x20000, v214
	global_load_dwordx4 v[186:189], v215, s[14:15]
	global_load_dwordx4 v[190:193], v215, s[14:15] offset:256
	v_add_u32_e32 v215, 0x30000, v214
	global_load_dwordx4 v[194:197], v215, s[14:15]
	global_load_dwordx4 v[198:201], v215, s[14:15] offset:256
	v_add_u32_e32 v215, 0x80000, v214
	global_load_dwordx4 v[202:205], v215, s[14:15]
	global_load_dwordx4 v[206:209], v215, s[14:15] offset:256
	v_add_u32_e32 v215, 0x90000, v214
	global_load_dwordx4 v[210:213], v215, s[14:15]
	v_lshl_add_u64 v[152:153], s[14:15], 0, v[138:139]
	s_waitcnt vmcnt(10)
	s_nop 1
	v_mov_b64_e32 v[148:149], v[170:171]
	v_mov_b64_e32 v[150:151], v[172:173]
	global_load_dwordx4 v[170:173], v215, s[14:15] offset:256
	v_lshl_add_u64 v[158:159], s[80:81], 0, v[138:139]
	v_cvt_f32_f16_e32 v154, v148
	v_cvt_f32_f16_sdwa v155, v148 dst_sel:DWORD dst_unused:UNUSED_PAD src0_sel:WORD_1
	v_cvt_f32_f16_e32 v148, v149
	v_cvt_f32_f16_sdwa v149, v149 dst_sel:DWORD dst_unused:UNUSED_PAD src0_sel:WORD_1
	v_cvt_f32_f16_e32 v156, v150
	v_cvt_f32_f16_sdwa v157, v150 dst_sel:DWORD dst_unused:UNUSED_PAD src0_sel:WORD_1
	v_cvt_f32_f16_e32 v150, v151
	v_cvt_f32_f16_sdwa v151, v151 dst_sel:DWORD dst_unused:UNUSED_PAD src0_sel:WORD_1
	v_pk_add_f32 v[154:155], v[124:125], v[154:155]
	v_pk_add_f32 v[148:149], v[126:127], v[148:149]
	v_pk_add_f32 v[156:157], v[120:121], v[156:157]
	v_pk_add_f32 v[150:151], v[122:123], v[150:151]
	v_cvt_pk_bf16_f32 v126, v156, v157
	v_cvt_pk_bf16_f32 v127, v150, v151
	v_cvt_pk_bf16_f32 v125, v148, v149
	v_cvt_pk_bf16_f32 v124, v154, v155
	v_cvt_pk_f16_f32 v123, v150, v151
	v_cvt_pk_f16_f32 v122, v156, v157
	v_cvt_pk_f16_f32 v121, v148, v149
	v_cvt_pk_f16_f32 v120, v154, v155
	global_store_dwordx4 v[158:159], v[124:127], off sc1
	global_store_dwordx4 v[152:153], v[120:123], off sc1
	v_or_b32_e32 v152, 0x100, v138
	v_mov_b32_e32 v153, v139
	v_pk_mul_f32 v[124:125], v[154:155], v[154:155]
	v_lshl_add_u64 v[154:155], s[14:15], 0, v[152:153]
	s_waitcnt vmcnt(12)
	s_nop 1
	v_mov_b64_e32 v[120:121], v[174:175]
	v_mov_b64_e32 v[122:123], v[176:177]
	v_add_u32_e32 v215, 0xa0000, v214
	global_load_dwordx4 v[174:177], v215, s[14:15]
	v_pk_mul_f32 v[126:127], v[148:149], v[148:149]
	v_pk_mul_f32 v[148:149], v[156:157], v[156:157]
	v_lshl_add_u64 v[152:153], s[80:81], 0, v[152:153]
	v_pk_mul_f32 v[150:151], v[150:151], v[150:151]
	v_cvt_f32_f16_e32 v156, v120
	v_cvt_f32_f16_sdwa v157, v120 dst_sel:DWORD dst_unused:UNUSED_PAD src0_sel:WORD_1
	v_cvt_f32_f16_e32 v120, v121
	v_cvt_f32_f16_sdwa v121, v121 dst_sel:DWORD dst_unused:UNUSED_PAD src0_sel:WORD_1
	v_cvt_f32_f16_e32 v158, v122
	v_cvt_f32_f16_sdwa v159, v122 dst_sel:DWORD dst_unused:UNUSED_PAD src0_sel:WORD_1
	v_cvt_f32_f16_e32 v122, v123
	v_cvt_f32_f16_sdwa v123, v123 dst_sel:DWORD dst_unused:UNUSED_PAD src0_sel:WORD_1
	v_pk_add_f32 v[156:157], v[116:117], v[156:157]
	v_pk_add_f32 v[120:121], v[118:119], v[120:121]
	v_pk_add_f32 v[158:159], v[112:113], v[158:159]
	v_pk_add_f32 v[122:123], v[114:115], v[122:123]
	v_cvt_pk_f16_f32 v113, v120, v121
	v_cvt_pk_f16_f32 v112, v156, v157
	v_cvt_pk_bf16_f32 v119, v122, v123
	v_cvt_pk_bf16_f32 v118, v158, v159
	v_cvt_pk_bf16_f32 v117, v120, v121
	v_cvt_pk_bf16_f32 v116, v156, v157
	v_cvt_pk_f16_f32 v115, v122, v123
	v_cvt_pk_f16_f32 v114, v158, v159
	global_store_dwordx4 v[152:153], v[116:119], off sc1
	global_store_dwordx4 v[154:155], v[112:115], off sc1
	s_nop 0
	v_pk_mul_f32 v[116:117], v[158:159], v[158:159]
	v_pk_mul_f32 v[112:113], v[156:157], v[156:157]
	v_pk_mul_f32 v[114:115], v[120:121], v[120:121]
	v_add_f32_e32 v112, v112, v113
	v_add_f32_e32 v113, v124, v125
	v_add_f32_e32 v112, v114, v112
	v_add_f32_e32 v113, v126, v113
	v_add_f32_e32 v112, v115, v112
	v_add_f32_e32 v113, v127, v113
	v_add_f32_e32 v112, v116, v112
	v_add_f32_e32 v113, v148, v113
	v_pk_mul_f32 v[118:119], v[122:123], v[122:123]
	v_add_f32_e32 v112, v117, v112
	v_add_f32_e32 v113, v149, v113
	v_add_f32_e32 v112, v118, v112
	v_add_f32_e32 v113, v150, v113
	v_add_f32_e32 v112, v119, v112
	v_add_f32_e32 v113, v151, v113
	v_and_b32_e32 v114, 64, v240
	v_add_f32_e32 v112, v113, v112
	v_xor_b32_e32 v113, 16, v240
	v_add_u32_e32 v115, 64, v114
	v_cmp_lt_i32_e32 vcc, v113, v115
	s_nop 1
	v_cndmask_b32_e32 v113, v240, v113, vcc
	v_lshlrev_b32_e32 v116, 2, v113
	ds_bpermute_b32 v113, v116, v112
	s_waitcnt lgkmcnt(0)
	v_add_f32_e32 v114, v112, v113
	v_xor_b32_e32 v112, 32, v240
	v_cmp_lt_i32_e32 vcc, v112, v115
	s_nop 1
	v_cndmask_b32_e32 v112, v240, v112, vcc
	v_lshlrev_b32_e32 v117, 2, v112
	ds_bpermute_b32 v115, v117, v114
	v_lshl_add_u64 v[112:113], v[142:143], 3, s[16:17]
	s_and_saveexec_b64 s[2:3], s[4:5]
	s_mov_b64 s[96:97], 0x80000
	s_mov_b32 s44, 0x3e0293ee
	s_cbranch_execz .LBB0_150
	s_waitcnt lgkmcnt(0)
	v_add_f32_e32 v114, v114, v115
	v_mul_f32_e32 v114, 0x4b800000, v114
	v_rndne_f32_e32 v114, v114
	v_mul_f32_e32 v115, 0x2f800000, v114
	v_floor_f32_e32 v115, v115
	v_fmac_f32_e32 v114, 0xcf800000, v115
	v_cvt_u32_f32_e32 v114, v114
	v_cvt_u32_f32_e32 v115, v115
	global_atomic_add_x2 v[112:113], v[114:115], off
; __device__ __forceinline__ unsigned cvt_pk_bf16(float lo, float hi) { const f32x2_t v = {lo, hi}; const bf16x2_t b = __builtin_convertvector(v, bf16x2_t); return __builtin_bit_cast(unsigned, b); }
; __device__ __forceinline__ unsigned cvt_pk_f16(float lo, float hi) { const f32x2 v = {lo, hi}; const h16x2_t h = __builtin_convertvector(v, h16x2_t); return __builtin_bit_cast(unsigned, h); }
; __device__ __forceinline__ f32x2 unpk_f16(unsigned u) { const h16x2_t h = __builtin_bit_cast(h16x2_t, u); return __builtin_convertvector(h, f32x2); }
; __device__ __forceinline__ u64 ssq_fix(float s) { return (u64)__float2ull_rn(s * 16777216.0f); }
;     __device__ __forceinline__ void operator()(const Acc& acc, const Unit& u, int wr, int wc, int fr, int fq) const {
;     ...
;             for (int m = 0; m < 4; ++m) {
;                 asm volatile("" ::: "memory");
;                 const int r = row0 + ai * HALF + m * 16; float part = 0.f;
; #pragma unroll
;                 for (int bj = 0; bj < 2; ++bj) {
;                     const size_t off = (size_t)r * D + col0 + bj * HALF;
;                     const u32x4 hw = *(const u32x4*)(H16 + off);
;                     const f32x2 a = unpk_f16(hw.x), b2 = unpk_f16(hw.y), c = unpk_f16(hw.z), d = unpk_f16(hw.w);
;                     f32x4 v0, v1;
;                     v0[0] = a.x + acc[ai][bj][m][0][0]; v0[1] = a.y + acc[ai][bj][m][0][1]; v0[2] = b2.x + acc[ai][bj][m][0][2]; v0[3] = b2.y + acc[ai][bj][m][0][3];
;                     v1[0] = c.x + acc[ai][bj][m][1][0]; v1[1] = c.y + acc[ai][bj][m][1][1]; v1[2] = d.x + acc[ai][bj][m][1][2]; v1[3] = d.y + acc[ai][bj][m][1][3];
;                     u32x4 w; w.x = cvt_pk_bf16(v0[0], v0[1]); w.y = cvt_pk_bf16(v0[2], v0[3]); w.z = cvt_pk_bf16(v1[0], v1[1]); w.w = cvt_pk_bf16(v1[2], v1[3]);
;                     u32x4 hq; hq.x = cvt_pk_f16(v0[0], v0[1]); hq.y = cvt_pk_f16(v0[2], v0[3]); hq.z = cvt_pk_f16(v1[0], v1[1]); hq.w = cvt_pk_f16(v1[2], v1[3]);
;                     if (!dry) { *(u32x4*)(HB + off) = w; *(u32x4*)(H16 + off) = hq; }
;                     part += v0[0] * v0[0] + v0[1] * v0[1] + v0[2] * v0[2] + v0[3] * v0[3] + v1[0] * v1[0] + v1[1] * v1[1] + v1[2] * v1[2] + v1[3] * v1[3];
;                 }
;                 part += __shfl_xor(part, 16); part += __shfl_xor(part, 32);
;                 if (fq == 0 && !dry) atomicAdd(ssq_out + r, ssq_fix(part));
.LBB0_150:
	s_or_b64 exec, exec, s[2:3]
	v_or_b32_e32 v114, 16, v142
	s_waitcnt lgkmcnt(0)
	v_ashrrev_i32_e32 v115, 31, v114
	v_lshlrev_b64 v[114:115], 11, v[114:115]
	v_lshl_add_u64 v[114:115], v[114:115], 0, v[140:141]
	v_lshlrev_b64 v[114:115], 1, v[114:115]
	v_lshl_add_u64 v[122:123], s[14:15], 0, v[114:115]
	s_waitcnt vmcnt(14)
	s_nop 1
	v_mov_b64_e32 v[118:119], v[178:179]
	v_mov_b64_e32 v[120:121], v[180:181]
	global_load_dwordx4 v[178:181], v215, s[14:15] offset:256
	v_lshl_add_u64 v[148:149], s[80:81], 0, v[114:115]
	v_or_b32_e32 v114, 0x100, v114
	v_cvt_f32_f16_e32 v124, v118
	v_cvt_f32_f16_sdwa v125, v118 dst_sel:DWORD dst_unused:UNUSED_PAD src0_sel:WORD_1
	v_cvt_f32_f16_e32 v118, v119
	v_cvt_f32_f16_sdwa v119, v119 dst_sel:DWORD dst_unused:UNUSED_PAD src0_sel:WORD_1
	v_cvt_f32_f16_e32 v126, v120
	v_cvt_f32_f16_sdwa v127, v120 dst_sel:DWORD dst_unused:UNUSED_PAD src0_sel:WORD_1
	v_cvt_f32_f16_e32 v120, v121
	v_cvt_f32_f16_sdwa v121, v121 dst_sel:DWORD dst_unused:UNUSED_PAD src0_sel:WORD_1
	v_pk_add_f32 v[124:125], v[108:109], v[124:125]
	v_pk_add_f32 v[118:119], v[110:111], v[118:119]
	v_pk_add_f32 v[126:127], v[104:105], v[126:127]
	v_pk_add_f32 v[120:121], v[106:107], v[120:121]
	v_cvt_pk_bf16_f32 v110, v126, v127
	v_cvt_pk_bf16_f32 v111, v120, v121
	v_cvt_pk_bf16_f32 v109, v118, v119
	v_cvt_pk_bf16_f32 v108, v124, v125
	v_cvt_pk_f16_f32 v107, v120, v121
	v_cvt_pk_f16_f32 v106, v126, v127
	v_cvt_pk_f16_f32 v105, v118, v119
	v_cvt_pk_f16_f32 v104, v124, v125
	global_store_dwordx4 v[148:149], v[108:111], off sc1
	global_store_dwordx4 v[122:123], v[104:107], off sc1
	v_lshl_add_u64 v[122:123], s[14:15], 0, v[114:115]
	v_pk_mul_f32 v[108:109], v[118:119], v[118:119]
	v_pk_mul_f32 v[104:105], v[120:121], v[120:121]
	s_waitcnt vmcnt(16)
	s_nop 1
	v_mov_b64_e32 v[118:119], v[182:183]
	v_mov_b64_e32 v[120:121], v[184:185]
	v_add_u32_e32 v215, 0xb0000, v214
	global_load_dwordx4 v[182:185], v215, s[14:15]
	v_pk_mul_f32 v[110:111], v[124:125], v[124:125]
	v_pk_mul_f32 v[106:107], v[126:127], v[126:127]
	v_lshl_add_u64 v[114:115], s[80:81], 0, v[114:115]
	v_cvt_f32_f16_e32 v124, v118
	v_cvt_f32_f16_sdwa v125, v118 dst_sel:DWORD dst_unused:UNUSED_PAD src0_sel:WORD_1
	v_cvt_f32_f16_e32 v118, v119
	v_cvt_f32_f16_sdwa v119, v119 dst_sel:DWORD dst_unused:UNUSED_PAD src0_sel:WORD_1
	v_cvt_f32_f16_e32 v126, v120
	v_cvt_f32_f16_sdwa v127, v120 dst_sel:DWORD dst_unused:UNUSED_PAD src0_sel:WORD_1
	v_cvt_f32_f16_e32 v120, v121
	v_cvt_f32_f16_sdwa v121, v121 dst_sel:DWORD dst_unused:UNUSED_PAD src0_sel:WORD_1
	v_pk_add_f32 v[124:125], v[100:101], v[124:125]
	v_pk_add_f32 v[118:119], v[102:103], v[118:119]
	v_pk_add_f32 v[126:127], v[96:97], v[126:127]
	v_pk_add_f32 v[120:121], v[98:99], v[120:121]
	v_cvt_pk_f16_f32 v97, v118, v119
	v_cvt_pk_f16_f32 v96, v124, v125
	v_cvt_pk_bf16_f32 v103, v120, v121
	v_cvt_pk_bf16_f32 v102, v126, v127
	v_cvt_pk_bf16_f32 v101, v118, v119
	v_cvt_pk_bf16_f32 v100, v124, v125
	v_cvt_pk_f16_f32 v99, v120, v121
	v_cvt_pk_f16_f32 v98, v126, v127
	global_store_dwordx4 v[114:115], v[100:103], off sc1
	global_store_dwordx4 v[122:123], v[96:99], off sc1
	s_nop 0
	v_pk_mul_f32 v[100:101], v[126:127], v[126:127]
	v_pk_mul_f32 v[96:97], v[124:125], v[124:125]
	v_pk_mul_f32 v[98:99], v[118:119], v[118:119]
	v_add_f32_e32 v96, v96, v97
	v_add_f32_e32 v97, v110, v111
	v_add_f32_e32 v96, v98, v96
	v_add_f32_e32 v97, v108, v97
	v_add_f32_e32 v96, v99, v96
	v_add_f32_e32 v97, v109, v97
	v_add_f32_e32 v96, v100, v96
	v_add_f32_e32 v97, v106, v97
	v_pk_mul_f32 v[102:103], v[120:121], v[120:121]
	v_add_f32_e32 v96, v101, v96
	v_add_f32_e32 v97, v107, v97
	v_add_f32_e32 v96, v102, v96
	v_add_f32_e32 v97, v104, v97
	v_add_f32_e32 v96, v103, v96
	v_add_f32_e32 v97, v105, v97
	v_add_f32_e32 v96, v97, v96
	ds_bpermute_b32 v97, v116, v96
	s_waitcnt lgkmcnt(0)
	v_add_f32_e32 v96, v96, v97
	ds_bpermute_b32 v97, v117, v96
	s_and_saveexec_b64 s[2:3], s[4:5]
	s_cbranch_execz .LBB0_152
	s_waitcnt lgkmcnt(0)
	v_add_f32_e32 v96, v96, v97
	v_mul_f32_e32 v96, 0x4b800000, v96
	v_rndne_f32_e32 v96, v96
	v_mul_f32_e32 v97, 0x2f800000, v96
	v_floor_f32_e32 v97, v97
	v_fmac_f32_e32 v96, 0xcf800000, v97
	v_cvt_u32_f32_e32 v96, v96
	v_cvt_u32_f32_e32 v97, v97
	global_atomic_add_x2 v[112:113], v[96:97], off offset:128
; __device__ __forceinline__ unsigned cvt_pk_bf16(float lo, float hi) { const f32x2_t v = {lo, hi}; const bf16x2_t b = __builtin_convertvector(v, bf16x2_t); return __builtin_bit_cast(unsigned, b); }
; __device__ __forceinline__ unsigned cvt_pk_f16(float lo, float hi) { const f32x2 v = {lo, hi}; const h16x2_t h = __builtin_convertvector(v, h16x2_t); return __builtin_bit_cast(unsigned, h); }
; __device__ __forceinline__ f32x2 unpk_f16(unsigned u) { const h16x2_t h = __builtin_bit_cast(h16x2_t, u); return __builtin_convertvector(h, f32x2); }
; __device__ __forceinline__ u64 ssq_fix(float s) { return (u64)__float2ull_rn(s * 16777216.0f); }
;     __device__ __forceinline__ void operator()(const Acc& acc, const Unit& u, int wr, int wc, int fr, int fq) const {
;     ...
;             for (int m = 0; m < 4; ++m) {
;                 asm volatile("" ::: "memory");
;                 const int r = row0 + ai * HALF + m * 16; float part = 0.f;
; #pragma unroll
;                 for (int bj = 0; bj < 2; ++bj) {
;                     const size_t off = (size_t)r * D + col0 + bj * HALF;
;                     const u32x4 hw = *(const u32x4*)(H16 + off);
;                     const f32x2 a = unpk_f16(hw.x), b2 = unpk_f16(hw.y), c = unpk_f16(hw.z), d = unpk_f16(hw.w);
;                     f32x4 v0, v1;
;                     v0[0] = a.x + acc[ai][bj][m][0][0]; v0[1] = a.y + acc[ai][bj][m][0][1]; v0[2] = b2.x + acc[ai][bj][m][0][2]; v0[3] = b2.y + acc[ai][bj][m][0][3];
;                     v1[0] = c.x + acc[ai][bj][m][1][0]; v1[1] = c.y + acc[ai][bj][m][1][1]; v1[2] = d.x + acc[ai][bj][m][1][2]; v1[3] = d.y + acc[ai][bj][m][1][3];
;                     u32x4 w; w.x = cvt_pk_bf16(v0[0], v0[1]); w.y = cvt_pk_bf16(v0[2], v0[3]); w.z = cvt_pk_bf16(v1[0], v1[1]); w.w = cvt_pk_bf16(v1[2], v1[3]);
;                     u32x4 hq; hq.x = cvt_pk_f16(v0[0], v0[1]); hq.y = cvt_pk_f16(v0[2], v0[3]); hq.z = cvt_pk_f16(v1[0], v1[1]); hq.w = cvt_pk_f16(v1[2], v1[3]);
;                     if (!dry) { *(u32x4*)(HB + off) = w; *(u32x4*)(H16 + off) = hq; }
;                     part += v0[0] * v0[0] + v0[1] * v0[1] + v0[2] * v0[2] + v0[3] * v0[3] + v1[0] * v1[0] + v1[1] * v1[1] + v1[2] * v1[2] + v1[3] * v1[3];
;                 }
;                 part += __shfl_xor(part, 16); part += __shfl_xor(part, 32);
;                 if (fq == 0 && !dry) atomicAdd(ssq_out + r, ssq_fix(part));
.LBB0_152:
	s_or_b64 exec, exec, s[2:3]
	v_or_b32_e32 v96, 32, v142
	s_waitcnt lgkmcnt(0)
	v_ashrrev_i32_e32 v97, 31, v96
	v_lshlrev_b64 v[96:97], 11, v[96:97]
	v_lshl_add_u64 v[96:97], v[96:97], 0, v[140:141]
	v_lshlrev_b64 v[96:97], 1, v[96:97]
	v_lshl_add_u64 v[102:103], s[14:15], 0, v[96:97]
	s_waitcnt vmcnt(18)
	s_nop 1
	v_mov_b64_e32 v[98:99], v[186:187]
	v_mov_b64_e32 v[100:101], v[188:189]
	global_load_dwordx4 v[186:189], v215, s[14:15] offset:256
	v_lshl_add_u64 v[108:109], s[80:81], 0, v[96:97]
	v_or_b32_e32 v96, 0x100, v96
	v_cvt_f32_f16_e32 v104, v98
	v_cvt_f32_f16_sdwa v105, v98 dst_sel:DWORD dst_unused:UNUSED_PAD src0_sel:WORD_1
	v_cvt_f32_f16_e32 v98, v99
	v_cvt_f32_f16_sdwa v99, v99 dst_sel:DWORD dst_unused:UNUSED_PAD src0_sel:WORD_1
	v_cvt_f32_f16_e32 v106, v100
	v_cvt_f32_f16_sdwa v107, v100 dst_sel:DWORD dst_unused:UNUSED_PAD src0_sel:WORD_1
	v_cvt_f32_f16_e32 v100, v101
	v_cvt_f32_f16_sdwa v101, v101 dst_sel:DWORD dst_unused:UNUSED_PAD src0_sel:WORD_1
	v_pk_add_f32 v[104:105], v[92:93], v[104:105]
	v_pk_add_f32 v[98:99], v[94:95], v[98:99]
	v_pk_add_f32 v[106:107], v[88:89], v[106:107]
	v_pk_add_f32 v[100:101], v[90:91], v[100:101]
	v_cvt_pk_bf16_f32 v94, v106, v107
	v_cvt_pk_bf16_f32 v95, v100, v101
	v_cvt_pk_bf16_f32 v93, v98, v99
	v_cvt_pk_bf16_f32 v92, v104, v105
	v_cvt_pk_f16_f32 v91, v100, v101
	v_cvt_pk_f16_f32 v90, v106, v107
	v_cvt_pk_f16_f32 v89, v98, v99
	v_cvt_pk_f16_f32 v88, v104, v105
	global_store_dwordx4 v[108:109], v[92:95], off sc1
	global_store_dwordx4 v[102:103], v[88:91], off sc1
	v_lshl_add_u64 v[102:103], s[14:15], 0, v[96:97]
	v_pk_mul_f32 v[92:93], v[98:99], v[98:99]
	v_pk_mul_f32 v[88:89], v[100:101], v[100:101]
	s_waitcnt vmcnt(20)
	s_nop 1
	v_mov_b64_e32 v[98:99], v[190:191]
	v_mov_b64_e32 v[100:101], v[192:193]
	v_pk_mul_f32 v[94:95], v[104:105], v[104:105]
	v_pk_mul_f32 v[90:91], v[106:107], v[106:107]
	v_lshl_add_u64 v[96:97], s[80:81], 0, v[96:97]
	v_cvt_f32_f16_e32 v104, v98
	v_cvt_f32_f16_sdwa v105, v98 dst_sel:DWORD dst_unused:UNUSED_PAD src0_sel:WORD_1
	v_cvt_f32_f16_e32 v98, v99
	v_cvt_f32_f16_sdwa v99, v99 dst_sel:DWORD dst_unused:UNUSED_PAD src0_sel:WORD_1
	v_cvt_f32_f16_e32 v106, v100
	v_cvt_f32_f16_sdwa v107, v100 dst_sel:DWORD dst_unused:UNUSED_PAD src0_sel:WORD_1
	v_cvt_f32_f16_e32 v100, v101
	v_cvt_f32_f16_sdwa v101, v101 dst_sel:DWORD dst_unused:UNUSED_PAD src0_sel:WORD_1
	v_pk_add_f32 v[104:105], v[84:85], v[104:105]
	v_pk_add_f32 v[98:99], v[86:87], v[98:99]
	v_pk_add_f32 v[106:107], v[80:81], v[106:107]
	v_pk_add_f32 v[100:101], v[82:83], v[100:101]
	v_cvt_pk_f16_f32 v81, v98, v99
	v_cvt_pk_f16_f32 v80, v104, v105
	v_cvt_pk_bf16_f32 v87, v100, v101
	v_cvt_pk_bf16_f32 v86, v106, v107
	v_cvt_pk_bf16_f32 v85, v98, v99
	v_cvt_pk_bf16_f32 v84, v104, v105
	v_cvt_pk_f16_f32 v83, v100, v101
	v_cvt_pk_f16_f32 v82, v106, v107
	global_store_dwordx4 v[96:97], v[84:87], off sc1
	global_store_dwordx4 v[102:103], v[80:83], off sc1
	s_nop 0
	v_pk_mul_f32 v[84:85], v[106:107], v[106:107]
	v_pk_mul_f32 v[80:81], v[104:105], v[104:105]
	v_pk_mul_f32 v[82:83], v[98:99], v[98:99]
	v_add_f32_e32 v80, v80, v81
	v_add_f32_e32 v81, v94, v95
	v_add_f32_e32 v80, v82, v80
	v_add_f32_e32 v81, v92, v81
	v_add_f32_e32 v80, v83, v80
	v_add_f32_e32 v81, v93, v81
	v_add_f32_e32 v80, v84, v80
	v_add_f32_e32 v81, v90, v81
	v_pk_mul_f32 v[86:87], v[100:101], v[100:101]
	v_add_f32_e32 v80, v85, v80
	v_add_f32_e32 v81, v91, v81
	v_add_f32_e32 v80, v86, v80
	v_add_f32_e32 v81, v88, v81
	v_add_f32_e32 v80, v87, v80
	v_add_f32_e32 v81, v89, v81
	v_add_f32_e32 v80, v81, v80
	ds_bpermute_b32 v81, v116, v80
	s_waitcnt lgkmcnt(0)
	v_add_f32_e32 v80, v80, v81
	ds_bpermute_b32 v81, v117, v80
	s_and_saveexec_b64 s[2:3], s[4:5]
	s_cbranch_execz .LBB0_154
	s_waitcnt lgkmcnt(0)
	v_add_f32_e32 v80, v80, v81
	v_mul_f32_e32 v80, 0x4b800000, v80
	v_rndne_f32_e32 v80, v80
	v_mul_f32_e32 v81, 0x2f800000, v80
	v_floor_f32_e32 v81, v81
	v_fmac_f32_e32 v80, 0xcf800000, v81
	v_cvt_u32_f32_e32 v80, v80
	v_cvt_u32_f32_e32 v81, v81
	global_atomic_add_x2 v[112:113], v[80:81], off offset:256
.LBB0_154:
	s_or_b64 exec, exec, s[2:3]
	v_or_b32_e32 v80, 48, v142
	s_waitcnt lgkmcnt(0)
	v_ashrrev_i32_e32 v81, 31, v80
	v_lshlrev_b64 v[80:81], 11, v[80:81]
	v_lshl_add_u64 v[80:81], v[80:81], 0, v[140:141]
	v_lshlrev_b64 v[80:81], 1, v[80:81]
	v_lshl_add_u64 v[86:87], s[14:15], 0, v[80:81]
	s_waitcnt vmcnt(21)
	s_nop 1
	v_mov_b64_e32 v[82:83], v[194:195]
	v_mov_b64_e32 v[84:85], v[196:197]
	v_lshl_add_u64 v[92:93], s[80:81], 0, v[80:81]
	v_or_b32_e32 v80, 0x100, v80
	v_cvt_f32_f16_e32 v88, v82
	v_cvt_f32_f16_sdwa v89, v82 dst_sel:DWORD dst_unused:UNUSED_PAD src0_sel:WORD_1
	v_cvt_f32_f16_e32 v82, v83
	v_cvt_f32_f16_sdwa v83, v83 dst_sel:DWORD dst_unused:UNUSED_PAD src0_sel:WORD_1
	v_cvt_f32_f16_e32 v90, v84
	v_cvt_f32_f16_sdwa v91, v84 dst_sel:DWORD dst_unused:UNUSED_PAD src0_sel:WORD_1
	v_cvt_f32_f16_e32 v84, v85
	v_cvt_f32_f16_sdwa v85, v85 dst_sel:DWORD dst_unused:UNUSED_PAD src0_sel:WORD_1
	v_pk_add_f32 v[88:89], v[76:77], v[88:89]
	v_pk_add_f32 v[82:83], v[78:79], v[82:83]
	v_pk_add_f32 v[90:91], v[72:73], v[90:91]
	v_pk_add_f32 v[84:85], v[74:75], v[84:85]
	v_cvt_pk_bf16_f32 v78, v90, v91
	v_cvt_pk_bf16_f32 v79, v84, v85
	v_cvt_pk_bf16_f32 v77, v82, v83
	v_cvt_pk_bf16_f32 v76, v88, v89
	v_cvt_pk_f16_f32 v75, v84, v85
	v_cvt_pk_f16_f32 v74, v90, v91
	v_cvt_pk_f16_f32 v73, v82, v83
	v_cvt_pk_f16_f32 v72, v88, v89
	global_store_dwordx4 v[92:93], v[76:79], off sc1
	global_store_dwordx4 v[86:87], v[72:75], off sc1
	v_lshl_add_u64 v[86:87], s[14:15], 0, v[80:81]
	v_pk_mul_f32 v[76:77], v[82:83], v[82:83]
	v_pk_mul_f32 v[72:73], v[84:85], v[84:85]
	s_waitcnt vmcnt(22)
; __device__ __forceinline__ unsigned cvt_pk_bf16(float lo, float hi) { const f32x2_t v = {lo, hi}; const bf16x2_t b = __builtin_convertvector(v, bf16x2_t); return __builtin_bit_cast(unsigned, b); }
; __device__ __forceinline__ unsigned cvt_pk_f16(float lo, float hi) { const f32x2 v = {lo, hi}; const h16x2_t h = __builtin_convertvector(v, h16x2_t); return __builtin_bit_cast(unsigned, h); }
; __device__ __forceinline__ f32x2 unpk_f16(unsigned u) { const h16x2_t h = __builtin_bit_cast(h16x2_t, u); return __builtin_convertvector(h, f32x2); }
; __device__ __forceinline__ u64 ssq_fix(float s) { return (u64)__float2ull_rn(s * 16777216.0f); }
;     __device__ __forceinline__ void operator()(const Acc& acc, const Unit& u, int wr, int wc, int fr, int fq) const {
;     ...
;             for (int m = 0; m < 4; ++m) {
;                 asm volatile("" ::: "memory");
;                 const int r = row0 + ai * HALF + m * 16; float part = 0.f;
; #pragma unroll
;                 for (int bj = 0; bj < 2; ++bj) {
;                     const size_t off = (size_t)r * D + col0 + bj * HALF;
;                     const u32x4 hw = *(const u32x4*)(H16 + off);
;                     const f32x2 a = unpk_f16(hw.x), b2 = unpk_f16(hw.y), c = unpk_f16(hw.z), d = unpk_f16(hw.w);
;                     f32x4 v0, v1;
;                     v0[0] = a.x + acc[ai][bj][m][0][0]; v0[1] = a.y + acc[ai][bj][m][0][1]; v0[2] = b2.x + acc[ai][bj][m][0][2]; v0[3] = b2.y + acc[ai][bj][m][0][3];
;                     v1[0] = c.x + acc[ai][bj][m][1][0]; v1[1] = c.y + acc[ai][bj][m][1][1]; v1[2] = d.x + acc[ai][bj][m][1][2]; v1[3] = d.y + acc[ai][bj][m][1][3];
;                     u32x4 w; w.x = cvt_pk_bf16(v0[0], v0[1]); w.y = cvt_pk_bf16(v0[2], v0[3]); w.z = cvt_pk_bf16(v1[0], v1[1]); w.w = cvt_pk_bf16(v1[2], v1[3]);
;                     u32x4 hq; hq.x = cvt_pk_f16(v0[0], v0[1]); hq.y = cvt_pk_f16(v0[2], v0[3]); hq.z = cvt_pk_f16(v1[0], v1[1]); hq.w = cvt_pk_f16(v1[2], v1[3]);
;                     if (!dry) { *(u32x4*)(HB + off) = w; *(u32x4*)(H16 + off) = hq; }
;                     part += v0[0] * v0[0] + v0[1] * v0[1] + v0[2] * v0[2] + v0[3] * v0[3] + v1[0] * v1[0] + v1[1] * v1[1] + v1[2] * v1[2] + v1[3] * v1[3];
;                 }
;                 part += __shfl_xor(part, 16); part += __shfl_xor(part, 32);
;                 if (fq == 0 && !dry) atomicAdd(ssq_out + r, ssq_fix(part));
	s_nop 1
	v_mov_b64_e32 v[82:83], v[198:199]
	v_mov_b64_e32 v[84:85], v[200:201]
	v_pk_mul_f32 v[78:79], v[88:89], v[88:89]
	v_pk_mul_f32 v[74:75], v[90:91], v[90:91]
	v_lshl_add_u64 v[80:81], s[80:81], 0, v[80:81]
	v_cvt_f32_f16_e32 v88, v82
	v_cvt_f32_f16_sdwa v89, v82 dst_sel:DWORD dst_unused:UNUSED_PAD src0_sel:WORD_1
	v_cvt_f32_f16_e32 v82, v83
	v_cvt_f32_f16_sdwa v83, v83 dst_sel:DWORD dst_unused:UNUSED_PAD src0_sel:WORD_1
	v_cvt_f32_f16_e32 v90, v84
	v_cvt_f32_f16_sdwa v91, v84 dst_sel:DWORD dst_unused:UNUSED_PAD src0_sel:WORD_1
	v_cvt_f32_f16_e32 v84, v85
	v_cvt_f32_f16_sdwa v85, v85 dst_sel:DWORD dst_unused:UNUSED_PAD src0_sel:WORD_1
	v_pk_add_f32 v[88:89], v[68:69], v[88:89]
	v_pk_add_f32 v[82:83], v[70:71], v[82:83]
	v_pk_add_f32 v[90:91], v[64:65], v[90:91]
	v_pk_add_f32 v[84:85], v[66:67], v[84:85]
	v_cvt_pk_f16_f32 v65, v82, v83
	v_cvt_pk_f16_f32 v64, v88, v89
	v_cvt_pk_bf16_f32 v71, v84, v85
	v_cvt_pk_bf16_f32 v70, v90, v91
	v_cvt_pk_bf16_f32 v69, v82, v83
	v_cvt_pk_bf16_f32 v68, v88, v89
	v_cvt_pk_f16_f32 v67, v84, v85
	v_cvt_pk_f16_f32 v66, v90, v91
	global_store_dwordx4 v[80:81], v[68:71], off sc1
	global_store_dwordx4 v[86:87], v[64:67], off sc1
	s_nop 0
	v_pk_mul_f32 v[68:69], v[90:91], v[90:91]
	v_pk_mul_f32 v[64:65], v[88:89], v[88:89]
	v_pk_mul_f32 v[66:67], v[82:83], v[82:83]
	v_add_f32_e32 v64, v64, v65
	v_add_f32_e32 v65, v78, v79
	v_add_f32_e32 v64, v66, v64
	v_add_f32_e32 v65, v76, v65
	v_add_f32_e32 v64, v67, v64
	v_add_f32_e32 v65, v77, v65
	v_add_f32_e32 v64, v68, v64
	v_add_f32_e32 v65, v74, v65
	v_pk_mul_f32 v[70:71], v[84:85], v[84:85]
	v_add_f32_e32 v64, v69, v64
	v_add_f32_e32 v65, v75, v65
	v_add_f32_e32 v64, v70, v64
	v_add_f32_e32 v65, v72, v65
	v_add_f32_e32 v64, v71, v64
	v_add_f32_e32 v65, v73, v65
	v_add_f32_e32 v64, v65, v64
	ds_bpermute_b32 v65, v116, v64
	s_waitcnt lgkmcnt(0)
	v_add_f32_e32 v64, v64, v65
	ds_bpermute_b32 v65, v117, v64
	s_and_saveexec_b64 s[2:3], s[4:5]
	s_cbranch_execz .LBB0_156
	s_waitcnt lgkmcnt(0)
	v_add_f32_e32 v64, v64, v65
	v_mul_f32_e32 v64, 0x4b800000, v64
	v_rndne_f32_e32 v64, v64
	v_mul_f32_e32 v65, 0x2f800000, v64
	v_floor_f32_e32 v65, v65
	v_fmac_f32_e32 v64, 0xcf800000, v65
	v_cvt_u32_f32_e32 v64, v64
	v_cvt_u32_f32_e32 v65, v65
	global_atomic_add_x2 v[112:113], v[64:65], off offset:384
.LBB0_156:
	s_or_b64 exec, exec, s[2:3]
	v_lshl_add_u64 v[68:69], v[138:139], 0, s[96:97]
	v_lshl_add_u64 v[70:71], s[14:15], 0, v[68:69]
	s_waitcnt lgkmcnt(0)
	s_waitcnt vmcnt(23)
	s_nop 1
	v_mov_b64_e32 v[64:65], v[202:203]
	v_mov_b64_e32 v[66:67], v[204:205]
	v_lshl_add_u64 v[68:69], s[80:81], 0, v[68:69]
	s_mov_b64 s[2:3], 0x80100
	v_cvt_f32_f16_e32 v72, v64
	v_cvt_f32_f16_sdwa v73, v64 dst_sel:DWORD dst_unused:UNUSED_PAD src0_sel:WORD_1
	v_cvt_f32_f16_e32 v64, v65
	v_cvt_f32_f16_sdwa v65, v65 dst_sel:DWORD dst_unused:UNUSED_PAD src0_sel:WORD_1
	v_cvt_f32_f16_e32 v74, v66
	v_cvt_f32_f16_sdwa v75, v66 dst_sel:DWORD dst_unused:UNUSED_PAD src0_sel:WORD_1
	v_cvt_f32_f16_e32 v66, v67
	v_cvt_f32_f16_sdwa v67, v67 dst_sel:DWORD dst_unused:UNUSED_PAD src0_sel:WORD_1
	v_pk_add_f32 v[72:73], v[60:61], v[72:73]
	v_pk_add_f32 v[64:65], v[62:63], v[64:65]
	v_pk_add_f32 v[74:75], v[56:57], v[74:75]
	v_pk_add_f32 v[66:67], v[58:59], v[66:67]
	v_cvt_pk_bf16_f32 v62, v74, v75
	v_cvt_pk_bf16_f32 v63, v66, v67
	v_cvt_pk_bf16_f32 v61, v64, v65
	v_cvt_pk_bf16_f32 v60, v72, v73
	v_cvt_pk_f16_f32 v59, v66, v67
	v_cvt_pk_f16_f32 v58, v74, v75
	v_cvt_pk_f16_f32 v57, v64, v65
	v_cvt_pk_f16_f32 v56, v72, v73
	global_store_dwordx4 v[68:69], v[60:63], off sc1
	global_store_dwordx4 v[70:71], v[56:59], off sc1
	v_lshl_add_u64 v[68:69], v[138:139], 0, s[2:3]
	v_lshl_add_u64 v[70:71], s[14:15], 0, v[68:69]
	v_pk_mul_f32 v[60:61], v[64:65], v[64:65]
	v_pk_mul_f32 v[56:57], v[66:67], v[66:67]
	s_waitcnt vmcnt(24)
	s_nop 1
	v_mov_b64_e32 v[64:65], v[206:207]
	v_mov_b64_e32 v[66:67], v[208:209]
	v_pk_mul_f32 v[62:63], v[72:73], v[72:73]
	v_pk_mul_f32 v[58:59], v[74:75], v[74:75]
	v_lshl_add_u64 v[68:69], s[80:81], 0, v[68:69]
	v_cvt_f32_f16_e32 v72, v64
	v_cvt_f32_f16_sdwa v73, v64 dst_sel:DWORD dst_unused:UNUSED_PAD src0_sel:WORD_1
	v_cvt_f32_f16_e32 v64, v65
	v_cvt_f32_f16_sdwa v65, v65 dst_sel:DWORD dst_unused:UNUSED_PAD src0_sel:WORD_1
	v_cvt_f32_f16_e32 v74, v66
	v_cvt_f32_f16_sdwa v75, v66 dst_sel:DWORD dst_unused:UNUSED_PAD src0_sel:WORD_1
	v_cvt_f32_f16_e32 v66, v67
	v_cvt_f32_f16_sdwa v67, v67 dst_sel:DWORD dst_unused:UNUSED_PAD src0_sel:WORD_1
	v_pk_add_f32 v[72:73], v[52:53], v[72:73]
	v_pk_add_f32 v[64:65], v[54:55], v[64:65]
	v_pk_add_f32 v[74:75], v[48:49], v[74:75]
	v_pk_add_f32 v[66:67], v[50:51], v[66:67]
	v_cvt_pk_f16_f32 v49, v64, v65
	v_cvt_pk_f16_f32 v48, v72, v73
	v_cvt_pk_bf16_f32 v55, v66, v67
	v_cvt_pk_bf16_f32 v54, v74, v75
	v_cvt_pk_bf16_f32 v53, v64, v65
	v_cvt_pk_bf16_f32 v52, v72, v73
	v_cvt_pk_f16_f32 v51, v66, v67
	v_cvt_pk_f16_f32 v50, v74, v75
	global_store_dwordx4 v[68:69], v[52:55], off sc1
	global_store_dwordx4 v[70:71], v[48:51], off sc1
	s_nop 0
	v_pk_mul_f32 v[52:53], v[74:75], v[74:75]
	v_pk_mul_f32 v[48:49], v[72:73], v[72:73]
	v_pk_mul_f32 v[50:51], v[64:65], v[64:65]
	v_add_f32_e32 v48, v48, v49
	v_add_f32_e32 v49, v62, v63
	v_add_f32_e32 v48, v50, v48
	v_add_f32_e32 v49, v60, v49
	v_add_f32_e32 v48, v51, v48
	v_add_f32_e32 v49, v61, v49
	v_add_f32_e32 v48, v52, v48
	v_add_f32_e32 v49, v58, v49
	v_pk_mul_f32 v[54:55], v[66:67], v[66:67]
	v_add_f32_e32 v48, v53, v48
	v_add_f32_e32 v49, v59, v49
	v_add_f32_e32 v48, v54, v48
	v_add_f32_e32 v49, v56, v49
	v_add_f32_e32 v48, v55, v48
	v_add_f32_e32 v49, v57, v49
	v_add_f32_e32 v48, v49, v48
	ds_bpermute_b32 v49, v116, v48
	s_waitcnt lgkmcnt(0)
	v_add_f32_e32 v48, v48, v49
	ds_bpermute_b32 v49, v117, v48
	s_and_saveexec_b64 s[2:3], s[4:5]
	s_cbranch_execz .LBB0_158
	s_waitcnt lgkmcnt(0)
	v_add_f32_e32 v48, v48, v49
	v_mul_f32_e32 v48, 0x4b800000, v48
	v_rndne_f32_e32 v48, v48
	v_mul_f32_e32 v49, 0x2f800000, v48
	v_floor_f32_e32 v49, v49
	v_fmac_f32_e32 v48, 0xcf800000, v49
	v_cvt_u32_f32_e32 v48, v48
	v_cvt_u32_f32_e32 v49, v49
	global_atomic_add_x2 v[112:113], v[48:49], off offset:1024
; __device__ __forceinline__ unsigned cvt_pk_bf16(float lo, float hi) { const f32x2_t v = {lo, hi}; const bf16x2_t b = __builtin_convertvector(v, bf16x2_t); return __builtin_bit_cast(unsigned, b); }
; __device__ __forceinline__ unsigned cvt_pk_f16(float lo, float hi) { const f32x2 v = {lo, hi}; const h16x2_t h = __builtin_convertvector(v, h16x2_t); return __builtin_bit_cast(unsigned, h); }
; __device__ __forceinline__ f32x2 unpk_f16(unsigned u) { const h16x2_t h = __builtin_bit_cast(h16x2_t, u); return __builtin_convertvector(h, f32x2); }
; __device__ __forceinline__ u64 ssq_fix(float s) { return (u64)__float2ull_rn(s * 16777216.0f); }
;     __device__ __forceinline__ void operator()(const Acc& acc, const Unit& u, int wr, int wc, int fr, int fq) const {
;     ...
;                 const int r = row0 + ai * HALF + m * 16; float part = 0.f;
; #pragma unroll
;                 for (int bj = 0; bj < 2; ++bj) {
;                     const size_t off = (size_t)r * D + col0 + bj * HALF;
;                     const u32x4 hw = *(const u32x4*)(H16 + off);
;                     const f32x2 a = unpk_f16(hw.x), b2 = unpk_f16(hw.y), c = unpk_f16(hw.z), d = unpk_f16(hw.w);
;                     f32x4 v0, v1;
;                     v0[0] = a.x + acc[ai][bj][m][0][0]; v0[1] = a.y + acc[ai][bj][m][0][1]; v0[2] = b2.x + acc[ai][bj][m][0][2]; v0[3] = b2.y + acc[ai][bj][m][0][3];
;                     v1[0] = c.x + acc[ai][bj][m][1][0]; v1[1] = c.y + acc[ai][bj][m][1][1]; v1[2] = d.x + acc[ai][bj][m][1][2]; v1[3] = d.y + acc[ai][bj][m][1][3];
;                     u32x4 w; w.x = cvt_pk_bf16(v0[0], v0[1]); w.y = cvt_pk_bf16(v0[2], v0[3]); w.z = cvt_pk_bf16(v1[0], v1[1]); w.w = cvt_pk_bf16(v1[2], v1[3]);
;                     u32x4 hq; hq.x = cvt_pk_f16(v0[0], v0[1]); hq.y = cvt_pk_f16(v0[2], v0[3]); hq.z = cvt_pk_f16(v1[0], v1[1]); hq.w = cvt_pk_f16(v1[2], v1[3]);
;                     if (!dry) { *(u32x4*)(HB + off) = w; *(u32x4*)(H16 + off) = hq; }
;                     part += v0[0] * v0[0] + v0[1] * v0[1] + v0[2] * v0[2] + v0[3] * v0[3] + v1[0] * v1[0] + v1[1] * v1[1] + v1[2] * v1[2] + v1[3] * v1[3];
;                 }
;                 part += __shfl_xor(part, 16); part += __shfl_xor(part, 32);
;                 if (fq == 0 && !dry) atomicAdd(ssq_out + r, ssq_fix(part));
.LBB0_158:
	s_or_b64 exec, exec, s[2:3]
	s_mov_b64 s[2:3], 0x90000
	v_lshl_add_u64 v[52:53], v[138:139], 0, s[2:3]
	v_lshl_add_u64 v[54:55], s[14:15], 0, v[52:53]
	s_waitcnt lgkmcnt(0)
	s_waitcnt vmcnt(25)
	s_nop 1
	v_mov_b64_e32 v[48:49], v[210:211]
	v_mov_b64_e32 v[50:51], v[212:213]
	v_lshl_add_u64 v[52:53], s[80:81], 0, v[52:53]
	s_mov_b64 s[2:3], 0x90100
	v_cvt_f32_f16_e32 v56, v48
	v_cvt_f32_f16_sdwa v57, v48 dst_sel:DWORD dst_unused:UNUSED_PAD src0_sel:WORD_1
	v_cvt_f32_f16_e32 v48, v49
	v_cvt_f32_f16_sdwa v49, v49 dst_sel:DWORD dst_unused:UNUSED_PAD src0_sel:WORD_1
	v_cvt_f32_f16_e32 v58, v50
	v_cvt_f32_f16_sdwa v59, v50 dst_sel:DWORD dst_unused:UNUSED_PAD src0_sel:WORD_1
	v_cvt_f32_f16_e32 v50, v51
	v_cvt_f32_f16_sdwa v51, v51 dst_sel:DWORD dst_unused:UNUSED_PAD src0_sel:WORD_1
	v_pk_add_f32 v[56:57], v[44:45], v[56:57]
	v_pk_add_f32 v[48:49], v[46:47], v[48:49]
	v_pk_add_f32 v[58:59], v[40:41], v[58:59]
	v_pk_add_f32 v[50:51], v[42:43], v[50:51]
	v_cvt_pk_bf16_f32 v46, v58, v59
	v_cvt_pk_bf16_f32 v47, v50, v51
	v_cvt_pk_bf16_f32 v45, v48, v49
	v_cvt_pk_bf16_f32 v44, v56, v57
	v_cvt_pk_f16_f32 v43, v50, v51
	v_cvt_pk_f16_f32 v42, v58, v59
	v_cvt_pk_f16_f32 v41, v48, v49
	v_cvt_pk_f16_f32 v40, v56, v57
	global_store_dwordx4 v[52:53], v[44:47], off sc1
	global_store_dwordx4 v[54:55], v[40:43], off sc1
	v_lshl_add_u64 v[52:53], v[138:139], 0, s[2:3]
	v_lshl_add_u64 v[54:55], s[14:15], 0, v[52:53]
	v_pk_mul_f32 v[44:45], v[48:49], v[48:49]
	v_pk_mul_f32 v[40:41], v[50:51], v[50:51]
	s_waitcnt vmcnt(26)
	s_nop 1
	v_mov_b64_e32 v[48:49], v[170:171]
	v_mov_b64_e32 v[50:51], v[172:173]
	v_pk_mul_f32 v[46:47], v[56:57], v[56:57]
	v_pk_mul_f32 v[42:43], v[58:59], v[58:59]
	v_lshl_add_u64 v[52:53], s[80:81], 0, v[52:53]
	v_cvt_f32_f16_e32 v56, v48
	v_cvt_f32_f16_sdwa v57, v48 dst_sel:DWORD dst_unused:UNUSED_PAD src0_sel:WORD_1
	v_cvt_f32_f16_e32 v48, v49
	v_cvt_f32_f16_sdwa v49, v49 dst_sel:DWORD dst_unused:UNUSED_PAD src0_sel:WORD_1
	v_cvt_f32_f16_e32 v58, v50
	v_cvt_f32_f16_sdwa v59, v50 dst_sel:DWORD dst_unused:UNUSED_PAD src0_sel:WORD_1
	v_cvt_f32_f16_e32 v50, v51
	v_cvt_f32_f16_sdwa v51, v51 dst_sel:DWORD dst_unused:UNUSED_PAD src0_sel:WORD_1
	v_pk_add_f32 v[56:57], v[36:37], v[56:57]
	v_pk_add_f32 v[48:49], v[38:39], v[48:49]
	v_pk_add_f32 v[58:59], v[32:33], v[58:59]
	v_pk_add_f32 v[50:51], v[34:35], v[50:51]
	v_cvt_pk_f16_f32 v33, v48, v49
	v_cvt_pk_f16_f32 v32, v56, v57
	v_cvt_pk_bf16_f32 v39, v50, v51
	v_cvt_pk_bf16_f32 v38, v58, v59
	v_cvt_pk_bf16_f32 v37, v48, v49
	v_cvt_pk_bf16_f32 v36, v56, v57
	v_cvt_pk_f16_f32 v35, v50, v51
	v_cvt_pk_f16_f32 v34, v58, v59
	global_store_dwordx4 v[52:53], v[36:39], off sc1
	global_store_dwordx4 v[54:55], v[32:35], off sc1
	s_nop 0
	v_pk_mul_f32 v[36:37], v[58:59], v[58:59]
	v_pk_mul_f32 v[32:33], v[56:57], v[56:57]
	v_pk_mul_f32 v[34:35], v[48:49], v[48:49]
	v_add_f32_e32 v32, v32, v33
	v_add_f32_e32 v33, v46, v47
	v_add_f32_e32 v32, v34, v32
	v_add_f32_e32 v33, v44, v33
	v_add_f32_e32 v32, v35, v32
	v_add_f32_e32 v33, v45, v33
	v_add_f32_e32 v32, v36, v32
	v_add_f32_e32 v33, v42, v33
	v_pk_mul_f32 v[38:39], v[50:51], v[50:51]
	v_add_f32_e32 v32, v37, v32
	v_add_f32_e32 v33, v43, v33
	v_add_f32_e32 v32, v38, v32
	v_add_f32_e32 v33, v40, v33
	v_add_f32_e32 v32, v39, v32
	v_add_f32_e32 v33, v41, v33
	v_add_f32_e32 v32, v33, v32
	ds_bpermute_b32 v33, v116, v32
	s_waitcnt lgkmcnt(0)
	v_add_f32_e32 v32, v32, v33
	ds_bpermute_b32 v33, v117, v32
	s_and_saveexec_b64 s[2:3], s[4:5]
	s_cbranch_execz .LBB0_160
	s_waitcnt lgkmcnt(0)
	v_add_f32_e32 v32, v32, v33
	v_mul_f32_e32 v32, 0x4b800000, v32
	v_rndne_f32_e32 v32, v32
	v_mul_f32_e32 v33, 0x2f800000, v32
	v_floor_f32_e32 v33, v33
	v_fmac_f32_e32 v32, 0xcf800000, v33
	v_cvt_u32_f32_e32 v32, v32
	v_cvt_u32_f32_e32 v33, v33
	global_atomic_add_x2 v[112:113], v[32:33], off offset:1152
.LBB0_160:
	s_or_b64 exec, exec, s[2:3]
	s_mov_b64 s[2:3], 0xa0000
	v_lshl_add_u64 v[36:37], v[138:139], 0, s[2:3]
	v_lshl_add_u64 v[38:39], s[14:15], 0, v[36:37]
	s_waitcnt lgkmcnt(0)
	s_waitcnt vmcnt(25)
	s_nop 1
	v_mov_b64_e32 v[32:33], v[174:175]
	v_mov_b64_e32 v[34:35], v[176:177]
	v_lshl_add_u64 v[36:37], s[80:81], 0, v[36:37]
	s_mov_b64 s[2:3], 0xa0100
	v_cvt_f32_f16_e32 v40, v32
	v_cvt_f32_f16_sdwa v41, v32 dst_sel:DWORD dst_unused:UNUSED_PAD src0_sel:WORD_1
	v_cvt_f32_f16_e32 v32, v33
	v_cvt_f32_f16_sdwa v33, v33 dst_sel:DWORD dst_unused:UNUSED_PAD src0_sel:WORD_1
	v_cvt_f32_f16_e32 v42, v34
	v_cvt_f32_f16_sdwa v43, v34 dst_sel:DWORD dst_unused:UNUSED_PAD src0_sel:WORD_1
	v_cvt_f32_f16_e32 v34, v35
	v_cvt_f32_f16_sdwa v35, v35 dst_sel:DWORD dst_unused:UNUSED_PAD src0_sel:WORD_1
	v_pk_add_f32 v[40:41], v[28:29], v[40:41]
	v_pk_add_f32 v[32:33], v[30:31], v[32:33]
	v_pk_add_f32 v[42:43], v[24:25], v[42:43]
	v_pk_add_f32 v[34:35], v[26:27], v[34:35]
	v_cvt_pk_bf16_f32 v30, v42, v43
	v_cvt_pk_bf16_f32 v31, v34, v35
	v_cvt_pk_bf16_f32 v29, v32, v33
	v_cvt_pk_bf16_f32 v28, v40, v41
	v_cvt_pk_f16_f32 v27, v34, v35
	v_cvt_pk_f16_f32 v26, v42, v43
	v_cvt_pk_f16_f32 v25, v32, v33
	v_cvt_pk_f16_f32 v24, v40, v41
	global_store_dwordx4 v[36:37], v[28:31], off sc1
	global_store_dwordx4 v[38:39], v[24:27], off sc1
	v_lshl_add_u64 v[36:37], v[138:139], 0, s[2:3]
	v_lshl_add_u64 v[38:39], s[14:15], 0, v[36:37]
	v_pk_mul_f32 v[28:29], v[32:33], v[32:33]
	v_pk_mul_f32 v[24:25], v[34:35], v[34:35]
	s_waitcnt vmcnt(24)
; __device__ __forceinline__ unsigned cvt_pk_bf16(float lo, float hi) { const f32x2_t v = {lo, hi}; const bf16x2_t b = __builtin_convertvector(v, bf16x2_t); return __builtin_bit_cast(unsigned, b); }
; __device__ __forceinline__ unsigned cvt_pk_f16(float lo, float hi) { const f32x2 v = {lo, hi}; const h16x2_t h = __builtin_convertvector(v, h16x2_t); return __builtin_bit_cast(unsigned, h); }
; __device__ __forceinline__ f32x2 unpk_f16(unsigned u) { const h16x2_t h = __builtin_bit_cast(h16x2_t, u); return __builtin_convertvector(h, f32x2); }
; __device__ __forceinline__ u64 ssq_fix(float s) { return (u64)__float2ull_rn(s * 16777216.0f); }
;     __device__ __forceinline__ void operator()(const Acc& acc, const Unit& u, int wr, int wc, int fr, int fq) const {
;     ...
;                 const int r = row0 + ai * HALF + m * 16; float part = 0.f;
; #pragma unroll
;                 for (int bj = 0; bj < 2; ++bj) {
;                     const size_t off = (size_t)r * D + col0 + bj * HALF;
;                     const u32x4 hw = *(const u32x4*)(H16 + off);
;                     const f32x2 a = unpk_f16(hw.x), b2 = unpk_f16(hw.y), c = unpk_f16(hw.z), d = unpk_f16(hw.w);
;                     f32x4 v0, v1;
;                     v0[0] = a.x + acc[ai][bj][m][0][0]; v0[1] = a.y + acc[ai][bj][m][0][1]; v0[2] = b2.x + acc[ai][bj][m][0][2]; v0[3] = b2.y + acc[ai][bj][m][0][3];
;                     v1[0] = c.x + acc[ai][bj][m][1][0]; v1[1] = c.y + acc[ai][bj][m][1][1]; v1[2] = d.x + acc[ai][bj][m][1][2]; v1[3] = d.y + acc[ai][bj][m][1][3];
;                     u32x4 w; w.x = cvt_pk_bf16(v0[0], v0[1]); w.y = cvt_pk_bf16(v0[2], v0[3]); w.z = cvt_pk_bf16(v1[0], v1[1]); w.w = cvt_pk_bf16(v1[2], v1[3]);
;                     u32x4 hq; hq.x = cvt_pk_f16(v0[0], v0[1]); hq.y = cvt_pk_f16(v0[2], v0[3]); hq.z = cvt_pk_f16(v1[0], v1[1]); hq.w = cvt_pk_f16(v1[2], v1[3]);
;                     if (!dry) { *(u32x4*)(HB + off) = w; *(u32x4*)(H16 + off) = hq; }
;                     part += v0[0] * v0[0] + v0[1] * v0[1] + v0[2] * v0[2] + v0[3] * v0[3] + v1[0] * v1[0] + v1[1] * v1[1] + v1[2] * v1[2] + v1[3] * v1[3];
;                 }
;                 part += __shfl_xor(part, 16); part += __shfl_xor(part, 32);
;                 if (fq == 0 && !dry) atomicAdd(ssq_out + r, ssq_fix(part));
	s_nop 1
	v_mov_b64_e32 v[32:33], v[178:179]
	v_mov_b64_e32 v[34:35], v[180:181]
	v_pk_mul_f32 v[30:31], v[40:41], v[40:41]
	v_pk_mul_f32 v[26:27], v[42:43], v[42:43]
	v_lshl_add_u64 v[36:37], s[80:81], 0, v[36:37]
	v_cvt_f32_f16_e32 v40, v32
	v_cvt_f32_f16_sdwa v41, v32 dst_sel:DWORD dst_unused:UNUSED_PAD src0_sel:WORD_1
	v_cvt_f32_f16_e32 v32, v33
	v_cvt_f32_f16_sdwa v33, v33 dst_sel:DWORD dst_unused:UNUSED_PAD src0_sel:WORD_1
	v_cvt_f32_f16_e32 v42, v34
	v_cvt_f32_f16_sdwa v43, v34 dst_sel:DWORD dst_unused:UNUSED_PAD src0_sel:WORD_1
	v_cvt_f32_f16_e32 v34, v35
	v_cvt_f32_f16_sdwa v35, v35 dst_sel:DWORD dst_unused:UNUSED_PAD src0_sel:WORD_1
	v_pk_add_f32 v[40:41], v[20:21], v[40:41]
	v_pk_add_f32 v[32:33], v[22:23], v[32:33]
	v_pk_add_f32 v[42:43], v[16:17], v[42:43]
	v_pk_add_f32 v[34:35], v[18:19], v[34:35]
	v_cvt_pk_f16_f32 v17, v32, v33
	v_cvt_pk_f16_f32 v16, v40, v41
	v_cvt_pk_bf16_f32 v23, v34, v35
	v_cvt_pk_bf16_f32 v22, v42, v43
	v_cvt_pk_bf16_f32 v21, v32, v33
	v_cvt_pk_bf16_f32 v20, v40, v41
	v_cvt_pk_f16_f32 v19, v34, v35
	v_cvt_pk_f16_f32 v18, v42, v43
	global_store_dwordx4 v[36:37], v[20:23], off sc1
	global_store_dwordx4 v[38:39], v[16:19], off sc1
	s_nop 0
	v_pk_mul_f32 v[20:21], v[42:43], v[42:43]
	v_pk_mul_f32 v[16:17], v[40:41], v[40:41]
	v_pk_mul_f32 v[18:19], v[32:33], v[32:33]
	v_add_f32_e32 v16, v16, v17
	v_add_f32_e32 v17, v30, v31
	v_add_f32_e32 v16, v18, v16
	v_add_f32_e32 v17, v28, v17
	v_add_f32_e32 v16, v19, v16
	v_add_f32_e32 v17, v29, v17
	v_add_f32_e32 v16, v20, v16
	v_add_f32_e32 v17, v26, v17
	v_pk_mul_f32 v[22:23], v[34:35], v[34:35]
	v_add_f32_e32 v16, v21, v16
	v_add_f32_e32 v17, v27, v17
	v_add_f32_e32 v16, v22, v16
	v_add_f32_e32 v17, v24, v17
	v_add_f32_e32 v16, v23, v16
	v_add_f32_e32 v17, v25, v17
	v_add_f32_e32 v16, v17, v16
	ds_bpermute_b32 v17, v116, v16
	s_waitcnt lgkmcnt(0)
	v_add_f32_e32 v16, v16, v17
	ds_bpermute_b32 v17, v117, v16
	s_and_saveexec_b64 s[2:3], s[4:5]
	s_cbranch_execz .LBB0_162
	s_waitcnt lgkmcnt(0)
	v_add_f32_e32 v16, v16, v17
	v_mul_f32_e32 v16, 0x4b800000, v16
	v_rndne_f32_e32 v16, v16
	v_mul_f32_e32 v17, 0x2f800000, v16
	v_floor_f32_e32 v17, v17
	v_fmac_f32_e32 v16, 0xcf800000, v17
	v_cvt_u32_f32_e32 v16, v16
	v_cvt_u32_f32_e32 v17, v17
	global_atomic_add_x2 v[112:113], v[16:17], off offset:1280
.LBB0_162:
	s_or_b64 exec, exec, s[2:3]
	s_mov_b64 s[2:3], 0xb0000
	v_lshl_add_u64 v[20:21], v[138:139], 0, s[2:3]
	v_lshl_add_u64 v[22:23], s[14:15], 0, v[20:21]
	s_waitcnt lgkmcnt(0)
	s_waitcnt vmcnt(23)
	s_nop 1
	v_mov_b64_e32 v[16:17], v[182:183]
	v_mov_b64_e32 v[18:19], v[184:185]
	v_lshl_add_u64 v[20:21], s[80:81], 0, v[20:21]
	s_mov_b64 s[2:3], 0xb0100
	v_cvt_f32_f16_e32 v24, v16
	v_cvt_f32_f16_sdwa v25, v16 dst_sel:DWORD dst_unused:UNUSED_PAD src0_sel:WORD_1
	v_cvt_f32_f16_e32 v16, v17
	v_cvt_f32_f16_sdwa v17, v17 dst_sel:DWORD dst_unused:UNUSED_PAD src0_sel:WORD_1
	v_cvt_f32_f16_e32 v26, v18
	v_cvt_f32_f16_sdwa v27, v18 dst_sel:DWORD dst_unused:UNUSED_PAD src0_sel:WORD_1
	v_cvt_f32_f16_e32 v18, v19
	v_cvt_f32_f16_sdwa v19, v19 dst_sel:DWORD dst_unused:UNUSED_PAD src0_sel:WORD_1
	v_pk_add_f32 v[24:25], v[12:13], v[24:25]
	v_pk_add_f32 v[16:17], v[14:15], v[16:17]
	v_pk_add_f32 v[26:27], v[8:9], v[26:27]
	v_pk_add_f32 v[18:19], v[10:11], v[18:19]
	v_cvt_pk_bf16_f32 v14, v26, v27
	v_cvt_pk_bf16_f32 v15, v18, v19
	v_cvt_pk_bf16_f32 v13, v16, v17
	v_cvt_pk_bf16_f32 v12, v24, v25
	v_cvt_pk_f16_f32 v11, v18, v19
	v_cvt_pk_f16_f32 v10, v26, v27
	v_cvt_pk_f16_f32 v9, v16, v17
	v_cvt_pk_f16_f32 v8, v24, v25
	global_store_dwordx4 v[20:21], v[12:15], off sc1
	global_store_dwordx4 v[22:23], v[8:11], off sc1
	v_lshl_add_u64 v[20:21], v[138:139], 0, s[2:3]
	v_lshl_add_u64 v[22:23], s[14:15], 0, v[20:21]
	v_pk_mul_f32 v[12:13], v[16:17], v[16:17]
	v_pk_mul_f32 v[8:9], v[18:19], v[18:19]
	s_waitcnt vmcnt(22)
	s_nop 1
	v_mov_b64_e32 v[16:17], v[186:187]
	v_mov_b64_e32 v[18:19], v[188:189]
	v_pk_mul_f32 v[14:15], v[24:25], v[24:25]
	v_pk_mul_f32 v[10:11], v[26:27], v[26:27]
	v_lshl_add_u64 v[20:21], s[80:81], 0, v[20:21]
	v_cvt_f32_f16_e32 v24, v16
	v_cvt_f32_f16_sdwa v25, v16 dst_sel:DWORD dst_unused:UNUSED_PAD src0_sel:WORD_1
	v_cvt_f32_f16_e32 v16, v17
	v_cvt_f32_f16_sdwa v17, v17 dst_sel:DWORD dst_unused:UNUSED_PAD src0_sel:WORD_1
	v_cvt_f32_f16_e32 v26, v18
	v_cvt_f32_f16_sdwa v27, v18 dst_sel:DWORD dst_unused:UNUSED_PAD src0_sel:WORD_1
	v_cvt_f32_f16_e32 v18, v19
	v_cvt_f32_f16_sdwa v19, v19 dst_sel:DWORD dst_unused:UNUSED_PAD src0_sel:WORD_1
	v_pk_add_f32 v[24:25], v[4:5], v[24:25]
	v_pk_add_f32 v[16:17], v[6:7], v[16:17]
	v_pk_add_f32 v[26:27], v[0:1], v[26:27]
	v_pk_add_f32 v[18:19], v[2:3], v[18:19]
	v_cvt_pk_f16_f32 v1, v16, v17
	v_cvt_pk_f16_f32 v0, v24, v25
	v_cvt_pk_bf16_f32 v7, v18, v19
	v_cvt_pk_bf16_f32 v6, v26, v27
	v_cvt_pk_bf16_f32 v5, v16, v17
	v_cvt_pk_bf16_f32 v4, v24, v25
	v_cvt_pk_f16_f32 v3, v18, v19
	v_cvt_pk_f16_f32 v2, v26, v27
	global_store_dwordx4 v[20:21], v[4:7], off sc1
	global_store_dwordx4 v[22:23], v[0:3], off sc1
	s_nop 0
	v_pk_mul_f32 v[4:5], v[26:27], v[26:27]
	v_pk_mul_f32 v[0:1], v[24:25], v[24:25]
	v_pk_mul_f32 v[2:3], v[16:17], v[16:17]
	v_add_f32_e32 v0, v0, v1
	v_add_f32_e32 v1, v14, v15
	v_add_f32_e32 v0, v2, v0
	v_add_f32_e32 v1, v12, v1
	v_add_f32_e32 v0, v3, v0
	v_add_f32_e32 v1, v13, v1
	v_add_f32_e32 v0, v4, v0
	v_add_f32_e32 v1, v10, v1
	v_pk_mul_f32 v[6:7], v[18:19], v[18:19]
	v_add_f32_e32 v0, v5, v0
	v_add_f32_e32 v1, v11, v1
	v_add_f32_e32 v0, v6, v0
	v_add_f32_e32 v1, v8, v1
	v_add_f32_e32 v0, v7, v0
	v_add_f32_e32 v1, v9, v1
	v_add_f32_e32 v0, v1, v0
	ds_bpermute_b32 v1, v116, v0
	s_waitcnt lgkmcnt(0)
	v_add_f32_e32 v0, v0, v1
	ds_bpermute_b32 v1, v117, v0
	s_and_saveexec_b64 s[2:3], s[4:5]
	s_cbranch_execz .LBB0_164
	s_waitcnt lgkmcnt(0)
	v_add_f32_e32 v0, v0, v1
	v_mul_f32_e32 v0, 0x4b800000, v0
	v_rndne_f32_e32 v0, v0
	v_mul_f32_e32 v1, 0x2f800000, v0
	v_floor_f32_e32 v1, v1
	v_fmac_f32_e32 v0, 0xcf800000, v1
	v_cvt_u32_f32_e32 v0, v0
	v_cvt_u32_f32_e32 v1, v1
	global_atomic_add_x2 v[112:113], v[0:1], off offset:1408

; __device__ __forceinline__ unsigned cvt_pk_bf16(float lo, float hi) { const f32x2_t v = {lo, hi}; const bf16x2_t b = __builtin_convertvector(v, bf16x2_t); return __builtin_bit_cast(unsigned, b); }
;     __device__ __forceinline__ void operator()(const Acc& acc, const Unit& u, int wr, int wc, int fr, int fq) const {
;     ...
;                 const int r = row0 + ai * HALF + m * 16;
; #pragma unroll
;                 for (int bj = 0; bj < 2; ++bj) {
;                     const int c = col0 + bj * HALF; const size_t off = (size_t)r * D + c;
;                     const u32x4 gw = *(const u32x4*)(gates + (size_t)r * 6144 + br * D + c);
;                     f32x4 v0, v1;
;                     v0[0] = acc[ai][bj][m][0][0] * bflo(gw.x); v0[1] = acc[ai][bj][m][0][1] * bfhi(gw.x); v0[2] = acc[ai][bj][m][0][2] * bflo(gw.y); v0[3] = acc[ai][bj][m][0][3] * bfhi(gw.y);
;                     v1[0] = acc[ai][bj][m][1][0] * bflo(gw.z); v1[1] = acc[ai][bj][m][1][1] * bfhi(gw.z); v1[2] = acc[ai][bj][m][1][2] * bflo(gw.w); v1[3] = acc[ai][bj][m][1][3] * bfhi(gw.w);
;                     if (br > 0) { const u32x4 ma = *(const u32x4*)(prev + off);
;                         v0[0] += bflo(ma.x); v0[1] += bfhi(ma.x); v0[2] += bflo(ma.y); v0[3] += bfhi(ma.y); v1[0] += bflo(ma.z); v1[1] += bfhi(ma.z); v1[2] += bflo(ma.w); v1[3] += bfhi(ma.w); }
;                     u32x4 w; w.x = cvt_pk_bf16(v0[0], v0[1]); w.y = cvt_pk_bf16(v0[2], v0[3]); w.z = cvt_pk_bf16(v1[0], v1[1]); w.w = cvt_pk_bf16(v1[2], v1[3]);
;                     *(u32x4*)(dst + off) = w;
.LBB0_190:
	v_lshl_add_u32 v140, s62, 8, v146
	v_lshl_or_b32 v138, s42, 8, v148
	v_ashrrev_i32_e32 v141, 31, v140
	v_lshlrev_b64 v[158:159], 11, v[140:141]
	v_ashrrev_i32_e32 v139, 31, v138
	v_mov_b64_e32 v[144:145], s[6:7]
	v_lshl_add_u64 v[154:155], v[158:159], 0, v[138:139]
	v_mad_i64_i32 v[142:143], s[2:3], v140, s26, v[144:145]
	v_lshl_add_u64 v[166:167], v[142:143], 0, s[56:57]
	v_lshlrev_b64 v[142:143], 1, v[138:139]
	v_lshlrev_b64 v[170:171], 1, v[154:155]
	v_lshl_add_u64 v[150:151], v[166:167], 0, v[142:143]
	v_lshl_add_u64 v[154:155], s[16:17], 0, v[170:171]
	global_load_dwordx4 v[150:153], v[150:151], off
	s_mov_b64 s[24:25], -1
	global_load_dwordx4 v[154:157], v[154:155], off
	s_andn2_b64 vcc, exec, s[4:5]
	s_waitcnt vmcnt(0)
	v_lshlrev_b32_e32 v172, 16, v150
	v_and_b32_e32 v173, 0xffff0000, v150
	v_lshlrev_b32_e32 v174, 16, v154
	v_and_b32_e32 v175, 0xffff0000, v154
	v_lshlrev_b32_e32 v150, 16, v151
	v_and_b32_e32 v151, 0xffff0000, v151
	v_lshlrev_b32_e32 v154, 16, v155
	v_and_b32_e32 v155, 0xffff0000, v155
	v_pk_fma_f32 v[126:127], v[126:127], v[150:151], v[154:155]
	v_lshlrev_b32_e32 v150, 16, v152
	v_and_b32_e32 v151, 0xffff0000, v152
	v_lshlrev_b32_e32 v154, 16, v156
	v_and_b32_e32 v155, 0xffff0000, v156
	v_pk_fma_f32 v[150:151], v[120:121], v[150:151], v[154:155]
	v_lshlrev_b32_e32 v120, 16, v153
	v_and_b32_e32 v121, 0xffff0000, v153
	v_lshlrev_b32_e32 v152, 16, v157
	v_and_b32_e32 v153, 0xffff0000, v157
	v_pk_fma_f32 v[124:125], v[124:125], v[172:173], v[174:175]
	v_pk_fma_f32 v[152:153], v[122:123], v[120:121], v[152:153]
	v_cvt_pk_bf16_f32 v120, v124, v125
	v_cvt_pk_bf16_f32 v121, v126, v127
	v_cvt_pk_bf16_f32 v122, v150, v151
	v_cvt_pk_bf16_f32 v123, v152, v153
	v_lshl_add_u64 v[124:125], s[88:89], 0, v[170:171]
	global_store_dwordx4 v[124:125], v[120:123], off sc1
	s_nop 1
	v_or_b32_e32 v120, 0x80, v138
	v_ashrrev_i32_e32 v121, 31, v120
	v_lshl_add_u64 v[150:151], v[158:159], 0, v[120:121]
	v_lshlrev_b64 v[122:123], 1, v[120:121]
	v_lshlrev_b64 v[154:155], 1, v[150:151]
	v_lshl_add_u64 v[124:125], v[166:167], 0, v[122:123]
	v_lshl_add_u64 v[150:151], s[16:17], 0, v[154:155]
	global_load_dwordx4 v[124:127], v[124:125], off
	s_nop 0
	global_load_dwordx4 v[150:153], v[150:151], off
	s_waitcnt vmcnt(1)
	v_lshlrev_b32_e32 v156, 16, v124
	v_and_b32_e32 v157, 0xffff0000, v124
	s_waitcnt vmcnt(0)
	v_lshlrev_b32_e32 v158, 16, v150
	v_and_b32_e32 v159, 0xffff0000, v150
	v_lshlrev_b32_e32 v124, 16, v125
	v_and_b32_e32 v125, 0xffff0000, v125
	v_lshlrev_b32_e32 v150, 16, v151
	v_and_b32_e32 v151, 0xffff0000, v151
	v_pk_fma_f32 v[118:119], v[118:119], v[124:125], v[150:151]
	v_lshlrev_b32_e32 v124, 16, v126
	v_and_b32_e32 v125, 0xffff0000, v126
	v_lshlrev_b32_e32 v150, 16, v152
	v_and_b32_e32 v151, 0xffff0000, v152
	v_pk_fma_f32 v[124:125], v[112:113], v[124:125], v[150:151]
	v_lshlrev_b32_e32 v112, 16, v127
	v_and_b32_e32 v113, 0xffff0000, v127
	v_lshlrev_b32_e32 v126, 16, v153
	v_and_b32_e32 v127, 0xffff0000, v153
	v_pk_fma_f32 v[116:117], v[116:117], v[156:157], v[158:159]
	v_pk_fma_f32 v[126:127], v[114:115], v[112:113], v[126:127]
	v_cvt_pk_bf16_f32 v112, v116, v117
	v_cvt_pk_bf16_f32 v113, v118, v119
	v_cvt_pk_bf16_f32 v114, v124, v125
	v_cvt_pk_bf16_f32 v115, v126, v127
	v_lshl_add_u64 v[116:117], s[88:89], 0, v[154:155]
	global_store_dwordx4 v[116:117], v[112:115], off sc1
	s_nop 1
	v_or_b32_e32 v114, 16, v140
	v_ashrrev_i32_e32 v115, 31, v114
	v_lshlrev_b64 v[112:113], 11, v[114:115]
	v_lshl_add_u64 v[124:125], v[112:113], 0, v[138:139]
	v_mad_i64_i32 v[114:115], s[2:3], v114, s26, v[144:145]
	v_lshl_add_u64 v[114:115], v[114:115], 0, s[56:57]
	v_lshlrev_b64 v[150:151], 1, v[124:125]
	v_lshl_add_u64 v[116:117], v[114:115], 0, v[142:143]
	v_lshl_add_u64 v[124:125], s[16:17], 0, v[150:151]
	global_load_dwordx4 v[116:119], v[116:117], off
	s_nop 0
	global_load_dwordx4 v[124:127], v[124:125], off
	s_waitcnt vmcnt(1)
	v_lshlrev_b32_e32 v152, 16, v116
	v_and_b32_e32 v153, 0xffff0000, v116
	s_waitcnt vmcnt(0)
	v_lshlrev_b32_e32 v154, 16, v124
	v_and_b32_e32 v155, 0xffff0000, v124
	v_lshlrev_b32_e32 v116, 16, v117
	v_and_b32_e32 v117, 0xffff0000, v117
	v_lshlrev_b32_e32 v124, 16, v125
	v_and_b32_e32 v125, 0xffff0000, v125
	v_pk_fma_f32 v[110:111], v[110:111], v[116:117], v[124:125]
	v_lshlrev_b32_e32 v116, 16, v118
	v_and_b32_e32 v117, 0xffff0000, v118
	v_lshlrev_b32_e32 v124, 16, v126
	v_and_b32_e32 v125, 0xffff0000, v126
	v_pk_fma_f32 v[116:117], v[104:105], v[116:117], v[124:125]
	v_lshlrev_b32_e32 v104, 16, v119
	v_and_b32_e32 v105, 0xffff0000, v119
	v_lshlrev_b32_e32 v118, 16, v127
	v_and_b32_e32 v119, 0xffff0000, v127
	v_pk_fma_f32 v[108:109], v[108:109], v[152:153], v[154:155]
	v_pk_fma_f32 v[118:119], v[106:107], v[104:105], v[118:119]
	v_cvt_pk_bf16_f32 v104, v108, v109
	v_cvt_pk_bf16_f32 v105, v110, v111
	v_cvt_pk_bf16_f32 v106, v116, v117
	v_cvt_pk_bf16_f32 v107, v118, v119
	v_lshl_add_u64 v[108:109], s[88:89], 0, v[150:151]
	global_store_dwordx4 v[108:109], v[104:107], off sc1
	v_lshl_add_u64 v[108:109], v[112:113], 0, v[120:121]
	v_lshlrev_b64 v[112:113], 1, v[108:109]
	v_lshl_add_u64 v[104:105], v[114:115], 0, v[122:123]
	v_lshl_add_u64 v[108:109], s[16:17], 0, v[112:113]
	global_load_dwordx4 v[104:107], v[104:105], off
	s_nop 0
	global_load_dwordx4 v[108:111], v[108:109], off
	s_waitcnt vmcnt(1)
	v_lshlrev_b32_e32 v114, 16, v104
	v_and_b32_e32 v115, 0xffff0000, v104
	s_waitcnt vmcnt(0)
; __device__ __forceinline__ unsigned cvt_pk_bf16(float lo, float hi) { const f32x2_t v = {lo, hi}; const bf16x2_t b = __builtin_convertvector(v, bf16x2_t); return __builtin_bit_cast(unsigned, b); }
;     __device__ __forceinline__ void operator()(const Acc& acc, const Unit& u, int wr, int wc, int fr, int fq) const {
;     ...
;                 const int r = row0 + ai * HALF + m * 16;
; #pragma unroll
;                 for (int bj = 0; bj < 2; ++bj) {
;                     const int c = col0 + bj * HALF; const size_t off = (size_t)r * D + c;
;                     const u32x4 gw = *(const u32x4*)(gates + (size_t)r * 6144 + br * D + c);
;                     f32x4 v0, v1;
;                     v0[0] = acc[ai][bj][m][0][0] * bflo(gw.x); v0[1] = acc[ai][bj][m][0][1] * bfhi(gw.x); v0[2] = acc[ai][bj][m][0][2] * bflo(gw.y); v0[3] = acc[ai][bj][m][0][3] * bfhi(gw.y);
;                     v1[0] = acc[ai][bj][m][1][0] * bflo(gw.z); v1[1] = acc[ai][bj][m][1][1] * bfhi(gw.z); v1[2] = acc[ai][bj][m][1][2] * bflo(gw.w); v1[3] = acc[ai][bj][m][1][3] * bfhi(gw.w);
;                     if (br > 0) { const u32x4 ma = *(const u32x4*)(prev + off);
;                         v0[0] += bflo(ma.x); v0[1] += bfhi(ma.x); v0[2] += bflo(ma.y); v0[3] += bfhi(ma.y); v1[0] += bflo(ma.z); v1[1] += bfhi(ma.z); v1[2] += bflo(ma.w); v1[3] += bfhi(ma.w); }
;                     u32x4 w; w.x = cvt_pk_bf16(v0[0], v0[1]); w.y = cvt_pk_bf16(v0[2], v0[3]); w.z = cvt_pk_bf16(v1[0], v1[1]); w.w = cvt_pk_bf16(v1[2], v1[3]);
;                     *(u32x4*)(dst + off) = w;
	v_lshlrev_b32_e32 v116, 16, v108
	v_and_b32_e32 v117, 0xffff0000, v108
	v_lshlrev_b32_e32 v104, 16, v105
	v_and_b32_e32 v105, 0xffff0000, v105
	v_lshlrev_b32_e32 v108, 16, v109
	v_and_b32_e32 v109, 0xffff0000, v109
	v_pk_fma_f32 v[102:103], v[102:103], v[104:105], v[108:109]
	v_lshlrev_b32_e32 v104, 16, v106
	v_and_b32_e32 v105, 0xffff0000, v106
	v_lshlrev_b32_e32 v108, 16, v110
	v_and_b32_e32 v109, 0xffff0000, v110
	v_pk_fma_f32 v[104:105], v[96:97], v[104:105], v[108:109]
	v_lshlrev_b32_e32 v96, 16, v107
	v_and_b32_e32 v97, 0xffff0000, v107
	v_lshlrev_b32_e32 v106, 16, v111
	v_and_b32_e32 v107, 0xffff0000, v111
	v_pk_fma_f32 v[100:101], v[100:101], v[114:115], v[116:117]
	v_pk_fma_f32 v[106:107], v[98:99], v[96:97], v[106:107]
	v_cvt_pk_bf16_f32 v96, v100, v101
	v_cvt_pk_bf16_f32 v97, v102, v103
	v_cvt_pk_bf16_f32 v98, v104, v105
	v_cvt_pk_bf16_f32 v99, v106, v107
	v_lshl_add_u64 v[100:101], s[88:89], 0, v[112:113]
	global_store_dwordx4 v[100:101], v[96:99], off sc1
	s_nop 1
	v_or_b32_e32 v98, 32, v140
	v_ashrrev_i32_e32 v99, 31, v98
	v_lshlrev_b64 v[96:97], 11, v[98:99]
	v_lshl_add_u64 v[104:105], v[96:97], 0, v[138:139]
	v_mad_i64_i32 v[98:99], s[2:3], v98, s26, v[144:145]
	v_lshl_add_u64 v[98:99], v[98:99], 0, s[56:57]
	v_lshlrev_b64 v[108:109], 1, v[104:105]
	v_lshl_add_u64 v[100:101], v[98:99], 0, v[142:143]
	v_lshl_add_u64 v[104:105], s[16:17], 0, v[108:109]
	global_load_dwordx4 v[100:103], v[100:101], off
	s_nop 0
	global_load_dwordx4 v[104:107], v[104:105], off
	s_waitcnt vmcnt(1)
	v_lshlrev_b32_e32 v110, 16, v100
	v_and_b32_e32 v111, 0xffff0000, v100
	s_waitcnt vmcnt(0)
	v_lshlrev_b32_e32 v112, 16, v104
	v_and_b32_e32 v113, 0xffff0000, v104
	v_lshlrev_b32_e32 v100, 16, v101
	v_and_b32_e32 v101, 0xffff0000, v101
	v_lshlrev_b32_e32 v104, 16, v105
	v_and_b32_e32 v105, 0xffff0000, v105
	v_pk_fma_f32 v[94:95], v[94:95], v[100:101], v[104:105]
	v_lshlrev_b32_e32 v100, 16, v102
	v_and_b32_e32 v101, 0xffff0000, v102
	v_lshlrev_b32_e32 v104, 16, v106
	v_and_b32_e32 v105, 0xffff0000, v106
	v_pk_fma_f32 v[100:101], v[88:89], v[100:101], v[104:105]
	v_lshlrev_b32_e32 v88, 16, v103
	v_and_b32_e32 v89, 0xffff0000, v103
	v_lshlrev_b32_e32 v102, 16, v107
	v_and_b32_e32 v103, 0xffff0000, v107
	v_pk_fma_f32 v[92:93], v[92:93], v[110:111], v[112:113]
	v_pk_fma_f32 v[102:103], v[90:91], v[88:89], v[102:103]
	v_cvt_pk_bf16_f32 v88, v92, v93
	v_cvt_pk_bf16_f32 v89, v94, v95
	v_cvt_pk_bf16_f32 v90, v100, v101
	v_cvt_pk_bf16_f32 v91, v102, v103
	v_lshl_add_u64 v[92:93], s[88:89], 0, v[108:109]
	global_store_dwordx4 v[92:93], v[88:91], off sc1
	v_lshl_add_u64 v[92:93], v[96:97], 0, v[120:121]
	v_lshlrev_b64 v[96:97], 1, v[92:93]
	v_lshl_add_u64 v[88:89], v[98:99], 0, v[122:123]
	v_lshl_add_u64 v[92:93], s[16:17], 0, v[96:97]
	global_load_dwordx4 v[88:91], v[88:89], off
	s_nop 0
	global_load_dwordx4 v[92:95], v[92:93], off
	s_waitcnt vmcnt(1)
	v_lshlrev_b32_e32 v98, 16, v88
	v_and_b32_e32 v99, 0xffff0000, v88
	s_waitcnt vmcnt(0)
	v_lshlrev_b32_e32 v100, 16, v92
	v_and_b32_e32 v101, 0xffff0000, v92
	v_lshlrev_b32_e32 v88, 16, v89
	v_and_b32_e32 v89, 0xffff0000, v89
	v_lshlrev_b32_e32 v92, 16, v93
	v_and_b32_e32 v93, 0xffff0000, v93
	v_pk_fma_f32 v[86:87], v[86:87], v[88:89], v[92:93]
	v_lshlrev_b32_e32 v88, 16, v90
	v_and_b32_e32 v89, 0xffff0000, v90
	v_lshlrev_b32_e32 v92, 16, v94
	v_and_b32_e32 v93, 0xffff0000, v94
	v_pk_fma_f32 v[88:89], v[80:81], v[88:89], v[92:93]
	v_lshlrev_b32_e32 v80, 16, v91
	v_and_b32_e32 v81, 0xffff0000, v91
	v_lshlrev_b32_e32 v90, 16, v95
	v_and_b32_e32 v91, 0xffff0000, v95
	v_pk_fma_f32 v[84:85], v[84:85], v[98:99], v[100:101]
	v_pk_fma_f32 v[90:91], v[82:83], v[80:81], v[90:91]
	v_cvt_pk_bf16_f32 v80, v84, v85
	v_cvt_pk_bf16_f32 v81, v86, v87
	v_cvt_pk_bf16_f32 v82, v88, v89
	v_cvt_pk_bf16_f32 v83, v90, v91
	v_lshl_add_u64 v[84:85], s[88:89], 0, v[96:97]
	global_store_dwordx4 v[84:85], v[80:83], off sc1
	s_nop 1
	v_or_b32_e32 v82, 48, v140
	v_ashrrev_i32_e32 v83, 31, v82
	v_lshlrev_b64 v[80:81], 11, v[82:83]
	v_lshl_add_u64 v[88:89], v[80:81], 0, v[138:139]
	v_mad_i64_i32 v[82:83], s[2:3], v82, s26, v[144:145]
	v_lshl_add_u64 v[82:83], v[82:83], 0, s[56:57]
	v_lshlrev_b64 v[92:93], 1, v[88:89]
	v_lshl_add_u64 v[84:85], v[82:83], 0, v[142:143]
	v_lshl_add_u64 v[88:89], s[16:17], 0, v[92:93]
	global_load_dwordx4 v[84:87], v[84:85], off
	s_nop 0
	global_load_dwordx4 v[88:91], v[88:89], off
	s_waitcnt vmcnt(1)
	v_lshlrev_b32_e32 v94, 16, v84
	v_and_b32_e32 v95, 0xffff0000, v84
	s_waitcnt vmcnt(0)
	v_lshlrev_b32_e32 v96, 16, v88
	v_and_b32_e32 v97, 0xffff0000, v88
	v_lshlrev_b32_e32 v84, 16, v85
	v_and_b32_e32 v85, 0xffff0000, v85
	v_lshlrev_b32_e32 v88, 16, v89
	v_and_b32_e32 v89, 0xffff0000, v89
	v_pk_fma_f32 v[78:79], v[78:79], v[84:85], v[88:89]
	v_lshlrev_b32_e32 v84, 16, v86
	v_and_b32_e32 v85, 0xffff0000, v86
	v_lshlrev_b32_e32 v88, 16, v90
	v_and_b32_e32 v89, 0xffff0000, v90
	v_pk_fma_f32 v[84:85], v[72:73], v[84:85], v[88:89]
	v_lshlrev_b32_e32 v72, 16, v87
	v_and_b32_e32 v73, 0xffff0000, v87
	v_lshlrev_b32_e32 v86, 16, v91
	v_and_b32_e32 v87, 0xffff0000, v91
	v_pk_fma_f32 v[76:77], v[76:77], v[94:95], v[96:97]
	v_pk_fma_f32 v[86:87], v[74:75], v[72:73], v[86:87]
	v_cvt_pk_bf16_f32 v72, v76, v77
	v_cvt_pk_bf16_f32 v73, v78, v79
	v_cvt_pk_bf16_f32 v74, v84, v85
	v_cvt_pk_bf16_f32 v75, v86, v87
	v_lshl_add_u64 v[76:77], s[88:89], 0, v[92:93]
	global_store_dwordx4 v[76:77], v[72:75], off sc1
	v_lshl_add_u64 v[76:77], v[80:81], 0, v[120:121]
	v_lshlrev_b64 v[80:81], 1, v[76:77]
	v_lshl_add_u64 v[72:73], v[82:83], 0, v[122:123]
	v_lshl_add_u64 v[76:77], s[16:17], 0, v[80:81]
	global_load_dwordx4 v[72:75], v[72:73], off
	s_nop 0
	global_load_dwordx4 v[76:79], v[76:77], off
	s_waitcnt vmcnt(1)
; __device__ __forceinline__ unsigned cvt_pk_bf16(float lo, float hi) { const f32x2_t v = {lo, hi}; const bf16x2_t b = __builtin_convertvector(v, bf16x2_t); return __builtin_bit_cast(unsigned, b); }
;     __device__ __forceinline__ void operator()(const Acc& acc, const Unit& u, int wr, int wc, int fr, int fq) const {
;     ...
;                 const int r = row0 + ai * HALF + m * 16;
; #pragma unroll
;                 for (int bj = 0; bj < 2; ++bj) {
;                     const int c = col0 + bj * HALF; const size_t off = (size_t)r * D + c;
;                     const u32x4 gw = *(const u32x4*)(gates + (size_t)r * 6144 + br * D + c);
;                     f32x4 v0, v1;
;                     v0[0] = acc[ai][bj][m][0][0] * bflo(gw.x); v0[1] = acc[ai][bj][m][0][1] * bfhi(gw.x); v0[2] = acc[ai][bj][m][0][2] * bflo(gw.y); v0[3] = acc[ai][bj][m][0][3] * bfhi(gw.y);
;                     v1[0] = acc[ai][bj][m][1][0] * bflo(gw.z); v1[1] = acc[ai][bj][m][1][1] * bfhi(gw.z); v1[2] = acc[ai][bj][m][1][2] * bflo(gw.w); v1[3] = acc[ai][bj][m][1][3] * bfhi(gw.w);
;                     if (br > 0) { const u32x4 ma = *(const u32x4*)(prev + off);
;                         v0[0] += bflo(ma.x); v0[1] += bfhi(ma.x); v0[2] += bflo(ma.y); v0[3] += bfhi(ma.y); v1[0] += bflo(ma.z); v1[1] += bfhi(ma.z); v1[2] += bflo(ma.w); v1[3] += bfhi(ma.w); }
;                     u32x4 w; w.x = cvt_pk_bf16(v0[0], v0[1]); w.y = cvt_pk_bf16(v0[2], v0[3]); w.z = cvt_pk_bf16(v1[0], v1[1]); w.w = cvt_pk_bf16(v1[2], v1[3]);
;                     *(u32x4*)(dst + off) = w;
	v_lshlrev_b32_e32 v82, 16, v72
	v_and_b32_e32 v83, 0xffff0000, v72
	s_waitcnt vmcnt(0)
	v_lshlrev_b32_e32 v84, 16, v76
	v_and_b32_e32 v85, 0xffff0000, v76
	v_lshlrev_b32_e32 v72, 16, v73
	v_and_b32_e32 v73, 0xffff0000, v73
	v_lshlrev_b32_e32 v76, 16, v77
	v_and_b32_e32 v77, 0xffff0000, v77
	v_pk_fma_f32 v[70:71], v[70:71], v[72:73], v[76:77]
	v_lshlrev_b32_e32 v72, 16, v74
	v_and_b32_e32 v73, 0xffff0000, v74
	v_lshlrev_b32_e32 v76, 16, v78
	v_and_b32_e32 v77, 0xffff0000, v78
	v_pk_fma_f32 v[72:73], v[64:65], v[72:73], v[76:77]
	v_lshlrev_b32_e32 v64, 16, v75
	v_and_b32_e32 v65, 0xffff0000, v75
	v_lshlrev_b32_e32 v74, 16, v79
	v_and_b32_e32 v75, 0xffff0000, v79
	v_pk_fma_f32 v[68:69], v[68:69], v[82:83], v[84:85]
	v_pk_fma_f32 v[74:75], v[66:67], v[64:65], v[74:75]
	v_cvt_pk_bf16_f32 v64, v68, v69
	v_cvt_pk_bf16_f32 v65, v70, v71
	v_cvt_pk_bf16_f32 v66, v72, v73
	v_cvt_pk_bf16_f32 v67, v74, v75
	v_lshl_add_u64 v[68:69], s[88:89], 0, v[80:81]
	global_store_dwordx4 v[68:69], v[64:67], off sc1
	s_nop 1
	v_add_u32_e32 v66, 0x80, v140
	v_ashrrev_i32_e32 v67, 31, v66
	v_lshlrev_b64 v[64:65], 11, v[66:67]
	v_lshl_add_u64 v[72:73], v[64:65], 0, v[138:139]
	v_mad_i64_i32 v[66:67], s[2:3], v66, s26, v[144:145]
	v_lshl_add_u64 v[66:67], v[66:67], 0, s[56:57]
	v_lshlrev_b64 v[76:77], 1, v[72:73]
	v_lshl_add_u64 v[68:69], v[66:67], 0, v[142:143]
	v_lshl_add_u64 v[72:73], s[16:17], 0, v[76:77]
	global_load_dwordx4 v[68:71], v[68:69], off
	s_nop 0
	global_load_dwordx4 v[72:75], v[72:73], off
	s_waitcnt vmcnt(1)
	v_lshlrev_b32_e32 v78, 16, v68
	v_and_b32_e32 v79, 0xffff0000, v68
	s_waitcnt vmcnt(0)
	v_lshlrev_b32_e32 v80, 16, v72
	v_and_b32_e32 v81, 0xffff0000, v72
	v_lshlrev_b32_e32 v68, 16, v69
	v_and_b32_e32 v69, 0xffff0000, v69
	v_lshlrev_b32_e32 v72, 16, v73
	v_and_b32_e32 v73, 0xffff0000, v73
	v_pk_fma_f32 v[62:63], v[62:63], v[68:69], v[72:73]
	v_lshlrev_b32_e32 v68, 16, v70
	v_and_b32_e32 v69, 0xffff0000, v70
	v_lshlrev_b32_e32 v72, 16, v74
	v_and_b32_e32 v73, 0xffff0000, v74
	v_pk_fma_f32 v[68:69], v[56:57], v[68:69], v[72:73]
	v_lshlrev_b32_e32 v56, 16, v71
	v_and_b32_e32 v57, 0xffff0000, v71
	v_lshlrev_b32_e32 v70, 16, v75
	v_and_b32_e32 v71, 0xffff0000, v75
	v_pk_fma_f32 v[60:61], v[60:61], v[78:79], v[80:81]
	v_pk_fma_f32 v[70:71], v[58:59], v[56:57], v[70:71]
	v_cvt_pk_bf16_f32 v56, v60, v61
	v_cvt_pk_bf16_f32 v57, v62, v63
	v_cvt_pk_bf16_f32 v58, v68, v69
	v_cvt_pk_bf16_f32 v59, v70, v71
	v_lshl_add_u64 v[60:61], s[88:89], 0, v[76:77]
	global_store_dwordx4 v[60:61], v[56:59], off sc1
	v_lshl_add_u64 v[60:61], v[64:65], 0, v[120:121]
	v_lshlrev_b64 v[64:65], 1, v[60:61]
	v_lshl_add_u64 v[56:57], v[66:67], 0, v[122:123]
	v_lshl_add_u64 v[60:61], s[16:17], 0, v[64:65]
	global_load_dwordx4 v[56:59], v[56:57], off
	s_nop 0
	global_load_dwordx4 v[60:63], v[60:61], off
	s_waitcnt vmcnt(1)
	v_lshlrev_b32_e32 v66, 16, v56
	v_and_b32_e32 v67, 0xffff0000, v56
	s_waitcnt vmcnt(0)
	v_lshlrev_b32_e32 v68, 16, v60
	v_and_b32_e32 v69, 0xffff0000, v60
	v_lshlrev_b32_e32 v56, 16, v57
	v_and_b32_e32 v57, 0xffff0000, v57
	v_lshlrev_b32_e32 v60, 16, v61
	v_and_b32_e32 v61, 0xffff0000, v61
	v_pk_fma_f32 v[54:55], v[54:55], v[56:57], v[60:61]
	v_lshlrev_b32_e32 v56, 16, v58
	v_and_b32_e32 v57, 0xffff0000, v58
	v_lshlrev_b32_e32 v60, 16, v62
	v_and_b32_e32 v61, 0xffff0000, v62
	v_pk_fma_f32 v[56:57], v[48:49], v[56:57], v[60:61]
	v_lshlrev_b32_e32 v48, 16, v59
	v_and_b32_e32 v49, 0xffff0000, v59
	v_lshlrev_b32_e32 v58, 16, v63
	v_and_b32_e32 v59, 0xffff0000, v63
	v_pk_fma_f32 v[52:53], v[52:53], v[66:67], v[68:69]
	v_pk_fma_f32 v[58:59], v[50:51], v[48:49], v[58:59]
	v_cvt_pk_bf16_f32 v48, v52, v53
	v_cvt_pk_bf16_f32 v49, v54, v55
	v_cvt_pk_bf16_f32 v50, v56, v57
	v_cvt_pk_bf16_f32 v51, v58, v59
	v_lshl_add_u64 v[52:53], s[88:89], 0, v[64:65]
	global_store_dwordx4 v[52:53], v[48:51], off sc1
	s_nop 1
	v_add_u32_e32 v50, 0x90, v140
	v_ashrrev_i32_e32 v51, 31, v50
	v_lshlrev_b64 v[48:49], 11, v[50:51]
	v_lshl_add_u64 v[56:57], v[48:49], 0, v[138:139]
	v_mad_i64_i32 v[50:51], s[2:3], v50, s26, v[144:145]
	v_lshl_add_u64 v[50:51], v[50:51], 0, s[56:57]
	v_lshlrev_b64 v[60:61], 1, v[56:57]
	v_lshl_add_u64 v[52:53], v[50:51], 0, v[142:143]
	v_lshl_add_u64 v[56:57], s[16:17], 0, v[60:61]
	global_load_dwordx4 v[52:55], v[52:53], off
	s_nop 0
	global_load_dwordx4 v[56:59], v[56:57], off
	s_waitcnt vmcnt(1)
	v_lshlrev_b32_e32 v62, 16, v52
	v_and_b32_e32 v63, 0xffff0000, v52
	s_waitcnt vmcnt(0)
	v_lshlrev_b32_e32 v64, 16, v56
	v_and_b32_e32 v65, 0xffff0000, v56
	v_lshlrev_b32_e32 v52, 16, v53
	v_and_b32_e32 v53, 0xffff0000, v53
	v_lshlrev_b32_e32 v56, 16, v57
	v_and_b32_e32 v57, 0xffff0000, v57
	v_pk_fma_f32 v[46:47], v[46:47], v[52:53], v[56:57]
	v_lshlrev_b32_e32 v52, 16, v54
	v_and_b32_e32 v53, 0xffff0000, v54
	v_lshlrev_b32_e32 v56, 16, v58
	v_and_b32_e32 v57, 0xffff0000, v58
	v_pk_fma_f32 v[52:53], v[40:41], v[52:53], v[56:57]
	v_lshlrev_b32_e32 v40, 16, v55
	v_and_b32_e32 v41, 0xffff0000, v55
	v_lshlrev_b32_e32 v54, 16, v59
	v_and_b32_e32 v55, 0xffff0000, v59
	v_pk_fma_f32 v[44:45], v[44:45], v[62:63], v[64:65]
	v_pk_fma_f32 v[54:55], v[42:43], v[40:41], v[54:55]
	v_cvt_pk_bf16_f32 v40, v44, v45
	v_cvt_pk_bf16_f32 v41, v46, v47
	v_cvt_pk_bf16_f32 v42, v52, v53
	v_cvt_pk_bf16_f32 v43, v54, v55
	v_lshl_add_u64 v[44:45], s[88:89], 0, v[60:61]
	global_store_dwordx4 v[44:45], v[40:43], off sc1
	v_lshl_add_u64 v[44:45], v[48:49], 0, v[120:121]
	v_lshlrev_b64 v[48:49], 1, v[44:45]
	v_lshl_add_u64 v[40:41], v[50:51], 0, v[122:123]
	v_lshl_add_u64 v[44:45], s[16:17], 0, v[48:49]
	global_load_dwordx4 v[40:43], v[40:41], off
	s_nop 0
	global_load_dwordx4 v[44:47], v[44:45], off
	s_waitcnt vmcnt(1)
; __device__ __forceinline__ unsigned cvt_pk_bf16(float lo, float hi) { const f32x2_t v = {lo, hi}; const bf16x2_t b = __builtin_convertvector(v, bf16x2_t); return __builtin_bit_cast(unsigned, b); }
;     __device__ __forceinline__ void operator()(const Acc& acc, const Unit& u, int wr, int wc, int fr, int fq) const {
;     ...
;                 const int r = row0 + ai * HALF + m * 16;
; #pragma unroll
;                 for (int bj = 0; bj < 2; ++bj) {
;                     const int c = col0 + bj * HALF; const size_t off = (size_t)r * D + c;
;                     const u32x4 gw = *(const u32x4*)(gates + (size_t)r * 6144 + br * D + c);
;                     f32x4 v0, v1;
;                     v0[0] = acc[ai][bj][m][0][0] * bflo(gw.x); v0[1] = acc[ai][bj][m][0][1] * bfhi(gw.x); v0[2] = acc[ai][bj][m][0][2] * bflo(gw.y); v0[3] = acc[ai][bj][m][0][3] * bfhi(gw.y);
;                     v1[0] = acc[ai][bj][m][1][0] * bflo(gw.z); v1[1] = acc[ai][bj][m][1][1] * bfhi(gw.z); v1[2] = acc[ai][bj][m][1][2] * bflo(gw.w); v1[3] = acc[ai][bj][m][1][3] * bfhi(gw.w);
;                     if (br > 0) { const u32x4 ma = *(const u32x4*)(prev + off);
;                         v0[0] += bflo(ma.x); v0[1] += bfhi(ma.x); v0[2] += bflo(ma.y); v0[3] += bfhi(ma.y); v1[0] += bflo(ma.z); v1[1] += bfhi(ma.z); v1[2] += bflo(ma.w); v1[3] += bfhi(ma.w); }
;                     u32x4 w; w.x = cvt_pk_bf16(v0[0], v0[1]); w.y = cvt_pk_bf16(v0[2], v0[3]); w.z = cvt_pk_bf16(v1[0], v1[1]); w.w = cvt_pk_bf16(v1[2], v1[3]);
;                     *(u32x4*)(dst + off) = w;
	v_lshlrev_b32_e32 v50, 16, v40
	v_and_b32_e32 v51, 0xffff0000, v40
	s_waitcnt vmcnt(0)
	v_lshlrev_b32_e32 v52, 16, v44
	v_and_b32_e32 v53, 0xffff0000, v44
	v_lshlrev_b32_e32 v40, 16, v41
	v_and_b32_e32 v41, 0xffff0000, v41
	v_lshlrev_b32_e32 v44, 16, v45
	v_and_b32_e32 v45, 0xffff0000, v45
	v_pk_fma_f32 v[38:39], v[38:39], v[40:41], v[44:45]
	v_lshlrev_b32_e32 v40, 16, v42
	v_and_b32_e32 v41, 0xffff0000, v42
	v_lshlrev_b32_e32 v44, 16, v46
	v_and_b32_e32 v45, 0xffff0000, v46
	v_pk_fma_f32 v[40:41], v[32:33], v[40:41], v[44:45]
	v_lshlrev_b32_e32 v32, 16, v43
	v_and_b32_e32 v33, 0xffff0000, v43
	v_lshlrev_b32_e32 v42, 16, v47
	v_and_b32_e32 v43, 0xffff0000, v47
	v_pk_fma_f32 v[36:37], v[36:37], v[50:51], v[52:53]
	v_pk_fma_f32 v[42:43], v[34:35], v[32:33], v[42:43]
	v_cvt_pk_bf16_f32 v32, v36, v37
	v_cvt_pk_bf16_f32 v33, v38, v39
	v_cvt_pk_bf16_f32 v34, v40, v41
	v_cvt_pk_bf16_f32 v35, v42, v43
	v_lshl_add_u64 v[36:37], s[88:89], 0, v[48:49]
	global_store_dwordx4 v[36:37], v[32:35], off sc1
	s_nop 1
	v_add_u32_e32 v34, 0xa0, v140
	v_ashrrev_i32_e32 v35, 31, v34
	v_lshlrev_b64 v[32:33], 11, v[34:35]
	v_lshl_add_u64 v[40:41], v[32:33], 0, v[138:139]
	v_mad_i64_i32 v[34:35], s[2:3], v34, s26, v[144:145]
	v_lshl_add_u64 v[34:35], v[34:35], 0, s[56:57]
	v_lshlrev_b64 v[44:45], 1, v[40:41]
	v_lshl_add_u64 v[36:37], v[34:35], 0, v[142:143]
	v_lshl_add_u64 v[40:41], s[16:17], 0, v[44:45]
	global_load_dwordx4 v[36:39], v[36:37], off
	s_nop 0
	global_load_dwordx4 v[40:43], v[40:41], off
	s_waitcnt vmcnt(1)
	v_lshlrev_b32_e32 v46, 16, v36
	v_and_b32_e32 v47, 0xffff0000, v36
	s_waitcnt vmcnt(0)
	v_lshlrev_b32_e32 v48, 16, v40
	v_and_b32_e32 v49, 0xffff0000, v40
	v_lshlrev_b32_e32 v36, 16, v37
	v_and_b32_e32 v37, 0xffff0000, v37
	v_lshlrev_b32_e32 v40, 16, v41
	v_and_b32_e32 v41, 0xffff0000, v41
	v_pk_fma_f32 v[30:31], v[30:31], v[36:37], v[40:41]
	v_lshlrev_b32_e32 v36, 16, v38
	v_and_b32_e32 v37, 0xffff0000, v38
	v_lshlrev_b32_e32 v40, 16, v42
	v_and_b32_e32 v41, 0xffff0000, v42
	v_pk_fma_f32 v[36:37], v[24:25], v[36:37], v[40:41]
	v_lshlrev_b32_e32 v24, 16, v39
	v_and_b32_e32 v25, 0xffff0000, v39
	v_lshlrev_b32_e32 v38, 16, v43
	v_and_b32_e32 v39, 0xffff0000, v43
	v_pk_fma_f32 v[28:29], v[28:29], v[46:47], v[48:49]
	v_pk_fma_f32 v[38:39], v[26:27], v[24:25], v[38:39]
	v_cvt_pk_bf16_f32 v24, v28, v29
	v_cvt_pk_bf16_f32 v25, v30, v31
	v_cvt_pk_bf16_f32 v26, v36, v37
	v_cvt_pk_bf16_f32 v27, v38, v39
	v_lshl_add_u64 v[28:29], s[88:89], 0, v[44:45]
	global_store_dwordx4 v[28:29], v[24:27], off sc1
	v_lshl_add_u64 v[28:29], v[32:33], 0, v[120:121]
	v_lshlrev_b64 v[32:33], 1, v[28:29]
	v_lshl_add_u64 v[24:25], v[34:35], 0, v[122:123]
	v_lshl_add_u64 v[28:29], s[16:17], 0, v[32:33]
	global_load_dwordx4 v[24:27], v[24:25], off
	s_nop 0
	global_load_dwordx4 v[28:31], v[28:29], off
	s_waitcnt vmcnt(1)
	v_lshlrev_b32_e32 v34, 16, v24
	v_and_b32_e32 v35, 0xffff0000, v24
	s_waitcnt vmcnt(0)
	v_lshlrev_b32_e32 v36, 16, v28
	v_and_b32_e32 v37, 0xffff0000, v28
	v_lshlrev_b32_e32 v24, 16, v25
	v_and_b32_e32 v25, 0xffff0000, v25
	v_lshlrev_b32_e32 v28, 16, v29
	v_and_b32_e32 v29, 0xffff0000, v29
	v_pk_fma_f32 v[22:23], v[22:23], v[24:25], v[28:29]
	v_lshlrev_b32_e32 v24, 16, v26
	v_and_b32_e32 v25, 0xffff0000, v26
	v_lshlrev_b32_e32 v28, 16, v30
	v_and_b32_e32 v29, 0xffff0000, v30
	v_pk_fma_f32 v[24:25], v[16:17], v[24:25], v[28:29]
	v_lshlrev_b32_e32 v16, 16, v27
	v_and_b32_e32 v17, 0xffff0000, v27
	v_lshlrev_b32_e32 v26, 16, v31
	v_and_b32_e32 v27, 0xffff0000, v31
	v_pk_fma_f32 v[20:21], v[20:21], v[34:35], v[36:37]
	v_pk_fma_f32 v[26:27], v[18:19], v[16:17], v[26:27]
	v_cvt_pk_bf16_f32 v16, v20, v21
	v_cvt_pk_bf16_f32 v17, v22, v23
	v_cvt_pk_bf16_f32 v18, v24, v25
	v_cvt_pk_bf16_f32 v19, v26, v27
	v_lshl_add_u64 v[20:21], s[88:89], 0, v[32:33]
	global_store_dwordx4 v[20:21], v[16:19], off sc1
	s_nop 1
	v_add_u32_e32 v18, 0xb0, v140
	v_ashrrev_i32_e32 v19, 31, v18
	v_lshlrev_b64 v[16:17], 11, v[18:19]
	v_lshl_add_u64 v[24:25], v[16:17], 0, v[138:139]
	v_mad_i64_i32 v[18:19], s[2:3], v18, s26, v[144:145]
	v_lshl_add_u64 v[18:19], v[18:19], 0, s[56:57]
	v_lshlrev_b64 v[28:29], 1, v[24:25]
	v_lshl_add_u64 v[20:21], v[18:19], 0, v[142:143]
	v_lshl_add_u64 v[24:25], s[16:17], 0, v[28:29]
	global_load_dwordx4 v[20:23], v[20:21], off
	s_nop 0
	global_load_dwordx4 v[24:27], v[24:25], off
	s_waitcnt vmcnt(1)
	v_lshlrev_b32_e32 v30, 16, v20
	v_and_b32_e32 v31, 0xffff0000, v20
	s_waitcnt vmcnt(0)
	v_lshlrev_b32_e32 v32, 16, v24
	v_and_b32_e32 v33, 0xffff0000, v24
	v_lshlrev_b32_e32 v20, 16, v21
	v_and_b32_e32 v21, 0xffff0000, v21
	v_lshlrev_b32_e32 v24, 16, v25
	v_and_b32_e32 v25, 0xffff0000, v25
	v_pk_fma_f32 v[14:15], v[14:15], v[20:21], v[24:25]
	v_lshlrev_b32_e32 v20, 16, v22
	v_and_b32_e32 v21, 0xffff0000, v22
	v_lshlrev_b32_e32 v24, 16, v26
	v_and_b32_e32 v25, 0xffff0000, v26
	v_pk_fma_f32 v[20:21], v[8:9], v[20:21], v[24:25]
	v_lshlrev_b32_e32 v8, 16, v23
	v_and_b32_e32 v9, 0xffff0000, v23
	v_lshlrev_b32_e32 v22, 16, v27
	v_and_b32_e32 v23, 0xffff0000, v27
	v_pk_fma_f32 v[12:13], v[12:13], v[30:31], v[32:33]
	v_pk_fma_f32 v[22:23], v[10:11], v[8:9], v[22:23]
	v_cvt_pk_bf16_f32 v8, v12, v13
	v_cvt_pk_bf16_f32 v9, v14, v15
	v_cvt_pk_bf16_f32 v10, v20, v21
	v_cvt_pk_bf16_f32 v11, v22, v23
	v_lshl_add_u64 v[12:13], s[88:89], 0, v[28:29]
	global_store_dwordx4 v[12:13], v[8:11], off sc1
	v_lshl_add_u64 v[12:13], v[16:17], 0, v[120:121]
	v_lshlrev_b64 v[16:17], 1, v[12:13]
	v_lshl_add_u64 v[8:9], v[18:19], 0, v[122:123]
	v_lshl_add_u64 v[12:13], s[16:17], 0, v[16:17]
	global_load_dwordx4 v[8:11], v[8:9], off
	s_nop 0
	global_load_dwordx4 v[12:15], v[12:13], off
	s_waitcnt vmcnt(1)
	v_lshlrev_b32_e32 v18, 16, v8
	v_and_b32_e32 v19, 0xffff0000, v8
	s_waitcnt vmcnt(0)
	v_lshlrev_b32_e32 v20, 16, v12
	v_and_b32_e32 v21, 0xffff0000, v12
	v_lshlrev_b32_e32 v8, 16, v9
	v_and_b32_e32 v9, 0xffff0000, v9
	v_lshlrev_b32_e32 v12, 16, v13
	v_and_b32_e32 v13, 0xffff0000, v13
	v_pk_fma_f32 v[6:7], v[6:7], v[8:9], v[12:13]
	v_lshlrev_b32_e32 v8, 16, v10
	v_and_b32_e32 v9, 0xffff0000, v10
	v_lshlrev_b32_e32 v12, 16, v14
	v_and_b32_e32 v13, 0xffff0000, v14
	v_pk_fma_f32 v[8:9], v[0:1], v[8:9], v[12:13]
	v_lshlrev_b32_e32 v0, 16, v11
	v_and_b32_e32 v1, 0xffff0000, v11
	v_lshlrev_b32_e32 v10, 16, v15
	v_and_b32_e32 v11, 0xffff0000, v15
	v_pk_fma_f32 v[4:5], v[4:5], v[18:19], v[20:21]
	v_pk_fma_f32 v[10:11], v[2:3], v[0:1], v[10:11]
	v_cvt_pk_bf16_f32 v0, v4, v5
	v_cvt_pk_bf16_f32 v1, v6, v7
	v_cvt_pk_bf16_f32 v2, v8, v9
	v_cvt_pk_bf16_f32 v3, v10, v11
	v_lshl_add_u64 v[4:5], s[88:89], 0, v[16:17]
	global_store_dwordx4 v[4:5], v[0:3], off sc1
	s_cbranch_vccnz .LBB0_179
	s_andn2_b64 vcc, exec, s[14:15]
	s_cbranch_vccnz .LBB0_178
	s_barrier
	s_branch .LBB0_178

; __device__ __forceinline__ unsigned cvt_pk_bf16(float lo, float hi) { const f32x2_t v = {lo, hi}; const bf16x2_t b = __builtin_convertvector(v, bf16x2_t); return __builtin_bit_cast(unsigned, b); }
;     __device__ __forceinline__ void operator()(const Acc& acc, const Unit& u, int wr, int wc, int fr, int fq) const {
;     ...
;                 const int r = row0 + ai * HALF + m * 16;
; #pragma unroll
;                 for (int bj = 0; bj < 2; ++bj) {
;                     const int c = col0 + bj * HALF; const size_t off = (size_t)r * D + c;
;                     const u32x4 gw = *(const u32x4*)(gates + (size_t)r * 6144 + br * D + c);
;                     f32x4 v0, v1;
;                     v0[0] = acc[ai][bj][m][0][0] * bflo(gw.x); v0[1] = acc[ai][bj][m][0][1] * bfhi(gw.x); v0[2] = acc[ai][bj][m][0][2] * bflo(gw.y); v0[3] = acc[ai][bj][m][0][3] * bfhi(gw.y);
;                     v1[0] = acc[ai][bj][m][1][0] * bflo(gw.z); v1[1] = acc[ai][bj][m][1][1] * bfhi(gw.z); v1[2] = acc[ai][bj][m][1][2] * bflo(gw.w); v1[3] = acc[ai][bj][m][1][3] * bfhi(gw.w);
;                     if (br > 0) { const u32x4 ma = *(const u32x4*)(prev + off);
;                         v0[0] += bflo(ma.x); v0[1] += bfhi(ma.x); v0[2] += bflo(ma.y); v0[3] += bfhi(ma.y); v1[0] += bflo(ma.z); v1[1] += bfhi(ma.z); v1[2] += bflo(ma.w); v1[3] += bfhi(ma.w); }
;                     u32x4 w; w.x = cvt_pk_bf16(v0[0], v0[1]); w.y = cvt_pk_bf16(v0[2], v0[3]); w.z = cvt_pk_bf16(v1[0], v1[1]); w.w = cvt_pk_bf16(v1[2], v1[3]);
;                     *(u32x4*)(dst + off) = w;
.LBB0_214:
	v_lshl_add_u32 v140, s54, 8, v146
	v_lshl_or_b32 v138, s42, 8, v148
	v_ashrrev_i32_e32 v141, 31, v140
	v_lshlrev_b64 v[158:159], 11, v[140:141]
	v_ashrrev_i32_e32 v139, 31, v138
	v_mov_b64_e32 v[144:145], s[6:7]
	v_lshl_add_u64 v[154:155], v[158:159], 0, v[138:139]
	v_mad_i64_i32 v[142:143], s[2:3], v140, s26, v[144:145]
	v_lshl_add_u64 v[166:167], v[142:143], 0, s[58:59]
	v_lshlrev_b64 v[142:143], 1, v[138:139]
	v_lshlrev_b64 v[170:171], 1, v[154:155]
	v_lshl_add_u64 v[150:151], v[166:167], 0, v[142:143]
	v_lshl_add_u64 v[154:155], s[88:89], 0, v[170:171]
	global_load_dwordx4 v[150:153], v[150:151], off
	s_mov_b64 s[24:25], -1
	global_load_dwordx4 v[154:157], v[154:155], off
	s_andn2_b64 vcc, exec, s[4:5]
	s_waitcnt vmcnt(0)
	v_lshlrev_b32_e32 v172, 16, v150
	v_and_b32_e32 v173, 0xffff0000, v150
	v_lshlrev_b32_e32 v174, 16, v154
	v_and_b32_e32 v175, 0xffff0000, v154
	v_lshlrev_b32_e32 v150, 16, v151
	v_and_b32_e32 v151, 0xffff0000, v151
	v_lshlrev_b32_e32 v154, 16, v155
	v_and_b32_e32 v155, 0xffff0000, v155
	v_pk_fma_f32 v[126:127], v[126:127], v[150:151], v[154:155]
	v_lshlrev_b32_e32 v150, 16, v152
	v_and_b32_e32 v151, 0xffff0000, v152
	v_lshlrev_b32_e32 v154, 16, v156
	v_and_b32_e32 v155, 0xffff0000, v156
	v_pk_fma_f32 v[150:151], v[120:121], v[150:151], v[154:155]
	v_lshlrev_b32_e32 v120, 16, v153
	v_and_b32_e32 v121, 0xffff0000, v153
	v_lshlrev_b32_e32 v152, 16, v157
	v_and_b32_e32 v153, 0xffff0000, v157
	v_pk_fma_f32 v[124:125], v[124:125], v[172:173], v[174:175]
	v_pk_fma_f32 v[152:153], v[122:123], v[120:121], v[152:153]
	v_cvt_pk_bf16_f32 v120, v124, v125
	v_cvt_pk_bf16_f32 v121, v126, v127
	v_cvt_pk_bf16_f32 v122, v150, v151
	v_cvt_pk_bf16_f32 v123, v152, v153
	v_lshl_add_u64 v[124:125], s[8:9], 0, v[170:171]
	global_store_dwordx4 v[124:125], v[120:123], off sc1
	s_nop 1
	v_or_b32_e32 v120, 0x80, v138
	v_ashrrev_i32_e32 v121, 31, v120
	v_lshl_add_u64 v[150:151], v[158:159], 0, v[120:121]
	v_lshlrev_b64 v[122:123], 1, v[120:121]
	v_lshlrev_b64 v[154:155], 1, v[150:151]
	v_lshl_add_u64 v[124:125], v[166:167], 0, v[122:123]
	v_lshl_add_u64 v[150:151], s[88:89], 0, v[154:155]
	global_load_dwordx4 v[124:127], v[124:125], off
	s_nop 0
	global_load_dwordx4 v[150:153], v[150:151], off
	s_waitcnt vmcnt(1)
	v_lshlrev_b32_e32 v156, 16, v124
	v_and_b32_e32 v157, 0xffff0000, v124
	s_waitcnt vmcnt(0)
	v_lshlrev_b32_e32 v158, 16, v150
	v_and_b32_e32 v159, 0xffff0000, v150
	v_lshlrev_b32_e32 v124, 16, v125
	v_and_b32_e32 v125, 0xffff0000, v125
	v_lshlrev_b32_e32 v150, 16, v151
	v_and_b32_e32 v151, 0xffff0000, v151
	v_pk_fma_f32 v[118:119], v[118:119], v[124:125], v[150:151]
	v_lshlrev_b32_e32 v124, 16, v126
	v_and_b32_e32 v125, 0xffff0000, v126
	v_lshlrev_b32_e32 v150, 16, v152
	v_and_b32_e32 v151, 0xffff0000, v152
	v_pk_fma_f32 v[124:125], v[112:113], v[124:125], v[150:151]
	v_lshlrev_b32_e32 v112, 16, v127
	v_and_b32_e32 v113, 0xffff0000, v127
	v_lshlrev_b32_e32 v126, 16, v153
	v_and_b32_e32 v127, 0xffff0000, v153
	v_pk_fma_f32 v[116:117], v[116:117], v[156:157], v[158:159]
	v_pk_fma_f32 v[126:127], v[114:115], v[112:113], v[126:127]
	v_cvt_pk_bf16_f32 v112, v116, v117
	v_cvt_pk_bf16_f32 v113, v118, v119
	v_cvt_pk_bf16_f32 v114, v124, v125
	v_cvt_pk_bf16_f32 v115, v126, v127
	v_lshl_add_u64 v[116:117], s[8:9], 0, v[154:155]
	global_store_dwordx4 v[116:117], v[112:115], off sc1
	s_nop 1
	v_or_b32_e32 v114, 16, v140
	v_ashrrev_i32_e32 v115, 31, v114
	v_lshlrev_b64 v[112:113], 11, v[114:115]
	v_lshl_add_u64 v[124:125], v[112:113], 0, v[138:139]
	v_mad_i64_i32 v[114:115], s[2:3], v114, s26, v[144:145]
	v_lshl_add_u64 v[114:115], v[114:115], 0, s[58:59]
	v_lshlrev_b64 v[150:151], 1, v[124:125]
	v_lshl_add_u64 v[116:117], v[114:115], 0, v[142:143]
	v_lshl_add_u64 v[124:125], s[88:89], 0, v[150:151]
	global_load_dwordx4 v[116:119], v[116:117], off
	s_nop 0
	global_load_dwordx4 v[124:127], v[124:125], off
	s_waitcnt vmcnt(1)
	v_lshlrev_b32_e32 v152, 16, v116
	v_and_b32_e32 v153, 0xffff0000, v116
	s_waitcnt vmcnt(0)
	v_lshlrev_b32_e32 v154, 16, v124
	v_and_b32_e32 v155, 0xffff0000, v124
	v_lshlrev_b32_e32 v116, 16, v117
	v_and_b32_e32 v117, 0xffff0000, v117
	v_lshlrev_b32_e32 v124, 16, v125
	v_and_b32_e32 v125, 0xffff0000, v125
	v_pk_fma_f32 v[110:111], v[110:111], v[116:117], v[124:125]
	v_lshlrev_b32_e32 v116, 16, v118
	v_and_b32_e32 v117, 0xffff0000, v118
	v_lshlrev_b32_e32 v124, 16, v126
	v_and_b32_e32 v125, 0xffff0000, v126
	v_pk_fma_f32 v[116:117], v[104:105], v[116:117], v[124:125]
	v_lshlrev_b32_e32 v104, 16, v119
	v_and_b32_e32 v105, 0xffff0000, v119
	v_lshlrev_b32_e32 v118, 16, v127
	v_and_b32_e32 v119, 0xffff0000, v127
	v_pk_fma_f32 v[108:109], v[108:109], v[152:153], v[154:155]
	v_pk_fma_f32 v[118:119], v[106:107], v[104:105], v[118:119]
	v_cvt_pk_bf16_f32 v104, v108, v109
	v_cvt_pk_bf16_f32 v105, v110, v111
	v_cvt_pk_bf16_f32 v106, v116, v117
	v_cvt_pk_bf16_f32 v107, v118, v119
	v_lshl_add_u64 v[108:109], s[8:9], 0, v[150:151]
	global_store_dwordx4 v[108:109], v[104:107], off sc1
	v_lshl_add_u64 v[108:109], v[112:113], 0, v[120:121]
	v_lshlrev_b64 v[112:113], 1, v[108:109]
	v_lshl_add_u64 v[104:105], v[114:115], 0, v[122:123]
	v_lshl_add_u64 v[108:109], s[88:89], 0, v[112:113]
	global_load_dwordx4 v[104:107], v[104:105], off
	s_nop 0
	global_load_dwordx4 v[108:111], v[108:109], off
	s_waitcnt vmcnt(1)
	v_lshlrev_b32_e32 v114, 16, v104
	v_and_b32_e32 v115, 0xffff0000, v104
	s_waitcnt vmcnt(0)
; __device__ __forceinline__ unsigned cvt_pk_bf16(float lo, float hi) { const f32x2_t v = {lo, hi}; const bf16x2_t b = __builtin_convertvector(v, bf16x2_t); return __builtin_bit_cast(unsigned, b); }
;     __device__ __forceinline__ void operator()(const Acc& acc, const Unit& u, int wr, int wc, int fr, int fq) const {
;     ...
;                 const int r = row0 + ai * HALF + m * 16;
; #pragma unroll
;                 for (int bj = 0; bj < 2; ++bj) {
;                     const int c = col0 + bj * HALF; const size_t off = (size_t)r * D + c;
;                     const u32x4 gw = *(const u32x4*)(gates + (size_t)r * 6144 + br * D + c);
;                     f32x4 v0, v1;
;                     v0[0] = acc[ai][bj][m][0][0] * bflo(gw.x); v0[1] = acc[ai][bj][m][0][1] * bfhi(gw.x); v0[2] = acc[ai][bj][m][0][2] * bflo(gw.y); v0[3] = acc[ai][bj][m][0][3] * bfhi(gw.y);
;                     v1[0] = acc[ai][bj][m][1][0] * bflo(gw.z); v1[1] = acc[ai][bj][m][1][1] * bfhi(gw.z); v1[2] = acc[ai][bj][m][1][2] * bflo(gw.w); v1[3] = acc[ai][bj][m][1][3] * bfhi(gw.w);
;                     if (br > 0) { const u32x4 ma = *(const u32x4*)(prev + off);
;                         v0[0] += bflo(ma.x); v0[1] += bfhi(ma.x); v0[2] += bflo(ma.y); v0[3] += bfhi(ma.y); v1[0] += bflo(ma.z); v1[1] += bfhi(ma.z); v1[2] += bflo(ma.w); v1[3] += bfhi(ma.w); }
;                     u32x4 w; w.x = cvt_pk_bf16(v0[0], v0[1]); w.y = cvt_pk_bf16(v0[2], v0[3]); w.z = cvt_pk_bf16(v1[0], v1[1]); w.w = cvt_pk_bf16(v1[2], v1[3]);
;                     *(u32x4*)(dst + off) = w;
	v_lshlrev_b32_e32 v116, 16, v108
	v_and_b32_e32 v117, 0xffff0000, v108
	v_lshlrev_b32_e32 v104, 16, v105
	v_and_b32_e32 v105, 0xffff0000, v105
	v_lshlrev_b32_e32 v108, 16, v109
	v_and_b32_e32 v109, 0xffff0000, v109
	v_pk_fma_f32 v[102:103], v[102:103], v[104:105], v[108:109]
	v_lshlrev_b32_e32 v104, 16, v106
	v_and_b32_e32 v105, 0xffff0000, v106
	v_lshlrev_b32_e32 v108, 16, v110
	v_and_b32_e32 v109, 0xffff0000, v110
	v_pk_fma_f32 v[104:105], v[96:97], v[104:105], v[108:109]
	v_lshlrev_b32_e32 v96, 16, v107
	v_and_b32_e32 v97, 0xffff0000, v107
	v_lshlrev_b32_e32 v106, 16, v111
	v_and_b32_e32 v107, 0xffff0000, v111
	v_pk_fma_f32 v[100:101], v[100:101], v[114:115], v[116:117]
	v_pk_fma_f32 v[106:107], v[98:99], v[96:97], v[106:107]
	v_cvt_pk_bf16_f32 v96, v100, v101
	v_cvt_pk_bf16_f32 v97, v102, v103
	v_cvt_pk_bf16_f32 v98, v104, v105
	v_cvt_pk_bf16_f32 v99, v106, v107
	v_lshl_add_u64 v[100:101], s[8:9], 0, v[112:113]
	global_store_dwordx4 v[100:101], v[96:99], off sc1
	s_nop 1
	v_or_b32_e32 v98, 32, v140
	v_ashrrev_i32_e32 v99, 31, v98
	v_lshlrev_b64 v[96:97], 11, v[98:99]
	v_lshl_add_u64 v[104:105], v[96:97], 0, v[138:139]
	v_mad_i64_i32 v[98:99], s[2:3], v98, s26, v[144:145]
	v_lshl_add_u64 v[98:99], v[98:99], 0, s[58:59]
	v_lshlrev_b64 v[108:109], 1, v[104:105]
	v_lshl_add_u64 v[100:101], v[98:99], 0, v[142:143]
	v_lshl_add_u64 v[104:105], s[88:89], 0, v[108:109]
	global_load_dwordx4 v[100:103], v[100:101], off
	s_nop 0
	global_load_dwordx4 v[104:107], v[104:105], off
	s_waitcnt vmcnt(1)
	v_lshlrev_b32_e32 v110, 16, v100
	v_and_b32_e32 v111, 0xffff0000, v100
	s_waitcnt vmcnt(0)
	v_lshlrev_b32_e32 v112, 16, v104
	v_and_b32_e32 v113, 0xffff0000, v104
	v_lshlrev_b32_e32 v100, 16, v101
	v_and_b32_e32 v101, 0xffff0000, v101
	v_lshlrev_b32_e32 v104, 16, v105
	v_and_b32_e32 v105, 0xffff0000, v105
	v_pk_fma_f32 v[94:95], v[94:95], v[100:101], v[104:105]
	v_lshlrev_b32_e32 v100, 16, v102
	v_and_b32_e32 v101, 0xffff0000, v102
	v_lshlrev_b32_e32 v104, 16, v106
	v_and_b32_e32 v105, 0xffff0000, v106
	v_pk_fma_f32 v[100:101], v[88:89], v[100:101], v[104:105]
	v_lshlrev_b32_e32 v88, 16, v103
	v_and_b32_e32 v89, 0xffff0000, v103
	v_lshlrev_b32_e32 v102, 16, v107
	v_and_b32_e32 v103, 0xffff0000, v107
	v_pk_fma_f32 v[92:93], v[92:93], v[110:111], v[112:113]
	v_pk_fma_f32 v[102:103], v[90:91], v[88:89], v[102:103]
	v_cvt_pk_bf16_f32 v88, v92, v93
	v_cvt_pk_bf16_f32 v89, v94, v95
	v_cvt_pk_bf16_f32 v90, v100, v101
	v_cvt_pk_bf16_f32 v91, v102, v103
	v_lshl_add_u64 v[92:93], s[8:9], 0, v[108:109]
	global_store_dwordx4 v[92:93], v[88:91], off sc1
	v_lshl_add_u64 v[92:93], v[96:97], 0, v[120:121]
	v_lshlrev_b64 v[96:97], 1, v[92:93]
	v_lshl_add_u64 v[88:89], v[98:99], 0, v[122:123]
	v_lshl_add_u64 v[92:93], s[88:89], 0, v[96:97]
	global_load_dwordx4 v[88:91], v[88:89], off
	s_nop 0
	global_load_dwordx4 v[92:95], v[92:93], off
	s_waitcnt vmcnt(1)
	v_lshlrev_b32_e32 v98, 16, v88
	v_and_b32_e32 v99, 0xffff0000, v88
	s_waitcnt vmcnt(0)
	v_lshlrev_b32_e32 v100, 16, v92
	v_and_b32_e32 v101, 0xffff0000, v92
	v_lshlrev_b32_e32 v88, 16, v89
	v_and_b32_e32 v89, 0xffff0000, v89
	v_lshlrev_b32_e32 v92, 16, v93
	v_and_b32_e32 v93, 0xffff0000, v93
	v_pk_fma_f32 v[86:87], v[86:87], v[88:89], v[92:93]
	v_lshlrev_b32_e32 v88, 16, v90
	v_and_b32_e32 v89, 0xffff0000, v90
	v_lshlrev_b32_e32 v92, 16, v94
	v_and_b32_e32 v93, 0xffff0000, v94
	v_pk_fma_f32 v[88:89], v[80:81], v[88:89], v[92:93]
	v_lshlrev_b32_e32 v80, 16, v91
	v_and_b32_e32 v81, 0xffff0000, v91
	v_lshlrev_b32_e32 v90, 16, v95
	v_and_b32_e32 v91, 0xffff0000, v95
	v_pk_fma_f32 v[84:85], v[84:85], v[98:99], v[100:101]
	v_pk_fma_f32 v[90:91], v[82:83], v[80:81], v[90:91]
	v_cvt_pk_bf16_f32 v80, v84, v85
	v_cvt_pk_bf16_f32 v81, v86, v87
	v_cvt_pk_bf16_f32 v82, v88, v89
	v_cvt_pk_bf16_f32 v83, v90, v91
	v_lshl_add_u64 v[84:85], s[8:9], 0, v[96:97]
	global_store_dwordx4 v[84:85], v[80:83], off sc1
	s_nop 1
	v_or_b32_e32 v82, 48, v140
	v_ashrrev_i32_e32 v83, 31, v82
	v_lshlrev_b64 v[80:81], 11, v[82:83]
	v_lshl_add_u64 v[88:89], v[80:81], 0, v[138:139]
	v_mad_i64_i32 v[82:83], s[2:3], v82, s26, v[144:145]
	v_lshl_add_u64 v[82:83], v[82:83], 0, s[58:59]
	v_lshlrev_b64 v[92:93], 1, v[88:89]
	v_lshl_add_u64 v[84:85], v[82:83], 0, v[142:143]
	v_lshl_add_u64 v[88:89], s[88:89], 0, v[92:93]
	global_load_dwordx4 v[84:87], v[84:85], off
	s_nop 0
	global_load_dwordx4 v[88:91], v[88:89], off
	s_waitcnt vmcnt(1)
	v_lshlrev_b32_e32 v94, 16, v84
	v_and_b32_e32 v95, 0xffff0000, v84
	s_waitcnt vmcnt(0)
	v_lshlrev_b32_e32 v96, 16, v88
	v_and_b32_e32 v97, 0xffff0000, v88
	v_lshlrev_b32_e32 v84, 16, v85
	v_and_b32_e32 v85, 0xffff0000, v85
	v_lshlrev_b32_e32 v88, 16, v89
	v_and_b32_e32 v89, 0xffff0000, v89
	v_pk_fma_f32 v[78:79], v[78:79], v[84:85], v[88:89]
	v_lshlrev_b32_e32 v84, 16, v86
	v_and_b32_e32 v85, 0xffff0000, v86
	v_lshlrev_b32_e32 v88, 16, v90
	v_and_b32_e32 v89, 0xffff0000, v90
	v_pk_fma_f32 v[84:85], v[72:73], v[84:85], v[88:89]
	v_lshlrev_b32_e32 v72, 16, v87
	v_and_b32_e32 v73, 0xffff0000, v87
	v_lshlrev_b32_e32 v86, 16, v91
	v_and_b32_e32 v87, 0xffff0000, v91
	v_pk_fma_f32 v[76:77], v[76:77], v[94:95], v[96:97]
	v_pk_fma_f32 v[86:87], v[74:75], v[72:73], v[86:87]
	v_cvt_pk_bf16_f32 v72, v76, v77
	v_cvt_pk_bf16_f32 v73, v78, v79
	v_cvt_pk_bf16_f32 v74, v84, v85
	v_cvt_pk_bf16_f32 v75, v86, v87
	v_lshl_add_u64 v[76:77], s[8:9], 0, v[92:93]
	global_store_dwordx4 v[76:77], v[72:75], off sc1
	v_lshl_add_u64 v[76:77], v[80:81], 0, v[120:121]
	v_lshlrev_b64 v[80:81], 1, v[76:77]
	v_lshl_add_u64 v[72:73], v[82:83], 0, v[122:123]
	v_lshl_add_u64 v[76:77], s[88:89], 0, v[80:81]
	global_load_dwordx4 v[72:75], v[72:73], off
	s_nop 0
	global_load_dwordx4 v[76:79], v[76:77], off
	s_waitcnt vmcnt(1)
; __device__ __forceinline__ unsigned cvt_pk_bf16(float lo, float hi) { const f32x2_t v = {lo, hi}; const bf16x2_t b = __builtin_convertvector(v, bf16x2_t); return __builtin_bit_cast(unsigned, b); }
;     __device__ __forceinline__ void operator()(const Acc& acc, const Unit& u, int wr, int wc, int fr, int fq) const {
;     ...
;                 const int r = row0 + ai * HALF + m * 16;
; #pragma unroll
;                 for (int bj = 0; bj < 2; ++bj) {
;                     const int c = col0 + bj * HALF; const size_t off = (size_t)r * D + c;
;                     const u32x4 gw = *(const u32x4*)(gates + (size_t)r * 6144 + br * D + c);
;                     f32x4 v0, v1;
;                     v0[0] = acc[ai][bj][m][0][0] * bflo(gw.x); v0[1] = acc[ai][bj][m][0][1] * bfhi(gw.x); v0[2] = acc[ai][bj][m][0][2] * bflo(gw.y); v0[3] = acc[ai][bj][m][0][3] * bfhi(gw.y);
;                     v1[0] = acc[ai][bj][m][1][0] * bflo(gw.z); v1[1] = acc[ai][bj][m][1][1] * bfhi(gw.z); v1[2] = acc[ai][bj][m][1][2] * bflo(gw.w); v1[3] = acc[ai][bj][m][1][3] * bfhi(gw.w);
;                     if (br > 0) { const u32x4 ma = *(const u32x4*)(prev + off);
;                         v0[0] += bflo(ma.x); v0[1] += bfhi(ma.x); v0[2] += bflo(ma.y); v0[3] += bfhi(ma.y); v1[0] += bflo(ma.z); v1[1] += bfhi(ma.z); v1[2] += bflo(ma.w); v1[3] += bfhi(ma.w); }
;                     u32x4 w; w.x = cvt_pk_bf16(v0[0], v0[1]); w.y = cvt_pk_bf16(v0[2], v0[3]); w.z = cvt_pk_bf16(v1[0], v1[1]); w.w = cvt_pk_bf16(v1[2], v1[3]);
;                     *(u32x4*)(dst + off) = w;
	v_lshlrev_b32_e32 v82, 16, v72
	v_and_b32_e32 v83, 0xffff0000, v72
	s_waitcnt vmcnt(0)
	v_lshlrev_b32_e32 v84, 16, v76
	v_and_b32_e32 v85, 0xffff0000, v76
	v_lshlrev_b32_e32 v72, 16, v73
	v_and_b32_e32 v73, 0xffff0000, v73
	v_lshlrev_b32_e32 v76, 16, v77
	v_and_b32_e32 v77, 0xffff0000, v77
	v_pk_fma_f32 v[70:71], v[70:71], v[72:73], v[76:77]
	v_lshlrev_b32_e32 v72, 16, v74
	v_and_b32_e32 v73, 0xffff0000, v74
	v_lshlrev_b32_e32 v76, 16, v78
	v_and_b32_e32 v77, 0xffff0000, v78
	v_pk_fma_f32 v[72:73], v[64:65], v[72:73], v[76:77]
	v_lshlrev_b32_e32 v64, 16, v75
	v_and_b32_e32 v65, 0xffff0000, v75
	v_lshlrev_b32_e32 v74, 16, v79
	v_and_b32_e32 v75, 0xffff0000, v79
	v_pk_fma_f32 v[68:69], v[68:69], v[82:83], v[84:85]
	v_pk_fma_f32 v[74:75], v[66:67], v[64:65], v[74:75]
	v_cvt_pk_bf16_f32 v64, v68, v69
	v_cvt_pk_bf16_f32 v65, v70, v71
	v_cvt_pk_bf16_f32 v66, v72, v73
	v_cvt_pk_bf16_f32 v67, v74, v75
	v_lshl_add_u64 v[68:69], s[8:9], 0, v[80:81]
	global_store_dwordx4 v[68:69], v[64:67], off sc1
	s_nop 1
	v_add_u32_e32 v66, 0x80, v140
	v_ashrrev_i32_e32 v67, 31, v66
	v_lshlrev_b64 v[64:65], 11, v[66:67]
	v_lshl_add_u64 v[72:73], v[64:65], 0, v[138:139]
	v_mad_i64_i32 v[66:67], s[2:3], v66, s26, v[144:145]
	v_lshl_add_u64 v[66:67], v[66:67], 0, s[58:59]
	v_lshlrev_b64 v[76:77], 1, v[72:73]
	v_lshl_add_u64 v[68:69], v[66:67], 0, v[142:143]
	v_lshl_add_u64 v[72:73], s[88:89], 0, v[76:77]
	global_load_dwordx4 v[68:71], v[68:69], off
	s_nop 0
	global_load_dwordx4 v[72:75], v[72:73], off
	s_waitcnt vmcnt(1)
	v_lshlrev_b32_e32 v78, 16, v68
	v_and_b32_e32 v79, 0xffff0000, v68
	s_waitcnt vmcnt(0)
	v_lshlrev_b32_e32 v80, 16, v72
	v_and_b32_e32 v81, 0xffff0000, v72
	v_lshlrev_b32_e32 v68, 16, v69
	v_and_b32_e32 v69, 0xffff0000, v69
	v_lshlrev_b32_e32 v72, 16, v73
	v_and_b32_e32 v73, 0xffff0000, v73
	v_pk_fma_f32 v[62:63], v[62:63], v[68:69], v[72:73]
	v_lshlrev_b32_e32 v68, 16, v70
	v_and_b32_e32 v69, 0xffff0000, v70
	v_lshlrev_b32_e32 v72, 16, v74
	v_and_b32_e32 v73, 0xffff0000, v74
	v_pk_fma_f32 v[68:69], v[56:57], v[68:69], v[72:73]
	v_lshlrev_b32_e32 v56, 16, v71
	v_and_b32_e32 v57, 0xffff0000, v71
	v_lshlrev_b32_e32 v70, 16, v75
	v_and_b32_e32 v71, 0xffff0000, v75
	v_pk_fma_f32 v[60:61], v[60:61], v[78:79], v[80:81]
	v_pk_fma_f32 v[70:71], v[58:59], v[56:57], v[70:71]
	v_cvt_pk_bf16_f32 v56, v60, v61
	v_cvt_pk_bf16_f32 v57, v62, v63
	v_cvt_pk_bf16_f32 v58, v68, v69
	v_cvt_pk_bf16_f32 v59, v70, v71
	v_lshl_add_u64 v[60:61], s[8:9], 0, v[76:77]
	global_store_dwordx4 v[60:61], v[56:59], off sc1
	v_lshl_add_u64 v[60:61], v[64:65], 0, v[120:121]
	v_lshlrev_b64 v[64:65], 1, v[60:61]
	v_lshl_add_u64 v[56:57], v[66:67], 0, v[122:123]
	v_lshl_add_u64 v[60:61], s[88:89], 0, v[64:65]
	global_load_dwordx4 v[56:59], v[56:57], off
	s_nop 0
	global_load_dwordx4 v[60:63], v[60:61], off
	s_waitcnt vmcnt(1)
	v_lshlrev_b32_e32 v66, 16, v56
	v_and_b32_e32 v67, 0xffff0000, v56
	s_waitcnt vmcnt(0)
	v_lshlrev_b32_e32 v68, 16, v60
	v_and_b32_e32 v69, 0xffff0000, v60
	v_lshlrev_b32_e32 v56, 16, v57
	v_and_b32_e32 v57, 0xffff0000, v57
	v_lshlrev_b32_e32 v60, 16, v61
	v_and_b32_e32 v61, 0xffff0000, v61
	v_pk_fma_f32 v[54:55], v[54:55], v[56:57], v[60:61]
	v_lshlrev_b32_e32 v56, 16, v58
	v_and_b32_e32 v57, 0xffff0000, v58
	v_lshlrev_b32_e32 v60, 16, v62
	v_and_b32_e32 v61, 0xffff0000, v62
	v_pk_fma_f32 v[56:57], v[48:49], v[56:57], v[60:61]
	v_lshlrev_b32_e32 v48, 16, v59
	v_and_b32_e32 v49, 0xffff0000, v59
	v_lshlrev_b32_e32 v58, 16, v63
	v_and_b32_e32 v59, 0xffff0000, v63
	v_pk_fma_f32 v[52:53], v[52:53], v[66:67], v[68:69]
	v_pk_fma_f32 v[58:59], v[50:51], v[48:49], v[58:59]
	v_cvt_pk_bf16_f32 v48, v52, v53
	v_cvt_pk_bf16_f32 v49, v54, v55
	v_cvt_pk_bf16_f32 v50, v56, v57
	v_cvt_pk_bf16_f32 v51, v58, v59
	v_lshl_add_u64 v[52:53], s[8:9], 0, v[64:65]
	global_store_dwordx4 v[52:53], v[48:51], off sc1
	s_nop 1
	v_add_u32_e32 v50, 0x90, v140
	v_ashrrev_i32_e32 v51, 31, v50
	v_lshlrev_b64 v[48:49], 11, v[50:51]
	v_lshl_add_u64 v[56:57], v[48:49], 0, v[138:139]
	v_mad_i64_i32 v[50:51], s[2:3], v50, s26, v[144:145]
	v_lshl_add_u64 v[50:51], v[50:51], 0, s[58:59]
	v_lshlrev_b64 v[60:61], 1, v[56:57]
	v_lshl_add_u64 v[52:53], v[50:51], 0, v[142:143]
	v_lshl_add_u64 v[56:57], s[88:89], 0, v[60:61]
	global_load_dwordx4 v[52:55], v[52:53], off
	s_nop 0
	global_load_dwordx4 v[56:59], v[56:57], off
	s_waitcnt vmcnt(1)
	v_lshlrev_b32_e32 v62, 16, v52
	v_and_b32_e32 v63, 0xffff0000, v52
	s_waitcnt vmcnt(0)
	v_lshlrev_b32_e32 v64, 16, v56
	v_and_b32_e32 v65, 0xffff0000, v56
	v_lshlrev_b32_e32 v52, 16, v53
	v_and_b32_e32 v53, 0xffff0000, v53
	v_lshlrev_b32_e32 v56, 16, v57
	v_and_b32_e32 v57, 0xffff0000, v57
	v_pk_fma_f32 v[46:47], v[46:47], v[52:53], v[56:57]
	v_lshlrev_b32_e32 v52, 16, v54
	v_and_b32_e32 v53, 0xffff0000, v54
	v_lshlrev_b32_e32 v56, 16, v58
	v_and_b32_e32 v57, 0xffff0000, v58
	v_pk_fma_f32 v[52:53], v[40:41], v[52:53], v[56:57]
	v_lshlrev_b32_e32 v40, 16, v55
	v_and_b32_e32 v41, 0xffff0000, v55
	v_lshlrev_b32_e32 v54, 16, v59
	v_and_b32_e32 v55, 0xffff0000, v59
	v_pk_fma_f32 v[44:45], v[44:45], v[62:63], v[64:65]
	v_pk_fma_f32 v[54:55], v[42:43], v[40:41], v[54:55]
	v_cvt_pk_bf16_f32 v40, v44, v45
	v_cvt_pk_bf16_f32 v41, v46, v47
	v_cvt_pk_bf16_f32 v42, v52, v53
	v_cvt_pk_bf16_f32 v43, v54, v55
	v_lshl_add_u64 v[44:45], s[8:9], 0, v[60:61]
	global_store_dwordx4 v[44:45], v[40:43], off sc1
	v_lshl_add_u64 v[44:45], v[48:49], 0, v[120:121]
	v_lshlrev_b64 v[48:49], 1, v[44:45]
	v_lshl_add_u64 v[40:41], v[50:51], 0, v[122:123]
	v_lshl_add_u64 v[44:45], s[88:89], 0, v[48:49]
	global_load_dwordx4 v[40:43], v[40:41], off
	s_nop 0
	global_load_dwordx4 v[44:47], v[44:45], off
	s_waitcnt vmcnt(1)
; __device__ __forceinline__ unsigned cvt_pk_bf16(float lo, float hi) { const f32x2_t v = {lo, hi}; const bf16x2_t b = __builtin_convertvector(v, bf16x2_t); return __builtin_bit_cast(unsigned, b); }
;     __device__ __forceinline__ void operator()(const Acc& acc, const Unit& u, int wr, int wc, int fr, int fq) const {
;     ...
;                 const int r = row0 + ai * HALF + m * 16;
; #pragma unroll
;                 for (int bj = 0; bj < 2; ++bj) {
;                     const int c = col0 + bj * HALF; const size_t off = (size_t)r * D + c;
;                     const u32x4 gw = *(const u32x4*)(gates + (size_t)r * 6144 + br * D + c);
;                     f32x4 v0, v1;
;                     v0[0] = acc[ai][bj][m][0][0] * bflo(gw.x); v0[1] = acc[ai][bj][m][0][1] * bfhi(gw.x); v0[2] = acc[ai][bj][m][0][2] * bflo(gw.y); v0[3] = acc[ai][bj][m][0][3] * bfhi(gw.y);
;                     v1[0] = acc[ai][bj][m][1][0] * bflo(gw.z); v1[1] = acc[ai][bj][m][1][1] * bfhi(gw.z); v1[2] = acc[ai][bj][m][1][2] * bflo(gw.w); v1[3] = acc[ai][bj][m][1][3] * bfhi(gw.w);
;                     if (br > 0) { const u32x4 ma = *(const u32x4*)(prev + off);
;                         v0[0] += bflo(ma.x); v0[1] += bfhi(ma.x); v0[2] += bflo(ma.y); v0[3] += bfhi(ma.y); v1[0] += bflo(ma.z); v1[1] += bfhi(ma.z); v1[2] += bflo(ma.w); v1[3] += bfhi(ma.w); }
;                     u32x4 w; w.x = cvt_pk_bf16(v0[0], v0[1]); w.y = cvt_pk_bf16(v0[2], v0[3]); w.z = cvt_pk_bf16(v1[0], v1[1]); w.w = cvt_pk_bf16(v1[2], v1[3]);
;                     *(u32x4*)(dst + off) = w;
	v_lshlrev_b32_e32 v50, 16, v40
	v_and_b32_e32 v51, 0xffff0000, v40
	s_waitcnt vmcnt(0)
	v_lshlrev_b32_e32 v52, 16, v44
	v_and_b32_e32 v53, 0xffff0000, v44
	v_lshlrev_b32_e32 v40, 16, v41
	v_and_b32_e32 v41, 0xffff0000, v41
	v_lshlrev_b32_e32 v44, 16, v45
	v_and_b32_e32 v45, 0xffff0000, v45
	v_pk_fma_f32 v[38:39], v[38:39], v[40:41], v[44:45]
	v_lshlrev_b32_e32 v40, 16, v42
	v_and_b32_e32 v41, 0xffff0000, v42
	v_lshlrev_b32_e32 v44, 16, v46
	v_and_b32_e32 v45, 0xffff0000, v46
	v_pk_fma_f32 v[40:41], v[32:33], v[40:41], v[44:45]
	v_lshlrev_b32_e32 v32, 16, v43
	v_and_b32_e32 v33, 0xffff0000, v43
	v_lshlrev_b32_e32 v42, 16, v47
	v_and_b32_e32 v43, 0xffff0000, v47
	v_pk_fma_f32 v[36:37], v[36:37], v[50:51], v[52:53]
	v_pk_fma_f32 v[42:43], v[34:35], v[32:33], v[42:43]
	v_cvt_pk_bf16_f32 v32, v36, v37
	v_cvt_pk_bf16_f32 v33, v38, v39
	v_cvt_pk_bf16_f32 v34, v40, v41
	v_cvt_pk_bf16_f32 v35, v42, v43
	v_lshl_add_u64 v[36:37], s[8:9], 0, v[48:49]
	global_store_dwordx4 v[36:37], v[32:35], off sc1
	s_nop 1
	v_add_u32_e32 v34, 0xa0, v140
	v_ashrrev_i32_e32 v35, 31, v34
	v_lshlrev_b64 v[32:33], 11, v[34:35]
	v_lshl_add_u64 v[40:41], v[32:33], 0, v[138:139]
	v_mad_i64_i32 v[34:35], s[2:3], v34, s26, v[144:145]
	v_lshl_add_u64 v[34:35], v[34:35], 0, s[58:59]
	v_lshlrev_b64 v[44:45], 1, v[40:41]
	v_lshl_add_u64 v[36:37], v[34:35], 0, v[142:143]
	v_lshl_add_u64 v[40:41], s[88:89], 0, v[44:45]
	global_load_dwordx4 v[36:39], v[36:37], off
	s_nop 0
	global_load_dwordx4 v[40:43], v[40:41], off
	s_waitcnt vmcnt(1)
	v_lshlrev_b32_e32 v46, 16, v36
	v_and_b32_e32 v47, 0xffff0000, v36
	s_waitcnt vmcnt(0)
	v_lshlrev_b32_e32 v48, 16, v40
	v_and_b32_e32 v49, 0xffff0000, v40
	v_lshlrev_b32_e32 v36, 16, v37
	v_and_b32_e32 v37, 0xffff0000, v37
	v_lshlrev_b32_e32 v40, 16, v41
	v_and_b32_e32 v41, 0xffff0000, v41
	v_pk_fma_f32 v[30:31], v[30:31], v[36:37], v[40:41]
	v_lshlrev_b32_e32 v36, 16, v38
	v_and_b32_e32 v37, 0xffff0000, v38
	v_lshlrev_b32_e32 v40, 16, v42
	v_and_b32_e32 v41, 0xffff0000, v42
	v_pk_fma_f32 v[36:37], v[24:25], v[36:37], v[40:41]
	v_lshlrev_b32_e32 v24, 16, v39
	v_and_b32_e32 v25, 0xffff0000, v39
	v_lshlrev_b32_e32 v38, 16, v43
	v_and_b32_e32 v39, 0xffff0000, v43
	v_pk_fma_f32 v[28:29], v[28:29], v[46:47], v[48:49]
	v_pk_fma_f32 v[38:39], v[26:27], v[24:25], v[38:39]
	v_cvt_pk_bf16_f32 v24, v28, v29
	v_cvt_pk_bf16_f32 v25, v30, v31
	v_cvt_pk_bf16_f32 v26, v36, v37
	v_cvt_pk_bf16_f32 v27, v38, v39
	v_lshl_add_u64 v[28:29], s[8:9], 0, v[44:45]
	global_store_dwordx4 v[28:29], v[24:27], off sc1
	v_lshl_add_u64 v[28:29], v[32:33], 0, v[120:121]
	v_lshlrev_b64 v[32:33], 1, v[28:29]
	v_lshl_add_u64 v[24:25], v[34:35], 0, v[122:123]
	v_lshl_add_u64 v[28:29], s[88:89], 0, v[32:33]
	global_load_dwordx4 v[24:27], v[24:25], off
	s_nop 0
	global_load_dwordx4 v[28:31], v[28:29], off
	s_waitcnt vmcnt(1)
	v_lshlrev_b32_e32 v34, 16, v24
	v_and_b32_e32 v35, 0xffff0000, v24
	s_waitcnt vmcnt(0)
	v_lshlrev_b32_e32 v36, 16, v28
	v_and_b32_e32 v37, 0xffff0000, v28
	v_lshlrev_b32_e32 v24, 16, v25
	v_and_b32_e32 v25, 0xffff0000, v25
	v_lshlrev_b32_e32 v28, 16, v29
	v_and_b32_e32 v29, 0xffff0000, v29
	v_pk_fma_f32 v[22:23], v[22:23], v[24:25], v[28:29]
	v_lshlrev_b32_e32 v24, 16, v26
	v_and_b32_e32 v25, 0xffff0000, v26
	v_lshlrev_b32_e32 v28, 16, v30
	v_and_b32_e32 v29, 0xffff0000, v30
	v_pk_fma_f32 v[24:25], v[16:17], v[24:25], v[28:29]
	v_lshlrev_b32_e32 v16, 16, v27
	v_and_b32_e32 v17, 0xffff0000, v27
	v_lshlrev_b32_e32 v26, 16, v31
	v_and_b32_e32 v27, 0xffff0000, v31
	v_pk_fma_f32 v[20:21], v[20:21], v[34:35], v[36:37]
	v_pk_fma_f32 v[26:27], v[18:19], v[16:17], v[26:27]
	v_cvt_pk_bf16_f32 v16, v20, v21
	v_cvt_pk_bf16_f32 v17, v22, v23
	v_cvt_pk_bf16_f32 v18, v24, v25
	v_cvt_pk_bf16_f32 v19, v26, v27
	v_lshl_add_u64 v[20:21], s[8:9], 0, v[32:33]
	global_store_dwordx4 v[20:21], v[16:19], off sc1
	s_nop 1
	v_add_u32_e32 v18, 0xb0, v140
	v_ashrrev_i32_e32 v19, 31, v18
	v_lshlrev_b64 v[16:17], 11, v[18:19]
	v_lshl_add_u64 v[24:25], v[16:17], 0, v[138:139]
	v_mad_i64_i32 v[18:19], s[2:3], v18, s26, v[144:145]
	v_lshl_add_u64 v[18:19], v[18:19], 0, s[58:59]
	v_lshlrev_b64 v[28:29], 1, v[24:25]
	v_lshl_add_u64 v[20:21], v[18:19], 0, v[142:143]
	v_lshl_add_u64 v[24:25], s[88:89], 0, v[28:29]
	global_load_dwordx4 v[20:23], v[20:21], off
	s_nop 0
	global_load_dwordx4 v[24:27], v[24:25], off
	s_waitcnt vmcnt(1)
	v_lshlrev_b32_e32 v30, 16, v20
	v_and_b32_e32 v31, 0xffff0000, v20
	s_waitcnt vmcnt(0)
	v_lshlrev_b32_e32 v32, 16, v24
	v_and_b32_e32 v33, 0xffff0000, v24
	v_lshlrev_b32_e32 v20, 16, v21
	v_and_b32_e32 v21, 0xffff0000, v21
	v_lshlrev_b32_e32 v24, 16, v25
	v_and_b32_e32 v25, 0xffff0000, v25
	v_pk_fma_f32 v[14:15], v[14:15], v[20:21], v[24:25]
	v_lshlrev_b32_e32 v20, 16, v22
	v_and_b32_e32 v21, 0xffff0000, v22
	v_lshlrev_b32_e32 v24, 16, v26
	v_and_b32_e32 v25, 0xffff0000, v26
	v_pk_fma_f32 v[20:21], v[8:9], v[20:21], v[24:25]
	v_lshlrev_b32_e32 v8, 16, v23
	v_and_b32_e32 v9, 0xffff0000, v23
	v_lshlrev_b32_e32 v22, 16, v27
	v_and_b32_e32 v23, 0xffff0000, v27
	v_pk_fma_f32 v[12:13], v[12:13], v[30:31], v[32:33]
	v_pk_fma_f32 v[22:23], v[10:11], v[8:9], v[22:23]
	v_cvt_pk_bf16_f32 v8, v12, v13
	v_cvt_pk_bf16_f32 v9, v14, v15
	v_cvt_pk_bf16_f32 v10, v20, v21
	v_cvt_pk_bf16_f32 v11, v22, v23
	v_lshl_add_u64 v[12:13], s[8:9], 0, v[28:29]
	global_store_dwordx4 v[12:13], v[8:11], off sc1
	v_lshl_add_u64 v[12:13], v[16:17], 0, v[120:121]
	v_lshlrev_b64 v[16:17], 1, v[12:13]
	v_lshl_add_u64 v[8:9], v[18:19], 0, v[122:123]
	v_lshl_add_u64 v[12:13], s[88:89], 0, v[16:17]
	global_load_dwordx4 v[8:11], v[8:9], off
	s_nop 0
	global_load_dwordx4 v[12:15], v[12:13], off
	s_waitcnt vmcnt(1)
	v_lshlrev_b32_e32 v18, 16, v8
	v_and_b32_e32 v19, 0xffff0000, v8
	s_waitcnt vmcnt(0)
	v_lshlrev_b32_e32 v20, 16, v12
	v_and_b32_e32 v21, 0xffff0000, v12
	v_lshlrev_b32_e32 v8, 16, v9
	v_and_b32_e32 v9, 0xffff0000, v9
	v_lshlrev_b32_e32 v12, 16, v13
	v_and_b32_e32 v13, 0xffff0000, v13
	v_pk_fma_f32 v[6:7], v[6:7], v[8:9], v[12:13]
	v_lshlrev_b32_e32 v8, 16, v10
	v_and_b32_e32 v9, 0xffff0000, v10
	v_lshlrev_b32_e32 v12, 16, v14
	v_and_b32_e32 v13, 0xffff0000, v14
	v_pk_fma_f32 v[8:9], v[0:1], v[8:9], v[12:13]
	v_lshlrev_b32_e32 v0, 16, v11
	v_and_b32_e32 v1, 0xffff0000, v11
	v_lshlrev_b32_e32 v10, 16, v15
	v_and_b32_e32 v11, 0xffff0000, v15
	v_pk_fma_f32 v[4:5], v[4:5], v[18:19], v[20:21]
	v_pk_fma_f32 v[10:11], v[2:3], v[0:1], v[10:11]
	v_cvt_pk_bf16_f32 v0, v4, v5
	v_cvt_pk_bf16_f32 v1, v6, v7
	v_cvt_pk_bf16_f32 v2, v8, v9
	v_cvt_pk_bf16_f32 v3, v10, v11
	v_lshl_add_u64 v[4:5], s[8:9], 0, v[16:17]
	global_store_dwordx4 v[4:5], v[0:3], off sc1
	s_cbranch_vccnz .LBB0_203
	s_andn2_b64 vcc, exec, s[10:11]
	s_cbranch_vccnz .LBB0_202
	s_barrier
	s_branch .LBB0_202

; __device__ __forceinline__ unsigned cvt_pk_bf16(float lo, float hi) { const f32x2_t v = {lo, hi}; const bf16x2_t b = __builtin_convertvector(v, bf16x2_t); return __builtin_bit_cast(unsigned, b); }
;     __device__ __forceinline__ void operator()(const Acc& acc, const Unit& u, int wr, int wc, int fr, int fq) const {
;     ...
;                 const int r = row0 + ai * HALF + m * 16;
; #pragma unroll
;                 for (int bj = 0; bj < 2; ++bj) {
;                     const int c = col0 + bj * HALF; const size_t off = (size_t)r * D + c;
;                     const u32x4 gw = *(const u32x4*)(gates + (size_t)r * 6144 + br * D + c);
;                     f32x4 v0, v1;
;                     v0[0] = acc[ai][bj][m][0][0] * bflo(gw.x); v0[1] = acc[ai][bj][m][0][1] * bfhi(gw.x); v0[2] = acc[ai][bj][m][0][2] * bflo(gw.y); v0[3] = acc[ai][bj][m][0][3] * bfhi(gw.y);
;                     v1[0] = acc[ai][bj][m][1][0] * bflo(gw.z); v1[1] = acc[ai][bj][m][1][1] * bfhi(gw.z); v1[2] = acc[ai][bj][m][1][2] * bflo(gw.w); v1[3] = acc[ai][bj][m][1][3] * bfhi(gw.w);
;                     if (br > 0) { const u32x4 ma = *(const u32x4*)(prev + off);
;                         v0[0] += bflo(ma.x); v0[1] += bfhi(ma.x); v0[2] += bflo(ma.y); v0[3] += bfhi(ma.y); v1[0] += bflo(ma.z); v1[1] += bfhi(ma.z); v1[2] += bflo(ma.w); v1[3] += bfhi(ma.w); }
;                     u32x4 w; w.x = cvt_pk_bf16(v0[0], v0[1]); w.y = cvt_pk_bf16(v0[2], v0[3]); w.z = cvt_pk_bf16(v1[0], v1[1]); w.w = cvt_pk_bf16(v1[2], v1[3]);
;                     *(u32x4*)(dst + off) = w;
.LBB0_240:
	v_lshl_or_b32 v138, s83, 8, v146
	v_lshl_add_u32 v140, s82, 8, v144
	v_ashrrev_i32_e32 v139, 31, v138
	v_mov_b64_e32 v[142:143], s[10:11]
	v_mad_i64_i32 v[148:149], s[2:3], v140, s26, v[142:143]
	v_lshlrev_b64 v[138:139], 1, v[138:139]
	v_lshl_add_u64 v[152:153], v[148:149], 0, v[138:139]
	global_load_dwordx4 v[148:151], v[152:153], off
	v_ashrrev_i32_e32 v141, 31, v140
	s_mov_b64 s[24:25], -1
	s_andn2_b64 vcc, exec, s[4:5]
	s_waitcnt vmcnt(0)
	v_lshlrev_b32_e32 v154, 16, v148
	v_and_b32_e32 v155, 0xffff0000, v148
	v_lshlrev_b32_e32 v148, 16, v149
	v_and_b32_e32 v149, 0xffff0000, v149
	v_pk_mul_f32 v[126:127], v[126:127], v[148:149]
	v_lshlrev_b32_e32 v148, 16, v150
	v_and_b32_e32 v149, 0xffff0000, v150
	v_pk_mul_f32 v[124:125], v[124:125], v[154:155]
	v_pk_mul_f32 v[148:149], v[120:121], v[148:149]
	v_lshlrev_b32_e32 v120, 16, v151
	v_and_b32_e32 v121, 0xffff0000, v151
	v_pk_mul_f32 v[150:151], v[122:123], v[120:121]
	v_cvt_pk_bf16_f32 v120, v124, v125
	v_lshlrev_b64 v[124:125], 12, v[140:141]
	v_lshl_add_u64 v[124:125], s[12:13], 0, v[124:125]
	v_cvt_pk_bf16_f32 v121, v126, v127
	v_cvt_pk_bf16_f32 v122, v148, v149
	v_cvt_pk_bf16_f32 v123, v150, v151
	v_lshl_add_u64 v[124:125], v[124:125], 0, v[138:139]
	global_store_dwordx4 v[124:125], v[120:123], off sc1
	global_load_dwordx4 v[120:123], v[152:153], off offset:256
	s_waitcnt vmcnt(0)
	v_lshlrev_b32_e32 v126, 16, v120
	v_and_b32_e32 v127, 0xffff0000, v120
	v_lshlrev_b32_e32 v120, 16, v121
	v_and_b32_e32 v121, 0xffff0000, v121
	v_pk_mul_f32 v[118:119], v[118:119], v[120:121]
	v_lshlrev_b32_e32 v120, 16, v122
	v_and_b32_e32 v121, 0xffff0000, v122
	v_pk_mul_f32 v[120:121], v[112:113], v[120:121]
	v_lshlrev_b32_e32 v112, 16, v123
	v_and_b32_e32 v113, 0xffff0000, v123
	v_pk_mul_f32 v[116:117], v[116:117], v[126:127]
	v_pk_mul_f32 v[122:123], v[114:115], v[112:113]
	v_cvt_pk_bf16_f32 v112, v116, v117
	v_cvt_pk_bf16_f32 v113, v118, v119
	v_cvt_pk_bf16_f32 v114, v120, v121
	v_cvt_pk_bf16_f32 v115, v122, v123
	v_or_b32_e32 v118, 16, v140
	global_store_dwordx4 v[124:125], v[112:115], off offset:256 sc1
	v_ashrrev_i32_e32 v119, 31, v118
	s_nop 0
	v_mad_i64_i32 v[112:113], s[2:3], v118, s26, v[142:143]
	v_lshl_add_u64 v[112:113], v[112:113], 0, v[138:139]
	global_load_dwordx4 v[114:117], v[112:113], off
	s_waitcnt vmcnt(0)
	v_lshlrev_b32_e32 v120, 16, v114
	v_and_b32_e32 v121, 0xffff0000, v114
	v_lshlrev_b32_e32 v114, 16, v115
	v_and_b32_e32 v115, 0xffff0000, v115
	v_pk_mul_f32 v[110:111], v[110:111], v[114:115]
	v_lshlrev_b32_e32 v114, 16, v116
	v_and_b32_e32 v115, 0xffff0000, v116
	v_pk_mul_f32 v[108:109], v[108:109], v[120:121]
	v_pk_mul_f32 v[114:115], v[104:105], v[114:115]
	v_lshlrev_b32_e32 v104, 16, v117
	v_and_b32_e32 v105, 0xffff0000, v117
	v_pk_mul_f32 v[116:117], v[106:107], v[104:105]
	v_cvt_pk_bf16_f32 v104, v108, v109
	v_lshlrev_b64 v[108:109], 12, v[118:119]
	v_lshl_add_u64 v[108:109], s[12:13], 0, v[108:109]
	v_cvt_pk_bf16_f32 v105, v110, v111
	v_cvt_pk_bf16_f32 v106, v114, v115
	v_cvt_pk_bf16_f32 v107, v116, v117
	v_lshl_add_u64 v[108:109], v[108:109], 0, v[138:139]
	global_store_dwordx4 v[108:109], v[104:107], off sc1
	global_load_dwordx4 v[104:107], v[112:113], off offset:256
	s_waitcnt vmcnt(0)
	v_lshlrev_b32_e32 v110, 16, v104
	v_and_b32_e32 v111, 0xffff0000, v104
	v_lshlrev_b32_e32 v104, 16, v105
	v_and_b32_e32 v105, 0xffff0000, v105
	v_pk_mul_f32 v[102:103], v[102:103], v[104:105]
	v_lshlrev_b32_e32 v104, 16, v106
	v_and_b32_e32 v105, 0xffff0000, v106
	v_pk_mul_f32 v[104:105], v[96:97], v[104:105]
	v_lshlrev_b32_e32 v96, 16, v107
	v_and_b32_e32 v97, 0xffff0000, v107
	v_pk_mul_f32 v[100:101], v[100:101], v[110:111]
	v_pk_mul_f32 v[106:107], v[98:99], v[96:97]
	v_cvt_pk_bf16_f32 v96, v100, v101
	v_cvt_pk_bf16_f32 v97, v102, v103
	v_cvt_pk_bf16_f32 v98, v104, v105
	v_cvt_pk_bf16_f32 v99, v106, v107
	v_or_b32_e32 v102, 32, v140
	global_store_dwordx4 v[108:109], v[96:99], off offset:256 sc1
	v_ashrrev_i32_e32 v103, 31, v102
	s_nop 0
	v_mad_i64_i32 v[96:97], s[2:3], v102, s26, v[142:143]
	v_lshl_add_u64 v[96:97], v[96:97], 0, v[138:139]
	global_load_dwordx4 v[98:101], v[96:97], off
	s_waitcnt vmcnt(0)
	v_lshlrev_b32_e32 v104, 16, v98
	v_and_b32_e32 v105, 0xffff0000, v98
	v_lshlrev_b32_e32 v98, 16, v99
	v_and_b32_e32 v99, 0xffff0000, v99
	v_pk_mul_f32 v[94:95], v[94:95], v[98:99]
	v_lshlrev_b32_e32 v98, 16, v100
	v_and_b32_e32 v99, 0xffff0000, v100
	v_pk_mul_f32 v[92:93], v[92:93], v[104:105]
	v_pk_mul_f32 v[98:99], v[88:89], v[98:99]
	v_lshlrev_b32_e32 v88, 16, v101
	v_and_b32_e32 v89, 0xffff0000, v101
	v_pk_mul_f32 v[100:101], v[90:91], v[88:89]
	v_cvt_pk_bf16_f32 v88, v92, v93
	v_lshlrev_b64 v[92:93], 12, v[102:103]
	v_lshl_add_u64 v[92:93], s[12:13], 0, v[92:93]
	v_cvt_pk_bf16_f32 v89, v94, v95
	v_cvt_pk_bf16_f32 v90, v98, v99
	v_cvt_pk_bf16_f32 v91, v100, v101
	v_lshl_add_u64 v[92:93], v[92:93], 0, v[138:139]
	global_store_dwordx4 v[92:93], v[88:91], off sc1
	global_load_dwordx4 v[88:91], v[96:97], off offset:256
	s_waitcnt vmcnt(0)
	v_lshlrev_b32_e32 v94, 16, v88
	v_and_b32_e32 v95, 0xffff0000, v88
	v_lshlrev_b32_e32 v88, 16, v89
	v_and_b32_e32 v89, 0xffff0000, v89
	v_pk_mul_f32 v[86:87], v[86:87], v[88:89]
	v_lshlrev_b32_e32 v88, 16, v90
	v_and_b32_e32 v89, 0xffff0000, v90
	v_pk_mul_f32 v[88:89], v[80:81], v[88:89]
	v_lshlrev_b32_e32 v80, 16, v91
	v_and_b32_e32 v81, 0xffff0000, v91
	v_pk_mul_f32 v[84:85], v[84:85], v[94:95]
	v_pk_mul_f32 v[90:91], v[82:83], v[80:81]
	v_cvt_pk_bf16_f32 v80, v84, v85
	v_cvt_pk_bf16_f32 v81, v86, v87
	v_cvt_pk_bf16_f32 v82, v88, v89
	v_cvt_pk_bf16_f32 v83, v90, v91
	v_or_b32_e32 v86, 48, v140
	global_store_dwordx4 v[92:93], v[80:83], off offset:256 sc1
	v_ashrrev_i32_e32 v87, 31, v86
	s_nop 0
	v_mad_i64_i32 v[80:81], s[2:3], v86, s26, v[142:143]
	v_lshl_add_u64 v[80:81], v[80:81], 0, v[138:139]
	global_load_dwordx4 v[82:85], v[80:81], off
	s_waitcnt vmcnt(0)
; __device__ __forceinline__ unsigned cvt_pk_bf16(float lo, float hi) { const f32x2_t v = {lo, hi}; const bf16x2_t b = __builtin_convertvector(v, bf16x2_t); return __builtin_bit_cast(unsigned, b); }
;     __device__ __forceinline__ void operator()(const Acc& acc, const Unit& u, int wr, int wc, int fr, int fq) const {
;     ...
;                 const int r = row0 + ai * HALF + m * 16;
; #pragma unroll
;                 for (int bj = 0; bj < 2; ++bj) {
;                     const int c = col0 + bj * HALF; const size_t off = (size_t)r * D + c;
;                     const u32x4 gw = *(const u32x4*)(gates + (size_t)r * 6144 + br * D + c);
;                     f32x4 v0, v1;
;                     v0[0] = acc[ai][bj][m][0][0] * bflo(gw.x); v0[1] = acc[ai][bj][m][0][1] * bfhi(gw.x); v0[2] = acc[ai][bj][m][0][2] * bflo(gw.y); v0[3] = acc[ai][bj][m][0][3] * bfhi(gw.y);
;                     v1[0] = acc[ai][bj][m][1][0] * bflo(gw.z); v1[1] = acc[ai][bj][m][1][1] * bfhi(gw.z); v1[2] = acc[ai][bj][m][1][2] * bflo(gw.w); v1[3] = acc[ai][bj][m][1][3] * bfhi(gw.w);
;                     if (br > 0) { const u32x4 ma = *(const u32x4*)(prev + off);
;                         v0[0] += bflo(ma.x); v0[1] += bfhi(ma.x); v0[2] += bflo(ma.y); v0[3] += bfhi(ma.y); v1[0] += bflo(ma.z); v1[1] += bfhi(ma.z); v1[2] += bflo(ma.w); v1[3] += bfhi(ma.w); }
;                     u32x4 w; w.x = cvt_pk_bf16(v0[0], v0[1]); w.y = cvt_pk_bf16(v0[2], v0[3]); w.z = cvt_pk_bf16(v1[0], v1[1]); w.w = cvt_pk_bf16(v1[2], v1[3]);
;                     *(u32x4*)(dst + off) = w;
	v_lshlrev_b32_e32 v88, 16, v82
	v_and_b32_e32 v89, 0xffff0000, v82
	v_lshlrev_b32_e32 v82, 16, v83
	v_and_b32_e32 v83, 0xffff0000, v83
	v_pk_mul_f32 v[78:79], v[78:79], v[82:83]
	v_lshlrev_b32_e32 v82, 16, v84
	v_and_b32_e32 v83, 0xffff0000, v84
	v_pk_mul_f32 v[76:77], v[76:77], v[88:89]
	v_pk_mul_f32 v[82:83], v[72:73], v[82:83]
	v_lshlrev_b32_e32 v72, 16, v85
	v_and_b32_e32 v73, 0xffff0000, v85
	v_pk_mul_f32 v[84:85], v[74:75], v[72:73]
	v_cvt_pk_bf16_f32 v72, v76, v77
	v_lshlrev_b64 v[76:77], 12, v[86:87]
	v_lshl_add_u64 v[76:77], s[12:13], 0, v[76:77]
	v_cvt_pk_bf16_f32 v73, v78, v79
	v_cvt_pk_bf16_f32 v74, v82, v83
	v_cvt_pk_bf16_f32 v75, v84, v85
	v_lshl_add_u64 v[76:77], v[76:77], 0, v[138:139]
	global_store_dwordx4 v[76:77], v[72:75], off sc1
	global_load_dwordx4 v[72:75], v[80:81], off offset:256
	s_waitcnt vmcnt(0)
	v_lshlrev_b32_e32 v78, 16, v72
	v_and_b32_e32 v79, 0xffff0000, v72
	v_lshlrev_b32_e32 v72, 16, v73
	v_and_b32_e32 v73, 0xffff0000, v73
	v_pk_mul_f32 v[70:71], v[70:71], v[72:73]
	v_lshlrev_b32_e32 v72, 16, v74
	v_and_b32_e32 v73, 0xffff0000, v74
	v_pk_mul_f32 v[72:73], v[64:65], v[72:73]
	v_lshlrev_b32_e32 v64, 16, v75
	v_and_b32_e32 v65, 0xffff0000, v75
	v_pk_mul_f32 v[68:69], v[68:69], v[78:79]
	v_pk_mul_f32 v[74:75], v[66:67], v[64:65]
	v_cvt_pk_bf16_f32 v64, v68, v69
	v_cvt_pk_bf16_f32 v65, v70, v71
	v_cvt_pk_bf16_f32 v66, v72, v73
	v_cvt_pk_bf16_f32 v67, v74, v75
	v_add_u32_e32 v70, 0x80, v140
	global_store_dwordx4 v[76:77], v[64:67], off offset:256 sc1
	v_ashrrev_i32_e32 v71, 31, v70
	s_nop 0
	v_mad_i64_i32 v[64:65], s[2:3], v70, s26, v[142:143]
	v_lshl_add_u64 v[64:65], v[64:65], 0, v[138:139]
	global_load_dwordx4 v[66:69], v[64:65], off
	s_waitcnt vmcnt(0)
	v_lshlrev_b32_e32 v72, 16, v66
	v_and_b32_e32 v73, 0xffff0000, v66
	v_lshlrev_b32_e32 v66, 16, v67
	v_and_b32_e32 v67, 0xffff0000, v67
	v_pk_mul_f32 v[62:63], v[62:63], v[66:67]
	v_lshlrev_b32_e32 v66, 16, v68
	v_and_b32_e32 v67, 0xffff0000, v68
	v_pk_mul_f32 v[60:61], v[60:61], v[72:73]
	v_pk_mul_f32 v[66:67], v[56:57], v[66:67]
	v_lshlrev_b32_e32 v56, 16, v69
	v_and_b32_e32 v57, 0xffff0000, v69
	v_pk_mul_f32 v[68:69], v[58:59], v[56:57]
	v_cvt_pk_bf16_f32 v56, v60, v61
	v_lshlrev_b64 v[60:61], 12, v[70:71]
	v_lshl_add_u64 v[60:61], s[12:13], 0, v[60:61]
	v_cvt_pk_bf16_f32 v57, v62, v63
	v_cvt_pk_bf16_f32 v58, v66, v67
	v_cvt_pk_bf16_f32 v59, v68, v69
	v_lshl_add_u64 v[60:61], v[60:61], 0, v[138:139]
	global_store_dwordx4 v[60:61], v[56:59], off sc1
	global_load_dwordx4 v[56:59], v[64:65], off offset:256
	s_waitcnt vmcnt(0)
	v_lshlrev_b32_e32 v62, 16, v56
	v_and_b32_e32 v63, 0xffff0000, v56
	v_lshlrev_b32_e32 v56, 16, v57
	v_and_b32_e32 v57, 0xffff0000, v57
	v_pk_mul_f32 v[54:55], v[54:55], v[56:57]
	v_lshlrev_b32_e32 v56, 16, v58
	v_and_b32_e32 v57, 0xffff0000, v58
	v_pk_mul_f32 v[56:57], v[48:49], v[56:57]
	v_lshlrev_b32_e32 v48, 16, v59
	v_and_b32_e32 v49, 0xffff0000, v59
	v_pk_mul_f32 v[52:53], v[52:53], v[62:63]
	v_pk_mul_f32 v[58:59], v[50:51], v[48:49]
	v_cvt_pk_bf16_f32 v48, v52, v53
	v_cvt_pk_bf16_f32 v49, v54, v55
	v_cvt_pk_bf16_f32 v50, v56, v57
	v_cvt_pk_bf16_f32 v51, v58, v59
	v_add_u32_e32 v54, 0x90, v140
	global_store_dwordx4 v[60:61], v[48:51], off offset:256 sc1
	v_ashrrev_i32_e32 v55, 31, v54
	s_nop 0
	v_mad_i64_i32 v[48:49], s[2:3], v54, s26, v[142:143]
	v_lshl_add_u64 v[48:49], v[48:49], 0, v[138:139]
	global_load_dwordx4 v[50:53], v[48:49], off
	s_waitcnt vmcnt(0)
	v_lshlrev_b32_e32 v56, 16, v50
	v_and_b32_e32 v57, 0xffff0000, v50
	v_lshlrev_b32_e32 v50, 16, v51
	v_and_b32_e32 v51, 0xffff0000, v51
	v_pk_mul_f32 v[46:47], v[46:47], v[50:51]
	v_lshlrev_b32_e32 v50, 16, v52
	v_and_b32_e32 v51, 0xffff0000, v52
	v_pk_mul_f32 v[44:45], v[44:45], v[56:57]
	v_pk_mul_f32 v[50:51], v[40:41], v[50:51]
	v_lshlrev_b32_e32 v40, 16, v53
	v_and_b32_e32 v41, 0xffff0000, v53
	v_pk_mul_f32 v[52:53], v[42:43], v[40:41]
	v_cvt_pk_bf16_f32 v40, v44, v45
	v_lshlrev_b64 v[44:45], 12, v[54:55]
	v_lshl_add_u64 v[44:45], s[12:13], 0, v[44:45]
	v_cvt_pk_bf16_f32 v41, v46, v47
	v_cvt_pk_bf16_f32 v42, v50, v51
	v_cvt_pk_bf16_f32 v43, v52, v53
	v_lshl_add_u64 v[44:45], v[44:45], 0, v[138:139]
	global_store_dwordx4 v[44:45], v[40:43], off sc1
	global_load_dwordx4 v[40:43], v[48:49], off offset:256
	s_waitcnt vmcnt(0)
; __device__ __forceinline__ unsigned cvt_pk_bf16(float lo, float hi) { const f32x2_t v = {lo, hi}; const bf16x2_t b = __builtin_convertvector(v, bf16x2_t); return __builtin_bit_cast(unsigned, b); }
;     __device__ __forceinline__ void operator()(const Acc& acc, const Unit& u, int wr, int wc, int fr, int fq) const {
;     ...
;                 const int r = row0 + ai * HALF + m * 16;
; #pragma unroll
;                 for (int bj = 0; bj < 2; ++bj) {
;                     const int c = col0 + bj * HALF; const size_t off = (size_t)r * D + c;
;                     const u32x4 gw = *(const u32x4*)(gates + (size_t)r * 6144 + br * D + c);
;                     f32x4 v0, v1;
;                     v0[0] = acc[ai][bj][m][0][0] * bflo(gw.x); v0[1] = acc[ai][bj][m][0][1] * bfhi(gw.x); v0[2] = acc[ai][bj][m][0][2] * bflo(gw.y); v0[3] = acc[ai][bj][m][0][3] * bfhi(gw.y);
;                     v1[0] = acc[ai][bj][m][1][0] * bflo(gw.z); v1[1] = acc[ai][bj][m][1][1] * bfhi(gw.z); v1[2] = acc[ai][bj][m][1][2] * bflo(gw.w); v1[3] = acc[ai][bj][m][1][3] * bfhi(gw.w);
;                     if (br > 0) { const u32x4 ma = *(const u32x4*)(prev + off);
;                         v0[0] += bflo(ma.x); v0[1] += bfhi(ma.x); v0[2] += bflo(ma.y); v0[3] += bfhi(ma.y); v1[0] += bflo(ma.z); v1[1] += bfhi(ma.z); v1[2] += bflo(ma.w); v1[3] += bfhi(ma.w); }
;                     u32x4 w; w.x = cvt_pk_bf16(v0[0], v0[1]); w.y = cvt_pk_bf16(v0[2], v0[3]); w.z = cvt_pk_bf16(v1[0], v1[1]); w.w = cvt_pk_bf16(v1[2], v1[3]);
;                     *(u32x4*)(dst + off) = w;
	v_lshlrev_b32_e32 v46, 16, v40
	v_and_b32_e32 v47, 0xffff0000, v40
	v_lshlrev_b32_e32 v40, 16, v41
	v_and_b32_e32 v41, 0xffff0000, v41
	v_pk_mul_f32 v[38:39], v[38:39], v[40:41]
	v_lshlrev_b32_e32 v40, 16, v42
	v_and_b32_e32 v41, 0xffff0000, v42
	v_pk_mul_f32 v[40:41], v[32:33], v[40:41]
	v_lshlrev_b32_e32 v32, 16, v43
	v_and_b32_e32 v33, 0xffff0000, v43
	v_pk_mul_f32 v[36:37], v[36:37], v[46:47]
	v_pk_mul_f32 v[42:43], v[34:35], v[32:33]
	v_cvt_pk_bf16_f32 v32, v36, v37
	v_cvt_pk_bf16_f32 v33, v38, v39
	v_cvt_pk_bf16_f32 v34, v40, v41
	v_cvt_pk_bf16_f32 v35, v42, v43
	v_add_u32_e32 v38, 0xa0, v140
	global_store_dwordx4 v[44:45], v[32:35], off offset:256 sc1
	v_ashrrev_i32_e32 v39, 31, v38
	s_nop 0
	v_mad_i64_i32 v[32:33], s[2:3], v38, s26, v[142:143]
	v_lshl_add_u64 v[32:33], v[32:33], 0, v[138:139]
	global_load_dwordx4 v[34:37], v[32:33], off
	s_waitcnt vmcnt(0)
	v_lshlrev_b32_e32 v40, 16, v34
	v_and_b32_e32 v41, 0xffff0000, v34
	v_lshlrev_b32_e32 v34, 16, v35
	v_and_b32_e32 v35, 0xffff0000, v35
	v_pk_mul_f32 v[30:31], v[30:31], v[34:35]
	v_lshlrev_b32_e32 v34, 16, v36
	v_and_b32_e32 v35, 0xffff0000, v36
	v_pk_mul_f32 v[28:29], v[28:29], v[40:41]
	v_pk_mul_f32 v[34:35], v[24:25], v[34:35]
	v_lshlrev_b32_e32 v24, 16, v37
	v_and_b32_e32 v25, 0xffff0000, v37
	v_pk_mul_f32 v[36:37], v[26:27], v[24:25]
	v_cvt_pk_bf16_f32 v24, v28, v29
	v_lshlrev_b64 v[28:29], 12, v[38:39]
	v_lshl_add_u64 v[28:29], s[12:13], 0, v[28:29]
	v_cvt_pk_bf16_f32 v25, v30, v31
	v_cvt_pk_bf16_f32 v26, v34, v35
	v_cvt_pk_bf16_f32 v27, v36, v37
	v_lshl_add_u64 v[28:29], v[28:29], 0, v[138:139]
	global_store_dwordx4 v[28:29], v[24:27], off sc1
	global_load_dwordx4 v[24:27], v[32:33], off offset:256
	s_waitcnt vmcnt(0)
	v_lshlrev_b32_e32 v30, 16, v24
	v_and_b32_e32 v31, 0xffff0000, v24
	v_lshlrev_b32_e32 v24, 16, v25
	v_and_b32_e32 v25, 0xffff0000, v25
	v_pk_mul_f32 v[22:23], v[22:23], v[24:25]
	v_lshlrev_b32_e32 v24, 16, v26
	v_and_b32_e32 v25, 0xffff0000, v26
	v_pk_mul_f32 v[24:25], v[16:17], v[24:25]
	v_lshlrev_b32_e32 v16, 16, v27
	v_and_b32_e32 v17, 0xffff0000, v27
	v_pk_mul_f32 v[20:21], v[20:21], v[30:31]
	v_pk_mul_f32 v[26:27], v[18:19], v[16:17]
	v_cvt_pk_bf16_f32 v16, v20, v21
	v_cvt_pk_bf16_f32 v17, v22, v23
	v_cvt_pk_bf16_f32 v18, v24, v25
	v_cvt_pk_bf16_f32 v19, v26, v27
	v_add_u32_e32 v22, 0xb0, v140
	global_store_dwordx4 v[28:29], v[16:19], off offset:256 sc1
	v_ashrrev_i32_e32 v23, 31, v22
	s_nop 0
	v_mad_i64_i32 v[16:17], s[2:3], v22, s26, v[142:143]
	v_lshl_add_u64 v[16:17], v[16:17], 0, v[138:139]
	global_load_dwordx4 v[18:21], v[16:17], off
	s_waitcnt vmcnt(0)
	v_lshlrev_b32_e32 v24, 16, v18
	v_and_b32_e32 v25, 0xffff0000, v18
	v_lshlrev_b32_e32 v18, 16, v19
	v_and_b32_e32 v19, 0xffff0000, v19
	v_pk_mul_f32 v[14:15], v[14:15], v[18:19]
	v_lshlrev_b32_e32 v18, 16, v20
	v_and_b32_e32 v19, 0xffff0000, v20
	v_pk_mul_f32 v[12:13], v[12:13], v[24:25]
	v_pk_mul_f32 v[18:19], v[8:9], v[18:19]
	v_lshlrev_b32_e32 v8, 16, v21
	v_and_b32_e32 v9, 0xffff0000, v21
	v_pk_mul_f32 v[20:21], v[10:11], v[8:9]
	v_cvt_pk_bf16_f32 v8, v12, v13
	v_lshlrev_b64 v[12:13], 12, v[22:23]
	v_lshl_add_u64 v[12:13], s[12:13], 0, v[12:13]
	v_cvt_pk_bf16_f32 v9, v14, v15
	v_cvt_pk_bf16_f32 v10, v18, v19
	v_cvt_pk_bf16_f32 v11, v20, v21
	v_lshl_add_u64 v[12:13], v[12:13], 0, v[138:139]
	global_store_dwordx4 v[12:13], v[8:11], off sc1
	global_load_dwordx4 v[8:11], v[16:17], off offset:256
	s_waitcnt vmcnt(0)
	v_lshlrev_b32_e32 v14, 16, v8
	v_and_b32_e32 v15, 0xffff0000, v8
	v_lshlrev_b32_e32 v8, 16, v9
	v_and_b32_e32 v9, 0xffff0000, v9
	v_pk_mul_f32 v[6:7], v[6:7], v[8:9]
	v_lshlrev_b32_e32 v8, 16, v10
	v_and_b32_e32 v9, 0xffff0000, v10
	v_pk_mul_f32 v[8:9], v[0:1], v[8:9]
	v_lshlrev_b32_e32 v0, 16, v11
	v_and_b32_e32 v1, 0xffff0000, v11
	v_pk_mul_f32 v[4:5], v[4:5], v[14:15]
	v_pk_mul_f32 v[10:11], v[2:3], v[0:1]
	v_cvt_pk_bf16_f32 v0, v4, v5
	v_cvt_pk_bf16_f32 v1, v6, v7
	v_cvt_pk_bf16_f32 v2, v8, v9
	v_cvt_pk_bf16_f32 v3, v10, v11
	global_store_dwordx4 v[12:13], v[0:3], off offset:256 sc1
	s_cbranch_vccnz .LBB0_229
	s_andn2_b64 vcc, exec, s[6:7]
	s_cbranch_vccnz .LBB0_228
	s_barrier
	s_branch .LBB0_228

; __device__ __forceinline__ unsigned cvt_pk_bf16(float lo, float hi) { const f32x2_t v = {lo, hi}; const bf16x2_t b = __builtin_convertvector(v, bf16x2_t); return __builtin_bit_cast(unsigned, b); }
; __device__ __forceinline__ f32x2 sigmoid2(f32x2 x, float na) { return rcp_2(exp2_2(x * na) + 1.0f); }
; __device__ __forceinline__ f32x2 gelu2(f32x2 x, float rs) { const f32x2 v = x * rs; const f32x2 w = v * (v * v * 0.044715f + 1.0f); return v * rcp_2(exp2_2(w * -2.3022082f) + 1.0f); }
; __device__ __forceinline__ float rstd_of(u64 ssq) { return frsq((float)ssq * (1.0f / (2048.0f * 16777216.0f)) + EPS); }
;     __device__ __forceinline__ void operator()(const Acc& acc, const Unit& u, int wr, int wc, int fr, int fq) const {
;     ...
;             for (int m = 0; m < 4; ++m) {
;                 asm volatile("" ::: "memory");
;                 const int r = row0 + ai * HALF + m * 16; const float rs = rstd_of(ssq[r]);
; #pragma unroll
;                 for (int bj = 0; bj < 2; ++bj) {
;                     const f32x4 x0 = acc[ai][bj][m][0], x1 = acc[ai][bj][m][1];
;                     f32x2 a, b, c, d;
;                     if (act == 1) { a = gelu2((f32x2){x0[0], x0[1]}, rs); b = gelu2((f32x2){x0[2], x0[3]}, rs); c = gelu2((f32x2){x1[0], x1[1]}, rs); d = gelu2((f32x2){x1[2], x1[3]}, rs); }
;                     else if (act == 2) { const float na = -rs * LOG2E; a = sigmoid2((f32x2){x0[0], x0[1]}, na); b = sigmoid2((f32x2){x0[2], x0[3]}, na); c = sigmoid2((f32x2){x1[0], x1[1]}, na); d = sigmoid2((f32x2){x1[2], x1[3]}, na); }
;                     else { a = (f32x2){x0[0], x0[1]} * rs; b = (f32x2){x0[2], x0[3]} * rs; c = (f32x2){x1[0], x1[1]} * rs; d = (f32x2){x1[2], x1[3]} * rs; }
;                     u32x4 w; w.x = cvt_pk_bf16(a.x, a.y); w.y = cvt_pk_bf16(b.x, b.y); w.z = cvt_pk_bf16(c.x, c.y); w.w = cvt_pk_bf16(d.x, d.y);
;                     *(u32x4*)(base + (size_t)r * ldc + col0 + bj * HALF) = w;
;                 }
.LBB0_400:
	v_add_u32_e32 v120, s42, v156
	v_ashrrev_i32_e32 v121, 31, v120
	v_mul_lo_u32 v124, s63, v138
	v_mul_lo_u32 v125, s62, v139
	v_mad_u64_u32 v[122:123], s[2:3], s62, v138, 0
	v_lshl_add_u64 v[120:121], v[120:121], 1, s[82:83]
	v_add3_u32 v123, v123, v125, v124
	v_lshl_add_u64 v[122:123], v[122:123], 1, v[120:121]
	v_cvt_pk_bf16_f32 v124, v146, v147
	v_cvt_pk_bf16_f32 v125, v148, v149
	v_cvt_pk_bf16_f32 v126, v150, v151
	v_cvt_pk_bf16_f32 v127, v152, v153
	global_store_dwordx4 v[122:123], v[124:127], off sc1
	s_mov_b64 s[2:3], -1
	s_andn2_b64 vcc, exec, s[6:7]
	v_cndmask_b32_e64 v124, 0, 1, s[6:7]
	v_cmp_ne_u32_e64 s[8:9], 1, v124
	v_cndmask_b32_e64 v124, 0, 1, s[24:25]
	v_cmp_ne_u32_e64 s[6:7], 1, v124
	s_cbranch_vccnz .LBB0_406
	s_and_b64 vcc, exec, s[6:7]
	s_cbranch_vccnz .LBB0_403
	v_pk_mul_f32 v[124:125], v[116:117], v[142:143]
	v_pk_mul_f32 v[126:127], v[118:119], v[142:143]
	v_pk_mul_f32 v[146:147], v[112:113], v[142:143]
	v_pk_mul_f32 v[148:149], v[114:115], v[142:143]
	s_mov_b64 s[2:3], 0

; __device__ __forceinline__ unsigned cvt_pk_bf16(float lo, float hi) { const f32x2_t v = {lo, hi}; const bf16x2_t b = __builtin_convertvector(v, bf16x2_t); return __builtin_bit_cast(unsigned, b); }
; __device__ __forceinline__ f32x2 sigmoid2(f32x2 x, float na) { return rcp_2(exp2_2(x * na) + 1.0f); }
; __device__ __forceinline__ f32x2 gelu2(f32x2 x, float rs) { const f32x2 v = x * rs; const f32x2 w = v * (v * v * 0.044715f + 1.0f); return v * rcp_2(exp2_2(w * -2.3022082f) + 1.0f); }
; __device__ __forceinline__ float rstd_of(u64 ssq) { return frsq((float)ssq * (1.0f / (2048.0f * 16777216.0f)) + EPS); }
;     __device__ __forceinline__ void operator()(const Acc& acc, const Unit& u, int wr, int wc, int fr, int fq) const {
;     ...
;             for (int m = 0; m < 4; ++m) {
;                 asm volatile("" ::: "memory");
;                 const int r = row0 + ai * HALF + m * 16; const float rs = rstd_of(ssq[r]);
; #pragma unroll
;                 for (int bj = 0; bj < 2; ++bj) {
;                     const f32x4 x0 = acc[ai][bj][m][0], x1 = acc[ai][bj][m][1];
;                     f32x2 a, b, c, d;
;                     if (act == 1) { a = gelu2((f32x2){x0[0], x0[1]}, rs); b = gelu2((f32x2){x0[2], x0[3]}, rs); c = gelu2((f32x2){x1[0], x1[1]}, rs); d = gelu2((f32x2){x1[2], x1[3]}, rs); }
;                     else if (act == 2) { const float na = -rs * LOG2E; a = sigmoid2((f32x2){x0[0], x0[1]}, na); b = sigmoid2((f32x2){x0[2], x0[3]}, na); c = sigmoid2((f32x2){x1[0], x1[1]}, na); d = sigmoid2((f32x2){x1[2], x1[3]}, na); }
;                     else { a = (f32x2){x0[0], x0[1]} * rs; b = (f32x2){x0[2], x0[3]} * rs; c = (f32x2){x1[0], x1[1]} * rs; d = (f32x2){x1[2], x1[3]} * rs; }
;                     u32x4 w; w.x = cvt_pk_bf16(a.x, a.y); w.y = cvt_pk_bf16(b.x, b.y); w.z = cvt_pk_bf16(c.x, c.y); w.w = cvt_pk_bf16(d.x, d.y);
;                     *(u32x4*)(base + (size_t)r * ldc + col0 + bj * HALF) = w;
;                 }
.LBB0_408:
	v_cvt_pk_bf16_f32 v112, v124, v125
	v_cvt_pk_bf16_f32 v113, v126, v127
	v_cvt_pk_bf16_f32 v114, v146, v147
	v_cvt_pk_bf16_f32 v115, v148, v149
	global_store_dwordx4 v[122:123], v[112:115], off offset:256 sc1
	s_nop 1
	v_mov_b64_e32 v[112:113], v[170:171]
	s_and_b64 vcc, exec, s[8:9]
	s_mov_b64 s[2:3], -1
	v_ffbh_u32_e32 v114, v113
	v_min_u32_e32 v114, 32, v114
	v_lshlrev_b64 v[112:113], v114, v[112:113]
	v_min_u32_e32 v112, 1, v112
	v_or_b32_e32 v112, v113, v112
	v_cvt_f32_u32_e32 v112, v112
	v_sub_u32_e32 v113, 32, v114
	v_ldexp_f32 v112, v112, v113
	v_fmamk_f32 v112, v112, 0x2e000000, v239
	v_rsq_f32_e32 v112, v112
	s_nop 0
	v_mul_f32_e32 v114, 0xbfb8aa3b, v112
	v_mov_b32_e32 v113, v112
	v_mov_b32_e32 v115, v114
	s_cbranch_vccnz .LBB0_414
	s_and_b64 vcc, exec, s[6:7]
	s_cbranch_vccnz .LBB0_411
	v_pk_mul_f32 v[116:117], v[108:109], v[112:113]
	v_pk_mul_f32 v[118:119], v[110:111], v[112:113]
	v_pk_mul_f32 v[122:123], v[104:105], v[112:113]
	v_pk_mul_f32 v[124:125], v[106:107], v[112:113]
	s_mov_b64 s[2:3], 0

; __device__ __forceinline__ unsigned cvt_pk_bf16(float lo, float hi) { const f32x2_t v = {lo, hi}; const bf16x2_t b = __builtin_convertvector(v, bf16x2_t); return __builtin_bit_cast(unsigned, b); }
; __device__ __forceinline__ f32x2 sigmoid2(f32x2 x, float na) { return rcp_2(exp2_2(x * na) + 1.0f); }
; __device__ __forceinline__ f32x2 gelu2(f32x2 x, float rs) { const f32x2 v = x * rs; const f32x2 w = v * (v * v * 0.044715f + 1.0f); return v * rcp_2(exp2_2(w * -2.3022082f) + 1.0f); }
; __device__ __forceinline__ float rstd_of(u64 ssq) { return frsq((float)ssq * (1.0f / (2048.0f * 16777216.0f)) + EPS); }
;     __device__ __forceinline__ void operator()(const Acc& acc, const Unit& u, int wr, int wc, int fr, int fq) const {
;     ...
;             for (int m = 0; m < 4; ++m) {
;                 asm volatile("" ::: "memory");
;                 const int r = row0 + ai * HALF + m * 16; const float rs = rstd_of(ssq[r]);
; #pragma unroll
;                 for (int bj = 0; bj < 2; ++bj) {
;                     const f32x4 x0 = acc[ai][bj][m][0], x1 = acc[ai][bj][m][1];
;                     f32x2 a, b, c, d;
;                     if (act == 1) { a = gelu2((f32x2){x0[0], x0[1]}, rs); b = gelu2((f32x2){x0[2], x0[3]}, rs); c = gelu2((f32x2){x1[0], x1[1]}, rs); d = gelu2((f32x2){x1[2], x1[3]}, rs); }
;                     else if (act == 2) { const float na = -rs * LOG2E; a = sigmoid2((f32x2){x0[0], x0[1]}, na); b = sigmoid2((f32x2){x0[2], x0[3]}, na); c = sigmoid2((f32x2){x1[0], x1[1]}, na); d = sigmoid2((f32x2){x1[2], x1[3]}, na); }
;                     else { a = (f32x2){x0[0], x0[1]} * rs; b = (f32x2){x0[2], x0[3]} * rs; c = (f32x2){x1[0], x1[1]} * rs; d = (f32x2){x1[2], x1[3]} * rs; }
;                     u32x4 w; w.x = cvt_pk_bf16(a.x, a.y); w.y = cvt_pk_bf16(b.x, b.y); w.z = cvt_pk_bf16(c.x, c.y); w.w = cvt_pk_bf16(d.x, d.y);
;                     *(u32x4*)(base + (size_t)r * ldc + col0 + bj * HALF) = w;
;                 }
.LBB0_416:
	v_or_b32_e32 v104, 16, v138
	v_mul_lo_u32 v106, s63, v104
	v_mul_lo_u32 v126, s62, v139
	v_mad_u64_u32 v[104:105], s[2:3], s62, v104, 0
	v_add3_u32 v105, v105, v126, v106
	v_lshl_add_u64 v[104:105], v[104:105], 1, v[120:121]
	v_cvt_pk_bf16_f32 v106, v116, v117
	v_cvt_pk_bf16_f32 v107, v118, v119
	v_cvt_pk_bf16_f32 v108, v122, v123
	v_cvt_pk_bf16_f32 v109, v124, v125
	s_and_b64 vcc, exec, s[8:9]
	s_mov_b64 s[2:3], -1
	global_store_dwordx4 v[104:105], v[106:109], off sc1
	s_cbranch_vccnz .LBB0_422
	s_and_b64 vcc, exec, s[6:7]
	s_cbranch_vccnz .LBB0_419
	v_pk_mul_f32 v[106:107], v[100:101], v[112:113]
	v_pk_mul_f32 v[108:109], v[102:103], v[112:113]
	v_pk_mul_f32 v[110:111], v[96:97], v[112:113]
	v_pk_mul_f32 v[116:117], v[98:99], v[112:113]
	s_mov_b64 s[2:3], 0

; __device__ __forceinline__ unsigned cvt_pk_bf16(float lo, float hi) { const f32x2_t v = {lo, hi}; const bf16x2_t b = __builtin_convertvector(v, bf16x2_t); return __builtin_bit_cast(unsigned, b); }
; __device__ __forceinline__ f32x2 sigmoid2(f32x2 x, float na) { return rcp_2(exp2_2(x * na) + 1.0f); }
; __device__ __forceinline__ f32x2 gelu2(f32x2 x, float rs) { const f32x2 v = x * rs; const f32x2 w = v * (v * v * 0.044715f + 1.0f); return v * rcp_2(exp2_2(w * -2.3022082f) + 1.0f); }
; __device__ __forceinline__ float rstd_of(u64 ssq) { return frsq((float)ssq * (1.0f / (2048.0f * 16777216.0f)) + EPS); }
;     __device__ __forceinline__ void operator()(const Acc& acc, const Unit& u, int wr, int wc, int fr, int fq) const {
;     ...
;             for (int m = 0; m < 4; ++m) {
;                 asm volatile("" ::: "memory");
;                 const int r = row0 + ai * HALF + m * 16; const float rs = rstd_of(ssq[r]);
; #pragma unroll
;                 for (int bj = 0; bj < 2; ++bj) {
;                     const f32x4 x0 = acc[ai][bj][m][0], x1 = acc[ai][bj][m][1];
;                     f32x2 a, b, c, d;
;                     if (act == 1) { a = gelu2((f32x2){x0[0], x0[1]}, rs); b = gelu2((f32x2){x0[2], x0[3]}, rs); c = gelu2((f32x2){x1[0], x1[1]}, rs); d = gelu2((f32x2){x1[2], x1[3]}, rs); }
;                     else if (act == 2) { const float na = -rs * LOG2E; a = sigmoid2((f32x2){x0[0], x0[1]}, na); b = sigmoid2((f32x2){x0[2], x0[3]}, na); c = sigmoid2((f32x2){x1[0], x1[1]}, na); d = sigmoid2((f32x2){x1[2], x1[3]}, na); }
;                     else { a = (f32x2){x0[0], x0[1]} * rs; b = (f32x2){x0[2], x0[3]} * rs; c = (f32x2){x1[0], x1[1]} * rs; d = (f32x2){x1[2], x1[3]} * rs; }
;                     u32x4 w; w.x = cvt_pk_bf16(a.x, a.y); w.y = cvt_pk_bf16(b.x, b.y); w.z = cvt_pk_bf16(c.x, c.y); w.w = cvt_pk_bf16(d.x, d.y);
;                     *(u32x4*)(base + (size_t)r * ldc + col0 + bj * HALF) = w;
;                 }
.LBB0_424:
	v_cvt_pk_bf16_f32 v96, v106, v107
	v_cvt_pk_bf16_f32 v97, v108, v109
	v_cvt_pk_bf16_f32 v98, v110, v111
	v_cvt_pk_bf16_f32 v99, v116, v117
	global_store_dwordx4 v[104:105], v[96:99], off offset:256 sc1
	s_nop 1
	v_mov_b64_e32 v[96:97], v[172:173]
	s_and_b64 vcc, exec, s[8:9]
	s_mov_b64 s[2:3], -1
	v_ffbh_u32_e32 v98, v97
	v_min_u32_e32 v98, 32, v98
	v_lshlrev_b64 v[96:97], v98, v[96:97]
	v_min_u32_e32 v96, 1, v96
	v_or_b32_e32 v96, v97, v96
	v_cvt_f32_u32_e32 v96, v96
	v_sub_u32_e32 v97, 32, v98
	v_ldexp_f32 v96, v96, v97
	v_fmamk_f32 v96, v96, 0x2e000000, v239
	v_rsq_f32_e32 v96, v96
	s_nop 0
	v_mul_f32_e32 v98, 0xbfb8aa3b, v96
	v_mov_b32_e32 v97, v96
	v_mov_b32_e32 v99, v98
	s_cbranch_vccnz .LBB0_430
	s_and_b64 vcc, exec, s[6:7]
	s_cbranch_vccnz .LBB0_427
	v_pk_mul_f32 v[100:101], v[92:93], v[96:97]
	v_pk_mul_f32 v[102:103], v[94:95], v[96:97]
	v_pk_mul_f32 v[104:105], v[88:89], v[96:97]
	v_pk_mul_f32 v[106:107], v[90:91], v[96:97]
	s_mov_b64 s[2:3], 0

; __device__ __forceinline__ unsigned cvt_pk_bf16(float lo, float hi) { const f32x2_t v = {lo, hi}; const bf16x2_t b = __builtin_convertvector(v, bf16x2_t); return __builtin_bit_cast(unsigned, b); }
; __device__ __forceinline__ f32x2 sigmoid2(f32x2 x, float na) { return rcp_2(exp2_2(x * na) + 1.0f); }
; __device__ __forceinline__ f32x2 gelu2(f32x2 x, float rs) { const f32x2 v = x * rs; const f32x2 w = v * (v * v * 0.044715f + 1.0f); return v * rcp_2(exp2_2(w * -2.3022082f) + 1.0f); }
; __device__ __forceinline__ float rstd_of(u64 ssq) { return frsq((float)ssq * (1.0f / (2048.0f * 16777216.0f)) + EPS); }
;     __device__ __forceinline__ void operator()(const Acc& acc, const Unit& u, int wr, int wc, int fr, int fq) const {
;     ...
;             for (int m = 0; m < 4; ++m) {
;                 asm volatile("" ::: "memory");
;                 const int r = row0 + ai * HALF + m * 16; const float rs = rstd_of(ssq[r]);
; #pragma unroll
;                 for (int bj = 0; bj < 2; ++bj) {
;                     const f32x4 x0 = acc[ai][bj][m][0], x1 = acc[ai][bj][m][1];
;                     f32x2 a, b, c, d;
;                     if (act == 1) { a = gelu2((f32x2){x0[0], x0[1]}, rs); b = gelu2((f32x2){x0[2], x0[3]}, rs); c = gelu2((f32x2){x1[0], x1[1]}, rs); d = gelu2((f32x2){x1[2], x1[3]}, rs); }
;                     else if (act == 2) { const float na = -rs * LOG2E; a = sigmoid2((f32x2){x0[0], x0[1]}, na); b = sigmoid2((f32x2){x0[2], x0[3]}, na); c = sigmoid2((f32x2){x1[0], x1[1]}, na); d = sigmoid2((f32x2){x1[2], x1[3]}, na); }
;                     else { a = (f32x2){x0[0], x0[1]} * rs; b = (f32x2){x0[2], x0[3]} * rs; c = (f32x2){x1[0], x1[1]} * rs; d = (f32x2){x1[2], x1[3]} * rs; }
;                     u32x4 w; w.x = cvt_pk_bf16(a.x, a.y); w.y = cvt_pk_bf16(b.x, b.y); w.z = cvt_pk_bf16(c.x, c.y); w.w = cvt_pk_bf16(d.x, d.y);
;                     *(u32x4*)(base + (size_t)r * ldc + col0 + bj * HALF) = w;
;                 }
.LBB0_432:
	v_or_b32_e32 v88, 32, v138
	v_mul_lo_u32 v90, s63, v88
	v_mad_u64_u32 v[88:89], s[2:3], s62, v88, 0
	v_add3_u32 v89, v89, v126, v90
	v_lshl_add_u64 v[88:89], v[88:89], 1, v[120:121]
	v_cvt_pk_bf16_f32 v90, v100, v101
	v_cvt_pk_bf16_f32 v91, v102, v103
	v_cvt_pk_bf16_f32 v92, v104, v105
	v_cvt_pk_bf16_f32 v93, v106, v107
	s_and_b64 vcc, exec, s[8:9]
	s_mov_b64 s[2:3], -1
	global_store_dwordx4 v[88:89], v[90:93], off sc1
	s_cbranch_vccnz .LBB0_438
	s_and_b64 vcc, exec, s[6:7]
	s_cbranch_vccnz .LBB0_435
	v_pk_mul_f32 v[90:91], v[84:85], v[96:97]
	v_pk_mul_f32 v[92:93], v[86:87], v[96:97]
	v_pk_mul_f32 v[94:95], v[80:81], v[96:97]
	v_pk_mul_f32 v[100:101], v[82:83], v[96:97]
	s_mov_b64 s[2:3], 0

; __device__ __forceinline__ unsigned cvt_pk_bf16(float lo, float hi) { const f32x2_t v = {lo, hi}; const bf16x2_t b = __builtin_convertvector(v, bf16x2_t); return __builtin_bit_cast(unsigned, b); }
; __device__ __forceinline__ f32x2 sigmoid2(f32x2 x, float na) { return rcp_2(exp2_2(x * na) + 1.0f); }
; __device__ __forceinline__ f32x2 gelu2(f32x2 x, float rs) { const f32x2 v = x * rs; const f32x2 w = v * (v * v * 0.044715f + 1.0f); return v * rcp_2(exp2_2(w * -2.3022082f) + 1.0f); }
; __device__ __forceinline__ float rstd_of(u64 ssq) { return frsq((float)ssq * (1.0f / (2048.0f * 16777216.0f)) + EPS); }
;     __device__ __forceinline__ void operator()(const Acc& acc, const Unit& u, int wr, int wc, int fr, int fq) const {
;     ...
;             for (int m = 0; m < 4; ++m) {
;                 asm volatile("" ::: "memory");
;                 const int r = row0 + ai * HALF + m * 16; const float rs = rstd_of(ssq[r]);
; #pragma unroll
;                 for (int bj = 0; bj < 2; ++bj) {
;                     const f32x4 x0 = acc[ai][bj][m][0], x1 = acc[ai][bj][m][1];
;                     f32x2 a, b, c, d;
;                     if (act == 1) { a = gelu2((f32x2){x0[0], x0[1]}, rs); b = gelu2((f32x2){x0[2], x0[3]}, rs); c = gelu2((f32x2){x1[0], x1[1]}, rs); d = gelu2((f32x2){x1[2], x1[3]}, rs); }
;                     else if (act == 2) { const float na = -rs * LOG2E; a = sigmoid2((f32x2){x0[0], x0[1]}, na); b = sigmoid2((f32x2){x0[2], x0[3]}, na); c = sigmoid2((f32x2){x1[0], x1[1]}, na); d = sigmoid2((f32x2){x1[2], x1[3]}, na); }
;                     else { a = (f32x2){x0[0], x0[1]} * rs; b = (f32x2){x0[2], x0[3]} * rs; c = (f32x2){x1[0], x1[1]} * rs; d = (f32x2){x1[2], x1[3]} * rs; }
;                     u32x4 w; w.x = cvt_pk_bf16(a.x, a.y); w.y = cvt_pk_bf16(b.x, b.y); w.z = cvt_pk_bf16(c.x, c.y); w.w = cvt_pk_bf16(d.x, d.y);
;                     *(u32x4*)(base + (size_t)r * ldc + col0 + bj * HALF) = w;
;                 }
.LBB0_440:
	v_cvt_pk_bf16_f32 v80, v90, v91
	v_cvt_pk_bf16_f32 v81, v92, v93
	v_cvt_pk_bf16_f32 v82, v94, v95
	v_cvt_pk_bf16_f32 v83, v100, v101
	global_store_dwordx4 v[88:89], v[80:83], off offset:256 sc1
	s_nop 1
	v_mov_b64_e32 v[80:81], v[174:175]
	s_and_b64 vcc, exec, s[8:9]
	s_mov_b64 s[2:3], -1
	v_ffbh_u32_e32 v82, v81
	v_min_u32_e32 v82, 32, v82
	v_lshlrev_b64 v[80:81], v82, v[80:81]
	v_min_u32_e32 v80, 1, v80
	v_or_b32_e32 v80, v81, v80
	v_cvt_f32_u32_e32 v80, v80
	v_sub_u32_e32 v81, 32, v82
	v_ldexp_f32 v80, v80, v81
	v_fmamk_f32 v80, v80, 0x2e000000, v239
	v_rsq_f32_e32 v80, v80
	s_nop 0
	v_mul_f32_e32 v82, 0xbfb8aa3b, v80
	v_mov_b32_e32 v81, v80
	v_mov_b32_e32 v83, v82
	s_cbranch_vccnz .LBB0_446
	s_and_b64 vcc, exec, s[6:7]
	s_cbranch_vccnz .LBB0_443
	v_pk_mul_f32 v[84:85], v[76:77], v[80:81]
	v_pk_mul_f32 v[86:87], v[78:79], v[80:81]
	v_pk_mul_f32 v[88:89], v[72:73], v[80:81]
	v_pk_mul_f32 v[90:91], v[74:75], v[80:81]
	s_mov_b64 s[2:3], 0

; __device__ __forceinline__ unsigned cvt_pk_bf16(float lo, float hi) { const f32x2_t v = {lo, hi}; const bf16x2_t b = __builtin_convertvector(v, bf16x2_t); return __builtin_bit_cast(unsigned, b); }
; __device__ __forceinline__ f32x2 sigmoid2(f32x2 x, float na) { return rcp_2(exp2_2(x * na) + 1.0f); }
; __device__ __forceinline__ f32x2 gelu2(f32x2 x, float rs) { const f32x2 v = x * rs; const f32x2 w = v * (v * v * 0.044715f + 1.0f); return v * rcp_2(exp2_2(w * -2.3022082f) + 1.0f); }
; __device__ __forceinline__ float rstd_of(u64 ssq) { return frsq((float)ssq * (1.0f / (2048.0f * 16777216.0f)) + EPS); }
;     __device__ __forceinline__ void operator()(const Acc& acc, const Unit& u, int wr, int wc, int fr, int fq) const {
;     ...
;             for (int m = 0; m < 4; ++m) {
;                 asm volatile("" ::: "memory");
;                 const int r = row0 + ai * HALF + m * 16; const float rs = rstd_of(ssq[r]);
; #pragma unroll
;                 for (int bj = 0; bj < 2; ++bj) {
;                     const f32x4 x0 = acc[ai][bj][m][0], x1 = acc[ai][bj][m][1];
;                     f32x2 a, b, c, d;
;                     if (act == 1) { a = gelu2((f32x2){x0[0], x0[1]}, rs); b = gelu2((f32x2){x0[2], x0[3]}, rs); c = gelu2((f32x2){x1[0], x1[1]}, rs); d = gelu2((f32x2){x1[2], x1[3]}, rs); }
;                     else if (act == 2) { const float na = -rs * LOG2E; a = sigmoid2((f32x2){x0[0], x0[1]}, na); b = sigmoid2((f32x2){x0[2], x0[3]}, na); c = sigmoid2((f32x2){x1[0], x1[1]}, na); d = sigmoid2((f32x2){x1[2], x1[3]}, na); }
;                     else { a = (f32x2){x0[0], x0[1]} * rs; b = (f32x2){x0[2], x0[3]} * rs; c = (f32x2){x1[0], x1[1]} * rs; d = (f32x2){x1[2], x1[3]} * rs; }
;                     u32x4 w; w.x = cvt_pk_bf16(a.x, a.y); w.y = cvt_pk_bf16(b.x, b.y); w.z = cvt_pk_bf16(c.x, c.y); w.w = cvt_pk_bf16(d.x, d.y);
;                     *(u32x4*)(base + (size_t)r * ldc + col0 + bj * HALF) = w;
;                 }
.LBB0_448:
	v_or_b32_e32 v72, 48, v138
	v_mul_lo_u32 v74, s63, v72
	v_mad_u64_u32 v[72:73], s[2:3], s62, v72, 0
	v_add3_u32 v73, v73, v126, v74
	v_lshl_add_u64 v[72:73], v[72:73], 1, v[120:121]
	v_cvt_pk_bf16_f32 v74, v84, v85
	v_cvt_pk_bf16_f32 v75, v86, v87
	v_cvt_pk_bf16_f32 v76, v88, v89
	v_cvt_pk_bf16_f32 v77, v90, v91
	s_and_b64 vcc, exec, s[8:9]
	s_mov_b64 s[2:3], -1
	global_store_dwordx4 v[72:73], v[74:77], off sc1
	s_cbranch_vccnz .LBB0_454
	s_and_b64 vcc, exec, s[6:7]
	s_cbranch_vccnz .LBB0_451
	v_pk_mul_f32 v[74:75], v[68:69], v[80:81]
	v_pk_mul_f32 v[76:77], v[70:71], v[80:81]
	v_pk_mul_f32 v[78:79], v[64:65], v[80:81]
	v_pk_mul_f32 v[84:85], v[66:67], v[80:81]
	s_mov_b64 s[2:3], 0

; __device__ __forceinline__ unsigned cvt_pk_bf16(float lo, float hi) { const f32x2_t v = {lo, hi}; const bf16x2_t b = __builtin_convertvector(v, bf16x2_t); return __builtin_bit_cast(unsigned, b); }
; __device__ __forceinline__ f32x2 sigmoid2(f32x2 x, float na) { return rcp_2(exp2_2(x * na) + 1.0f); }
; __device__ __forceinline__ f32x2 gelu2(f32x2 x, float rs) { const f32x2 v = x * rs; const f32x2 w = v * (v * v * 0.044715f + 1.0f); return v * rcp_2(exp2_2(w * -2.3022082f) + 1.0f); }
; __device__ __forceinline__ float rstd_of(u64 ssq) { return frsq((float)ssq * (1.0f / (2048.0f * 16777216.0f)) + EPS); }
;     __device__ __forceinline__ void operator()(const Acc& acc, const Unit& u, int wr, int wc, int fr, int fq) const {
;     ...
;             for (int m = 0; m < 4; ++m) {
;                 asm volatile("" ::: "memory");
;                 const int r = row0 + ai * HALF + m * 16; const float rs = rstd_of(ssq[r]);
; #pragma unroll
;                 for (int bj = 0; bj < 2; ++bj) {
;                     const f32x4 x0 = acc[ai][bj][m][0], x1 = acc[ai][bj][m][1];
;                     f32x2 a, b, c, d;
;                     if (act == 1) { a = gelu2((f32x2){x0[0], x0[1]}, rs); b = gelu2((f32x2){x0[2], x0[3]}, rs); c = gelu2((f32x2){x1[0], x1[1]}, rs); d = gelu2((f32x2){x1[2], x1[3]}, rs); }
;                     else if (act == 2) { const float na = -rs * LOG2E; a = sigmoid2((f32x2){x0[0], x0[1]}, na); b = sigmoid2((f32x2){x0[2], x0[3]}, na); c = sigmoid2((f32x2){x1[0], x1[1]}, na); d = sigmoid2((f32x2){x1[2], x1[3]}, na); }
;                     else { a = (f32x2){x0[0], x0[1]} * rs; b = (f32x2){x0[2], x0[3]} * rs; c = (f32x2){x1[0], x1[1]} * rs; d = (f32x2){x1[2], x1[3]} * rs; }
;                     u32x4 w; w.x = cvt_pk_bf16(a.x, a.y); w.y = cvt_pk_bf16(b.x, b.y); w.z = cvt_pk_bf16(c.x, c.y); w.w = cvt_pk_bf16(d.x, d.y);
;                     *(u32x4*)(base + (size_t)r * ldc + col0 + bj * HALF) = w;
;                 }
.LBB0_456:
	v_cvt_pk_bf16_f32 v64, v74, v75
	v_cvt_pk_bf16_f32 v65, v76, v77
	v_cvt_pk_bf16_f32 v66, v78, v79
	v_cvt_pk_bf16_f32 v67, v84, v85
	global_store_dwordx4 v[72:73], v[64:67], off offset:256 sc1
	s_nop 1
	v_mov_b64_e32 v[64:65], v[176:177]
	s_and_b64 vcc, exec, s[8:9]
	s_mov_b64 s[2:3], -1
	v_ffbh_u32_e32 v66, v65
	v_min_u32_e32 v66, 32, v66
	v_lshlrev_b64 v[64:65], v66, v[64:65]
	v_min_u32_e32 v64, 1, v64
	v_or_b32_e32 v64, v65, v64
	v_cvt_f32_u32_e32 v64, v64
	v_sub_u32_e32 v65, 32, v66
	v_ldexp_f32 v64, v64, v65
	v_fmamk_f32 v64, v64, 0x2e000000, v239
	v_rsq_f32_e32 v64, v64
	s_nop 0
	v_mul_f32_e32 v66, 0xbfb8aa3b, v64
	v_mov_b32_e32 v65, v64
	v_mov_b32_e32 v67, v66
	s_cbranch_vccnz .LBB0_462
	s_and_b64 vcc, exec, s[6:7]
	s_cbranch_vccnz .LBB0_459
	v_pk_mul_f32 v[68:69], v[60:61], v[64:65]
	v_pk_mul_f32 v[70:71], v[62:63], v[64:65]
	v_pk_mul_f32 v[72:73], v[56:57], v[64:65]
	v_pk_mul_f32 v[74:75], v[58:59], v[64:65]
	s_mov_b64 s[2:3], 0

; __device__ __forceinline__ unsigned cvt_pk_bf16(float lo, float hi) { const f32x2_t v = {lo, hi}; const bf16x2_t b = __builtin_convertvector(v, bf16x2_t); return __builtin_bit_cast(unsigned, b); }
; __device__ __forceinline__ unsigned cvt_pk_f16(float lo, float hi) { const f32x2 v = {lo, hi}; const h16x2_t h = __builtin_convertvector(v, h16x2_t); return __builtin_bit_cast(unsigned, h); }
; __device__ __forceinline__ f32x2 unpk_f16(unsigned u) { const h16x2_t h = __builtin_bit_cast(h16x2_t, u); return __builtin_convertvector(h, f32x2); }
; __device__ __forceinline__ u64 ssq_fix(float s) { return (u64)__float2ull_rn(s * 16777216.0f); }
;     __device__ __forceinline__ void operator()(const Acc& acc, const Unit& u, int wr, int wc, int fr, int fq) const {
;     ...
;                 const int r = row0 + ai * HALF + m * 16; float part = 0.f;
; #pragma unroll
;                 for (int bj = 0; bj < 2; ++bj) {
;                     const size_t off = (size_t)r * D + col0 + bj * HALF;
;                     const u32x4 hw = *(const u32x4*)(H16 + off);
;                     const f32x2 a = unpk_f16(hw.x), b2 = unpk_f16(hw.y), c = unpk_f16(hw.z), d = unpk_f16(hw.w);
;                     f32x4 v0, v1;
;                     v0[0] = a.x + acc[ai][bj][m][0][0]; v0[1] = a.y + acc[ai][bj][m][0][1]; v0[2] = b2.x + acc[ai][bj][m][0][2]; v0[3] = b2.y + acc[ai][bj][m][0][3];
;                     v1[0] = c.x + acc[ai][bj][m][1][0]; v1[1] = c.y + acc[ai][bj][m][1][1]; v1[2] = d.x + acc[ai][bj][m][1][2]; v1[3] = d.y + acc[ai][bj][m][1][3];
;                     u32x4 w; w.x = cvt_pk_bf16(v0[0], v0[1]); w.y = cvt_pk_bf16(v0[2], v0[3]); w.z = cvt_pk_bf16(v1[0], v1[1]); w.w = cvt_pk_bf16(v1[2], v1[3]);
;                     u32x4 hq; hq.x = cvt_pk_f16(v0[0], v0[1]); hq.y = cvt_pk_f16(v0[2], v0[3]); hq.z = cvt_pk_f16(v1[0], v1[1]); hq.w = cvt_pk_f16(v1[2], v1[3]);
;                     if (!dry) { *(u32x4*)(HB + off) = w; *(u32x4*)(H16 + off) = hq; }
;                     part += v0[0] * v0[0] + v0[1] * v0[1] + v0[2] * v0[2] + v0[3] * v0[3] + v1[0] * v1[0] + v1[1] * v1[1] + v1[2] * v1[2] + v1[3] * v1[3];
;                 }
;                 part += __shfl_xor(part, 16); part += __shfl_xor(part, 32);
;                 if (fq == 0 && !dry) atomicAdd(ssq_out + r, ssq_fix(part));
.LBB0_569:
	v_lshl_add_u32 v142, s83, 8, v144
	v_lshl_or_b32 v140, s88, 8, v146
	v_ashrrev_i32_e32 v143, 31, v142
	v_ashrrev_i32_e32 v141, 31, v140
	v_lshlrev_b64 v[138:139], 11, v[142:143]
	v_lshl_add_u64 v[138:139], v[138:139], 0, v[140:141]
	v_lshlrev_b64 v[138:139], 1, v[138:139]
	v_mov_b32_e32 v214, v138
	global_load_dwordx4 v[170:173], v214, s[14:15]
	global_load_dwordx4 v[174:177], v214, s[14:15] offset:256
	v_add_u32_e32 v215, 0x10000, v214
	global_load_dwordx4 v[178:181], v215, s[14:15]
	global_load_dwordx4 v[182:185], v215, s[14:15] offset:256
	v_add_u32_e32 v215, 0x20000, v214
	global_load_dwordx4 v[186:189], v215, s[14:15]
	global_load_dwordx4 v[190:193], v215, s[14:15] offset:256
	v_add_u32_e32 v215, 0x30000, v214
	global_load_dwordx4 v[194:197], v215, s[14:15]
	global_load_dwordx4 v[198:201], v215, s[14:15] offset:256
	v_add_u32_e32 v215, 0x80000, v214
	global_load_dwordx4 v[202:205], v215, s[14:15]
	global_load_dwordx4 v[206:209], v215, s[14:15] offset:256
	v_add_u32_e32 v215, 0x90000, v214
	global_load_dwordx4 v[210:213], v215, s[14:15]
	v_lshl_add_u64 v[152:153], s[14:15], 0, v[138:139]
	s_waitcnt vmcnt(10)
	s_nop 1
	v_mov_b64_e32 v[148:149], v[170:171]
	v_mov_b64_e32 v[150:151], v[172:173]
	global_load_dwordx4 v[170:173], v215, s[14:15] offset:256
	v_lshl_add_u64 v[158:159], s[80:81], 0, v[138:139]
	v_cvt_f32_f16_e32 v154, v148
	v_cvt_f32_f16_sdwa v155, v148 dst_sel:DWORD dst_unused:UNUSED_PAD src0_sel:WORD_1
	v_cvt_f32_f16_e32 v148, v149
	v_cvt_f32_f16_sdwa v149, v149 dst_sel:DWORD dst_unused:UNUSED_PAD src0_sel:WORD_1
	v_cvt_f32_f16_e32 v156, v150
	v_cvt_f32_f16_sdwa v157, v150 dst_sel:DWORD dst_unused:UNUSED_PAD src0_sel:WORD_1
	v_cvt_f32_f16_e32 v150, v151
	v_cvt_f32_f16_sdwa v151, v151 dst_sel:DWORD dst_unused:UNUSED_PAD src0_sel:WORD_1
	v_pk_add_f32 v[154:155], v[124:125], v[154:155]
	v_pk_add_f32 v[148:149], v[126:127], v[148:149]
	v_pk_add_f32 v[156:157], v[120:121], v[156:157]
	v_pk_add_f32 v[150:151], v[122:123], v[150:151]
	v_cvt_pk_bf16_f32 v126, v156, v157
	v_cvt_pk_bf16_f32 v127, v150, v151
	v_cvt_pk_bf16_f32 v125, v148, v149
	v_cvt_pk_bf16_f32 v124, v154, v155
	v_cvt_pk_f16_f32 v123, v150, v151
	v_cvt_pk_f16_f32 v122, v156, v157
	v_cvt_pk_f16_f32 v121, v148, v149
	v_cvt_pk_f16_f32 v120, v154, v155
	global_store_dwordx4 v[158:159], v[124:127], off sc1
	global_store_dwordx4 v[152:153], v[120:123], off sc1
	v_or_b32_e32 v152, 0x100, v138
	v_mov_b32_e32 v153, v139
	v_pk_mul_f32 v[124:125], v[154:155], v[154:155]
	v_lshl_add_u64 v[154:155], s[14:15], 0, v[152:153]
	s_waitcnt vmcnt(12)
	s_nop 1
	v_mov_b64_e32 v[120:121], v[174:175]
	v_mov_b64_e32 v[122:123], v[176:177]
	v_add_u32_e32 v215, 0xa0000, v214
	global_load_dwordx4 v[174:177], v215, s[14:15]
	v_pk_mul_f32 v[126:127], v[148:149], v[148:149]
	v_pk_mul_f32 v[148:149], v[156:157], v[156:157]
	v_lshl_add_u64 v[152:153], s[80:81], 0, v[152:153]
	v_pk_mul_f32 v[150:151], v[150:151], v[150:151]
	v_cvt_f32_f16_e32 v156, v120
	v_cvt_f32_f16_sdwa v157, v120 dst_sel:DWORD dst_unused:UNUSED_PAD src0_sel:WORD_1
	v_cvt_f32_f16_e32 v120, v121
	v_cvt_f32_f16_sdwa v121, v121 dst_sel:DWORD dst_unused:UNUSED_PAD src0_sel:WORD_1
	v_cvt_f32_f16_e32 v158, v122
	v_cvt_f32_f16_sdwa v159, v122 dst_sel:DWORD dst_unused:UNUSED_PAD src0_sel:WORD_1
	v_cvt_f32_f16_e32 v122, v123
	v_cvt_f32_f16_sdwa v123, v123 dst_sel:DWORD dst_unused:UNUSED_PAD src0_sel:WORD_1
	v_pk_add_f32 v[156:157], v[116:117], v[156:157]
	v_pk_add_f32 v[120:121], v[118:119], v[120:121]
	v_pk_add_f32 v[158:159], v[112:113], v[158:159]
	v_pk_add_f32 v[122:123], v[114:115], v[122:123]
	v_cvt_pk_f16_f32 v113, v120, v121
	v_cvt_pk_f16_f32 v112, v156, v157
	v_cvt_pk_bf16_f32 v119, v122, v123
	v_cvt_pk_bf16_f32 v118, v158, v159
	v_cvt_pk_bf16_f32 v117, v120, v121
	v_cvt_pk_bf16_f32 v116, v156, v157
	v_cvt_pk_f16_f32 v115, v122, v123
	v_cvt_pk_f16_f32 v114, v158, v159
	global_store_dwordx4 v[152:153], v[116:119], off sc1
	global_store_dwordx4 v[154:155], v[112:115], off sc1
	s_nop 0
	v_pk_mul_f32 v[116:117], v[158:159], v[158:159]
	v_pk_mul_f32 v[112:113], v[156:157], v[156:157]
	v_pk_mul_f32 v[114:115], v[120:121], v[120:121]
	v_add_f32_e32 v112, v112, v113
	v_add_f32_e32 v113, v124, v125
	v_add_f32_e32 v112, v114, v112
	v_add_f32_e32 v113, v126, v113
	v_add_f32_e32 v112, v115, v112
	v_add_f32_e32 v113, v127, v113
	v_add_f32_e32 v112, v116, v112
	v_add_f32_e32 v113, v148, v113
	v_pk_mul_f32 v[118:119], v[122:123], v[122:123]
	v_add_f32_e32 v112, v117, v112
	v_add_f32_e32 v113, v149, v113
	v_add_f32_e32 v112, v118, v112
	v_add_f32_e32 v113, v150, v113
	v_add_f32_e32 v112, v119, v112
	v_add_f32_e32 v113, v151, v113
	v_and_b32_e32 v114, 64, v240
	v_add_f32_e32 v112, v113, v112
	v_xor_b32_e32 v113, 16, v240
	v_add_u32_e32 v115, 64, v114
	v_cmp_lt_i32_e32 vcc, v113, v115
	s_nop 1
	v_cndmask_b32_e32 v113, v240, v113, vcc
	v_lshlrev_b32_e32 v116, 2, v113
	ds_bpermute_b32 v113, v116, v112
	s_waitcnt lgkmcnt(0)
	v_add_f32_e32 v114, v112, v113
	v_xor_b32_e32 v112, 32, v240
	v_cmp_lt_i32_e32 vcc, v112, v115
	s_nop 1
	v_cndmask_b32_e32 v112, v240, v112, vcc
	v_lshlrev_b32_e32 v117, 2, v112
	ds_bpermute_b32 v115, v117, v114
	v_lshl_add_u64 v[112:113], v[142:143], 3, s[16:17]
	s_and_saveexec_b64 s[2:3], s[4:5]
	s_cbranch_execz .LBB0_571
	s_waitcnt lgkmcnt(0)
	v_add_f32_e32 v114, v114, v115
	v_mul_f32_e32 v114, 0x4b800000, v114
	v_rndne_f32_e32 v114, v114
	v_mul_f32_e32 v115, 0x2f800000, v114
	v_floor_f32_e32 v115, v115
	v_fmac_f32_e32 v114, 0xcf800000, v115
	v_cvt_u32_f32_e32 v114, v114
	v_cvt_u32_f32_e32 v115, v115
	global_atomic_add_x2 v[112:113], v[114:115], off

; __device__ __forceinline__ unsigned cvt_pk_bf16(float lo, float hi) { const f32x2_t v = {lo, hi}; const bf16x2_t b = __builtin_convertvector(v, bf16x2_t); return __builtin_bit_cast(unsigned, b); }
; __device__ __forceinline__ f32x2 swiglu2(f32x2 g, f32x2 u, float na, float rs2) { const f32x2 r = rcp_2(exp2_2(g * na) + 1.0f); return (g * u) * (r * rs2); }
; __device__ __forceinline__ float rstd_of(u64 ssq) { return frsq((float)ssq * (1.0f / (2048.0f * 16777216.0f)) + EPS); }
;     __device__ __forceinline__ void operator()(const Acc& acc, const Unit& u, int wr, int wc, int fr, int fq) const {
;     ...
;             for (int m = 0; m < 4; ++m) {
;                 asm volatile("" ::: "memory");
;                 const int r = row0 + ai * HALF + m * 16; const float rs = rstd_of(ssq[r]); const float na = -rs * LOG2E, rs2 = rs * rs;
;                 const f32x4 g0 = acc[ai][0][m][0], g1 = acc[ai][0][m][1], u0 = acc[ai][1][m][0], u1 = acc[ai][1][m][1];
;                 const f32x2 oa = swiglu2((f32x2){g0[0], g0[1]}, (f32x2){u0[0], u0[1]}, na, rs2), ob = swiglu2((f32x2){g0[2], g0[3]}, (f32x2){u0[2], u0[3]}, na, rs2);
;                 const f32x2 oc = swiglu2((f32x2){g1[0], g1[1]}, (f32x2){u1[0], u1[1]}, na, rs2), od = swiglu2((f32x2){g1[2], g1[3]}, (f32x2){u1[2], u1[3]}, na, rs2);
;                 u32x4 w; w.x = cvt_pk_bf16(oa.x, oa.y); w.y = cvt_pk_bf16(ob.x, ob.y); w.z = cvt_pk_bf16(oc.x, oc.y); w.w = cvt_pk_bf16(od.x, od.y);
;                 *(u32x4*)(O + (size_t)r * DFF + col0) = w;
.LBB0_603:
	v_lshl_add_u32 v138, s52, 8, v144
	v_ashrrev_i32_e32 v139, 31, v138
	v_lshl_add_u64 v[140:141], v[138:139], 3, s[8:9]
	global_load_dwordx2 v[148:149], v[140:141], off
	global_load_dwordx2 v[170:171], v[140:141], off offset:128
	global_load_dwordx2 v[172:173], v[140:141], off offset:256
	global_load_dwordx2 v[174:175], v[140:141], off offset:384
	global_load_dwordx2 v[176:177], v[140:141], off offset:1024
	global_load_dwordx2 v[178:179], v[140:141], off offset:1152
	global_load_dwordx2 v[180:181], v[140:141], off offset:1280
	global_load_dwordx2 v[182:183], v[140:141], off offset:1408
	v_pk_mul_f32 v[120:121], v[124:125], v[120:121]
	v_pk_mul_f32 v[122:123], v[126:127], v[122:123]
	v_pk_mul_f32 v[112:113], v[116:117], v[112:113]
	v_lshl_or_b32 v142, s73, 7, v146
	v_pk_mul_f32 v[114:115], v[118:119], v[114:115]
	v_ashrrev_i32_e32 v143, 31, v142
	v_pk_mul_f32 v[104:105], v[108:109], v[104:105]
	v_pk_mul_f32 v[106:107], v[110:111], v[106:107]
	v_pk_mul_f32 v[96:97], v[100:101], v[96:97]
	v_pk_mul_f32 v[98:99], v[102:103], v[98:99]
	v_pk_mul_f32 v[88:89], v[92:93], v[88:89]
	v_pk_mul_f32 v[90:91], v[94:95], v[90:91]
	v_pk_mul_f32 v[80:81], v[84:85], v[80:81]
	v_pk_mul_f32 v[82:83], v[86:87], v[82:83]
	v_pk_mul_f32 v[72:73], v[76:77], v[72:73]
	v_pk_mul_f32 v[74:75], v[78:79], v[74:75]
	v_pk_mul_f32 v[64:65], v[68:69], v[64:65]
	v_pk_mul_f32 v[66:67], v[70:71], v[66:67]
	v_pk_mul_f32 v[56:57], v[60:61], v[56:57]
	v_pk_mul_f32 v[58:59], v[62:63], v[58:59]
	v_pk_mul_f32 v[48:49], v[52:53], v[48:49]
	v_pk_mul_f32 v[50:51], v[54:55], v[50:51]
	v_pk_mul_f32 v[40:41], v[44:45], v[40:41]
	v_pk_mul_f32 v[42:43], v[46:47], v[42:43]
	v_pk_mul_f32 v[32:33], v[36:37], v[32:33]
	v_pk_mul_f32 v[34:35], v[38:39], v[34:35]
	v_pk_mul_f32 v[24:25], v[28:29], v[24:25]
	v_pk_mul_f32 v[26:27], v[30:31], v[26:27]
	v_pk_mul_f32 v[16:17], v[20:21], v[16:17]
	v_pk_mul_f32 v[18:19], v[22:23], v[18:19]
	v_pk_mul_f32 v[8:9], v[12:13], v[8:9]
	v_pk_mul_f32 v[10:11], v[14:15], v[10:11]
	v_pk_mul_f32 v[0:1], v[4:5], v[0:1]
	v_pk_mul_f32 v[2:3], v[6:7], v[2:3]
	s_mov_b64 s[24:25], -1
	s_andn2_b64 vcc, exec, s[4:5]
	s_waitcnt vmcnt(0)
	v_ffbh_u32_e32 v139, v149
	v_min_u32_e32 v139, 32, v139
	v_lshlrev_b64 v[148:149], v139, v[148:149]
	v_min_u32_e32 v148, 1, v148
	v_or_b32_e32 v148, v149, v148
	v_cvt_f32_u32_e32 v148, v148
	v_sub_u32_e32 v139, 32, v139
	v_ldexp_f32 v139, v148, v139
	v_fmamk_f32 v139, v139, 0x2e000000, v239
	v_rsq_f32_e32 v139, v139
	s_nop 0
	v_mul_f32_e32 v148, 0xbfb8aa3b, v139
	v_pk_mul_f32 v[152:153], v[124:125], v[148:149] op_sel_hi:[1,0]
	v_mul_f32_e32 v150, v139, v139
	v_exp_f32_e32 v152, v152
	v_exp_f32_e32 v153, v153
	s_nop 0
	v_pk_add_f32 v[152:153], v[152:153], 1.0 op_sel_hi:[1,0]
	s_nop 0
	v_rcp_f32_e32 v152, v152
	v_rcp_f32_e32 v153, v153
	s_nop 0
	v_pk_mul_f32 v[124:125], v[150:151], v[152:153] op_sel_hi:[0,1]
	v_pk_mul_f32 v[120:121], v[120:121], v[124:125]
	v_pk_mul_f32 v[124:125], v[126:127], v[148:149] op_sel_hi:[1,0]
	s_nop 0
	v_exp_f32_e32 v124, v124
	v_exp_f32_e32 v125, v125
	s_nop 0
	v_pk_add_f32 v[124:125], v[124:125], 1.0 op_sel_hi:[1,0]
	s_nop 0
	v_rcp_f32_e32 v124, v124
	v_rcp_f32_e32 v125, v125
	s_nop 0
	v_pk_mul_f32 v[124:125], v[150:151], v[124:125] op_sel_hi:[0,1]
	v_pk_mul_f32 v[122:123], v[122:123], v[124:125]
	v_pk_mul_f32 v[124:125], v[116:117], v[148:149] op_sel_hi:[1,0]
	s_nop 0
	v_exp_f32_e32 v124, v124
	v_exp_f32_e32 v125, v125
	s_nop 0
	v_pk_add_f32 v[124:125], v[124:125], 1.0 op_sel_hi:[1,0]
	s_nop 0
	v_rcp_f32_e32 v124, v124
	v_rcp_f32_e32 v125, v125
	s_nop 0
	v_pk_mul_f32 v[116:117], v[150:151], v[124:125] op_sel_hi:[0,1]
	v_pk_mul_f32 v[116:117], v[112:113], v[116:117]
	v_pk_mul_f32 v[112:113], v[118:119], v[148:149] op_sel_hi:[1,0]
	s_nop 0
	v_exp_f32_e32 v112, v112
	v_exp_f32_e32 v113, v113
	s_nop 0
	v_pk_add_f32 v[112:113], v[112:113], 1.0 op_sel_hi:[1,0]
	s_nop 0
	v_rcp_f32_e32 v112, v112
	v_rcp_f32_e32 v113, v113
	s_nop 0
	v_pk_mul_f32 v[112:113], v[150:151], v[112:113] op_sel_hi:[0,1]
	v_pk_mul_f32 v[118:119], v[114:115], v[112:113]
	v_cvt_pk_bf16_f32 v114, v116, v117
	v_mov_b64_e32 v[116:117], s[64:65]
	v_cvt_pk_bf16_f32 v112, v120, v121
	v_cvt_pk_bf16_f32 v115, v118, v119
	v_mad_i64_i32 v[120:121], s[2:3], v138, s50, v[116:117]
	v_lshlrev_b64 v[118:119], 1, v[142:143]
	v_cvt_pk_bf16_f32 v113, v122, v123
	v_lshl_add_u64 v[120:121], v[120:121], 0, v[118:119]
	global_store_dwordx4 v[120:121], v[112:115], off sc1
	s_nop 1
	v_mov_b64_e32 v[112:113], v[170:171]
	s_nop 0
	v_or_b32_e32 v115, 16, v138
	v_ffbh_u32_e32 v114, v113
	v_min_u32_e32 v114, 32, v114
	v_lshlrev_b64 v[112:113], v114, v[112:113]
	v_min_u32_e32 v112, 1, v112
	v_or_b32_e32 v112, v113, v112
	v_cvt_f32_u32_e32 v112, v112
	v_sub_u32_e32 v113, 32, v114
	v_ldexp_f32 v112, v112, v113
	v_fmamk_f32 v112, v112, 0x2e000000, v239
	v_rsq_f32_e32 v113, v112
	s_nop 0
	v_mul_f32_e32 v112, 0xbfb8aa3b, v113
	v_pk_mul_f32 v[120:121], v[108:109], v[112:113] op_sel_hi:[1,0]
	v_mul_f32_e32 v114, v113, v113
	v_exp_f32_e32 v120, v120
	v_exp_f32_e32 v121, v121
	s_nop 0
	v_pk_add_f32 v[120:121], v[120:121], 1.0 op_sel_hi:[1,0]
	s_nop 0
	v_rcp_f32_e32 v120, v120
	v_rcp_f32_e32 v121, v121
	s_nop 0
	v_pk_mul_f32 v[108:109], v[114:115], v[120:121] op_sel_hi:[0,1]
	v_pk_mul_f32 v[104:105], v[104:105], v[108:109]
	v_pk_mul_f32 v[108:109], v[110:111], v[112:113] op_sel_hi:[1,0]
	s_nop 0
	v_exp_f32_e32 v108, v108
	v_exp_f32_e32 v109, v109
	s_nop 0
	v_pk_add_f32 v[108:109], v[108:109], 1.0 op_sel_hi:[1,0]
	s_nop 0
	v_rcp_f32_e32 v108, v108
	v_rcp_f32_e32 v109, v109
	s_nop 0
	v_pk_mul_f32 v[108:109], v[114:115], v[108:109] op_sel_hi:[0,1]
	v_pk_mul_f32 v[106:107], v[106:107], v[108:109]
; __device__ __forceinline__ unsigned cvt_pk_bf16(float lo, float hi) { const f32x2_t v = {lo, hi}; const bf16x2_t b = __builtin_convertvector(v, bf16x2_t); return __builtin_bit_cast(unsigned, b); }
; __device__ __forceinline__ f32x2 swiglu2(f32x2 g, f32x2 u, float na, float rs2) { const f32x2 r = rcp_2(exp2_2(g * na) + 1.0f); return (g * u) * (r * rs2); }
; __device__ __forceinline__ float rstd_of(u64 ssq) { return frsq((float)ssq * (1.0f / (2048.0f * 16777216.0f)) + EPS); }
;     __device__ __forceinline__ void operator()(const Acc& acc, const Unit& u, int wr, int wc, int fr, int fq) const {
;     ...
;             for (int m = 0; m < 4; ++m) {
;                 asm volatile("" ::: "memory");
;                 const int r = row0 + ai * HALF + m * 16; const float rs = rstd_of(ssq[r]); const float na = -rs * LOG2E, rs2 = rs * rs;
;                 const f32x4 g0 = acc[ai][0][m][0], g1 = acc[ai][0][m][1], u0 = acc[ai][1][m][0], u1 = acc[ai][1][m][1];
;                 const f32x2 oa = swiglu2((f32x2){g0[0], g0[1]}, (f32x2){u0[0], u0[1]}, na, rs2), ob = swiglu2((f32x2){g0[2], g0[3]}, (f32x2){u0[2], u0[3]}, na, rs2);
;                 const f32x2 oc = swiglu2((f32x2){g1[0], g1[1]}, (f32x2){u1[0], u1[1]}, na, rs2), od = swiglu2((f32x2){g1[2], g1[3]}, (f32x2){u1[2], u1[3]}, na, rs2);
;                 u32x4 w; w.x = cvt_pk_bf16(oa.x, oa.y); w.y = cvt_pk_bf16(ob.x, ob.y); w.z = cvt_pk_bf16(oc.x, oc.y); w.w = cvt_pk_bf16(od.x, od.y);
;                 *(u32x4*)(O + (size_t)r * DFF + col0) = w;
	v_pk_mul_f32 v[108:109], v[100:101], v[112:113] op_sel_hi:[1,0]
	s_nop 0
	v_exp_f32_e32 v108, v108
	v_exp_f32_e32 v109, v109
	s_nop 0
	v_pk_add_f32 v[108:109], v[108:109], 1.0 op_sel_hi:[1,0]
	s_nop 0
	v_rcp_f32_e32 v108, v108
	v_rcp_f32_e32 v109, v109
	s_nop 0
	v_pk_mul_f32 v[100:101], v[114:115], v[108:109] op_sel_hi:[0,1]
	v_pk_mul_f32 v[100:101], v[96:97], v[100:101]
	v_pk_mul_f32 v[96:97], v[102:103], v[112:113] op_sel_hi:[1,0]
	s_nop 0
	v_exp_f32_e32 v96, v96
	v_exp_f32_e32 v97, v97
	s_nop 0
	v_pk_add_f32 v[96:97], v[96:97], 1.0 op_sel_hi:[1,0]
	s_nop 0
	v_rcp_f32_e32 v96, v96
	v_rcp_f32_e32 v97, v97
	s_nop 0
	v_pk_mul_f32 v[96:97], v[114:115], v[96:97] op_sel_hi:[0,1]
	v_pk_mul_f32 v[102:103], v[98:99], v[96:97]
	v_cvt_pk_bf16_f32 v98, v100, v101
	v_mad_i64_i32 v[100:101], s[2:3], v115, s50, v[116:117]
	v_cvt_pk_bf16_f32 v96, v104, v105
	v_cvt_pk_bf16_f32 v97, v106, v107
	v_cvt_pk_bf16_f32 v99, v102, v103
	v_lshl_add_u64 v[100:101], v[100:101], 0, v[118:119]
	global_store_dwordx4 v[100:101], v[96:99], off sc1
	s_nop 1
	v_mov_b64_e32 v[96:97], v[172:173]
	s_nop 0
	v_or_b32_e32 v99, 32, v138
	v_ffbh_u32_e32 v98, v97
	v_min_u32_e32 v98, 32, v98
	v_lshlrev_b64 v[96:97], v98, v[96:97]
	v_min_u32_e32 v96, 1, v96
	v_or_b32_e32 v96, v97, v96
	v_cvt_f32_u32_e32 v96, v96
	v_sub_u32_e32 v97, 32, v98
	v_ldexp_f32 v96, v96, v97
	v_fmamk_f32 v96, v96, 0x2e000000, v239
	v_rsq_f32_e32 v97, v96
	s_nop 0
	v_mul_f32_e32 v96, 0xbfb8aa3b, v97
	v_pk_mul_f32 v[100:101], v[92:93], v[96:97] op_sel_hi:[1,0]
	v_mul_f32_e32 v98, v97, v97
	v_exp_f32_e32 v100, v100
	v_exp_f32_e32 v101, v101
	s_nop 0
	v_pk_add_f32 v[100:101], v[100:101], 1.0 op_sel_hi:[1,0]
	s_nop 0
	v_rcp_f32_e32 v100, v100
	v_rcp_f32_e32 v101, v101
	s_nop 0
	v_pk_mul_f32 v[92:93], v[98:99], v[100:101] op_sel_hi:[0,1]
	v_pk_mul_f32 v[88:89], v[88:89], v[92:93]
	v_pk_mul_f32 v[92:93], v[94:95], v[96:97] op_sel_hi:[1,0]
	s_nop 0
	v_exp_f32_e32 v92, v92
	v_exp_f32_e32 v93, v93
	s_nop 0
	v_pk_add_f32 v[92:93], v[92:93], 1.0 op_sel_hi:[1,0]
	s_nop 0
	v_rcp_f32_e32 v92, v92
	v_rcp_f32_e32 v93, v93
	s_nop 0
	v_pk_mul_f32 v[92:93], v[98:99], v[92:93] op_sel_hi:[0,1]
	v_pk_mul_f32 v[90:91], v[90:91], v[92:93]
	v_pk_mul_f32 v[92:93], v[84:85], v[96:97] op_sel_hi:[1,0]
	s_nop 0
	v_exp_f32_e32 v92, v92
	v_exp_f32_e32 v93, v93
	s_nop 0
	v_pk_add_f32 v[92:93], v[92:93], 1.0 op_sel_hi:[1,0]
	s_nop 0
	v_rcp_f32_e32 v92, v92
	v_rcp_f32_e32 v93, v93
	s_nop 0
	v_pk_mul_f32 v[84:85], v[98:99], v[92:93] op_sel_hi:[0,1]
	v_pk_mul_f32 v[84:85], v[80:81], v[84:85]
	v_pk_mul_f32 v[80:81], v[86:87], v[96:97] op_sel_hi:[1,0]
	s_nop 0
	v_exp_f32_e32 v80, v80
	v_exp_f32_e32 v81, v81
	s_nop 0
	v_pk_add_f32 v[80:81], v[80:81], 1.0 op_sel_hi:[1,0]
	s_nop 0
	v_rcp_f32_e32 v80, v80
	v_rcp_f32_e32 v81, v81
	s_nop 0
	v_pk_mul_f32 v[80:81], v[98:99], v[80:81] op_sel_hi:[0,1]
	v_pk_mul_f32 v[86:87], v[82:83], v[80:81]
	v_cvt_pk_bf16_f32 v82, v84, v85
	v_mad_i64_i32 v[84:85], s[2:3], v99, s50, v[116:117]
	v_cvt_pk_bf16_f32 v80, v88, v89
	v_cvt_pk_bf16_f32 v81, v90, v91
	v_cvt_pk_bf16_f32 v83, v86, v87
	v_lshl_add_u64 v[84:85], v[84:85], 0, v[118:119]
	global_store_dwordx4 v[84:85], v[80:83], off sc1
	s_nop 1
	v_mov_b64_e32 v[80:81], v[174:175]
	s_nop 0
	v_or_b32_e32 v83, 48, v138
	v_ffbh_u32_e32 v82, v81
	v_min_u32_e32 v82, 32, v82
	v_lshlrev_b64 v[80:81], v82, v[80:81]
	v_min_u32_e32 v80, 1, v80
	v_or_b32_e32 v80, v81, v80
	v_cvt_f32_u32_e32 v80, v80
	v_sub_u32_e32 v81, 32, v82
	v_ldexp_f32 v80, v80, v81
	v_fmamk_f32 v80, v80, 0x2e000000, v239
	v_rsq_f32_e32 v81, v80
	s_nop 0
	v_mul_f32_e32 v80, 0xbfb8aa3b, v81
	v_pk_mul_f32 v[84:85], v[76:77], v[80:81] op_sel_hi:[1,0]
	v_mul_f32_e32 v82, v81, v81
	v_exp_f32_e32 v84, v84
	v_exp_f32_e32 v85, v85
	s_nop 0
	v_pk_add_f32 v[84:85], v[84:85], 1.0 op_sel_hi:[1,0]
	s_nop 0
	v_rcp_f32_e32 v84, v84
	v_rcp_f32_e32 v85, v85
	s_nop 0
	v_pk_mul_f32 v[76:77], v[82:83], v[84:85] op_sel_hi:[0,1]
	v_pk_mul_f32 v[72:73], v[72:73], v[76:77]
	v_pk_mul_f32 v[76:77], v[78:79], v[80:81] op_sel_hi:[1,0]
	s_nop 0
	v_exp_f32_e32 v76, v76
	v_exp_f32_e32 v77, v77
	s_nop 0
	v_pk_add_f32 v[76:77], v[76:77], 1.0 op_sel_hi:[1,0]
	s_nop 0
	v_rcp_f32_e32 v76, v76
	v_rcp_f32_e32 v77, v77
	s_nop 0
	v_pk_mul_f32 v[76:77], v[82:83], v[76:77] op_sel_hi:[0,1]
	v_pk_mul_f32 v[74:75], v[74:75], v[76:77]
	v_pk_mul_f32 v[76:77], v[68:69], v[80:81] op_sel_hi:[1,0]
	s_nop 0
	v_exp_f32_e32 v76, v76
	v_exp_f32_e32 v77, v77
	s_nop 0
	v_pk_add_f32 v[76:77], v[76:77], 1.0 op_sel_hi:[1,0]
	s_nop 0
	v_rcp_f32_e32 v76, v76
	v_rcp_f32_e32 v77, v77
	s_nop 0
	v_pk_mul_f32 v[68:69], v[82:83], v[76:77] op_sel_hi:[0,1]
	v_pk_mul_f32 v[68:69], v[64:65], v[68:69]
	v_pk_mul_f32 v[64:65], v[70:71], v[80:81] op_sel_hi:[1,0]
	s_nop 0
	v_exp_f32_e32 v64, v64
	v_exp_f32_e32 v65, v65
	s_nop 0
	v_pk_add_f32 v[64:65], v[64:65], 1.0 op_sel_hi:[1,0]
	s_nop 0
	v_rcp_f32_e32 v64, v64
	v_rcp_f32_e32 v65, v65
	s_nop 0
	v_pk_mul_f32 v[64:65], v[82:83], v[64:65] op_sel_hi:[0,1]
	v_pk_mul_f32 v[70:71], v[66:67], v[64:65]
	v_cvt_pk_bf16_f32 v66, v68, v69
	v_mad_i64_i32 v[68:69], s[2:3], v83, s50, v[116:117]
	v_cvt_pk_bf16_f32 v64, v72, v73
	v_cvt_pk_bf16_f32 v65, v74, v75
	v_cvt_pk_bf16_f32 v67, v70, v71
	v_lshl_add_u64 v[68:69], v[68:69], 0, v[118:119]
	global_store_dwordx4 v[68:69], v[64:67], off sc1
	s_nop 1
	v_mov_b64_e32 v[64:65], v[176:177]
	s_nop 0
	v_add_u32_e32 v67, 0x80, v138
	v_ffbh_u32_e32 v66, v65
	v_min_u32_e32 v66, 32, v66
	v_lshlrev_b64 v[64:65], v66, v[64:65]
	v_min_u32_e32 v64, 1, v64
	v_or_b32_e32 v64, v65, v64
	v_cvt_f32_u32_e32 v64, v64
	v_sub_u32_e32 v65, 32, v66
	v_ldexp_f32 v64, v64, v65
	v_fmamk_f32 v64, v64, 0x2e000000, v239
; __device__ __forceinline__ unsigned cvt_pk_bf16(float lo, float hi) { const f32x2_t v = {lo, hi}; const bf16x2_t b = __builtin_convertvector(v, bf16x2_t); return __builtin_bit_cast(unsigned, b); }
; __device__ __forceinline__ f32x2 swiglu2(f32x2 g, f32x2 u, float na, float rs2) { const f32x2 r = rcp_2(exp2_2(g * na) + 1.0f); return (g * u) * (r * rs2); }
; __device__ __forceinline__ float rstd_of(u64 ssq) { return frsq((float)ssq * (1.0f / (2048.0f * 16777216.0f)) + EPS); }
;     __device__ __forceinline__ void operator()(const Acc& acc, const Unit& u, int wr, int wc, int fr, int fq) const {
;     ...
;             for (int m = 0; m < 4; ++m) {
;                 asm volatile("" ::: "memory");
;                 const int r = row0 + ai * HALF + m * 16; const float rs = rstd_of(ssq[r]); const float na = -rs * LOG2E, rs2 = rs * rs;
;                 const f32x4 g0 = acc[ai][0][m][0], g1 = acc[ai][0][m][1], u0 = acc[ai][1][m][0], u1 = acc[ai][1][m][1];
;                 const f32x2 oa = swiglu2((f32x2){g0[0], g0[1]}, (f32x2){u0[0], u0[1]}, na, rs2), ob = swiglu2((f32x2){g0[2], g0[3]}, (f32x2){u0[2], u0[3]}, na, rs2);
;                 const f32x2 oc = swiglu2((f32x2){g1[0], g1[1]}, (f32x2){u1[0], u1[1]}, na, rs2), od = swiglu2((f32x2){g1[2], g1[3]}, (f32x2){u1[2], u1[3]}, na, rs2);
;                 u32x4 w; w.x = cvt_pk_bf16(oa.x, oa.y); w.y = cvt_pk_bf16(ob.x, ob.y); w.z = cvt_pk_bf16(oc.x, oc.y); w.w = cvt_pk_bf16(od.x, od.y);
;                 *(u32x4*)(O + (size_t)r * DFF + col0) = w;
	v_rsq_f32_e32 v65, v64
	s_nop 0
	v_mul_f32_e32 v64, 0xbfb8aa3b, v65
	v_pk_mul_f32 v[68:69], v[60:61], v[64:65] op_sel_hi:[1,0]
	v_mul_f32_e32 v66, v65, v65
	v_exp_f32_e32 v68, v68
	v_exp_f32_e32 v69, v69
	s_nop 0
	v_pk_add_f32 v[68:69], v[68:69], 1.0 op_sel_hi:[1,0]
	s_nop 0
	v_rcp_f32_e32 v68, v68
	v_rcp_f32_e32 v69, v69
	s_nop 0
	v_pk_mul_f32 v[60:61], v[66:67], v[68:69] op_sel_hi:[0,1]
	v_pk_mul_f32 v[56:57], v[56:57], v[60:61]
	v_pk_mul_f32 v[60:61], v[62:63], v[64:65] op_sel_hi:[1,0]
	s_nop 0
	v_exp_f32_e32 v60, v60
	v_exp_f32_e32 v61, v61
	s_nop 0
	v_pk_add_f32 v[60:61], v[60:61], 1.0 op_sel_hi:[1,0]
	s_nop 0
	v_rcp_f32_e32 v60, v60
	v_rcp_f32_e32 v61, v61
	s_nop 0
	v_pk_mul_f32 v[60:61], v[66:67], v[60:61] op_sel_hi:[0,1]
	v_pk_mul_f32 v[58:59], v[58:59], v[60:61]
	v_pk_mul_f32 v[60:61], v[52:53], v[64:65] op_sel_hi:[1,0]
	s_nop 0
	v_exp_f32_e32 v60, v60
	v_exp_f32_e32 v61, v61
	s_nop 0
	v_pk_add_f32 v[60:61], v[60:61], 1.0 op_sel_hi:[1,0]
	s_nop 0
	v_rcp_f32_e32 v60, v60
	v_rcp_f32_e32 v61, v61
	s_nop 0
	v_pk_mul_f32 v[52:53], v[66:67], v[60:61] op_sel_hi:[0,1]
	v_pk_mul_f32 v[52:53], v[48:49], v[52:53]
	v_pk_mul_f32 v[48:49], v[54:55], v[64:65] op_sel_hi:[1,0]
	s_nop 0
	v_exp_f32_e32 v48, v48
	v_exp_f32_e32 v49, v49
	s_nop 0
	v_pk_add_f32 v[48:49], v[48:49], 1.0 op_sel_hi:[1,0]
	s_nop 0
	v_rcp_f32_e32 v48, v48
	v_rcp_f32_e32 v49, v49
	s_nop 0
	v_pk_mul_f32 v[48:49], v[66:67], v[48:49] op_sel_hi:[0,1]
	v_pk_mul_f32 v[54:55], v[50:51], v[48:49]
	v_cvt_pk_bf16_f32 v50, v52, v53
	v_mad_i64_i32 v[52:53], s[2:3], v67, s50, v[116:117]
	v_cvt_pk_bf16_f32 v48, v56, v57
	v_cvt_pk_bf16_f32 v49, v58, v59
	v_cvt_pk_bf16_f32 v51, v54, v55
	v_lshl_add_u64 v[52:53], v[52:53], 0, v[118:119]
	global_store_dwordx4 v[52:53], v[48:51], off sc1
	s_nop 1
	v_mov_b64_e32 v[48:49], v[178:179]
	s_nop 0
	v_add_u32_e32 v51, 0x90, v138
	v_ffbh_u32_e32 v50, v49
	v_min_u32_e32 v50, 32, v50
	v_lshlrev_b64 v[48:49], v50, v[48:49]
	v_min_u32_e32 v48, 1, v48
	v_or_b32_e32 v48, v49, v48
	v_cvt_f32_u32_e32 v48, v48
	v_sub_u32_e32 v49, 32, v50
	v_ldexp_f32 v48, v48, v49
	v_fmamk_f32 v48, v48, 0x2e000000, v239
	v_rsq_f32_e32 v49, v48
	s_nop 0
	v_mul_f32_e32 v48, 0xbfb8aa3b, v49
	v_pk_mul_f32 v[52:53], v[44:45], v[48:49] op_sel_hi:[1,0]
	v_mul_f32_e32 v50, v49, v49
	v_exp_f32_e32 v52, v52
	v_exp_f32_e32 v53, v53
	s_nop 0
	v_pk_add_f32 v[52:53], v[52:53], 1.0 op_sel_hi:[1,0]
	s_nop 0
	v_rcp_f32_e32 v52, v52
	v_rcp_f32_e32 v53, v53
	s_nop 0
	v_pk_mul_f32 v[44:45], v[50:51], v[52:53] op_sel_hi:[0,1]
	v_pk_mul_f32 v[40:41], v[40:41], v[44:45]
	v_pk_mul_f32 v[44:45], v[46:47], v[48:49] op_sel_hi:[1,0]
	s_nop 0
	v_exp_f32_e32 v44, v44
	v_exp_f32_e32 v45, v45
	s_nop 0
	v_pk_add_f32 v[44:45], v[44:45], 1.0 op_sel_hi:[1,0]
	s_nop 0
	v_rcp_f32_e32 v44, v44
	v_rcp_f32_e32 v45, v45
	s_nop 0
	v_pk_mul_f32 v[44:45], v[50:51], v[44:45] op_sel_hi:[0,1]
	v_pk_mul_f32 v[42:43], v[42:43], v[44:45]
	v_pk_mul_f32 v[44:45], v[36:37], v[48:49] op_sel_hi:[1,0]
	s_nop 0
	v_exp_f32_e32 v44, v44
	v_exp_f32_e32 v45, v45
	s_nop 0
	v_pk_add_f32 v[44:45], v[44:45], 1.0 op_sel_hi:[1,0]
	s_nop 0
	v_rcp_f32_e32 v44, v44
	v_rcp_f32_e32 v45, v45
	s_nop 0
	v_pk_mul_f32 v[36:37], v[50:51], v[44:45] op_sel_hi:[0,1]
	v_pk_mul_f32 v[36:37], v[32:33], v[36:37]
	v_pk_mul_f32 v[32:33], v[38:39], v[48:49] op_sel_hi:[1,0]
	s_nop 0
	v_exp_f32_e32 v32, v32
	v_exp_f32_e32 v33, v33
	s_nop 0
	v_pk_add_f32 v[32:33], v[32:33], 1.0 op_sel_hi:[1,0]
	s_nop 0
	v_rcp_f32_e32 v32, v32
	v_rcp_f32_e32 v33, v33
	s_nop 0
	v_pk_mul_f32 v[32:33], v[50:51], v[32:33] op_sel_hi:[0,1]
	v_pk_mul_f32 v[38:39], v[34:35], v[32:33]
	v_cvt_pk_bf16_f32 v34, v36, v37
	v_mad_i64_i32 v[36:37], s[2:3], v51, s50, v[116:117]
	v_cvt_pk_bf16_f32 v32, v40, v41
	v_cvt_pk_bf16_f32 v33, v42, v43
	v_cvt_pk_bf16_f32 v35, v38, v39
	v_lshl_add_u64 v[36:37], v[36:37], 0, v[118:119]
	global_store_dwordx4 v[36:37], v[32:35], off sc1
	s_nop 1
	v_mov_b64_e32 v[32:33], v[180:181]
	s_nop 0
	v_add_u32_e32 v35, 0xa0, v138
	v_ffbh_u32_e32 v34, v33
	v_min_u32_e32 v34, 32, v34
	v_lshlrev_b64 v[32:33], v34, v[32:33]
	v_min_u32_e32 v32, 1, v32
; __device__ __forceinline__ unsigned cvt_pk_bf16(float lo, float hi) { const f32x2_t v = {lo, hi}; const bf16x2_t b = __builtin_convertvector(v, bf16x2_t); return __builtin_bit_cast(unsigned, b); }
; __device__ __forceinline__ f32x2 swiglu2(f32x2 g, f32x2 u, float na, float rs2) { const f32x2 r = rcp_2(exp2_2(g * na) + 1.0f); return (g * u) * (r * rs2); }
; __device__ __forceinline__ float rstd_of(u64 ssq) { return frsq((float)ssq * (1.0f / (2048.0f * 16777216.0f)) + EPS); }
;     __device__ __forceinline__ void operator()(const Acc& acc, const Unit& u, int wr, int wc, int fr, int fq) const {
;     ...
;             for (int m = 0; m < 4; ++m) {
;                 asm volatile("" ::: "memory");
;                 const int r = row0 + ai * HALF + m * 16; const float rs = rstd_of(ssq[r]); const float na = -rs * LOG2E, rs2 = rs * rs;
;                 const f32x4 g0 = acc[ai][0][m][0], g1 = acc[ai][0][m][1], u0 = acc[ai][1][m][0], u1 = acc[ai][1][m][1];
;                 const f32x2 oa = swiglu2((f32x2){g0[0], g0[1]}, (f32x2){u0[0], u0[1]}, na, rs2), ob = swiglu2((f32x2){g0[2], g0[3]}, (f32x2){u0[2], u0[3]}, na, rs2);
;                 const f32x2 oc = swiglu2((f32x2){g1[0], g1[1]}, (f32x2){u1[0], u1[1]}, na, rs2), od = swiglu2((f32x2){g1[2], g1[3]}, (f32x2){u1[2], u1[3]}, na, rs2);
;                 u32x4 w; w.x = cvt_pk_bf16(oa.x, oa.y); w.y = cvt_pk_bf16(ob.x, ob.y); w.z = cvt_pk_bf16(oc.x, oc.y); w.w = cvt_pk_bf16(od.x, od.y);
;                 *(u32x4*)(O + (size_t)r * DFF + col0) = w;
	v_or_b32_e32 v32, v33, v32
	v_cvt_f32_u32_e32 v32, v32
	v_sub_u32_e32 v33, 32, v34
	v_ldexp_f32 v32, v32, v33
	v_fmamk_f32 v32, v32, 0x2e000000, v239
	v_rsq_f32_e32 v33, v32
	s_nop 0
	v_mul_f32_e32 v32, 0xbfb8aa3b, v33
	v_pk_mul_f32 v[36:37], v[28:29], v[32:33] op_sel_hi:[1,0]
	v_mul_f32_e32 v34, v33, v33
	v_exp_f32_e32 v36, v36
	v_exp_f32_e32 v37, v37
	s_nop 0
	v_pk_add_f32 v[36:37], v[36:37], 1.0 op_sel_hi:[1,0]
	s_nop 0
	v_rcp_f32_e32 v36, v36
	v_rcp_f32_e32 v37, v37
	s_nop 0
	v_pk_mul_f32 v[28:29], v[34:35], v[36:37] op_sel_hi:[0,1]
	v_pk_mul_f32 v[24:25], v[24:25], v[28:29]
	v_pk_mul_f32 v[28:29], v[30:31], v[32:33] op_sel_hi:[1,0]
	s_nop 0
	v_exp_f32_e32 v28, v28
	v_exp_f32_e32 v29, v29
	s_nop 0
	v_pk_add_f32 v[28:29], v[28:29], 1.0 op_sel_hi:[1,0]
	s_nop 0
	v_rcp_f32_e32 v28, v28
	v_rcp_f32_e32 v29, v29
	s_nop 0
	v_pk_mul_f32 v[28:29], v[34:35], v[28:29] op_sel_hi:[0,1]
	v_pk_mul_f32 v[26:27], v[26:27], v[28:29]
	v_pk_mul_f32 v[28:29], v[20:21], v[32:33] op_sel_hi:[1,0]
	s_nop 0
	v_exp_f32_e32 v28, v28
	v_exp_f32_e32 v29, v29
	s_nop 0
	v_pk_add_f32 v[28:29], v[28:29], 1.0 op_sel_hi:[1,0]
	s_nop 0
	v_rcp_f32_e32 v28, v28
	v_rcp_f32_e32 v29, v29
	s_nop 0
	v_pk_mul_f32 v[20:21], v[34:35], v[28:29] op_sel_hi:[0,1]
	v_pk_mul_f32 v[20:21], v[16:17], v[20:21]
	v_pk_mul_f32 v[16:17], v[22:23], v[32:33] op_sel_hi:[1,0]
	s_nop 0
	v_exp_f32_e32 v16, v16
	v_exp_f32_e32 v17, v17
	s_nop 0
	v_pk_add_f32 v[16:17], v[16:17], 1.0 op_sel_hi:[1,0]
	s_nop 0
	v_rcp_f32_e32 v16, v16
	v_rcp_f32_e32 v17, v17
	s_nop 0
	v_pk_mul_f32 v[16:17], v[34:35], v[16:17] op_sel_hi:[0,1]
	v_pk_mul_f32 v[22:23], v[18:19], v[16:17]
	v_cvt_pk_bf16_f32 v18, v20, v21
	v_mad_i64_i32 v[20:21], s[2:3], v35, s50, v[116:117]
	v_cvt_pk_bf16_f32 v16, v24, v25
	v_cvt_pk_bf16_f32 v17, v26, v27
	v_cvt_pk_bf16_f32 v19, v22, v23
	v_lshl_add_u64 v[20:21], v[20:21], 0, v[118:119]
	global_store_dwordx4 v[20:21], v[16:19], off sc1
	s_nop 1
	v_mov_b64_e32 v[16:17], v[182:183]
	s_nop 0
	v_add_u32_e32 v19, 0xb0, v138
	v_ffbh_u32_e32 v18, v17
	v_min_u32_e32 v18, 32, v18
	v_lshlrev_b64 v[16:17], v18, v[16:17]
	v_min_u32_e32 v16, 1, v16
	v_or_b32_e32 v16, v17, v16
	v_cvt_f32_u32_e32 v16, v16
	v_sub_u32_e32 v17, 32, v18
	v_ldexp_f32 v16, v16, v17
	v_fmamk_f32 v16, v16, 0x2e000000, v239
	v_rsq_f32_e32 v17, v16
	s_nop 0
	v_mul_f32_e32 v16, 0xbfb8aa3b, v17
	v_pk_mul_f32 v[20:21], v[12:13], v[16:17] op_sel_hi:[1,0]
	v_mul_f32_e32 v18, v17, v17
	v_exp_f32_e32 v20, v20
	v_exp_f32_e32 v21, v21
	s_nop 0
	v_pk_add_f32 v[20:21], v[20:21], 1.0 op_sel_hi:[1,0]
	s_nop 0
	v_rcp_f32_e32 v20, v20
	v_rcp_f32_e32 v21, v21
	s_nop 0
	v_pk_mul_f32 v[12:13], v[18:19], v[20:21] op_sel_hi:[0,1]
	v_pk_mul_f32 v[8:9], v[8:9], v[12:13]
	v_pk_mul_f32 v[12:13], v[14:15], v[16:17] op_sel_hi:[1,0]
	s_nop 0
	v_exp_f32_e32 v12, v12
	v_exp_f32_e32 v13, v13
	s_nop 0
	v_pk_add_f32 v[12:13], v[12:13], 1.0 op_sel_hi:[1,0]
	s_nop 0
	v_rcp_f32_e32 v12, v12
	v_rcp_f32_e32 v13, v13
	s_nop 0
	v_pk_mul_f32 v[12:13], v[18:19], v[12:13] op_sel_hi:[0,1]
	v_pk_mul_f32 v[10:11], v[10:11], v[12:13]
	v_pk_mul_f32 v[12:13], v[4:5], v[16:17] op_sel_hi:[1,0]
	s_nop 0
	v_exp_f32_e32 v12, v12
	v_exp_f32_e32 v13, v13
	s_nop 0
	v_pk_add_f32 v[12:13], v[12:13], 1.0 op_sel_hi:[1,0]
	s_nop 0
	v_rcp_f32_e32 v12, v12
	v_rcp_f32_e32 v13, v13
	s_nop 0
	v_pk_mul_f32 v[4:5], v[18:19], v[12:13] op_sel_hi:[0,1]
	v_pk_mul_f32 v[4:5], v[0:1], v[4:5]
	v_pk_mul_f32 v[0:1], v[6:7], v[16:17] op_sel_hi:[1,0]
	s_nop 0
	v_exp_f32_e32 v0, v0
	v_exp_f32_e32 v1, v1
	s_nop 0
	v_pk_add_f32 v[0:1], v[0:1], 1.0 op_sel_hi:[1,0]
	s_nop 0
	v_rcp_f32_e32 v0, v0
	v_rcp_f32_e32 v1, v1
	s_nop 0
	v_pk_mul_f32 v[0:1], v[18:19], v[0:1] op_sel_hi:[0,1]
	v_pk_mul_f32 v[6:7], v[2:3], v[0:1]
	v_cvt_pk_bf16_f32 v2, v4, v5
	v_mad_i64_i32 v[4:5], s[2:3], v19, s50, v[116:117]
	v_cvt_pk_bf16_f32 v0, v8, v9
	v_cvt_pk_bf16_f32 v1, v10, v11
	v_cvt_pk_bf16_f32 v3, v6, v7
	v_lshl_add_u64 v[4:5], v[4:5], 0, v[118:119]
	global_store_dwordx4 v[4:5], v[0:3], off sc1
	s_cbranch_vccnz .LBB0_596
	s_andn2_b64 vcc, exec, s[6:7]
	s_cbranch_vccnz .LBB0_595
	s_barrier
	s_branch .LBB0_595
